# combo8 + GEMM K-loops use a static issue priority (younger wave half at 1, older at 0) instead of per-segment s_setprio flips
# speedup vs baseline: 1.0110x; 1.0002x over previous
; #define PG8_STAGE(bufoff, gbase, voff) do { _Pragma("unroll") for (int _i = 0; _i < 2; ++_i) \
;         __builtin_amdgcn_global_load_lds((const unsigned*)((const char*)(gbase) + (voff)[_i]), (LAS unsigned*)(lds + (bufoff) + ldsw + _i * 8192), 16, 0, 0); } while (0)
; #define PG8_LDA(dst, b, h) do { _Pragma("unroll") for (int m = 0; m < 4; ++m) _Pragma("unroll") for (int k = 0; k < 2; ++k) dst[m][k] = *(const LAS bf16x8*)(lds + PG8_SA(b, h) + aoff + m * 2048 + k * 1024); } while (0)
; #define PG8_LDB(dst, b, h) do { _Pragma("unroll") for (int n = 0; n < 2; ++n) _Pragma("unroll") for (int k = 0; k < 2; ++k) dst[n][k] = *(const LAS bf16x8*)(lds + PG8_SB(b, h) + boff + n * 2048 + k * 1024); } while (0)
; #define PG8_MMA(ai, bj, At, Bt) do { __builtin_amdgcn_s_setprio(1); _Pragma("unroll") for (int m = 0; m < 4; ++m) _Pragma("unroll") for (int n = 0; n < 2; ++n) _Pragma("unroll") for (int k = 0; k < 2; ++k) \
;         acc[ai][bj][m][n] = __builtin_amdgcn_mfma_f32_16x16x32_bf16(Bt[n][k], At[m][k], acc[ai][bj][m][n], 0, 0, 0); __builtin_amdgcn_s_setprio(0); } while (0)
; #define PG8_WAIT_V(n) asm volatile("s_waitcnt vmcnt(" #n ")" ::: "memory")
; #define PG8_WAIT_L(n) asm volatile("s_waitcnt lgkmcnt(" #n ")" ::: "memory")
; #define PG8_BAR __builtin_amdgcn_s_barrier()
; #define PG8_SCHED __builtin_amdgcn_sched_barrier(0)
; template <class Epi>
; __device__ __forceinline__ void gemm_phase(LAS unsigned char* lds, const Gemm g, const StaticOrder& S, const Epi& E, const int tid) {
;     ...
;         const bool has_next = S.next(ui + 1, nxt);
;         const char* nA = has_next ? PG8_APTR(nxt) : cA; const char* nB = has_next ? PG8_BPTR(nxt) : cB;
;         for (int t = 0; t < nt; t += 2) {
;             const bool last = (t == nt - 2);
;             const char* a1 = cA + (size_t)(t + 1) * kstep;
;             const char* a2 = last ? nA : cA + (size_t)(t + 2) * kstep; const char* b2 = last ? nB : cB + (size_t)(t + 2) * kstep;
;             const char* a3 = a2 + kstep; const char* b3 = b2 + kstep;
;             PG8_LDB(B0, 0, 0); PG8_LDB(B1, 0, 1); PG8_SCHED; PG8_LDA(At, 0, 0); PG8_STAGE(PG8_SA(1, 1), a1 + hsA, voffA);
;             PG8_WAIT_V(8); PG8_WAIT_L(0); PG8_BAR; PG8_MMA(0, 0, At, B0); PG8_MMA(0, 1, At, B1); PG8_BAR; PG8_SCHED;
.LBB0_160:
	s_ashr_i32 s15, s14, 31
	s_lshl_b64 s[16:17], s[14:15], 20
	s_add_u32 s16, s58, s16
	s_addc_u32 s17, s59, s17
	s_and_b64 s[18:19], s[36:37], exec
	s_cselect_b32 s15, s17, s35
	s_cselect_b32 s53, s16, s34
	s_ashr_i32 s13, s12, 31
	s_lshl_b64 s[18:19], s[12:13], 20
	s_add_u32 s18, s40, s18
	s_addc_u32 s19, s41, s19
	s_and_b64 s[38:39], s[36:37], exec
	s_cselect_b32 s13, s19, s1
	s_cselect_b32 s56, s18, s0
	s_add_u32 s34, s34, 0x80080
	s_addc_u32 s35, s35, 0
	s_add_u32 s57, s0, 0x100
	v_mov_b32_e32 v0, 0
	s_addc_u32 s58, s1, 0
	s_mov_b32 s59, -2
	v_mov_b32_e32 v1, v0
	v_mov_b32_e32 v2, v0
	v_mov_b32_e32 v3, v0
	v_mov_b32_e32 v8, v0
	v_mov_b32_e32 v9, v0
	v_mov_b32_e32 v10, v0
	v_mov_b32_e32 v11, v0
	v_mov_b32_e32 v16, v0
	v_mov_b32_e32 v17, v0
	v_mov_b32_e32 v18, v0
	v_mov_b32_e32 v19, v0
	v_mov_b32_e32 v24, v0
	v_mov_b32_e32 v25, v0
	v_mov_b32_e32 v26, v0
	v_mov_b32_e32 v27, v0
	v_mov_b32_e32 v32, v0
	v_mov_b32_e32 v33, v0
	v_mov_b32_e32 v34, v0
	v_mov_b32_e32 v35, v0
	v_mov_b32_e32 v40, v0
	v_mov_b32_e32 v41, v0
	v_mov_b32_e32 v42, v0
	v_mov_b32_e32 v43, v0
	v_mov_b32_e32 v48, v0
	v_mov_b32_e32 v49, v0
	v_mov_b32_e32 v50, v0
	v_mov_b32_e32 v51, v0
	v_mov_b32_e32 v56, v0
	v_mov_b32_e32 v57, v0
	v_mov_b32_e32 v58, v0
	v_mov_b32_e32 v59, v0
	v_mov_b32_e32 v4, v0
	v_mov_b32_e32 v5, v0
	v_mov_b32_e32 v6, v0
	v_mov_b32_e32 v7, v0
	v_mov_b32_e32 v12, v0
	v_mov_b32_e32 v13, v0
	v_mov_b32_e32 v14, v0
	v_mov_b32_e32 v15, v0
	v_mov_b32_e32 v20, v0
	v_mov_b32_e32 v21, v0
	v_mov_b32_e32 v22, v0
	v_mov_b32_e32 v23, v0
	v_mov_b32_e32 v28, v0
	v_mov_b32_e32 v29, v0
	v_mov_b32_e32 v30, v0
	v_mov_b32_e32 v31, v0
	v_mov_b32_e32 v36, v0
	v_mov_b32_e32 v37, v0
	v_mov_b32_e32 v38, v0
	v_mov_b32_e32 v39, v0
	v_mov_b32_e32 v44, v0
	v_mov_b32_e32 v45, v0
	v_mov_b32_e32 v46, v0
	v_mov_b32_e32 v47, v0
	v_mov_b32_e32 v52, v0
	v_mov_b32_e32 v53, v0
	v_mov_b32_e32 v54, v0
	v_mov_b32_e32 v55, v0
	v_mov_b32_e32 v60, v0
	v_mov_b32_e32 v61, v0
	v_mov_b32_e32 v62, v0
	v_mov_b32_e32 v63, v0
	v_mov_b32_e32 v64, v0
	v_mov_b32_e32 v65, v0
	v_mov_b32_e32 v66, v0
	v_mov_b32_e32 v67, v0
	v_mov_b32_e32 v72, v0
	v_mov_b32_e32 v73, v0
	v_mov_b32_e32 v74, v0
	v_mov_b32_e32 v75, v0
	v_mov_b32_e32 v80, v0
	v_mov_b32_e32 v81, v0
	v_mov_b32_e32 v82, v0
	v_mov_b32_e32 v83, v0
	v_mov_b32_e32 v88, v0
	v_mov_b32_e32 v89, v0
	v_mov_b32_e32 v90, v0
	v_mov_b32_e32 v91, v0
	v_mov_b32_e32 v96, v0
	v_mov_b32_e32 v97, v0
	v_mov_b32_e32 v98, v0
	v_mov_b32_e32 v99, v0
	v_mov_b32_e32 v104, v0
	v_mov_b32_e32 v105, v0
	v_mov_b32_e32 v106, v0
	v_mov_b32_e32 v107, v0
	v_mov_b32_e32 v112, v0
	v_mov_b32_e32 v113, v0
	v_mov_b32_e32 v114, v0
	v_mov_b32_e32 v115, v0
	v_mov_b32_e32 v120, v0
	v_mov_b32_e32 v121, v0
	v_mov_b32_e32 v122, v0
	v_mov_b32_e32 v123, v0
	v_mov_b32_e32 v68, v0
	v_mov_b32_e32 v69, v0
	v_mov_b32_e32 v70, v0
	v_mov_b32_e32 v71, v0
	v_mov_b32_e32 v76, v0
	v_mov_b32_e32 v77, v0
	v_mov_b32_e32 v78, v0
	v_mov_b32_e32 v79, v0
	v_mov_b32_e32 v84, v0
	v_mov_b32_e32 v85, v0
	v_mov_b32_e32 v86, v0
	v_mov_b32_e32 v87, v0
	v_mov_b32_e32 v92, v0
	v_mov_b32_e32 v93, v0
	v_mov_b32_e32 v94, v0
	v_mov_b32_e32 v95, v0
	v_mov_b32_e32 v100, v0
	v_mov_b32_e32 v101, v0
	v_mov_b32_e32 v102, v0
	v_mov_b32_e32 v103, v0
	v_mov_b32_e32 v108, v0
	v_mov_b32_e32 v109, v0
	v_mov_b32_e32 v110, v0
	v_mov_b32_e32 v111, v0
	v_mov_b32_e32 v116, v0
	v_mov_b32_e32 v117, v0
	v_mov_b32_e32 v118, v0
	v_mov_b32_e32 v119, v0
	v_mov_b32_e32 v124, v0
	v_mov_b32_e32 v125, v0
	v_mov_b32_e32 v126, v0
	v_mov_b32_e32 v127, v0
	s_cmp_lg_u64 s[10:11], 0
	s_cbranch_scc1 .Lgprio_a
	s_setprio 1
.Lgprio_a:
.LBB0_161:
	s_add_u32 s0, s34, 0xfff80080
	s_addc_u32 s1, s35, -1
	s_add_i32 s24, 0, 0x10000
	s_cmp_eq_u32 s59, 28
	s_cselect_b32 s39, s15, s1
	s_cselect_b32 s38, s53, s0
	s_cselect_b32 s1, s13, s58
	s_cselect_b32 s0, s56, s57
	s_add_i32 s25, 0, 0x14000
	v_add_u32_e32 v154, s24, v143
	v_add_u32_e32 v166, s25, v143
	ds_read_b128 v[138:141], v154
	ds_read_b128 v[146:149], v154 offset:1024
	ds_read_b128 v[150:153], v154 offset:2048
	ds_read_b128 v[154:157], v154 offset:3072
	ds_read_b128 v[158:161], v166
	ds_read_b128 v[162:165], v166 offset:1024
	ds_read_b128 v[184:187], v166 offset:2048
	ds_read_b128 v[188:191], v166 offset:3072
	v_lshl_add_u64 v[166:167], s[34:35], 0, v[134:135]
	s_add_i32 m0, s42, 0xc000
	ds_read_b128 v[192:195], v145
	ds_read_b128 v[196:199], v145 offset:1024
	ds_read_b128 v[200:203], v145 offset:2048
	ds_read_b128 v[204:207], v145 offset:3072
	ds_read_b128 v[208:211], v145 offset:4096
	ds_read_b128 v[230:233], v145 offset:5120
	ds_read_b128 v[234:237], v145 offset:6144
	ds_read_b128 v[238:241], v145 offset:7168
	global_load_lds_dwordx4 v[166:167], off
	v_lshl_add_u64 v[166:167], s[34:35], 0, v[136:137]
	s_add_i32 m0, s42, 0xe000
	s_nop 0
	global_load_lds_dwordx4 v[166:167], off
	s_waitcnt vmcnt(8)
	s_waitcnt lgkmcnt(0)
	s_barrier
; #define PG8_STAGE(bufoff, gbase, voff) do { _Pragma("unroll") for (int _i = 0; _i < 2; ++_i) \
;         __builtin_amdgcn_global_load_lds((const unsigned*)((const char*)(gbase) + (voff)[_i]), (LAS unsigned*)(lds + (bufoff) + ldsw + _i * 8192), 16, 0, 0); } while (0)
; #define PG8_LDA(dst, b, h) do { _Pragma("unroll") for (int m = 0; m < 4; ++m) _Pragma("unroll") for (int k = 0; k < 2; ++k) dst[m][k] = *(const LAS bf16x8*)(lds + PG8_SA(b, h) + aoff + m * 2048 + k * 1024); } while (0)
; #define PG8_MMA(ai, bj, At, Bt) do { __builtin_amdgcn_s_setprio(1); _Pragma("unroll") for (int m = 0; m < 4; ++m) _Pragma("unroll") for (int n = 0; n < 2; ++n) _Pragma("unroll") for (int k = 0; k < 2; ++k) \
;         acc[ai][bj][m][n] = __builtin_amdgcn_mfma_f32_16x16x32_bf16(Bt[n][k], At[m][k], acc[ai][bj][m][n], 0, 0, 0); __builtin_amdgcn_s_setprio(0); } while (0)
; #define PG8_WAIT_V(n) asm volatile("s_waitcnt vmcnt(" #n ")" ::: "memory")
; #define PG8_WAIT_L(n) asm volatile("s_waitcnt lgkmcnt(" #n ")" ::: "memory")
; #define PG8_BAR __builtin_amdgcn_s_barrier()
; #define PG8_SCHED __builtin_amdgcn_sched_barrier(0)
; template <class Epi>
; __device__ __forceinline__ void gemm_phase(LAS unsigned char* lds, const Gemm g, const StaticOrder& S, const Epi& E, const int tid) {
;     ...
;             PG8_WAIT_V(8); PG8_WAIT_L(0); PG8_BAR; PG8_MMA(0, 0, At, B0); PG8_MMA(0, 1, At, B1); PG8_BAR; PG8_SCHED;
;             PG8_LDA(At, 0, 1); PG8_STAGE(PG8_SB(0, 0), b2, voffB); PG8_STAGE(PG8_SB(0, 1), b2 + hsB, voffB); PG8_STAGE(PG8_SA(0, 0), a2, voffA);
;             PG8_WAIT_V(8); PG8_WAIT_L(0); PG8_BAR; PG8_MMA(1, 0, At, B0); PG8_MMA(1, 1, At, B1); PG8_BAR; PG8_SCHED;
	s_waitcnt lgkmcnt(0)
	v_mfma_f32_16x16x32_bf16 v[124:127], v[138:141], v[192:195], v[124:127]
	v_mfma_f32_16x16x32_bf16 v[116:119], v[150:153], v[192:195], v[116:119]
	v_mfma_f32_16x16x32_bf16 v[108:111], v[138:141], v[200:203], v[108:111]
	v_mfma_f32_16x16x32_bf16 v[100:103], v[150:153], v[200:203], v[100:103]
	v_mfma_f32_16x16x32_bf16 v[92:95], v[138:141], v[208:211], v[92:95]
	v_mfma_f32_16x16x32_bf16 v[84:87], v[150:153], v[208:211], v[84:87]
	v_mfma_f32_16x16x32_bf16 v[76:79], v[138:141], v[234:237], v[76:79]
	v_mfma_f32_16x16x32_bf16 v[68:71], v[150:153], v[234:237], v[68:71]
	v_mfma_f32_16x16x32_bf16 v[124:127], v[146:149], v[196:199], v[124:127]
	v_mfma_f32_16x16x32_bf16 v[116:119], v[154:157], v[196:199], v[116:119]
	v_mfma_f32_16x16x32_bf16 v[108:111], v[146:149], v[204:207], v[108:111]
	v_mfma_f32_16x16x32_bf16 v[100:103], v[154:157], v[204:207], v[100:103]
	v_mfma_f32_16x16x32_bf16 v[92:95], v[146:149], v[230:233], v[92:95]
	v_mfma_f32_16x16x32_bf16 v[84:87], v[154:157], v[230:233], v[84:87]
	v_mfma_f32_16x16x32_bf16 v[76:79], v[146:149], v[238:241], v[76:79]
	v_mfma_f32_16x16x32_bf16 v[68:71], v[154:157], v[238:241], v[68:71]
	v_mfma_f32_16x16x32_bf16 v[120:123], v[158:161], v[192:195], v[120:123]
	v_mfma_f32_16x16x32_bf16 v[112:115], v[184:187], v[192:195], v[112:115]
	v_mfma_f32_16x16x32_bf16 v[104:107], v[158:161], v[200:203], v[104:107]
	v_mfma_f32_16x16x32_bf16 v[96:99], v[184:187], v[200:203], v[96:99]
	v_mfma_f32_16x16x32_bf16 v[88:91], v[158:161], v[208:211], v[88:91]
	v_mfma_f32_16x16x32_bf16 v[80:83], v[184:187], v[208:211], v[80:83]
	v_mfma_f32_16x16x32_bf16 v[72:75], v[158:161], v[234:237], v[72:75]
	v_mfma_f32_16x16x32_bf16 v[64:67], v[184:187], v[234:237], v[64:67]
	v_mfma_f32_16x16x32_bf16 v[120:123], v[162:165], v[196:199], v[120:123]
	v_mfma_f32_16x16x32_bf16 v[112:115], v[188:191], v[196:199], v[112:115]
	v_mfma_f32_16x16x32_bf16 v[104:107], v[162:165], v[204:207], v[104:107]
	v_mfma_f32_16x16x32_bf16 v[96:99], v[188:191], v[204:207], v[96:99]
	v_mfma_f32_16x16x32_bf16 v[88:91], v[162:165], v[230:233], v[88:91]
	v_mfma_f32_16x16x32_bf16 v[80:83], v[188:191], v[230:233], v[80:83]
	v_mfma_f32_16x16x32_bf16 v[72:75], v[162:165], v[238:241], v[72:75]
	v_mfma_f32_16x16x32_bf16 v[64:67], v[188:191], v[238:241], v[64:67]
	s_barrier
	s_add_i32 s24, s24, s27
	v_lshl_add_u64 v[166:167], s[0:1], 0, v[168:169]
	s_mov_b32 m0, s24
	ds_read_b128 v[192:195], v145 offset:16384
	ds_read_b128 v[196:199], v145 offset:17408
	ds_read_b128 v[200:203], v145 offset:18432
	ds_read_b128 v[204:207], v145 offset:19456
	ds_read_b128 v[208:211], v145 offset:20480
	ds_read_b128 v[230:233], v145 offset:21504
	ds_read_b128 v[234:237], v145 offset:22528
	ds_read_b128 v[238:241], v145 offset:23552
	global_load_lds_dwordx4 v[166:167], off
	s_add_i32 m0, s24, 0x2000
	s_add_u32 s68, s0, 0x80000
	v_lshl_add_u64 v[212:213], s[0:1], 0, v[132:133]
	s_addc_u32 s69, s1, 0
	s_add_i32 s24, s25, s27
	global_load_lds_dwordx4 v[212:213], off
	v_lshl_add_u64 v[242:243], s[68:69], 0, v[168:169]
	s_mov_b32 m0, s24
	v_lshl_add_u64 v[244:245], s[38:39], 0, v[130:131]
	global_load_lds_dwordx4 v[242:243], off
	v_lshl_add_u64 v[242:243], s[68:69], 0, v[132:133]
	s_add_i32 m0, s24, 0x2000
	s_nop 0
	global_load_lds_dwordx4 v[242:243], off
	v_lshl_add_u64 v[242:243], s[38:39], 0, v[128:129]
	s_mov_b32 m0, s42
	s_nop 0
	global_load_lds_dwordx4 v[242:243], off
	s_mov_b32 m0, s43
	s_nop 0
	global_load_lds_dwordx4 v[244:245], off
	s_waitcnt vmcnt(8)
	s_waitcnt lgkmcnt(0)
	s_barrier
	s_waitcnt lgkmcnt(0)
	v_mfma_f32_16x16x32_bf16 v[60:63], v[138:141], v[192:195], v[60:63]
	v_mfma_f32_16x16x32_bf16 v[52:55], v[150:153], v[192:195], v[52:55]
	v_mfma_f32_16x16x32_bf16 v[44:47], v[138:141], v[200:203], v[44:47]
	v_mfma_f32_16x16x32_bf16 v[36:39], v[150:153], v[200:203], v[36:39]
	v_mfma_f32_16x16x32_bf16 v[28:31], v[138:141], v[208:211], v[28:31]
	v_mfma_f32_16x16x32_bf16 v[20:23], v[150:153], v[208:211], v[20:23]
	v_mfma_f32_16x16x32_bf16 v[12:15], v[138:141], v[234:237], v[12:15]
	v_mfma_f32_16x16x32_bf16 v[4:7], v[150:153], v[234:237], v[4:7]
	v_mfma_f32_16x16x32_bf16 v[60:63], v[146:149], v[196:199], v[60:63]
	v_mfma_f32_16x16x32_bf16 v[52:55], v[154:157], v[196:199], v[52:55]
	v_mfma_f32_16x16x32_bf16 v[44:47], v[146:149], v[204:207], v[44:47]
	v_mfma_f32_16x16x32_bf16 v[36:39], v[154:157], v[204:207], v[36:39]
	v_mfma_f32_16x16x32_bf16 v[28:31], v[146:149], v[230:233], v[28:31]
	v_mfma_f32_16x16x32_bf16 v[20:23], v[154:157], v[230:233], v[20:23]
	v_mfma_f32_16x16x32_bf16 v[12:15], v[146:149], v[238:241], v[12:15]
	v_mfma_f32_16x16x32_bf16 v[4:7], v[154:157], v[238:241], v[4:7]
	v_mfma_f32_16x16x32_bf16 v[56:59], v[158:161], v[192:195], v[56:59]
	v_mfma_f32_16x16x32_bf16 v[48:51], v[184:187], v[192:195], v[48:51]
	v_mfma_f32_16x16x32_bf16 v[40:43], v[158:161], v[200:203], v[40:43]
	v_mfma_f32_16x16x32_bf16 v[32:35], v[184:187], v[200:203], v[32:35]
	v_mfma_f32_16x16x32_bf16 v[24:27], v[158:161], v[208:211], v[24:27]
	v_mfma_f32_16x16x32_bf16 v[16:19], v[184:187], v[208:211], v[16:19]
	v_mfma_f32_16x16x32_bf16 v[8:11], v[158:161], v[234:237], v[8:11]
	v_mfma_f32_16x16x32_bf16 v[0:3], v[184:187], v[234:237], v[0:3]
	v_mfma_f32_16x16x32_bf16 v[56:59], v[162:165], v[196:199], v[56:59]
	v_mfma_f32_16x16x32_bf16 v[48:51], v[188:191], v[196:199], v[48:51]
	v_mfma_f32_16x16x32_bf16 v[40:43], v[162:165], v[204:207], v[40:43]
	v_mfma_f32_16x16x32_bf16 v[32:35], v[188:191], v[204:207], v[32:35]
	v_mfma_f32_16x16x32_bf16 v[24:27], v[162:165], v[230:233], v[24:27]
	v_mfma_f32_16x16x32_bf16 v[16:19], v[188:191], v[230:233], v[16:19]
	v_mfma_f32_16x16x32_bf16 v[8:11], v[162:165], v[238:241], v[8:11]
	v_mfma_f32_16x16x32_bf16 v[0:3], v[188:191], v[238:241], v[0:3]
	s_barrier
; #define PG8_STAGE(bufoff, gbase, voff) do { _Pragma("unroll") for (int _i = 0; _i < 2; ++_i) \
;         __builtin_amdgcn_global_load_lds((const unsigned*)((const char*)(gbase) + (voff)[_i]), (LAS unsigned*)(lds + (bufoff) + ldsw + _i * 8192), 16, 0, 0); } while (0)
; #define PG8_LDA(dst, b, h) do { _Pragma("unroll") for (int m = 0; m < 4; ++m) _Pragma("unroll") for (int k = 0; k < 2; ++k) dst[m][k] = *(const LAS bf16x8*)(lds + PG8_SA(b, h) + aoff + m * 2048 + k * 1024); } while (0)
; #define PG8_LDB(dst, b, h) do { _Pragma("unroll") for (int n = 0; n < 2; ++n) _Pragma("unroll") for (int k = 0; k < 2; ++k) dst[n][k] = *(const LAS bf16x8*)(lds + PG8_SB(b, h) + boff + n * 2048 + k * 1024); } while (0)
; #define PG8_MMA(ai, bj, At, Bt) do { __builtin_amdgcn_s_setprio(1); _Pragma("unroll") for (int m = 0; m < 4; ++m) _Pragma("unroll") for (int n = 0; n < 2; ++n) _Pragma("unroll") for (int k = 0; k < 2; ++k) \
;         acc[ai][bj][m][n] = __builtin_amdgcn_mfma_f32_16x16x32_bf16(Bt[n][k], At[m][k], acc[ai][bj][m][n], 0, 0, 0); __builtin_amdgcn_s_setprio(0); } while (0)
; #define PG8_WAIT_V(n) asm volatile("s_waitcnt vmcnt(" #n ")" ::: "memory")
; #define PG8_WAIT_L(n) asm volatile("s_waitcnt lgkmcnt(" #n ")" ::: "memory")
; #define PG8_BAR __builtin_amdgcn_s_barrier()
; #define PG8_SCHED __builtin_amdgcn_sched_barrier(0)
; template <class Epi>
; __device__ __forceinline__ void gemm_phase(LAS unsigned char* lds, const Gemm g, const StaticOrder& S, const Epi& E, const int tid) {
;     ...
;             PG8_LDB(B0, 1, 0); PG8_LDB(B1, 1, 1); PG8_SCHED; PG8_LDA(At, 1, 0); PG8_STAGE(PG8_SA(0, 1), a2 + hsA, voffA);
;             PG8_WAIT_V(8); PG8_WAIT_L(0); PG8_BAR; PG8_MMA(0, 0, At, B0); PG8_MMA(0, 1, At, B1); PG8_BAR; PG8_SCHED;
;             PG8_LDA(At, 1, 1); PG8_STAGE(PG8_SB(1, 0), b3, voffB); PG8_STAGE(PG8_SB(1, 1), b3 + hsB, voffB); PG8_STAGE(PG8_SA(1, 0), a3, voffA);
;             PG8_WAIT_V(8); PG8_WAIT_L(0); PG8_BAR; PG8_MMA(1, 0, At, B0); PG8_MMA(1, 1, At, B1); PG8_BAR; PG8_SCHED;
	s_add_i32 s24, 0, 0x18000
	s_add_i32 s25, 0, 0x1c000
	v_add_u32_e32 v154, s24, v143
	v_add_u32_e32 v170, s25, v143
	ds_read_b128 v[138:141], v154
	ds_read_b128 v[146:149], v154 offset:1024
	ds_read_b128 v[150:153], v154 offset:2048
	ds_read_b128 v[154:157], v154 offset:3072
	ds_read_b128 v[158:161], v170
	ds_read_b128 v[162:165], v170 offset:1024
	ds_read_b128 v[184:187], v170 offset:2048
	ds_read_b128 v[188:191], v170 offset:3072
	s_add_u32 s38, s38, 0x80000
	s_addc_u32 s39, s39, 0
	s_mov_b32 m0, s44
	v_lshl_add_u64 v[246:247], s[38:39], 0, v[128:129]
	ds_read_b128 v[192:195], v145 offset:32768
	ds_read_b128 v[196:199], v145 offset:33792
	ds_read_b128 v[200:203], v145 offset:34816
	ds_read_b128 v[204:207], v145 offset:35840
	ds_read_b128 v[208:211], v145 offset:36864
	ds_read_b128 v[230:233], v145 offset:37888
	ds_read_b128 v[234:237], v145 offset:38912
	ds_read_b128 v[238:241], v145 offset:39936
	global_load_lds_dwordx4 v[246:247], off
	v_lshl_add_u64 v[246:247], s[38:39], 0, v[130:131]
	s_mov_b32 m0, s45
	s_nop 0
	global_load_lds_dwordx4 v[246:247], off
	s_waitcnt vmcnt(8)
	s_waitcnt lgkmcnt(0)
	s_barrier
	s_waitcnt lgkmcnt(0)
	v_mfma_f32_16x16x32_bf16 v[124:127], v[138:141], v[192:195], v[124:127]
	v_mfma_f32_16x16x32_bf16 v[116:119], v[150:153], v[192:195], v[116:119]
	v_mfma_f32_16x16x32_bf16 v[108:111], v[138:141], v[200:203], v[108:111]
	v_mfma_f32_16x16x32_bf16 v[100:103], v[150:153], v[200:203], v[100:103]
	v_mfma_f32_16x16x32_bf16 v[92:95], v[138:141], v[208:211], v[92:95]
	v_mfma_f32_16x16x32_bf16 v[84:87], v[150:153], v[208:211], v[84:87]
	v_mfma_f32_16x16x32_bf16 v[76:79], v[138:141], v[234:237], v[76:79]
	v_mfma_f32_16x16x32_bf16 v[68:71], v[150:153], v[234:237], v[68:71]
	v_mfma_f32_16x16x32_bf16 v[124:127], v[146:149], v[196:199], v[124:127]
	v_mfma_f32_16x16x32_bf16 v[116:119], v[154:157], v[196:199], v[116:119]
	v_mfma_f32_16x16x32_bf16 v[108:111], v[146:149], v[204:207], v[108:111]
	v_mfma_f32_16x16x32_bf16 v[100:103], v[154:157], v[204:207], v[100:103]
	v_mfma_f32_16x16x32_bf16 v[92:95], v[146:149], v[230:233], v[92:95]
	v_mfma_f32_16x16x32_bf16 v[84:87], v[154:157], v[230:233], v[84:87]
	v_mfma_f32_16x16x32_bf16 v[76:79], v[146:149], v[238:241], v[76:79]
	v_mfma_f32_16x16x32_bf16 v[68:71], v[154:157], v[238:241], v[68:71]
	v_mfma_f32_16x16x32_bf16 v[120:123], v[158:161], v[192:195], v[120:123]
	v_mfma_f32_16x16x32_bf16 v[112:115], v[184:187], v[192:195], v[112:115]
	v_mfma_f32_16x16x32_bf16 v[104:107], v[158:161], v[200:203], v[104:107]
	v_mfma_f32_16x16x32_bf16 v[96:99], v[184:187], v[200:203], v[96:99]
	v_mfma_f32_16x16x32_bf16 v[88:91], v[158:161], v[208:211], v[88:91]
	v_mfma_f32_16x16x32_bf16 v[80:83], v[184:187], v[208:211], v[80:83]
	v_mfma_f32_16x16x32_bf16 v[72:75], v[158:161], v[234:237], v[72:75]
	v_mfma_f32_16x16x32_bf16 v[64:67], v[184:187], v[234:237], v[64:67]
	v_mfma_f32_16x16x32_bf16 v[120:123], v[162:165], v[196:199], v[120:123]
	v_mfma_f32_16x16x32_bf16 v[112:115], v[188:191], v[196:199], v[112:115]
	v_mfma_f32_16x16x32_bf16 v[104:107], v[162:165], v[204:207], v[104:107]
	v_mfma_f32_16x16x32_bf16 v[96:99], v[188:191], v[204:207], v[96:99]
	v_mfma_f32_16x16x32_bf16 v[88:91], v[162:165], v[230:233], v[88:91]
	v_mfma_f32_16x16x32_bf16 v[80:83], v[188:191], v[230:233], v[80:83]
	v_mfma_f32_16x16x32_bf16 v[72:75], v[162:165], v[238:241], v[72:75]
	v_mfma_f32_16x16x32_bf16 v[64:67], v[188:191], v[238:241], v[64:67]
	s_barrier
	s_add_i32 s24, s24, s27
	v_lshl_add_u64 v[166:167], v[166:167], 0, s[28:29]
	s_mov_b32 m0, s24
	ds_read_b128 v[192:195], v145 offset:49152
	ds_read_b128 v[196:199], v145 offset:50176
	ds_read_b128 v[200:203], v145 offset:51200
	ds_read_b128 v[204:207], v145 offset:52224
	ds_read_b128 v[208:211], v145 offset:53248
	ds_read_b128 v[230:233], v145 offset:54272
	ds_read_b128 v[234:237], v145 offset:55296
	ds_read_b128 v[238:241], v145 offset:56320
	global_load_lds_dwordx4 v[166:167], off
	s_add_i32 m0, s24, 0x2000
	s_add_u32 s0, s0, 0x80080
	v_lshl_add_u64 v[166:167], v[212:213], 0, s[28:29]
	s_addc_u32 s1, s1, 0
	s_add_i32 s24, s25, s27
	global_load_lds_dwordx4 v[166:167], off
	v_lshl_add_u64 v[166:167], s[0:1], 0, v[168:169]
	s_mov_b32 m0, s24
	s_nop 0
	global_load_lds_dwordx4 v[166:167], off
	v_lshl_add_u64 v[166:167], s[0:1], 0, v[132:133]
	s_add_i32 m0, s24, 0x2000
	s_nop 0
	global_load_lds_dwordx4 v[166:167], off
	v_lshl_add_u64 v[166:167], v[242:243], 0, s[28:29]
	s_mov_b32 m0, s46
	s_nop 0
	global_load_lds_dwordx4 v[166:167], off
	v_lshl_add_u64 v[166:167], v[244:245], 0, s[28:29]
	s_mov_b32 m0, s47
	s_nop 0
	global_load_lds_dwordx4 v[166:167], off
	s_waitcnt vmcnt(8)
	s_waitcnt lgkmcnt(0)
	s_barrier
; __device__ __forceinline__ unsigned cvt_pk_bf16(float lo, float hi) { unsigned r; asm volatile("v_cvt_pk_bf16_f32 %0, %1, %2" : "=v"(r) : "v"(lo), "v"(hi)); return r; }
; #define PG8_MMA(ai, bj, At, Bt) do { __builtin_amdgcn_s_setprio(1); _Pragma("unroll") for (int m = 0; m < 4; ++m) _Pragma("unroll") for (int n = 0; n < 2; ++n) _Pragma("unroll") for (int k = 0; k < 2; ++k) \
;         acc[ai][bj][m][n] = __builtin_amdgcn_mfma_f32_16x16x32_bf16(Bt[n][k], At[m][k], acc[ai][bj][m][n], 0, 0, 0); __builtin_amdgcn_s_setprio(0); } while (0)
; #define PG8_WAIT_V(n) asm volatile("s_waitcnt vmcnt(" #n ")" ::: "memory")
; #define PG8_WAIT_L(n) asm volatile("s_waitcnt lgkmcnt(" #n ")" ::: "memory")
; #define PG8_BAR __builtin_amdgcn_s_barrier()
; #define PG8_SCHED __builtin_amdgcn_sched_barrier(0)
; template <class Epi>
; __device__ __forceinline__ void gemm_phase(LAS unsigned char* lds, const Gemm g, const StaticOrder& S, const Epi& E, const int tid) {
;     ...
;             PG8_WAIT_V(8); PG8_WAIT_L(0); PG8_BAR; PG8_MMA(1, 0, At, B0); PG8_MMA(1, 1, At, B1); PG8_BAR; PG8_SCHED;
;         }
;         if (wr == 0) PG8_BAR;
;     __device__ __forceinline__ void operator()(f32x4 (&acc)[2][2][4][2], const Unit& u, int wr, int wc, int fr, int fq) const {
;     ...
;             for (int m = 0; m < 4; ++m) {
;                 bf16* rowp = O + (size_t)(row0 + ai * HALF + m * 16) * FF + col0;
;                 const f32x4 g0 = acc[ai][0][m][0], g1 = acc[ai][0][m][1], u0 = acc[ai][1][m][0], u1 = acc[ai][1][m][1];
;                 u32x4 w;
;                 const f32x4 a0 = swiglu4(g0, u0), a1 = swiglu4(g1, u1);
;                 w.x = cvt_pk_bf16(a0[0], a0[1]); w.y = cvt_pk_bf16(a0[2], a0[3]); w.z = cvt_pk_bf16(a1[0], a1[1]); w.w = cvt_pk_bf16(a1[2], a1[3]);
;                 __builtin_nontemporal_store(w, (u32x4*)rowp);
	s_waitcnt lgkmcnt(0)
	v_mfma_f32_16x16x32_bf16 v[60:63], v[138:141], v[192:195], v[60:63]
	v_mfma_f32_16x16x32_bf16 v[52:55], v[150:153], v[192:195], v[52:55]
	v_mfma_f32_16x16x32_bf16 v[44:47], v[138:141], v[200:203], v[44:47]
	v_mfma_f32_16x16x32_bf16 v[36:39], v[150:153], v[200:203], v[36:39]
	v_mfma_f32_16x16x32_bf16 v[28:31], v[138:141], v[208:211], v[28:31]
	v_mfma_f32_16x16x32_bf16 v[20:23], v[150:153], v[208:211], v[20:23]
	v_mfma_f32_16x16x32_bf16 v[12:15], v[138:141], v[234:237], v[12:15]
	v_mfma_f32_16x16x32_bf16 v[4:7], v[150:153], v[234:237], v[4:7]
	v_mfma_f32_16x16x32_bf16 v[60:63], v[146:149], v[196:199], v[60:63]
	v_mfma_f32_16x16x32_bf16 v[52:55], v[154:157], v[196:199], v[52:55]
	v_mfma_f32_16x16x32_bf16 v[44:47], v[146:149], v[204:207], v[44:47]
	v_mfma_f32_16x16x32_bf16 v[36:39], v[154:157], v[204:207], v[36:39]
	v_mfma_f32_16x16x32_bf16 v[28:31], v[146:149], v[230:233], v[28:31]
	v_mfma_f32_16x16x32_bf16 v[20:23], v[154:157], v[230:233], v[20:23]
	v_mfma_f32_16x16x32_bf16 v[12:15], v[146:149], v[238:241], v[12:15]
	v_mfma_f32_16x16x32_bf16 v[4:7], v[154:157], v[238:241], v[4:7]
	v_mfma_f32_16x16x32_bf16 v[56:59], v[158:161], v[192:195], v[56:59]
	v_mfma_f32_16x16x32_bf16 v[48:51], v[184:187], v[192:195], v[48:51]
	v_mfma_f32_16x16x32_bf16 v[40:43], v[158:161], v[200:203], v[40:43]
	v_mfma_f32_16x16x32_bf16 v[32:35], v[184:187], v[200:203], v[32:35]
	v_mfma_f32_16x16x32_bf16 v[24:27], v[158:161], v[208:211], v[24:27]
	v_mfma_f32_16x16x32_bf16 v[16:19], v[184:187], v[208:211], v[16:19]
	v_mfma_f32_16x16x32_bf16 v[8:11], v[158:161], v[234:237], v[8:11]
	v_mfma_f32_16x16x32_bf16 v[0:3], v[184:187], v[234:237], v[0:3]
	v_mfma_f32_16x16x32_bf16 v[56:59], v[162:165], v[196:199], v[56:59]
	v_mfma_f32_16x16x32_bf16 v[48:51], v[188:191], v[196:199], v[48:51]
	v_mfma_f32_16x16x32_bf16 v[40:43], v[162:165], v[204:207], v[40:43]
	v_mfma_f32_16x16x32_bf16 v[32:35], v[188:191], v[204:207], v[32:35]
	v_mfma_f32_16x16x32_bf16 v[24:27], v[162:165], v[230:233], v[24:27]
	v_mfma_f32_16x16x32_bf16 v[16:19], v[188:191], v[230:233], v[16:19]
	v_mfma_f32_16x16x32_bf16 v[8:11], v[162:165], v[238:241], v[8:11]
	v_mfma_f32_16x16x32_bf16 v[0:3], v[188:191], v[238:241], v[0:3]
	s_barrier
	s_add_i32 s59, s59, 2
	s_add_u32 s34, s34, 0x100
	s_addc_u32 s35, s35, 0
	s_add_u32 s57, s57, 0x100
	s_addc_u32 s58, s58, 0
	s_cmp_gt_u32 s59, 29
	s_cbranch_scc0 .LBB0_161
	s_and_b64 vcc, exec, s[10:11]
	s_cbranch_vccz .LBB0_164
	s_barrier
.LBB0_164:
	s_setprio 0
	v_pk_mul_f32 v[150:151], v[126:127], s[74:75] op_sel_hi:[1,0]
	v_pk_mul_f32 v[152:153], v[124:125], s[74:75] op_sel_hi:[1,0]
	v_pk_mul_f32 v[122:123], v[126:127], v[122:123]
	v_pk_mul_f32 v[120:121], v[124:125], v[120:121]
	v_pk_mul_f32 v[124:125], v[118:119], s[74:75] op_sel_hi:[1,0]
	v_pk_mul_f32 v[126:127], v[116:117], s[74:75] op_sel_hi:[1,0]
	v_exp_f32_e32 v124, v124
	v_exp_f32_e32 v126, v126
	v_exp_f32_e32 v125, v125
	v_exp_f32_e32 v127, v127
	v_exp_f32_e32 v152, v152
	v_exp_f32_e32 v150, v150
	v_exp_f32_e32 v151, v151
	v_exp_f32_e32 v153, v153
	v_pk_add_f32 v[124:125], v[124:125], 1.0 op_sel_hi:[1,0]
	v_pk_add_f32 v[126:127], v[126:127], 1.0 op_sel_hi:[1,0]
	v_pk_add_f32 v[150:151], v[150:151], 1.0 op_sel_hi:[1,0]
	v_pk_add_f32 v[152:153], v[152:153], 1.0 op_sel_hi:[1,0]
	v_rcp_f32_e32 v126, v126
	v_rcp_f32_e32 v124, v124
	v_rcp_f32_e32 v125, v125
	v_rcp_f32_e32 v127, v127
	v_readlane_b32 s0, v254, 23
	v_rcp_f32_e32 v152, v152
	v_rcp_f32_e32 v153, v153
	v_rcp_f32_e32 v150, v150
	v_rcp_f32_e32 v151, v151
	v_lshl_or_b32 v140, s49, 7, v144
	v_readlane_b32 s1, v254, 24
	v_lshl_add_u32 v146, s52, 8, v142
	v_ashrrev_i32_e32 v141, 31, v140
	v_mov_b64_e32 v[138:139], s[0:1]
	s_movk_i32 s2, 0x2c00
	v_pk_mul_f32 v[114:115], v[118:119], v[114:115]
	v_pk_mul_f32 v[112:113], v[116:117], v[112:113]
	v_mad_i64_i32 v[148:149], s[0:1], v146, s2, v[138:139]
	v_lshlrev_b64 v[140:141], 1, v[140:141]
	v_pk_mul_f32 v[116:117], v[124:125], v[114:115]
	v_pk_mul_f32 v[114:115], v[126:127], v[112:113]
	v_lshl_add_u64 v[148:149], v[148:149], 0, v[140:141]
	v_pk_mul_f32 v[122:123], v[150:151], v[122:123]
	v_pk_mul_f32 v[120:121], v[152:153], v[120:121]
	v_pk_mul_f32 v[106:107], v[110:111], v[106:107]
	v_cvt_pk_bf16_f32 v112, v120, v121
	v_cvt_pk_bf16_f32 v113, v122, v123
	v_cvt_pk_bf16_f32 v114, v114, v115
	v_cvt_pk_bf16_f32 v115, v116, v117
	global_store_dwordx4 v[148:149], v[112:115], off nt
	v_pk_mul_f32 v[104:105], v[108:109], v[104:105]
	v_or_b32_e32 v116, 16, v146
	v_pk_mul_f32 v[112:113], v[110:111], s[74:75] op_sel_hi:[1,0]
	v_pk_mul_f32 v[114:115], v[108:109], s[74:75] op_sel_hi:[1,0]
	v_pk_mul_f32 v[108:109], v[102:103], s[74:75] op_sel_hi:[1,0]
	v_pk_mul_f32 v[110:111], v[100:101], s[74:75] op_sel_hi:[1,0]
	v_exp_f32_e32 v108, v108
	v_exp_f32_e32 v110, v110
	v_exp_f32_e32 v109, v109
	v_exp_f32_e32 v111, v111
	v_exp_f32_e32 v114, v114
	v_exp_f32_e32 v115, v115
	v_exp_f32_e32 v112, v112
	v_exp_f32_e32 v113, v113
	v_pk_add_f32 v[108:109], v[108:109], 1.0 op_sel_hi:[1,0]
	v_pk_add_f32 v[110:111], v[110:111], 1.0 op_sel_hi:[1,0]
	v_pk_add_f32 v[114:115], v[114:115], 1.0 op_sel_hi:[1,0]
	v_pk_add_f32 v[112:113], v[112:113], 1.0 op_sel_hi:[1,0]
	v_rcp_f32_e32 v110, v110
	v_rcp_f32_e32 v108, v108
	v_rcp_f32_e32 v109, v109
	v_rcp_f32_e32 v111, v111
	v_rcp_f32_e32 v114, v114
	v_rcp_f32_e32 v115, v115
	v_rcp_f32_e32 v112, v112
	v_rcp_f32_e32 v113, v113
	v_pk_mul_f32 v[98:99], v[102:103], v[98:99]
	v_pk_mul_f32 v[96:97], v[100:101], v[96:97]
	v_mad_i64_i32 v[116:117], s[0:1], v116, s2, v[138:139]
	v_pk_mul_f32 v[100:101], v[108:109], v[98:99]
	v_pk_mul_f32 v[98:99], v[110:111], v[96:97]
	v_lshl_add_u64 v[116:117], v[116:117], 0, v[140:141]
; __device__ __forceinline__ unsigned cvt_pk_bf16(float lo, float hi) { unsigned r; asm volatile("v_cvt_pk_bf16_f32 %0, %1, %2" : "=v"(r) : "v"(lo), "v"(hi)); return r; }
;     __device__ __forceinline__ void operator()(f32x4 (&acc)[2][2][4][2], const Unit& u, int wr, int wc, int fr, int fq) const {
;     ...
;             for (int m = 0; m < 4; ++m) {
;                 bf16* rowp = O + (size_t)(row0 + ai * HALF + m * 16) * FF + col0;
;                 const f32x4 g0 = acc[ai][0][m][0], g1 = acc[ai][0][m][1], u0 = acc[ai][1][m][0], u1 = acc[ai][1][m][1];
;                 u32x4 w;
;                 const f32x4 a0 = swiglu4(g0, u0), a1 = swiglu4(g1, u1);
;                 w.x = cvt_pk_bf16(a0[0], a0[1]); w.y = cvt_pk_bf16(a0[2], a0[3]); w.z = cvt_pk_bf16(a1[0], a1[1]); w.w = cvt_pk_bf16(a1[2], a1[3]);
;                 __builtin_nontemporal_store(w, (u32x4*)rowp);
	v_pk_mul_f32 v[106:107], v[112:113], v[106:107]
	v_pk_mul_f32 v[104:105], v[114:115], v[104:105]
	v_pk_mul_f32 v[90:91], v[94:95], v[90:91]
	v_cvt_pk_bf16_f32 v96, v104, v105
	v_cvt_pk_bf16_f32 v97, v106, v107
	v_cvt_pk_bf16_f32 v98, v98, v99
	v_cvt_pk_bf16_f32 v99, v100, v101
	global_store_dwordx4 v[116:117], v[96:99], off nt
	v_pk_mul_f32 v[88:89], v[92:93], v[88:89]
	v_or_b32_e32 v100, 32, v146
	v_pk_mul_f32 v[96:97], v[94:95], s[74:75] op_sel_hi:[1,0]
	v_pk_mul_f32 v[98:99], v[92:93], s[74:75] op_sel_hi:[1,0]
	v_pk_mul_f32 v[92:93], v[86:87], s[74:75] op_sel_hi:[1,0]
	v_pk_mul_f32 v[94:95], v[84:85], s[74:75] op_sel_hi:[1,0]
	v_exp_f32_e32 v92, v92
	v_exp_f32_e32 v94, v94
	v_exp_f32_e32 v93, v93
	v_exp_f32_e32 v95, v95
	v_exp_f32_e32 v98, v98
	v_exp_f32_e32 v99, v99
	v_exp_f32_e32 v96, v96
	v_exp_f32_e32 v97, v97
	v_pk_add_f32 v[92:93], v[92:93], 1.0 op_sel_hi:[1,0]
	v_pk_add_f32 v[94:95], v[94:95], 1.0 op_sel_hi:[1,0]
	v_pk_add_f32 v[98:99], v[98:99], 1.0 op_sel_hi:[1,0]
	v_pk_add_f32 v[96:97], v[96:97], 1.0 op_sel_hi:[1,0]
	v_rcp_f32_e32 v94, v94
	v_rcp_f32_e32 v92, v92
	v_rcp_f32_e32 v93, v93
	v_rcp_f32_e32 v95, v95
	v_rcp_f32_e32 v98, v98
	v_rcp_f32_e32 v99, v99
	v_rcp_f32_e32 v96, v96
	v_rcp_f32_e32 v97, v97
	v_pk_mul_f32 v[82:83], v[86:87], v[82:83]
	v_pk_mul_f32 v[80:81], v[84:85], v[80:81]
	v_mad_i64_i32 v[100:101], s[0:1], v100, s2, v[138:139]
	v_pk_mul_f32 v[84:85], v[92:93], v[82:83]
	v_pk_mul_f32 v[82:83], v[94:95], v[80:81]
	v_lshl_add_u64 v[100:101], v[100:101], 0, v[140:141]
	v_pk_mul_f32 v[90:91], v[96:97], v[90:91]
	v_pk_mul_f32 v[88:89], v[98:99], v[88:89]
	v_pk_mul_f32 v[74:75], v[78:79], v[74:75]
	v_cvt_pk_bf16_f32 v80, v88, v89
	v_cvt_pk_bf16_f32 v81, v90, v91
	v_cvt_pk_bf16_f32 v82, v82, v83
	v_cvt_pk_bf16_f32 v83, v84, v85
	global_store_dwordx4 v[100:101], v[80:83], off nt
	v_pk_mul_f32 v[72:73], v[76:77], v[72:73]
	v_or_b32_e32 v84, 48, v146
	v_pk_mul_f32 v[80:81], v[78:79], s[74:75] op_sel_hi:[1,0]
	v_pk_mul_f32 v[82:83], v[76:77], s[74:75] op_sel_hi:[1,0]
	v_pk_mul_f32 v[76:77], v[70:71], s[74:75] op_sel_hi:[1,0]
	v_pk_mul_f32 v[78:79], v[68:69], s[74:75] op_sel_hi:[1,0]
	v_exp_f32_e32 v76, v76
	v_exp_f32_e32 v78, v78
	v_exp_f32_e32 v77, v77
	v_exp_f32_e32 v79, v79
	v_exp_f32_e32 v82, v82
	v_exp_f32_e32 v83, v83
	v_exp_f32_e32 v80, v80
	v_exp_f32_e32 v81, v81
	v_pk_add_f32 v[76:77], v[76:77], 1.0 op_sel_hi:[1,0]
	v_pk_add_f32 v[78:79], v[78:79], 1.0 op_sel_hi:[1,0]
	v_pk_add_f32 v[82:83], v[82:83], 1.0 op_sel_hi:[1,0]
	v_pk_add_f32 v[80:81], v[80:81], 1.0 op_sel_hi:[1,0]
	v_rcp_f32_e32 v78, v78
	v_rcp_f32_e32 v76, v76
	v_rcp_f32_e32 v77, v77
	v_rcp_f32_e32 v79, v79
	v_rcp_f32_e32 v82, v82
	v_rcp_f32_e32 v83, v83
	v_rcp_f32_e32 v80, v80
	v_rcp_f32_e32 v81, v81
	v_pk_mul_f32 v[66:67], v[70:71], v[66:67]
	v_pk_mul_f32 v[64:65], v[68:69], v[64:65]
	v_mad_i64_i32 v[84:85], s[0:1], v84, s2, v[138:139]
	v_pk_mul_f32 v[68:69], v[76:77], v[66:67]
	v_pk_mul_f32 v[66:67], v[78:79], v[64:65]
	v_lshl_add_u64 v[84:85], v[84:85], 0, v[140:141]
	v_pk_mul_f32 v[74:75], v[80:81], v[74:75]
	v_pk_mul_f32 v[72:73], v[82:83], v[72:73]
	v_pk_mul_f32 v[58:59], v[62:63], v[58:59]
	v_cvt_pk_bf16_f32 v64, v72, v73
	v_cvt_pk_bf16_f32 v65, v74, v75
	v_cvt_pk_bf16_f32 v66, v66, v67
	v_cvt_pk_bf16_f32 v67, v68, v69
	global_store_dwordx4 v[84:85], v[64:67], off nt
	v_pk_mul_f32 v[56:57], v[60:61], v[56:57]
	v_add_u32_e32 v68, 0x80, v146
	v_pk_mul_f32 v[64:65], v[62:63], s[74:75] op_sel_hi:[1,0]
	v_pk_mul_f32 v[66:67], v[60:61], s[74:75] op_sel_hi:[1,0]
	v_pk_mul_f32 v[60:61], v[54:55], s[74:75] op_sel_hi:[1,0]
	v_pk_mul_f32 v[62:63], v[52:53], s[74:75] op_sel_hi:[1,0]
	v_exp_f32_e32 v60, v60
	v_exp_f32_e32 v62, v62
	v_exp_f32_e32 v61, v61
	v_exp_f32_e32 v63, v63
	v_exp_f32_e32 v66, v66
	v_exp_f32_e32 v67, v67
	v_exp_f32_e32 v64, v64
	v_exp_f32_e32 v65, v65
	v_pk_add_f32 v[60:61], v[60:61], 1.0 op_sel_hi:[1,0]
	v_pk_add_f32 v[62:63], v[62:63], 1.0 op_sel_hi:[1,0]
	v_pk_add_f32 v[66:67], v[66:67], 1.0 op_sel_hi:[1,0]
	v_pk_add_f32 v[64:65], v[64:65], 1.0 op_sel_hi:[1,0]
	v_rcp_f32_e32 v62, v62
	v_rcp_f32_e32 v60, v60
	v_rcp_f32_e32 v61, v61
	v_rcp_f32_e32 v63, v63
	v_rcp_f32_e32 v66, v66
	v_rcp_f32_e32 v67, v67
	v_rcp_f32_e32 v64, v64
	v_rcp_f32_e32 v65, v65
	v_pk_mul_f32 v[50:51], v[54:55], v[50:51]
	v_pk_mul_f32 v[48:49], v[52:53], v[48:49]
	v_mad_i64_i32 v[68:69], s[0:1], v68, s2, v[138:139]
	v_pk_mul_f32 v[52:53], v[60:61], v[50:51]
	v_pk_mul_f32 v[50:51], v[62:63], v[48:49]
	v_lshl_add_u64 v[68:69], v[68:69], 0, v[140:141]
	v_pk_mul_f32 v[58:59], v[64:65], v[58:59]
	v_pk_mul_f32 v[56:57], v[66:67], v[56:57]
	v_pk_mul_f32 v[42:43], v[46:47], v[42:43]
	v_cvt_pk_bf16_f32 v48, v56, v57
	v_cvt_pk_bf16_f32 v49, v58, v59
	v_cvt_pk_bf16_f32 v50, v50, v51
; __device__ __forceinline__ unsigned cvt_pk_bf16(float lo, float hi) { unsigned r; asm volatile("v_cvt_pk_bf16_f32 %0, %1, %2" : "=v"(r) : "v"(lo), "v"(hi)); return r; }
; #define PG8_BAR __builtin_amdgcn_s_barrier()
; template <class Epi>
; __device__ __forceinline__ void gemm_phase(LAS unsigned char* lds, const Gemm g, const StaticOrder& S, const Epi& E, const int tid) {
;     ...
;         if (!has_next) break;
;         if (!(Epi::CHAIN && cur.n + 1 < S.NS)) {
; #pragma unroll
;         for (int a = 0; a < 2; ++a)
; #pragma unroll
;             for (int b = 0; b < 2; ++b)
; #pragma unroll
;                 for (int m = 0; m < 4; ++m)
; #pragma unroll
;                     for (int n = 0; n < 2; ++n) acc[a][b][m][n] = (f32x4){0.f, 0.f, 0.f, 0.f};
;         }
;         cur = nxt; cA = nA; cB = nB; ++ui;
;         if (wr == 1) PG8_BAR;
;     __device__ __forceinline__ void operator()(f32x4 (&acc)[2][2][4][2], const Unit& u, int wr, int wc, int fr, int fq) const {
;     ...
;             for (int m = 0; m < 4; ++m) {
;                 bf16* rowp = O + (size_t)(row0 + ai * HALF + m * 16) * FF + col0;
;                 const f32x4 g0 = acc[ai][0][m][0], g1 = acc[ai][0][m][1], u0 = acc[ai][1][m][0], u1 = acc[ai][1][m][1];
;                 u32x4 w;
;                 const f32x4 a0 = swiglu4(g0, u0), a1 = swiglu4(g1, u1);
;                 w.x = cvt_pk_bf16(a0[0], a0[1]); w.y = cvt_pk_bf16(a0[2], a0[3]); w.z = cvt_pk_bf16(a1[0], a1[1]); w.w = cvt_pk_bf16(a1[2], a1[3]);
;                 __builtin_nontemporal_store(w, (u32x4*)rowp);
	v_cvt_pk_bf16_f32 v51, v52, v53
	global_store_dwordx4 v[68:69], v[48:51], off nt
	v_pk_mul_f32 v[40:41], v[44:45], v[40:41]
	v_add_u32_e32 v52, 0x90, v146
	v_pk_mul_f32 v[48:49], v[46:47], s[74:75] op_sel_hi:[1,0]
	v_pk_mul_f32 v[50:51], v[44:45], s[74:75] op_sel_hi:[1,0]
	v_pk_mul_f32 v[44:45], v[38:39], s[74:75] op_sel_hi:[1,0]
	v_pk_mul_f32 v[46:47], v[36:37], s[74:75] op_sel_hi:[1,0]
	v_exp_f32_e32 v44, v44
	v_exp_f32_e32 v46, v46
	v_exp_f32_e32 v45, v45
	v_exp_f32_e32 v47, v47
	v_exp_f32_e32 v50, v50
	v_exp_f32_e32 v51, v51
	v_exp_f32_e32 v48, v48
	v_exp_f32_e32 v49, v49
	v_pk_add_f32 v[44:45], v[44:45], 1.0 op_sel_hi:[1,0]
	v_pk_add_f32 v[46:47], v[46:47], 1.0 op_sel_hi:[1,0]
	v_pk_add_f32 v[50:51], v[50:51], 1.0 op_sel_hi:[1,0]
	v_pk_add_f32 v[48:49], v[48:49], 1.0 op_sel_hi:[1,0]
	v_rcp_f32_e32 v46, v46
	v_rcp_f32_e32 v44, v44
	v_rcp_f32_e32 v45, v45
	v_rcp_f32_e32 v47, v47
	v_rcp_f32_e32 v50, v50
	v_rcp_f32_e32 v51, v51
	v_rcp_f32_e32 v48, v48
	v_rcp_f32_e32 v49, v49
	v_pk_mul_f32 v[34:35], v[38:39], v[34:35]
	v_pk_mul_f32 v[32:33], v[36:37], v[32:33]
	v_mad_i64_i32 v[52:53], s[0:1], v52, s2, v[138:139]
	v_pk_mul_f32 v[36:37], v[44:45], v[34:35]
	v_pk_mul_f32 v[34:35], v[46:47], v[32:33]
	v_lshl_add_u64 v[52:53], v[52:53], 0, v[140:141]
	v_pk_mul_f32 v[42:43], v[48:49], v[42:43]
	v_pk_mul_f32 v[40:41], v[50:51], v[40:41]
	v_pk_mul_f32 v[26:27], v[30:31], v[26:27]
	v_cvt_pk_bf16_f32 v32, v40, v41
	v_cvt_pk_bf16_f32 v33, v42, v43
	v_cvt_pk_bf16_f32 v34, v34, v35
	v_cvt_pk_bf16_f32 v35, v36, v37
	global_store_dwordx4 v[52:53], v[32:35], off nt
	v_pk_mul_f32 v[24:25], v[28:29], v[24:25]
	v_add_u32_e32 v36, 0xa0, v146
	v_pk_mul_f32 v[32:33], v[30:31], s[74:75] op_sel_hi:[1,0]
	v_pk_mul_f32 v[34:35], v[28:29], s[74:75] op_sel_hi:[1,0]
	v_pk_mul_f32 v[28:29], v[22:23], s[74:75] op_sel_hi:[1,0]
	v_pk_mul_f32 v[30:31], v[20:21], s[74:75] op_sel_hi:[1,0]
	v_exp_f32_e32 v28, v28
	v_exp_f32_e32 v30, v30
	v_exp_f32_e32 v29, v29
	v_exp_f32_e32 v31, v31
	v_exp_f32_e32 v34, v34
	v_exp_f32_e32 v35, v35
	v_exp_f32_e32 v32, v32
	v_exp_f32_e32 v33, v33
	v_pk_add_f32 v[28:29], v[28:29], 1.0 op_sel_hi:[1,0]
	v_pk_add_f32 v[30:31], v[30:31], 1.0 op_sel_hi:[1,0]
	v_pk_add_f32 v[34:35], v[34:35], 1.0 op_sel_hi:[1,0]
	v_pk_add_f32 v[32:33], v[32:33], 1.0 op_sel_hi:[1,0]
	v_rcp_f32_e32 v30, v30
	v_rcp_f32_e32 v28, v28
	v_rcp_f32_e32 v29, v29
	v_rcp_f32_e32 v31, v31
	v_rcp_f32_e32 v34, v34
	v_rcp_f32_e32 v35, v35
	v_rcp_f32_e32 v32, v32
	v_rcp_f32_e32 v33, v33
	v_pk_mul_f32 v[18:19], v[22:23], v[18:19]
	v_pk_mul_f32 v[16:17], v[20:21], v[16:17]
	v_mad_i64_i32 v[36:37], s[0:1], v36, s2, v[138:139]
	v_pk_mul_f32 v[20:21], v[28:29], v[18:19]
	v_pk_mul_f32 v[18:19], v[30:31], v[16:17]
	v_lshl_add_u64 v[36:37], v[36:37], 0, v[140:141]
	v_pk_mul_f32 v[26:27], v[32:33], v[26:27]
	v_pk_mul_f32 v[24:25], v[34:35], v[24:25]
	v_pk_mul_f32 v[10:11], v[14:15], v[10:11]
	v_cvt_pk_bf16_f32 v16, v24, v25
	v_cvt_pk_bf16_f32 v17, v26, v27
	v_cvt_pk_bf16_f32 v18, v18, v19
	v_cvt_pk_bf16_f32 v19, v20, v21
	global_store_dwordx4 v[36:37], v[16:19], off nt
	v_pk_mul_f32 v[8:9], v[12:13], v[8:9]
	v_add_u32_e32 v20, 0xb0, v146
	v_pk_mul_f32 v[16:17], v[14:15], s[74:75] op_sel_hi:[1,0]
	v_pk_mul_f32 v[18:19], v[12:13], s[74:75] op_sel_hi:[1,0]
	v_pk_mul_f32 v[12:13], v[6:7], s[74:75] op_sel_hi:[1,0]
	v_pk_mul_f32 v[14:15], v[4:5], s[74:75] op_sel_hi:[1,0]
	v_exp_f32_e32 v12, v12
	v_exp_f32_e32 v14, v14
	v_exp_f32_e32 v13, v13
	v_exp_f32_e32 v15, v15
	v_exp_f32_e32 v18, v18
	v_exp_f32_e32 v19, v19
	v_exp_f32_e32 v16, v16
	v_exp_f32_e32 v17, v17
	v_pk_add_f32 v[12:13], v[12:13], 1.0 op_sel_hi:[1,0]
	v_pk_add_f32 v[14:15], v[14:15], 1.0 op_sel_hi:[1,0]
	v_pk_add_f32 v[18:19], v[18:19], 1.0 op_sel_hi:[1,0]
	v_pk_add_f32 v[16:17], v[16:17], 1.0 op_sel_hi:[1,0]
	v_rcp_f32_e32 v14, v14
	v_rcp_f32_e32 v12, v12
	v_rcp_f32_e32 v13, v13
	v_rcp_f32_e32 v15, v15
	v_rcp_f32_e32 v18, v18
	v_rcp_f32_e32 v19, v19
	v_rcp_f32_e32 v16, v16
	v_rcp_f32_e32 v17, v17
	v_mad_i64_i32 v[20:21], s[0:1], v20, s2, v[138:139]
	v_pk_mul_f32 v[2:3], v[6:7], v[2:3]
	v_pk_mul_f32 v[0:1], v[4:5], v[0:1]
	v_lshl_add_u64 v[20:21], v[20:21], 0, v[140:141]
	v_pk_mul_f32 v[4:5], v[12:13], v[2:3]
	v_pk_mul_f32 v[2:3], v[14:15], v[0:1]
	s_andn2_b64 vcc, exec, s[36:37]
	s_mov_b64 s[0:1], -1
	v_readlane_b32 s58, v254, 62
	v_readlane_b32 s59, v254, 63
	v_pk_mul_f32 v[10:11], v[16:17], v[10:11]
	v_pk_mul_f32 v[8:9], v[18:19], v[8:9]
	s_nop 0
	v_cvt_pk_bf16_f32 v0, v8, v9
	v_cvt_pk_bf16_f32 v1, v10, v11
	v_cvt_pk_bf16_f32 v2, v2, v3
	v_cvt_pk_bf16_f32 v3, v4, v5
	global_store_dwordx4 v[20:21], v[0:3], off nt
	s_cbranch_vccnz .LBB0_157
	s_andn2_b64 vcc, exec, s[8:9]
	s_cbranch_vccnz .LBB0_156
	s_barrier
	s_branch .LBB0_156

; #define PG8_STAGE(bufoff, gbase, voff) do { _Pragma("unroll") for (int _i = 0; _i < 2; ++_i) \
;         __builtin_amdgcn_global_load_lds((const unsigned*)((const char*)(gbase) + (voff)[_i]), (LAS unsigned*)(lds + (bufoff) + ldsw + _i * 8192), 16, 0, 0); } while (0)
; #define PG8_LDA(dst, b, h) do { _Pragma("unroll") for (int m = 0; m < 4; ++m) _Pragma("unroll") for (int k = 0; k < 2; ++k) dst[m][k] = *(const LAS bf16x8*)(lds + PG8_SA(b, h) + aoff + m * 2048 + k * 1024); } while (0)
; #define PG8_LDB(dst, b, h) do { _Pragma("unroll") for (int n = 0; n < 2; ++n) _Pragma("unroll") for (int k = 0; k < 2; ++k) dst[n][k] = *(const LAS bf16x8*)(lds + PG8_SB(b, h) + boff + n * 2048 + k * 1024); } while (0)
; #define PG8_MMA(ai, bj, At, Bt) do { __builtin_amdgcn_s_setprio(1); _Pragma("unroll") for (int m = 0; m < 4; ++m) _Pragma("unroll") for (int n = 0; n < 2; ++n) _Pragma("unroll") for (int k = 0; k < 2; ++k) \
;         acc[ai][bj][m][n] = __builtin_amdgcn_mfma_f32_16x16x32_bf16(Bt[n][k], At[m][k], acc[ai][bj][m][n], 0, 0, 0); __builtin_amdgcn_s_setprio(0); } while (0)
; #define PG8_WAIT_V(n) asm volatile("s_waitcnt vmcnt(" #n ")" ::: "memory")
; #define PG8_WAIT_L(n) asm volatile("s_waitcnt lgkmcnt(" #n ")" ::: "memory")
; #define PG8_BAR __builtin_amdgcn_s_barrier()
; #define PG8_SCHED __builtin_amdgcn_sched_barrier(0)
; template <class Epi>
; __device__ __forceinline__ void gemm_phase(LAS unsigned char* lds, const Gemm g, const StaticOrder& S, const Epi& E, const int tid) {
;     ...
;         for (int t = 0; t < nt; t += 2) {
;             const bool last = (t == nt - 2);
;             const char* a1 = cA + (size_t)(t + 1) * kstep;
;             const char* a2 = last ? nA : cA + (size_t)(t + 2) * kstep; const char* b2 = last ? nB : cB + (size_t)(t + 2) * kstep;
;             const char* a3 = a2 + kstep; const char* b3 = b2 + kstep;
;             PG8_LDB(B0, 0, 0); PG8_LDB(B1, 0, 1); PG8_SCHED; PG8_LDA(At, 0, 0); PG8_STAGE(PG8_SA(1, 1), a1 + hsA, voffA);
;             PG8_WAIT_V(8); PG8_WAIT_L(0); PG8_BAR; PG8_MMA(0, 0, At, B0); PG8_MMA(0, 1, At, B1); PG8_BAR; PG8_SCHED;
;     ...
;         for (int a = 0; a < 2; ++a)
; #pragma unroll
;             for (int b = 0; b < 2; ++b)
; #pragma unroll
;                 for (int m = 0; m < 4; ++m)
; #pragma unroll
;                     for (int n = 0; n < 2; ++n) acc[a][b][m][n] = (f32x4){0.f, 0.f, 0.f, 0.f};
.LBB0_232:
	s_add_u32 s42, s0, 0x100
	v_mov_b32_e32 v0, 0
	s_addc_u32 s43, s1, 0
	s_mov_b32 s69, -2
	v_mov_b32_e32 v1, v0
	v_mov_b32_e32 v2, v0
	v_mov_b32_e32 v3, v0
	v_mov_b32_e32 v4, v0
	v_mov_b32_e32 v5, v0
	v_mov_b32_e32 v6, v0
	v_mov_b32_e32 v7, v0
	v_mov_b32_e32 v16, v0
	v_mov_b32_e32 v17, v0
	v_mov_b32_e32 v18, v0
	v_mov_b32_e32 v19, v0
	v_mov_b32_e32 v20, v0
	v_mov_b32_e32 v21, v0
	v_mov_b32_e32 v22, v0
	v_mov_b32_e32 v23, v0
	v_mov_b32_e32 v32, v0
	v_mov_b32_e32 v33, v0
	v_mov_b32_e32 v34, v0
	v_mov_b32_e32 v35, v0
	v_mov_b32_e32 v36, v0
	v_mov_b32_e32 v37, v0
	v_mov_b32_e32 v38, v0
	v_mov_b32_e32 v39, v0
	v_mov_b32_e32 v48, v0
	v_mov_b32_e32 v49, v0
	v_mov_b32_e32 v50, v0
	v_mov_b32_e32 v51, v0
	v_mov_b32_e32 v52, v0
	v_mov_b32_e32 v53, v0
	v_mov_b32_e32 v54, v0
	v_mov_b32_e32 v55, v0
	v_mov_b32_e32 v8, v0
	v_mov_b32_e32 v9, v0
	v_mov_b32_e32 v10, v0
	v_mov_b32_e32 v11, v0
	v_mov_b32_e32 v12, v0
	v_mov_b32_e32 v13, v0
	v_mov_b32_e32 v14, v0
	v_mov_b32_e32 v15, v0
	v_mov_b32_e32 v24, v0
	v_mov_b32_e32 v25, v0
	v_mov_b32_e32 v26, v0
	v_mov_b32_e32 v27, v0
	v_mov_b32_e32 v28, v0
	v_mov_b32_e32 v29, v0
	v_mov_b32_e32 v30, v0
	v_mov_b32_e32 v31, v0
	v_mov_b32_e32 v40, v0
	v_mov_b32_e32 v41, v0
	v_mov_b32_e32 v42, v0
	v_mov_b32_e32 v43, v0
	v_mov_b32_e32 v44, v0
	v_mov_b32_e32 v45, v0
	v_mov_b32_e32 v46, v0
	v_mov_b32_e32 v47, v0
	v_mov_b32_e32 v56, v0
	v_mov_b32_e32 v57, v0
	v_mov_b32_e32 v58, v0
	v_mov_b32_e32 v59, v0
	v_mov_b32_e32 v60, v0
	v_mov_b32_e32 v61, v0
	v_mov_b32_e32 v62, v0
	v_mov_b32_e32 v63, v0
	v_mov_b32_e32 v64, v0
	v_mov_b32_e32 v65, v0
	v_mov_b32_e32 v66, v0
	v_mov_b32_e32 v67, v0
	v_mov_b32_e32 v68, v0
	v_mov_b32_e32 v69, v0
	v_mov_b32_e32 v70, v0
	v_mov_b32_e32 v71, v0
	v_mov_b32_e32 v76, v0
	v_mov_b32_e32 v77, v0
	v_mov_b32_e32 v78, v0
	v_mov_b32_e32 v79, v0
	v_mov_b32_e32 v84, v0
	v_mov_b32_e32 v85, v0
	v_mov_b32_e32 v86, v0
	v_mov_b32_e32 v87, v0
	v_mov_b32_e32 v96, v0
	v_mov_b32_e32 v97, v0
	v_mov_b32_e32 v98, v0
	v_mov_b32_e32 v99, v0
	v_mov_b32_e32 v100, v0
	v_mov_b32_e32 v101, v0
	v_mov_b32_e32 v102, v0
	v_mov_b32_e32 v103, v0
	v_mov_b32_e32 v104, v0
	v_mov_b32_e32 v105, v0
	v_mov_b32_e32 v106, v0
	v_mov_b32_e32 v107, v0
	v_mov_b32_e32 v112, v0
	v_mov_b32_e32 v113, v0
	v_mov_b32_e32 v114, v0
	v_mov_b32_e32 v115, v0
	v_mov_b32_e32 v72, v0
	v_mov_b32_e32 v73, v0
	v_mov_b32_e32 v74, v0
	v_mov_b32_e32 v75, v0
	v_mov_b32_e32 v80, v0
	v_mov_b32_e32 v81, v0
	v_mov_b32_e32 v82, v0
	v_mov_b32_e32 v83, v0
	v_mov_b32_e32 v88, v0
	v_mov_b32_e32 v89, v0
	v_mov_b32_e32 v90, v0
	v_mov_b32_e32 v91, v0
	v_mov_b32_e32 v92, v0
	v_mov_b32_e32 v93, v0
	v_mov_b32_e32 v94, v0
	v_mov_b32_e32 v95, v0
	v_mov_b32_e32 v108, v0
	v_mov_b32_e32 v109, v0
	v_mov_b32_e32 v110, v0
	v_mov_b32_e32 v111, v0
	v_mov_b32_e32 v116, v0
	v_mov_b32_e32 v117, v0
	v_mov_b32_e32 v118, v0
	v_mov_b32_e32 v119, v0
	v_mov_b32_e32 v120, v0
	v_mov_b32_e32 v121, v0
	v_mov_b32_e32 v122, v0
	v_mov_b32_e32 v123, v0
	v_mov_b32_e32 v124, v0
	v_mov_b32_e32 v125, v0
	v_mov_b32_e32 v126, v0
	v_mov_b32_e32 v127, v0
	s_cmp_lg_u64 s[10:11], 0
	s_cbranch_scc1 .Lgprio_b
	s_setprio 1
.Lgprio_b:
.LBB0_233:
	s_add_u32 s0, s18, 0x100
	s_addc_u32 s1, s19, 0
	s_add_i32 s24, 0, 0x10000
	s_cmpk_eq_i32 s69, 0x54
	s_cselect_b32 s37, s15, s1
	s_cselect_b32 s36, s14, s0
	s_cselect_b32 s35, s17, s43
	s_cselect_b32 s34, s16, s42
	s_add_i32 s25, 0, 0x14000
	v_add_u32_e32 v152, s24, v193
	v_add_u32_e32 v170, s25, v193
	ds_read_b128 v[128:131], v152
	ds_read_b128 v[132:135], v152 offset:1024
	ds_read_b128 v[136:139], v152 offset:2048
	ds_read_b128 v[152:155], v152 offset:3072
	ds_read_b128 v[156:159], v170
	ds_read_b128 v[160:163], v170 offset:1024
	ds_read_b128 v[164:167], v170 offset:2048
	ds_read_b128 v[184:187], v170 offset:3072
	v_lshl_add_u64 v[212:213], s[18:19], 0, v[148:149]
	s_add_i32 m0, s44, 0xc000
	ds_read_b128 v[188:191], v198
	ds_read_b128 v[200:203], v198 offset:1024
	ds_read_b128 v[204:207], v198 offset:2048
	ds_read_b128 v[208:211], v198 offset:3072
	ds_read_b128 v[230:233], v198 offset:4096
	ds_read_b128 v[234:237], v198 offset:5120
	ds_read_b128 v[238:241], v198 offset:6144
	ds_read_b128 v[242:245], v198 offset:7168
	global_load_lds_dwordx4 v[212:213], off
	v_lshl_add_u64 v[212:213], s[18:19], 0, v[150:151]
	s_add_i32 m0, s44, 0xe000
	s_nop 0
	global_load_lds_dwordx4 v[212:213], off
	s_waitcnt vmcnt(8)
	s_waitcnt lgkmcnt(0)
	s_barrier
	s_waitcnt lgkmcnt(0)
	v_mfma_f32_16x16x32_bf16 v[124:127], v[128:131], v[188:191], v[124:127]
	v_mfma_f32_16x16x32_bf16 v[120:123], v[136:139], v[188:191], v[120:123]
	v_mfma_f32_16x16x32_bf16 v[116:119], v[128:131], v[204:207], v[116:119]
	v_mfma_f32_16x16x32_bf16 v[108:111], v[136:139], v[204:207], v[108:111]
	v_mfma_f32_16x16x32_bf16 v[92:95], v[128:131], v[230:233], v[92:95]
	v_mfma_f32_16x16x32_bf16 v[88:91], v[136:139], v[230:233], v[88:91]
	v_mfma_f32_16x16x32_bf16 v[80:83], v[128:131], v[238:241], v[80:83]
	v_mfma_f32_16x16x32_bf16 v[72:75], v[136:139], v[238:241], v[72:75]
	v_mfma_f32_16x16x32_bf16 v[124:127], v[132:135], v[200:203], v[124:127]
	v_mfma_f32_16x16x32_bf16 v[120:123], v[152:155], v[200:203], v[120:123]
	v_mfma_f32_16x16x32_bf16 v[116:119], v[132:135], v[208:211], v[116:119]
	v_mfma_f32_16x16x32_bf16 v[108:111], v[152:155], v[208:211], v[108:111]
	v_mfma_f32_16x16x32_bf16 v[92:95], v[132:135], v[234:237], v[92:95]
	v_mfma_f32_16x16x32_bf16 v[88:91], v[152:155], v[234:237], v[88:91]
	v_mfma_f32_16x16x32_bf16 v[80:83], v[132:135], v[242:245], v[80:83]
	v_mfma_f32_16x16x32_bf16 v[72:75], v[152:155], v[242:245], v[72:75]
	v_mfma_f32_16x16x32_bf16 v[112:115], v[156:159], v[188:191], v[112:115]
	v_mfma_f32_16x16x32_bf16 v[104:107], v[164:167], v[188:191], v[104:107]
	v_mfma_f32_16x16x32_bf16 v[100:103], v[156:159], v[204:207], v[100:103]
	v_mfma_f32_16x16x32_bf16 v[96:99], v[164:167], v[204:207], v[96:99]
	v_mfma_f32_16x16x32_bf16 v[84:87], v[156:159], v[230:233], v[84:87]
	v_mfma_f32_16x16x32_bf16 v[76:79], v[164:167], v[230:233], v[76:79]
	v_mfma_f32_16x16x32_bf16 v[68:71], v[156:159], v[238:241], v[68:71]
	v_mfma_f32_16x16x32_bf16 v[64:67], v[164:167], v[238:241], v[64:67]
	v_mfma_f32_16x16x32_bf16 v[112:115], v[160:163], v[200:203], v[112:115]
	v_mfma_f32_16x16x32_bf16 v[104:107], v[184:187], v[200:203], v[104:107]
	v_mfma_f32_16x16x32_bf16 v[100:103], v[160:163], v[208:211], v[100:103]
	v_mfma_f32_16x16x32_bf16 v[96:99], v[184:187], v[208:211], v[96:99]
	v_mfma_f32_16x16x32_bf16 v[84:87], v[160:163], v[234:237], v[84:87]
	v_mfma_f32_16x16x32_bf16 v[76:79], v[184:187], v[234:237], v[76:79]
	v_mfma_f32_16x16x32_bf16 v[68:71], v[160:163], v[242:245], v[68:71]
	v_mfma_f32_16x16x32_bf16 v[64:67], v[184:187], v[242:245], v[64:67]
	s_barrier
; #define PG8_STAGE(bufoff, gbase, voff) do { _Pragma("unroll") for (int _i = 0; _i < 2; ++_i) \
;         __builtin_amdgcn_global_load_lds((const unsigned*)((const char*)(gbase) + (voff)[_i]), (LAS unsigned*)(lds + (bufoff) + ldsw + _i * 8192), 16, 0, 0); } while (0)
; #define PG8_LDA(dst, b, h) do { _Pragma("unroll") for (int m = 0; m < 4; ++m) _Pragma("unroll") for (int k = 0; k < 2; ++k) dst[m][k] = *(const LAS bf16x8*)(lds + PG8_SA(b, h) + aoff + m * 2048 + k * 1024); } while (0)
; #define PG8_LDB(dst, b, h) do { _Pragma("unroll") for (int n = 0; n < 2; ++n) _Pragma("unroll") for (int k = 0; k < 2; ++k) dst[n][k] = *(const LAS bf16x8*)(lds + PG8_SB(b, h) + boff + n * 2048 + k * 1024); } while (0)
; #define PG8_MMA(ai, bj, At, Bt) do { __builtin_amdgcn_s_setprio(1); _Pragma("unroll") for (int m = 0; m < 4; ++m) _Pragma("unroll") for (int n = 0; n < 2; ++n) _Pragma("unroll") for (int k = 0; k < 2; ++k) \
;         acc[ai][bj][m][n] = __builtin_amdgcn_mfma_f32_16x16x32_bf16(Bt[n][k], At[m][k], acc[ai][bj][m][n], 0, 0, 0); __builtin_amdgcn_s_setprio(0); } while (0)
; #define PG8_WAIT_V(n) asm volatile("s_waitcnt vmcnt(" #n ")" ::: "memory")
; #define PG8_WAIT_L(n) asm volatile("s_waitcnt lgkmcnt(" #n ")" ::: "memory")
; #define PG8_BAR __builtin_amdgcn_s_barrier()
; #define PG8_SCHED __builtin_amdgcn_sched_barrier(0)
; template <class Epi>
; __device__ __forceinline__ void gemm_phase(LAS unsigned char* lds, const Gemm g, const StaticOrder& S, const Epi& E, const int tid) {
;     ...
;             PG8_LDA(At, 0, 1); PG8_STAGE(PG8_SB(0, 0), b2, voffB); PG8_STAGE(PG8_SB(0, 1), b2 + hsB, voffB); PG8_STAGE(PG8_SA(0, 0), a2, voffA);
;             PG8_WAIT_V(8); PG8_WAIT_L(0); PG8_BAR; PG8_MMA(1, 0, At, B0); PG8_MMA(1, 1, At, B1); PG8_BAR; PG8_SCHED;
;             PG8_LDB(B0, 1, 0); PG8_LDB(B1, 1, 1); PG8_SCHED; PG8_LDA(At, 1, 0); PG8_STAGE(PG8_SA(0, 1), a2 + hsA, voffA);
;             PG8_WAIT_V(8); PG8_WAIT_L(0); PG8_BAR; PG8_MMA(0, 0, At, B0); PG8_MMA(0, 1, At, B1); PG8_BAR; PG8_SCHED;
	s_add_i32 s18, s24, s39
	v_lshl_add_u64 v[212:213], s[34:35], 0, v[144:145]
	s_mov_b32 m0, s18
	ds_read_b128 v[188:191], v198 offset:16384
	ds_read_b128 v[200:203], v198 offset:17408
	ds_read_b128 v[204:207], v198 offset:18432
	ds_read_b128 v[208:211], v198 offset:19456
	ds_read_b128 v[230:233], v198 offset:20480
	ds_read_b128 v[234:237], v198 offset:21504
	ds_read_b128 v[238:241], v198 offset:22528
	ds_read_b128 v[242:245], v198 offset:23552
	global_load_lds_dwordx4 v[212:213], off
	s_add_i32 m0, s18, 0x2000
	s_add_u32 s18, s34, 0x160000
	v_lshl_add_u64 v[246:247], s[34:35], 0, v[140:141]
	s_addc_u32 s19, s35, 0
	s_add_i32 s24, s25, s39
	global_load_lds_dwordx4 v[246:247], off
	v_lshl_add_u64 v[248:249], s[18:19], 0, v[144:145]
	s_mov_b32 m0, s24
	v_lshl_add_u64 v[250:251], s[36:37], 0, v[142:143]
	global_load_lds_dwordx4 v[248:249], off
	v_lshl_add_u64 v[248:249], s[18:19], 0, v[140:141]
	s_add_i32 m0, s24, 0x2000
	s_nop 0
	global_load_lds_dwordx4 v[248:249], off
	v_lshl_add_u64 v[248:249], s[36:37], 0, v[146:147]
	s_mov_b32 m0, s44
	s_nop 0
	global_load_lds_dwordx4 v[248:249], off
	s_mov_b32 m0, s45
	s_nop 0
	global_load_lds_dwordx4 v[250:251], off
	s_waitcnt vmcnt(8)
	s_waitcnt lgkmcnt(0)
	s_barrier
	s_waitcnt lgkmcnt(0)
	v_mfma_f32_16x16x32_bf16 v[60:63], v[128:131], v[188:191], v[60:63]
	v_mfma_f32_16x16x32_bf16 v[56:59], v[136:139], v[188:191], v[56:59]
	v_mfma_f32_16x16x32_bf16 v[44:47], v[128:131], v[204:207], v[44:47]
	v_mfma_f32_16x16x32_bf16 v[40:43], v[136:139], v[204:207], v[40:43]
	v_mfma_f32_16x16x32_bf16 v[28:31], v[128:131], v[230:233], v[28:31]
	v_mfma_f32_16x16x32_bf16 v[24:27], v[136:139], v[230:233], v[24:27]
	v_mfma_f32_16x16x32_bf16 v[12:15], v[128:131], v[238:241], v[12:15]
	v_mfma_f32_16x16x32_bf16 v[8:11], v[136:139], v[238:241], v[8:11]
	v_mfma_f32_16x16x32_bf16 v[60:63], v[132:135], v[200:203], v[60:63]
	v_mfma_f32_16x16x32_bf16 v[56:59], v[152:155], v[200:203], v[56:59]
	v_mfma_f32_16x16x32_bf16 v[44:47], v[132:135], v[208:211], v[44:47]
	v_mfma_f32_16x16x32_bf16 v[40:43], v[152:155], v[208:211], v[40:43]
	v_mfma_f32_16x16x32_bf16 v[28:31], v[132:135], v[234:237], v[28:31]
	v_mfma_f32_16x16x32_bf16 v[24:27], v[152:155], v[234:237], v[24:27]
	v_mfma_f32_16x16x32_bf16 v[12:15], v[132:135], v[242:245], v[12:15]
	v_mfma_f32_16x16x32_bf16 v[8:11], v[152:155], v[242:245], v[8:11]
	v_mfma_f32_16x16x32_bf16 v[52:55], v[156:159], v[188:191], v[52:55]
	v_mfma_f32_16x16x32_bf16 v[48:51], v[164:167], v[188:191], v[48:51]
	v_mfma_f32_16x16x32_bf16 v[36:39], v[156:159], v[204:207], v[36:39]
	v_mfma_f32_16x16x32_bf16 v[32:35], v[164:167], v[204:207], v[32:35]
	v_mfma_f32_16x16x32_bf16 v[20:23], v[156:159], v[230:233], v[20:23]
	v_mfma_f32_16x16x32_bf16 v[16:19], v[164:167], v[230:233], v[16:19]
	v_mfma_f32_16x16x32_bf16 v[4:7], v[156:159], v[238:241], v[4:7]
	v_mfma_f32_16x16x32_bf16 v[0:3], v[164:167], v[238:241], v[0:3]
	v_mfma_f32_16x16x32_bf16 v[52:55], v[160:163], v[200:203], v[52:55]
	v_mfma_f32_16x16x32_bf16 v[48:51], v[184:187], v[200:203], v[48:51]
	v_mfma_f32_16x16x32_bf16 v[36:39], v[160:163], v[208:211], v[36:39]
	v_mfma_f32_16x16x32_bf16 v[32:35], v[184:187], v[208:211], v[32:35]
	v_mfma_f32_16x16x32_bf16 v[20:23], v[160:163], v[234:237], v[20:23]
	v_mfma_f32_16x16x32_bf16 v[16:19], v[184:187], v[234:237], v[16:19]
	v_mfma_f32_16x16x32_bf16 v[4:7], v[160:163], v[242:245], v[4:7]
	v_mfma_f32_16x16x32_bf16 v[0:3], v[184:187], v[242:245], v[0:3]
	s_barrier
	s_add_i32 s24, 0, 0x18000
	s_add_i32 s25, 0, 0x1c000
	v_add_u32_e32 v152, s24, v193
	v_add_u32_e32 v170, s25, v193
	ds_read_b128 v[128:131], v152
	ds_read_b128 v[132:135], v152 offset:1024
	ds_read_b128 v[136:139], v152 offset:2048
	ds_read_b128 v[152:155], v152 offset:3072
	ds_read_b128 v[156:159], v170
	ds_read_b128 v[160:163], v170 offset:1024
	ds_read_b128 v[164:167], v170 offset:2048
	ds_read_b128 v[184:187], v170 offset:3072
	s_add_u32 s18, s36, 0x160000
	s_addc_u32 s19, s37, 0
	s_mov_b32 m0, s46
	v_lshl_add_u64 v[170:171], s[18:19], 0, v[146:147]
	ds_read_b128 v[188:191], v198 offset:32768
	ds_read_b128 v[200:203], v198 offset:33792
	ds_read_b128 v[204:207], v198 offset:34816
	ds_read_b128 v[208:211], v198 offset:35840
	ds_read_b128 v[230:233], v198 offset:36864
	ds_read_b128 v[234:237], v198 offset:37888
	ds_read_b128 v[238:241], v198 offset:38912
	ds_read_b128 v[242:245], v198 offset:39936
	global_load_lds_dwordx4 v[170:171], off
	v_lshl_add_u64 v[170:171], s[18:19], 0, v[142:143]
	s_mov_b32 m0, s47
	s_nop 0
	global_load_lds_dwordx4 v[170:171], off
	s_waitcnt vmcnt(8)
	s_waitcnt lgkmcnt(0)
	s_barrier
; #define PG8_STAGE(bufoff, gbase, voff) do { _Pragma("unroll") for (int _i = 0; _i < 2; ++_i) \
;         __builtin_amdgcn_global_load_lds((const unsigned*)((const char*)(gbase) + (voff)[_i]), (LAS unsigned*)(lds + (bufoff) + ldsw + _i * 8192), 16, 0, 0); } while (0)
; #define PG8_LDA(dst, b, h) do { _Pragma("unroll") for (int m = 0; m < 4; ++m) _Pragma("unroll") for (int k = 0; k < 2; ++k) dst[m][k] = *(const LAS bf16x8*)(lds + PG8_SA(b, h) + aoff + m * 2048 + k * 1024); } while (0)
; #define PG8_MMA(ai, bj, At, Bt) do { __builtin_amdgcn_s_setprio(1); _Pragma("unroll") for (int m = 0; m < 4; ++m) _Pragma("unroll") for (int n = 0; n < 2; ++n) _Pragma("unroll") for (int k = 0; k < 2; ++k) \
;         acc[ai][bj][m][n] = __builtin_amdgcn_mfma_f32_16x16x32_bf16(Bt[n][k], At[m][k], acc[ai][bj][m][n], 0, 0, 0); __builtin_amdgcn_s_setprio(0); } while (0)
; #define PG8_WAIT_V(n) asm volatile("s_waitcnt vmcnt(" #n ")" ::: "memory")
; #define PG8_WAIT_L(n) asm volatile("s_waitcnt lgkmcnt(" #n ")" ::: "memory")
; #define PG8_BAR __builtin_amdgcn_s_barrier()
; #define PG8_SCHED __builtin_amdgcn_sched_barrier(0)
; template <class Epi>
; __device__ __forceinline__ void gemm_phase(LAS unsigned char* lds, const Gemm g, const StaticOrder& S, const Epi& E, const int tid) {
;     ...
;             PG8_WAIT_V(8); PG8_WAIT_L(0); PG8_BAR; PG8_MMA(0, 0, At, B0); PG8_MMA(0, 1, At, B1); PG8_BAR; PG8_SCHED;
;             PG8_LDA(At, 1, 1); PG8_STAGE(PG8_SB(1, 0), b3, voffB); PG8_STAGE(PG8_SB(1, 1), b3 + hsB, voffB); PG8_STAGE(PG8_SA(1, 0), a3, voffA);
;             PG8_WAIT_V(8); PG8_WAIT_L(0); PG8_BAR; PG8_MMA(1, 0, At, B0); PG8_MMA(1, 1, At, B1); PG8_BAR; PG8_SCHED;
;         }
;         if (wr == 0) PG8_BAR;
	s_waitcnt lgkmcnt(0)
	v_mfma_f32_16x16x32_bf16 v[124:127], v[128:131], v[188:191], v[124:127]
	v_mfma_f32_16x16x32_bf16 v[120:123], v[136:139], v[188:191], v[120:123]
	v_mfma_f32_16x16x32_bf16 v[116:119], v[128:131], v[204:207], v[116:119]
	v_mfma_f32_16x16x32_bf16 v[108:111], v[136:139], v[204:207], v[108:111]
	v_mfma_f32_16x16x32_bf16 v[92:95], v[128:131], v[230:233], v[92:95]
	v_mfma_f32_16x16x32_bf16 v[88:91], v[136:139], v[230:233], v[88:91]
	v_mfma_f32_16x16x32_bf16 v[80:83], v[128:131], v[238:241], v[80:83]
	v_mfma_f32_16x16x32_bf16 v[72:75], v[136:139], v[238:241], v[72:75]
	v_mfma_f32_16x16x32_bf16 v[124:127], v[132:135], v[200:203], v[124:127]
	v_mfma_f32_16x16x32_bf16 v[120:123], v[152:155], v[200:203], v[120:123]
	v_mfma_f32_16x16x32_bf16 v[116:119], v[132:135], v[208:211], v[116:119]
	v_mfma_f32_16x16x32_bf16 v[108:111], v[152:155], v[208:211], v[108:111]
	v_mfma_f32_16x16x32_bf16 v[92:95], v[132:135], v[234:237], v[92:95]
	v_mfma_f32_16x16x32_bf16 v[88:91], v[152:155], v[234:237], v[88:91]
	v_mfma_f32_16x16x32_bf16 v[80:83], v[132:135], v[242:245], v[80:83]
	v_mfma_f32_16x16x32_bf16 v[72:75], v[152:155], v[242:245], v[72:75]
	v_mfma_f32_16x16x32_bf16 v[112:115], v[156:159], v[188:191], v[112:115]
	v_mfma_f32_16x16x32_bf16 v[104:107], v[164:167], v[188:191], v[104:107]
	v_mfma_f32_16x16x32_bf16 v[100:103], v[156:159], v[204:207], v[100:103]
	v_mfma_f32_16x16x32_bf16 v[96:99], v[164:167], v[204:207], v[96:99]
	v_mfma_f32_16x16x32_bf16 v[84:87], v[156:159], v[230:233], v[84:87]
	v_mfma_f32_16x16x32_bf16 v[76:79], v[164:167], v[230:233], v[76:79]
	v_mfma_f32_16x16x32_bf16 v[68:71], v[156:159], v[238:241], v[68:71]
	v_mfma_f32_16x16x32_bf16 v[64:67], v[164:167], v[238:241], v[64:67]
	v_mfma_f32_16x16x32_bf16 v[112:115], v[160:163], v[200:203], v[112:115]
	v_mfma_f32_16x16x32_bf16 v[104:107], v[184:187], v[200:203], v[104:107]
	v_mfma_f32_16x16x32_bf16 v[100:103], v[160:163], v[208:211], v[100:103]
	v_mfma_f32_16x16x32_bf16 v[96:99], v[184:187], v[208:211], v[96:99]
	v_mfma_f32_16x16x32_bf16 v[84:87], v[160:163], v[234:237], v[84:87]
	v_mfma_f32_16x16x32_bf16 v[76:79], v[184:187], v[234:237], v[76:79]
	v_mfma_f32_16x16x32_bf16 v[68:71], v[160:163], v[242:245], v[68:71]
	v_mfma_f32_16x16x32_bf16 v[64:67], v[184:187], v[242:245], v[64:67]
	s_barrier
	s_add_i32 s18, s24, s39
	v_lshl_add_u64 v[170:171], v[212:213], 0, s[28:29]
	s_mov_b32 m0, s18
	ds_read_b128 v[188:191], v198 offset:49152
	ds_read_b128 v[200:203], v198 offset:50176
	ds_read_b128 v[204:207], v198 offset:51200
	ds_read_b128 v[208:211], v198 offset:52224
	ds_read_b128 v[230:233], v198 offset:53248
	ds_read_b128 v[234:237], v198 offset:54272
	ds_read_b128 v[238:241], v198 offset:55296
	ds_read_b128 v[242:245], v198 offset:56320
	global_load_lds_dwordx4 v[170:171], off
	s_add_i32 m0, s18, 0x2000
	s_add_u32 s18, s34, 0x160080
	v_lshl_add_u64 v[170:171], v[246:247], 0, s[28:29]
	s_addc_u32 s19, s35, 0
	s_add_i32 s24, s25, s39
	global_load_lds_dwordx4 v[170:171], off
	v_lshl_add_u64 v[170:171], s[18:19], 0, v[144:145]
	s_mov_b32 m0, s24
	s_nop 0
	global_load_lds_dwordx4 v[170:171], off
	v_lshl_add_u64 v[170:171], s[18:19], 0, v[140:141]
	s_add_i32 m0, s24, 0x2000
	s_nop 0
	global_load_lds_dwordx4 v[170:171], off
	v_lshl_add_u64 v[170:171], v[248:249], 0, s[28:29]
	s_mov_b32 m0, s56
	s_nop 0
	global_load_lds_dwordx4 v[170:171], off
	v_lshl_add_u64 v[170:171], v[250:251], 0, s[28:29]
	s_mov_b32 m0, s57
	s_nop 0
	global_load_lds_dwordx4 v[170:171], off
	s_waitcnt vmcnt(8)
	s_waitcnt lgkmcnt(0)
	s_barrier
	s_waitcnt lgkmcnt(0)
	v_mfma_f32_16x16x32_bf16 v[60:63], v[128:131], v[188:191], v[60:63]
	v_mfma_f32_16x16x32_bf16 v[56:59], v[136:139], v[188:191], v[56:59]
	v_mfma_f32_16x16x32_bf16 v[44:47], v[128:131], v[204:207], v[44:47]
	v_mfma_f32_16x16x32_bf16 v[40:43], v[136:139], v[204:207], v[40:43]
	v_mfma_f32_16x16x32_bf16 v[28:31], v[128:131], v[230:233], v[28:31]
	v_mfma_f32_16x16x32_bf16 v[24:27], v[136:139], v[230:233], v[24:27]
	v_mfma_f32_16x16x32_bf16 v[12:15], v[128:131], v[238:241], v[12:15]
	v_mfma_f32_16x16x32_bf16 v[8:11], v[136:139], v[238:241], v[8:11]
	v_mfma_f32_16x16x32_bf16 v[60:63], v[132:135], v[200:203], v[60:63]
	v_mfma_f32_16x16x32_bf16 v[56:59], v[152:155], v[200:203], v[56:59]
	v_mfma_f32_16x16x32_bf16 v[44:47], v[132:135], v[208:211], v[44:47]
	v_mfma_f32_16x16x32_bf16 v[40:43], v[152:155], v[208:211], v[40:43]
	v_mfma_f32_16x16x32_bf16 v[28:31], v[132:135], v[234:237], v[28:31]
	v_mfma_f32_16x16x32_bf16 v[24:27], v[152:155], v[234:237], v[24:27]
	v_mfma_f32_16x16x32_bf16 v[12:15], v[132:135], v[242:245], v[12:15]
	v_mfma_f32_16x16x32_bf16 v[8:11], v[152:155], v[242:245], v[8:11]
	v_mfma_f32_16x16x32_bf16 v[52:55], v[156:159], v[188:191], v[52:55]
	v_mfma_f32_16x16x32_bf16 v[48:51], v[164:167], v[188:191], v[48:51]
	v_mfma_f32_16x16x32_bf16 v[36:39], v[156:159], v[204:207], v[36:39]
	v_mfma_f32_16x16x32_bf16 v[32:35], v[164:167], v[204:207], v[32:35]
	v_mfma_f32_16x16x32_bf16 v[20:23], v[156:159], v[230:233], v[20:23]
	v_mfma_f32_16x16x32_bf16 v[16:19], v[164:167], v[230:233], v[16:19]
	v_mfma_f32_16x16x32_bf16 v[4:7], v[156:159], v[238:241], v[4:7]
	v_mfma_f32_16x16x32_bf16 v[0:3], v[164:167], v[238:241], v[0:3]
	v_mfma_f32_16x16x32_bf16 v[52:55], v[160:163], v[200:203], v[52:55]
	v_mfma_f32_16x16x32_bf16 v[48:51], v[184:187], v[200:203], v[48:51]
	v_mfma_f32_16x16x32_bf16 v[36:39], v[160:163], v[208:211], v[36:39]
	v_mfma_f32_16x16x32_bf16 v[32:35], v[184:187], v[208:211], v[32:35]
	v_mfma_f32_16x16x32_bf16 v[20:23], v[160:163], v[234:237], v[20:23]
	v_mfma_f32_16x16x32_bf16 v[16:19], v[184:187], v[234:237], v[16:19]
	v_mfma_f32_16x16x32_bf16 v[4:7], v[160:163], v[242:245], v[4:7]
	v_mfma_f32_16x16x32_bf16 v[0:3], v[184:187], v[242:245], v[0:3]
	s_barrier
	s_add_i32 s69, s69, 2
	s_add_u32 s42, s42, 0x100
	s_addc_u32 s43, s43, 0
	s_cmpk_gt_u32 s69, 0x55
	s_mov_b64 s[18:19], s[0:1]
	s_cbranch_scc0 .LBB0_233
	s_and_b64 vcc, exec, s[10:11]
	s_cbranch_vccz .LBB0_236
	s_barrier
; __device__ __forceinline__ h16x8 f_to_h8(const f32x4 a, const f32x4 b) { return (h16x8){(_Float16)a[0], (_Float16)a[1], (_Float16)a[2], (_Float16)a[3], (_Float16)b[0], (_Float16)b[1], (_Float16)b[2], (_Float16)b[3]}; }
;     __device__ __forceinline__ void operator()(f32x4 (&acc)[2][2][4][2], const Unit& u, int wr, int wc, int fr, int fq) const {
;         const int lrow0 = row_off + u.pm * BM + wr * 64 + fr, col0 = u.pn * BM + wc * 32 + 8 * fq;
;         const int b = (row_off + u.pm * BM) >> 12;
;         const float* gp = gate + (size_t)b * NMOD + col0;
;         f32x4 gv[2][2];
; #pragma unroll
;         for (int bj = 0; bj < 2; ++bj)
; #pragma unroll
;             for (int n = 0; n < 2; ++n) gv[bj][n] = *(const f32x4*)(gp + bj * HALF + 4 * n) * coef;
;         _Float16* xp = xh + (size_t)lrow0 * D + col0;
;         if (base32) {
;             const float* bp = base32 + (size_t)lrow0 * D + col0;
; #pragma unroll
;             for (int am = 0; am < 8; am += 2) {
;                 f32x4 xb[2][2][2];
; #pragma unroll
;                 for (int mm = 0; mm < 2; ++mm)
; #pragma unroll
;                     for (int bj = 0; bj < 2; ++bj) { const int ai = (am + mm) >> 2, m = (am + mm) & 3; const float* p = bp + (size_t)(ai * HALF + m * 16) * D + bj * HALF; xb[mm][bj][0] = *(const f32x4*)p; xb[mm][bj][1] = *(const f32x4*)(p + 4); }
; #pragma unroll
;                 for (int mm = 0; mm < 2; ++mm)
; #pragma unroll
;                     for (int bj = 0; bj < 2; ++bj) { const int ai = (am + mm) >> 2, m = (am + mm) & 3;
;                         *(h16x8*)(xp + (size_t)(ai * HALF + m * 16) * D + bj * HALF) = f_to_h8(xb[mm][bj][0] + gv[bj][0] * acc[ai][bj][m][0], xb[mm][bj][1] + gv[bj][1] * acc[ai][bj][m][1]); }
;                 __builtin_amdgcn_sched_barrier(0);
;             }
.LBB0_236:
	s_setprio 0
	s_lshl_b32 s19, s68, 8
	s_ashr_i32 s0, s68, 4
	s_add_i32 s19, s19, s53
	s_lshl_b32 s18, s67, 8
	s_mul_hi_i32 s1, s0, 0x12000
	s_mul_i32 s0, s0, 0x12000
	v_or_b32_e32 v128, s18, v194
	s_add_u32 s0, s49, s0
	s_addc_u32 s1, s52, s1
	v_ashrrev_i32_e32 v129, 31, v128
	v_lshl_add_u64 v[138:139], v[128:129], 2, s[0:1]
	global_load_dwordx4 v[130:133], v[138:139], off
	global_load_dwordx4 v[134:137], v[138:139], off offset:16
	global_load_dwordx4 v[152:155], v[138:139], off offset:512
	global_load_dwordx4 v[184:187], v[138:139], off offset:528
	s_andn2_b64 vcc, exec, s[12:13]
	s_waitcnt vmcnt(0)
	v_pk_mul_f32 v[164:165], v[132:133], 0.5 op_sel_hi:[1,0]
	v_pk_mul_f32 v[166:167], v[130:131], 0.5 op_sel_hi:[1,0]
	v_pk_mul_f32 v[160:161], v[136:137], 0.5 op_sel_hi:[1,0]
	v_pk_mul_f32 v[162:163], v[134:135], 0.5 op_sel_hi:[1,0]
	v_pk_mul_f32 v[156:157], v[154:155], 0.5 op_sel_hi:[1,0]
	v_pk_mul_f32 v[158:159], v[152:153], 0.5 op_sel_hi:[1,0]
	v_pk_mul_f32 v[152:153], v[186:187], 0.5 op_sel_hi:[1,0]
	v_pk_mul_f32 v[154:155], v[184:185], 0.5 op_sel_hi:[1,0]
	s_cbranch_vccnz .LBB0_242
	v_or_b32_e32 v130, s19, v192
	v_ashrrev_i32_e32 v131, 31, v130
	v_lshlrev_b64 v[132:133], 12, v[130:131]
	v_lshlrev_b64 v[130:131], 13, v[130:131]
	v_lshl_add_u64 v[130:131], s[8:9], 0, v[130:131]
	v_lshl_add_u64 v[134:135], v[128:129], 2, v[130:131]
	v_readlane_b32 s0, v252, 63
	global_load_dwordx4 v[136:139], v[134:135], off offset:16
	global_load_dwordx4 v[184:187], v[134:135], off
	global_load_dwordx4 v[188:191], v[134:135], off offset:528
	global_load_dwordx4 v[200:203], v[134:135], off offset:512
	v_readlane_b32 s1, v253, 0
	v_add_co_u32_e32 v130, vcc, 0x20000, v134
	s_nop 0
	v_lshl_add_u64 v[132:133], s[0:1], 0, v[132:133]
	s_mov_b64 s[0:1], 0x20000
	v_addc_co_u32_e32 v131, vcc, 0, v135, vcc
	v_lshl_add_u64 v[132:133], v[128:129], 1, v[132:133]
	v_lshl_add_u64 v[128:129], v[134:135], 0, s[0:1]
	global_load_dwordx4 v[204:207], v[130:131], off
	global_load_dwordx4 v[208:211], v[128:129], off offset:16
	s_mov_b64 s[0:1], 0x20200
	v_lshl_add_u64 v[128:129], v[134:135], 0, s[0:1]
	global_load_dwordx4 v[230:233], v[130:131], off offset:512
	s_nop 0
	global_load_dwordx4 v[128:131], v[128:129], off offset:16
	s_mov_b32 s0, 0x10000
	s_waitcnt vmcnt(7)
	v_pk_fma_f32 v[138:139], v[122:123], v[160:161], v[138:139]
	s_waitcnt vmcnt(6)
	v_pk_fma_f32 v[170:171], v[126:127], v[164:165], v[186:187]
	v_pk_fma_f32 v[184:185], v[124:125], v[166:167], v[184:185]
	v_pk_fma_f32 v[186:187], v[120:121], v[162:163], v[136:137]
	v_cvt_pk_f16_f32 v139, v138, v139
	v_cvt_pk_f16_f32 v137, v170, v171
	v_cvt_pk_f16_f32 v138, v186, v187
	v_cvt_pk_f16_f32 v136, v184, v185
	global_store_dwordx4 v[132:133], v[136:139], off
	s_waitcnt vmcnt(5)
	v_pk_fma_f32 v[170:171], v[112:113], v[158:159], v[200:201]
	v_pk_fma_f32 v[184:185], v[104:105], v[154:155], v[188:189]
	v_pk_fma_f32 v[136:137], v[114:115], v[156:157], v[202:203]
	v_pk_fma_f32 v[138:139], v[106:107], v[152:153], v[190:191]
	v_cvt_pk_f16_f32 v137, v136, v137
	v_cvt_pk_f16_f32 v139, v138, v139
	v_cvt_pk_f16_f32 v138, v184, v185
	v_cvt_pk_f16_f32 v136, v170, v171
	global_store_dwordx4 v[132:133], v[136:139], off offset:256
	s_waitcnt vmcnt(5)
	v_pk_fma_f32 v[170:171], v[116:117], v[166:167], v[204:205]
	s_waitcnt vmcnt(4)
	v_pk_fma_f32 v[184:185], v[108:109], v[162:163], v[208:209]
	v_pk_fma_f32 v[136:137], v[118:119], v[164:165], v[206:207]
	v_pk_fma_f32 v[138:139], v[110:111], v[160:161], v[210:211]
	v_cvt_pk_f16_f32 v137, v136, v137
	v_cvt_pk_f16_f32 v136, v170, v171
	v_add_co_u32_e32 v170, vcc, s0, v132
	v_cvt_pk_f16_f32 v139, v138, v139
	v_cvt_pk_f16_f32 v138, v184, v185
	v_addc_co_u32_e32 v171, vcc, 0, v133, vcc
	global_store_dwordx4 v[170:171], v[136:139], off
	s_waitcnt vmcnt(3)
	v_pk_fma_f32 v[130:131], v[98:99], v[152:153], v[130:131]
	v_pk_fma_f32 v[184:185], v[96:97], v[154:155], v[128:129]
	v_pk_fma_f32 v[136:137], v[102:103], v[156:157], v[232:233]
	v_pk_fma_f32 v[138:139], v[100:101], v[158:159], v[230:231]
	v_cvt_pk_f16_f32 v129, v136, v137
	v_cvt_pk_f16_f32 v131, v130, v131
	v_cvt_pk_f16_f32 v128, v138, v139
	v_cvt_pk_f16_f32 v130, v184, v185
	global_store_dwordx4 v[170:171], v[128:131], off offset:256
	s_mov_b64 s[0:1], 0x40000
	v_lshl_add_u64 v[136:137], v[134:135], 0, s[0:1]
	s_mov_b32 s0, 0x40000
	v_add_co_u32_e32 v170, vcc, s0, v134
	s_mov_b64 s[0:1], 0x40200
	s_nop 0
	v_addc_co_u32_e32 v171, vcc, 0, v135, vcc
	global_load_dwordx4 v[128:131], v[170:171], off
	s_nop 0
	global_load_dwordx4 v[136:139], v[136:137], off offset:16
	v_lshl_add_u64 v[188:189], v[134:135], 0, s[0:1]
	s_mov_b32 s0, 0x60000
	global_load_dwordx4 v[184:187], v[170:171], off offset:512
	s_nop 0
	global_load_dwordx4 v[188:191], v[188:189], off offset:16
	v_add_co_u32_e32 v208, vcc, s0, v134
	v_lshl_add_u64 v[170:171], v[134:135], 0, s[76:77]
	s_nop 0
	v_addc_co_u32_e32 v209, vcc, 0, v135, vcc
	global_load_dwordx4 v[200:203], v[208:209], off
	global_load_dwordx4 v[204:207], v[170:171], off offset:16
	s_mov_b64 s[0:1], 0x60200
	v_lshl_add_u64 v[170:171], v[134:135], 0, s[0:1]
	global_load_dwordx4 v[208:211], v[208:209], off offset:512
	s_nop 0
	global_load_dwordx4 v[230:233], v[170:171], off offset:16
	s_mov_b32 s0, 0x20000
	s_waitcnt vmcnt(7)
	v_pk_fma_f32 v[130:131], v[94:95], v[164:165], v[130:131]
	s_waitcnt vmcnt(6)
	v_pk_fma_f32 v[136:137], v[88:89], v[162:163], v[136:137]
	v_pk_fma_f32 v[170:171], v[92:93], v[166:167], v[128:129]
	v_pk_fma_f32 v[138:139], v[90:91], v[160:161], v[138:139]
	v_cvt_pk_f16_f32 v129, v130, v131
	v_cvt_pk_f16_f32 v130, v136, v137
	v_add_co_u32_e32 v136, vcc, s0, v132
	v_cvt_pk_f16_f32 v128, v170, v171
	v_cvt_pk_f16_f32 v131, v138, v139
	v_addc_co_u32_e32 v137, vcc, 0, v133, vcc
	global_store_dwordx4 v[136:137], v[128:131], off
	s_waitcnt vmcnt(5)
; __device__ __forceinline__ h16x8 f_to_h8(const f32x4 a, const f32x4 b) { return (h16x8){(_Float16)a[0], (_Float16)a[1], (_Float16)a[2], (_Float16)a[3], (_Float16)b[0], (_Float16)b[1], (_Float16)b[2], (_Float16)b[3]}; }
;     __device__ __forceinline__ void operator()(f32x4 (&acc)[2][2][4][2], const Unit& u, int wr, int wc, int fr, int fq) const {
;     ...
;             for (int am = 0; am < 8; am += 2) {
;                 f32x4 xb[2][2][2];
; #pragma unroll
;                 for (int mm = 0; mm < 2; ++mm)
; #pragma unroll
;                     for (int bj = 0; bj < 2; ++bj) { const int ai = (am + mm) >> 2, m = (am + mm) & 3; const float* p = bp + (size_t)(ai * HALF + m * 16) * D + bj * HALF; xb[mm][bj][0] = *(const f32x4*)p; xb[mm][bj][1] = *(const f32x4*)(p + 4); }
; #pragma unroll
;                 for (int mm = 0; mm < 2; ++mm)
; #pragma unroll
;                     for (int bj = 0; bj < 2; ++bj) { const int ai = (am + mm) >> 2, m = (am + mm) & 3;
;                         *(h16x8*)(xp + (size_t)(ai * HALF + m * 16) * D + bj * HALF) = f_to_h8(xb[mm][bj][0] + gv[bj][0] * acc[ai][bj][m][0], xb[mm][bj][1] + gv[bj][1] * acc[ai][bj][m][1]); }
;                 __builtin_amdgcn_sched_barrier(0);
;             }
	v_pk_fma_f32 v[138:139], v[78:79], v[152:153], v[190:191]
	v_pk_fma_f32 v[170:171], v[76:77], v[154:155], v[188:189]
	v_pk_fma_f32 v[128:129], v[86:87], v[156:157], v[186:187]
	v_pk_fma_f32 v[130:131], v[84:85], v[158:159], v[184:185]
	v_cvt_pk_f16_f32 v129, v128, v129
	v_cvt_pk_f16_f32 v128, v130, v131
	v_cvt_pk_f16_f32 v131, v138, v139
	v_cvt_pk_f16_f32 v130, v170, v171
	global_store_dwordx4 v[136:137], v[128:131], off offset:256
	s_waitcnt vmcnt(4)
	v_pk_fma_f32 v[136:137], v[74:75], v[160:161], v[206:207]
	s_mov_b32 s0, 0x30000
	v_pk_fma_f32 v[128:129], v[82:83], v[164:165], v[202:203]
	v_pk_fma_f32 v[130:131], v[80:81], v[166:167], v[200:201]
	v_pk_fma_f32 v[138:139], v[72:73], v[162:163], v[204:205]
	v_cvt_pk_f16_f32 v129, v128, v129
	v_cvt_pk_f16_f32 v128, v130, v131
	v_cvt_pk_f16_f32 v131, v136, v137
	v_add_co_u32_e32 v136, vcc, s0, v132
	v_cvt_pk_f16_f32 v130, v138, v139
	s_nop 0
	v_addc_co_u32_e32 v137, vcc, 0, v133, vcc
	global_store_dwordx4 v[136:137], v[128:131], off
	s_waitcnt vmcnt(3)
	v_pk_fma_f32 v[138:139], v[66:67], v[152:153], v[232:233]
	v_pk_fma_f32 v[170:171], v[64:65], v[154:155], v[230:231]
	v_pk_fma_f32 v[128:129], v[70:71], v[156:157], v[210:211]
	v_pk_fma_f32 v[130:131], v[68:69], v[158:159], v[208:209]
	v_cvt_pk_f16_f32 v129, v128, v129
	v_cvt_pk_f16_f32 v128, v130, v131
	v_cvt_pk_f16_f32 v131, v138, v139
	v_cvt_pk_f16_f32 v130, v170, v171
	global_store_dwordx4 v[136:137], v[128:131], off offset:256
	s_mov_b64 s[0:1], 0x100000
	v_lshl_add_u64 v[136:137], v[134:135], 0, s[0:1]
	s_mov_b32 s0, 0x100000
	v_add_co_u32_e32 v170, vcc, s0, v134
	s_mov_b64 s[0:1], 0x100200
	s_nop 0
	v_addc_co_u32_e32 v171, vcc, 0, v135, vcc
	global_load_dwordx4 v[128:131], v[170:171], off
	s_nop 0
	global_load_dwordx4 v[136:139], v[136:137], off offset:16
	v_lshl_add_u64 v[188:189], v[134:135], 0, s[0:1]
	s_mov_b64 s[0:1], 0x120000
	global_load_dwordx4 v[184:187], v[170:171], off offset:512
	s_nop 0
	global_load_dwordx4 v[188:191], v[188:189], off offset:16
	v_lshl_add_u64 v[170:171], v[134:135], 0, s[0:1]
	s_mov_b32 s0, 0x120000
	v_add_co_u32_e32 v208, vcc, s0, v134
	s_mov_b64 s[0:1], 0x120200
	s_nop 0
	v_addc_co_u32_e32 v209, vcc, 0, v135, vcc
	global_load_dwordx4 v[200:203], v[208:209], off
	global_load_dwordx4 v[204:207], v[170:171], off offset:16
	v_lshl_add_u64 v[170:171], v[134:135], 0, s[0:1]
	global_load_dwordx4 v[208:211], v[208:209], off offset:512
	s_nop 0
	global_load_dwordx4 v[230:233], v[170:171], off offset:16
	s_mov_b32 s0, 0x80000
	s_waitcnt vmcnt(7)
	v_pk_fma_f32 v[130:131], v[62:63], v[164:165], v[130:131]
	s_waitcnt vmcnt(6)
	v_pk_fma_f32 v[136:137], v[56:57], v[162:163], v[136:137]
	v_pk_fma_f32 v[170:171], v[60:61], v[166:167], v[128:129]
	v_pk_fma_f32 v[138:139], v[58:59], v[160:161], v[138:139]
	v_cvt_pk_f16_f32 v129, v130, v131
	v_cvt_pk_f16_f32 v130, v136, v137
	v_add_co_u32_e32 v136, vcc, s0, v132
	v_cvt_pk_f16_f32 v128, v170, v171
	v_cvt_pk_f16_f32 v131, v138, v139
	v_addc_co_u32_e32 v137, vcc, 0, v133, vcc
	global_store_dwordx4 v[136:137], v[128:131], off
	s_waitcnt vmcnt(5)
	v_pk_fma_f32 v[138:139], v[50:51], v[152:153], v[190:191]
	v_pk_fma_f32 v[170:171], v[48:49], v[154:155], v[188:189]
	v_pk_fma_f32 v[128:129], v[54:55], v[156:157], v[186:187]
	v_pk_fma_f32 v[130:131], v[52:53], v[158:159], v[184:185]
	v_cvt_pk_f16_f32 v129, v128, v129
	v_cvt_pk_f16_f32 v128, v130, v131
	v_cvt_pk_f16_f32 v131, v138, v139
	v_cvt_pk_f16_f32 v130, v170, v171
	global_store_dwordx4 v[136:137], v[128:131], off offset:256
	s_waitcnt vmcnt(4)
; __device__ __forceinline__ h16x8 f_to_h8(const f32x4 a, const f32x4 b) { return (h16x8){(_Float16)a[0], (_Float16)a[1], (_Float16)a[2], (_Float16)a[3], (_Float16)b[0], (_Float16)b[1], (_Float16)b[2], (_Float16)b[3]}; }
;     __device__ __forceinline__ void operator()(f32x4 (&acc)[2][2][4][2], const Unit& u, int wr, int wc, int fr, int fq) const {
;     ...
;             for (int am = 0; am < 8; am += 2) {
;                 f32x4 xb[2][2][2];
; #pragma unroll
;                 for (int mm = 0; mm < 2; ++mm)
; #pragma unroll
;                     for (int bj = 0; bj < 2; ++bj) { const int ai = (am + mm) >> 2, m = (am + mm) & 3; const float* p = bp + (size_t)(ai * HALF + m * 16) * D + bj * HALF; xb[mm][bj][0] = *(const f32x4*)p; xb[mm][bj][1] = *(const f32x4*)(p + 4); }
; #pragma unroll
;                 for (int mm = 0; mm < 2; ++mm)
; #pragma unroll
;                     for (int bj = 0; bj < 2; ++bj) { const int ai = (am + mm) >> 2, m = (am + mm) & 3;
;                         *(h16x8*)(xp + (size_t)(ai * HALF + m * 16) * D + bj * HALF) = f_to_h8(xb[mm][bj][0] + gv[bj][0] * acc[ai][bj][m][0], xb[mm][bj][1] + gv[bj][1] * acc[ai][bj][m][1]); }
;                 __builtin_amdgcn_sched_barrier(0);
;             }
	v_pk_fma_f32 v[136:137], v[42:43], v[160:161], v[206:207]
	s_mov_b32 s0, 0x90000
	v_pk_fma_f32 v[128:129], v[46:47], v[164:165], v[202:203]
	v_pk_fma_f32 v[130:131], v[44:45], v[166:167], v[200:201]
	v_pk_fma_f32 v[138:139], v[40:41], v[162:163], v[204:205]
	v_cvt_pk_f16_f32 v129, v128, v129
	v_cvt_pk_f16_f32 v128, v130, v131
	v_cvt_pk_f16_f32 v131, v136, v137
	v_add_co_u32_e32 v136, vcc, s0, v132
	v_cvt_pk_f16_f32 v130, v138, v139
	s_nop 0
	v_addc_co_u32_e32 v137, vcc, 0, v133, vcc
	global_store_dwordx4 v[136:137], v[128:131], off
	s_waitcnt vmcnt(3)
	v_pk_fma_f32 v[138:139], v[34:35], v[152:153], v[232:233]
	v_pk_fma_f32 v[170:171], v[32:33], v[154:155], v[230:231]
	v_pk_fma_f32 v[128:129], v[38:39], v[156:157], v[210:211]
	v_pk_fma_f32 v[130:131], v[36:37], v[158:159], v[208:209]
	v_cvt_pk_f16_f32 v129, v128, v129
	v_cvt_pk_f16_f32 v128, v130, v131
	v_cvt_pk_f16_f32 v131, v138, v139
	v_cvt_pk_f16_f32 v130, v170, v171
	global_store_dwordx4 v[136:137], v[128:131], off offset:256
	s_mov_b64 s[0:1], 0x140000
	v_lshl_add_u64 v[136:137], v[134:135], 0, s[0:1]
	s_mov_b32 s0, 0x140000
	v_add_co_u32_e32 v170, vcc, s0, v134
	s_mov_b64 s[0:1], 0x140200
	s_nop 0
	v_addc_co_u32_e32 v171, vcc, 0, v135, vcc
	global_load_dwordx4 v[128:131], v[170:171], off
	s_nop 0
	global_load_dwordx4 v[136:139], v[136:137], off offset:16
	v_lshl_add_u64 v[188:189], v[134:135], 0, s[0:1]
	s_mov_b64 s[0:1], 0x160000
	global_load_dwordx4 v[184:187], v[170:171], off offset:512
	s_nop 0
	global_load_dwordx4 v[188:191], v[188:189], off offset:16
	v_lshl_add_u64 v[170:171], v[134:135], 0, s[0:1]
	s_mov_b32 s0, 0x160000
	v_add_co_u32_e32 v208, vcc, s0, v134
	s_mov_b64 s[0:1], 0x160200
	s_nop 0
	v_addc_co_u32_e32 v209, vcc, 0, v135, vcc
	global_load_dwordx4 v[200:203], v[208:209], off
	global_load_dwordx4 v[204:207], v[170:171], off offset:16
	v_lshl_add_u64 v[134:135], v[134:135], 0, s[0:1]
	global_load_dwordx4 v[208:211], v[208:209], off offset:512
	s_nop 0
	global_load_dwordx4 v[230:233], v[134:135], off offset:16
	s_mov_b32 s0, 0xa0000
	s_waitcnt vmcnt(7)
	v_pk_fma_f32 v[134:135], v[28:29], v[166:167], v[128:129]
	v_pk_fma_f32 v[130:131], v[30:31], v[164:165], v[130:131]
	s_waitcnt vmcnt(6)
	v_pk_fma_f32 v[138:139], v[26:27], v[160:161], v[138:139]
	v_pk_fma_f32 v[136:137], v[24:25], v[162:163], v[136:137]
	v_cvt_pk_f16_f32 v128, v134, v135
	v_add_co_u32_e32 v134, vcc, s0, v132
	v_cvt_pk_f16_f32 v129, v130, v131
	v_cvt_pk_f16_f32 v131, v138, v139
	v_cvt_pk_f16_f32 v130, v136, v137
	v_addc_co_u32_e32 v135, vcc, 0, v133, vcc
	global_store_dwordx4 v[134:135], v[128:131], off
	s_waitcnt vmcnt(5)
	v_pk_fma_f32 v[136:137], v[18:19], v[152:153], v[190:191]
	v_pk_fma_f32 v[138:139], v[16:17], v[154:155], v[188:189]
	v_pk_fma_f32 v[128:129], v[22:23], v[156:157], v[186:187]
	v_pk_fma_f32 v[130:131], v[20:21], v[158:159], v[184:185]
	v_cvt_pk_f16_f32 v129, v128, v129
	v_cvt_pk_f16_f32 v128, v130, v131
	v_cvt_pk_f16_f32 v131, v136, v137
	v_cvt_pk_f16_f32 v130, v138, v139
	s_mov_b32 s0, 0xb0000
	global_store_dwordx4 v[134:135], v[128:131], off offset:256
	s_waitcnt vmcnt(4)
	v_pk_fma_f32 v[134:135], v[10:11], v[160:161], v[206:207]
	v_pk_fma_f32 v[136:137], v[8:9], v[162:163], v[204:205]
	v_pk_fma_f32 v[128:129], v[14:15], v[164:165], v[202:203]
	v_pk_fma_f32 v[130:131], v[12:13], v[166:167], v[200:201]
	v_add_co_u32_e32 v132, vcc, s0, v132
	v_cvt_pk_f16_f32 v129, v128, v129
	v_cvt_pk_f16_f32 v128, v130, v131
	v_cvt_pk_f16_f32 v131, v134, v135
	v_cvt_pk_f16_f32 v130, v136, v137
	v_addc_co_u32_e32 v133, vcc, 0, v133, vcc
	global_store_dwordx4 v[132:133], v[128:131], off
	s_waitcnt vmcnt(3)
	v_pk_fma_f32 v[134:135], v[2:3], v[152:153], v[232:233]
	v_pk_fma_f32 v[136:137], v[0:1], v[154:155], v[230:231]
	v_pk_fma_f32 v[128:129], v[6:7], v[156:157], v[210:211]
	v_pk_fma_f32 v[130:131], v[4:5], v[158:159], v[208:209]
	v_cvt_pk_f16_f32 v129, v128, v129
	v_cvt_pk_f16_f32 v128, v130, v131
	v_cvt_pk_f16_f32 v131, v134, v135
	v_cvt_pk_f16_f32 v130, v136, v137
	global_store_dwordx4 v[132:133], v[128:131], off offset:256
	s_cbranch_execnz .LBB0_239

; #define PG8_STAGE(bufoff, gbase, voff) do { _Pragma("unroll") for (int _i = 0; _i < 2; ++_i) \
;         __builtin_amdgcn_global_load_lds((const unsigned*)((const char*)(gbase) + (voff)[_i]), (LAS unsigned*)(lds + (bufoff) + ldsw + _i * 8192), 16, 0, 0); } while (0)
; #define PG8_LDA(dst, b, h) do { _Pragma("unroll") for (int m = 0; m < 4; ++m) _Pragma("unroll") for (int k = 0; k < 2; ++k) dst[m][k] = *(const LAS bf16x8*)(lds + PG8_SA(b, h) + aoff + m * 2048 + k * 1024); } while (0)
; #define PG8_LDB(dst, b, h) do { _Pragma("unroll") for (int n = 0; n < 2; ++n) _Pragma("unroll") for (int k = 0; k < 2; ++k) dst[n][k] = *(const LAS bf16x8*)(lds + PG8_SB(b, h) + boff + n * 2048 + k * 1024); } while (0)
; #define PG8_MMA(ai, bj, At, Bt) do { __builtin_amdgcn_s_setprio(1); _Pragma("unroll") for (int m = 0; m < 4; ++m) _Pragma("unroll") for (int n = 0; n < 2; ++n) _Pragma("unroll") for (int k = 0; k < 2; ++k) \
;         acc[ai][bj][m][n] = __builtin_amdgcn_mfma_f32_16x16x32_bf16(Bt[n][k], At[m][k], acc[ai][bj][m][n], 0, 0, 0); __builtin_amdgcn_s_setprio(0); } while (0)
; #define PG8_WAIT_V(n) asm volatile("s_waitcnt vmcnt(" #n ")" ::: "memory")
; #define PG8_WAIT_L(n) asm volatile("s_waitcnt lgkmcnt(" #n ")" ::: "memory")
; template <class Epi>
; __device__ __forceinline__ void gemm_phase(LAS unsigned char* lds, const Gemm g, const StaticOrder& S, const Epi& E, const int tid) {
;     ...
;         const char* nA = has_next ? PG8_APTR(nxt) : cA; const char* nB = has_next ? PG8_BPTR(nxt) : cB;
;         for (int t = 0; t < nt; t += 2) {
;             const bool last = (t == nt - 2);
;             const char* a1 = cA + (size_t)(t + 1) * kstep;
;             const char* a2 = last ? nA : cA + (size_t)(t + 2) * kstep; const char* b2 = last ? nB : cB + (size_t)(t + 2) * kstep;
;             const char* a3 = a2 + kstep; const char* b3 = b2 + kstep;
;             PG8_LDB(B0, 0, 0); PG8_LDB(B1, 0, 1); PG8_SCHED; PG8_LDA(At, 0, 0); PG8_STAGE(PG8_SA(1, 1), a1 + hsA, voffA);
;             PG8_WAIT_V(8); PG8_WAIT_L(0); PG8_BAR; PG8_MMA(0, 0, At, B0); PG8_MMA(0, 1, At, B1); PG8_BAR; PG8_SCHED;
;     ...
;         for (int a = 0; a < 2; ++a)
; #pragma unroll
;             for (int b = 0; b < 2; ++b)
; #pragma unroll
;                 for (int m = 0; m < 4; ++m)
; #pragma unroll
;                     for (int n = 0; n < 2; ++n) acc[a][b][m][n] = (f32x4){0.f, 0.f, 0.f, 0.f};
.LBB0_353:
	s_ashr_i32 s49, s48, 31
	s_lshl_b64 s[10:11], s[48:49], 20
	s_add_u32 s52, s38, s10
	s_addc_u32 s53, s39, s11
	s_and_b64 s[10:11], s[40:41], exec
	s_cselect_b32 s10, s53, s1
	s_cselect_b32 s11, s52, s0
	s_ashr_i32 s47, s46, 31
	s_lshl_b64 s[12:13], s[46:47], 20
	v_readlane_b32 s16, v255, 32
	s_add_u32 s12, s16, s12
	v_readlane_b32 s16, v255, 33
	s_addc_u32 s13, s16, s13
	s_and_b64 s[36:37], s[40:41], exec
	s_cselect_b32 s47, s13, s43
	s_cselect_b32 s49, s12, s42
	s_add_u32 s36, s0, 0x80080
	s_addc_u32 s37, s1, 0
	s_add_u32 s69, s42, 0x100
	v_mov_b32_e32 v0, 0
	s_addc_u32 vcc_lo, s43, 0
	s_mov_b32 vcc_hi, -2
	v_mov_b32_e32 v1, v0
	v_mov_b32_e32 v2, v0
	v_mov_b32_e32 v3, v0
	v_mov_b32_e32 v4, v0
	v_mov_b32_e32 v5, v0
	v_mov_b32_e32 v6, v0
	v_mov_b32_e32 v7, v0
	v_mov_b32_e32 v16, v0
	v_mov_b32_e32 v17, v0
	v_mov_b32_e32 v18, v0
	v_mov_b32_e32 v19, v0
	v_mov_b32_e32 v20, v0
	v_mov_b32_e32 v21, v0
	v_mov_b32_e32 v22, v0
	v_mov_b32_e32 v23, v0
	v_mov_b32_e32 v32, v0
	v_mov_b32_e32 v33, v0
	v_mov_b32_e32 v34, v0
	v_mov_b32_e32 v35, v0
	v_mov_b32_e32 v36, v0
	v_mov_b32_e32 v37, v0
	v_mov_b32_e32 v38, v0
	v_mov_b32_e32 v39, v0
	v_mov_b32_e32 v48, v0
	v_mov_b32_e32 v49, v0
	v_mov_b32_e32 v50, v0
	v_mov_b32_e32 v51, v0
	v_mov_b32_e32 v52, v0
	v_mov_b32_e32 v53, v0
	v_mov_b32_e32 v54, v0
	v_mov_b32_e32 v55, v0
	v_mov_b32_e32 v8, v0
	v_mov_b32_e32 v9, v0
	v_mov_b32_e32 v10, v0
	v_mov_b32_e32 v11, v0
	v_mov_b32_e32 v12, v0
	v_mov_b32_e32 v13, v0
	v_mov_b32_e32 v14, v0
	v_mov_b32_e32 v15, v0
	v_mov_b32_e32 v24, v0
	v_mov_b32_e32 v25, v0
	v_mov_b32_e32 v26, v0
	v_mov_b32_e32 v27, v0
	v_mov_b32_e32 v28, v0
	v_mov_b32_e32 v29, v0
	v_mov_b32_e32 v30, v0
	v_mov_b32_e32 v31, v0
	v_mov_b32_e32 v40, v0
	v_mov_b32_e32 v41, v0
	v_mov_b32_e32 v42, v0
	v_mov_b32_e32 v43, v0
	v_mov_b32_e32 v44, v0
	v_mov_b32_e32 v45, v0
	v_mov_b32_e32 v46, v0
	v_mov_b32_e32 v47, v0
	v_mov_b32_e32 v56, v0
	v_mov_b32_e32 v57, v0
	v_mov_b32_e32 v58, v0
	v_mov_b32_e32 v59, v0
	v_mov_b32_e32 v60, v0
	v_mov_b32_e32 v61, v0
	v_mov_b32_e32 v62, v0
	v_mov_b32_e32 v63, v0
	v_mov_b32_e32 v64, v0
	v_mov_b32_e32 v65, v0
	v_mov_b32_e32 v66, v0
	v_mov_b32_e32 v67, v0
	v_mov_b32_e32 v68, v0
	v_mov_b32_e32 v69, v0
	v_mov_b32_e32 v70, v0
	v_mov_b32_e32 v71, v0
	v_mov_b32_e32 v80, v0
	v_mov_b32_e32 v81, v0
	v_mov_b32_e32 v82, v0
	v_mov_b32_e32 v83, v0
	v_mov_b32_e32 v84, v0
	v_mov_b32_e32 v85, v0
	v_mov_b32_e32 v86, v0
	v_mov_b32_e32 v87, v0
	v_mov_b32_e32 v96, v0
	v_mov_b32_e32 v97, v0
	v_mov_b32_e32 v98, v0
	v_mov_b32_e32 v99, v0
	v_mov_b32_e32 v100, v0
	v_mov_b32_e32 v101, v0
	v_mov_b32_e32 v102, v0
	v_mov_b32_e32 v103, v0
	v_mov_b32_e32 v112, v0
	v_mov_b32_e32 v113, v0
	v_mov_b32_e32 v114, v0
	v_mov_b32_e32 v115, v0
	v_mov_b32_e32 v116, v0
	v_mov_b32_e32 v117, v0
	v_mov_b32_e32 v118, v0
	v_mov_b32_e32 v119, v0
	v_mov_b32_e32 v72, v0
	v_mov_b32_e32 v73, v0
	v_mov_b32_e32 v74, v0
	v_mov_b32_e32 v75, v0
	v_mov_b32_e32 v76, v0
	v_mov_b32_e32 v77, v0
	v_mov_b32_e32 v78, v0
	v_mov_b32_e32 v79, v0
	v_mov_b32_e32 v88, v0
	v_mov_b32_e32 v89, v0
	v_mov_b32_e32 v90, v0
	v_mov_b32_e32 v91, v0
	v_mov_b32_e32 v92, v0
	v_mov_b32_e32 v93, v0
	v_mov_b32_e32 v94, v0
	v_mov_b32_e32 v95, v0
	v_mov_b32_e32 v104, v0
	v_mov_b32_e32 v105, v0
	v_mov_b32_e32 v106, v0
	v_mov_b32_e32 v107, v0
	v_mov_b32_e32 v108, v0
	v_mov_b32_e32 v109, v0
	v_mov_b32_e32 v110, v0
	v_mov_b32_e32 v111, v0
	v_mov_b32_e32 v120, v0
	v_mov_b32_e32 v121, v0
	v_mov_b32_e32 v122, v0
	v_mov_b32_e32 v123, v0
	v_mov_b32_e32 v124, v0
	v_mov_b32_e32 v125, v0
	v_mov_b32_e32 v126, v0
	v_mov_b32_e32 v127, v0
	s_cmp_lg_u64 s[34:35], 0
	s_cbranch_scc1 .Lgprio_c
	s_setprio 1
.Lgprio_c:
.LBB0_354:
	s_add_u32 s0, s36, 0xfff80080
	s_addc_u32 s1, s37, -1
	s_add_i32 s24, 0, 0x10000
	s_cmp_eq_u32 vcc_hi, 28
	s_cselect_b32 s43, s10, s1
	s_cselect_b32 s42, s11, s0
	v_add_u32_e32 v143, s24, v163
	s_cselect_b32 s1, s47, vcc_lo
	s_cselect_b32 s0, s49, s69
	s_add_i32 s55, 0, 0x14000
	ds_read_b128 v[144:147], v143
	ds_read_b128 v[148:151], v143 offset:1024
	ds_read_b128 v[152:155], v143 offset:2048
	ds_read_b128 v[156:159], v143 offset:3072
	v_add_u32_e32 v143, s55, v163
	ds_read_b128 v[184:187], v143
	ds_read_b128 v[188:191], v143 offset:1024
	ds_read_b128 v[192:195], v143 offset:2048
	ds_read_b128 v[196:199], v143 offset:3072
	v_lshl_add_u64 v[160:161], s[36:37], 0, v[138:139]
	s_add_i32 m0, s58, 0xc000
	ds_read_b128 v[200:203], v165
	ds_read_b128 v[204:207], v165 offset:1024
	ds_read_b128 v[208:211], v165 offset:2048
	ds_read_b128 v[232:235], v165 offset:3072
	ds_read_b128 v[236:239], v165 offset:4096
	ds_read_b128 v[240:243], v165 offset:5120
	ds_read_b128 v[244:247], v165 offset:6144
	ds_read_b128 v[248:251], v165 offset:7168
	global_load_lds_dwordx4 v[160:161], off
	v_lshl_add_u64 v[160:161], s[36:37], 0, v[140:141]
	s_add_i32 m0, s58, 0xe000
	s_nop 0
	global_load_lds_dwordx4 v[160:161], off
	s_waitcnt vmcnt(8)
	s_waitcnt lgkmcnt(0)
	s_barrier
; #define PG8_STAGE(bufoff, gbase, voff) do { _Pragma("unroll") for (int _i = 0; _i < 2; ++_i) \
;         __builtin_amdgcn_global_load_lds((const unsigned*)((const char*)(gbase) + (voff)[_i]), (LAS unsigned*)(lds + (bufoff) + ldsw + _i * 8192), 16, 0, 0); } while (0)
; #define PG8_LDA(dst, b, h) do { _Pragma("unroll") for (int m = 0; m < 4; ++m) _Pragma("unroll") for (int k = 0; k < 2; ++k) dst[m][k] = *(const LAS bf16x8*)(lds + PG8_SA(b, h) + aoff + m * 2048 + k * 1024); } while (0)
; #define PG8_MMA(ai, bj, At, Bt) do { __builtin_amdgcn_s_setprio(1); _Pragma("unroll") for (int m = 0; m < 4; ++m) _Pragma("unroll") for (int n = 0; n < 2; ++n) _Pragma("unroll") for (int k = 0; k < 2; ++k) \
;         acc[ai][bj][m][n] = __builtin_amdgcn_mfma_f32_16x16x32_bf16(Bt[n][k], At[m][k], acc[ai][bj][m][n], 0, 0, 0); __builtin_amdgcn_s_setprio(0); } while (0)
; #define PG8_WAIT_V(n) asm volatile("s_waitcnt vmcnt(" #n ")" ::: "memory")
; #define PG8_WAIT_L(n) asm volatile("s_waitcnt lgkmcnt(" #n ")" ::: "memory")
; #define PG8_BAR __builtin_amdgcn_s_barrier()
; #define PG8_SCHED __builtin_amdgcn_sched_barrier(0)
; template <class Epi>
; __device__ __forceinline__ void gemm_phase(LAS unsigned char* lds, const Gemm g, const StaticOrder& S, const Epi& E, const int tid) {
;     ...
;             PG8_WAIT_V(8); PG8_WAIT_L(0); PG8_BAR; PG8_MMA(0, 0, At, B0); PG8_MMA(0, 1, At, B1); PG8_BAR; PG8_SCHED;
;             PG8_LDA(At, 0, 1); PG8_STAGE(PG8_SB(0, 0), b2, voffB); PG8_STAGE(PG8_SB(0, 1), b2 + hsB, voffB); PG8_STAGE(PG8_SA(0, 0), a2, voffA);
;             PG8_WAIT_V(8); PG8_WAIT_L(0); PG8_BAR; PG8_MMA(1, 0, At, B0); PG8_MMA(1, 1, At, B1); PG8_BAR; PG8_SCHED;
	s_waitcnt lgkmcnt(0)
	v_mfma_f32_16x16x32_bf16 v[124:127], v[144:147], v[200:203], v[124:127]
	v_mfma_f32_16x16x32_bf16 v[120:123], v[152:155], v[200:203], v[120:123]
	v_mfma_f32_16x16x32_bf16 v[108:111], v[144:147], v[208:211], v[108:111]
	v_mfma_f32_16x16x32_bf16 v[104:107], v[152:155], v[208:211], v[104:107]
	v_mfma_f32_16x16x32_bf16 v[92:95], v[144:147], v[236:239], v[92:95]
	v_mfma_f32_16x16x32_bf16 v[88:91], v[152:155], v[236:239], v[88:91]
	v_mfma_f32_16x16x32_bf16 v[76:79], v[144:147], v[244:247], v[76:79]
	v_mfma_f32_16x16x32_bf16 v[72:75], v[152:155], v[244:247], v[72:75]
	v_mfma_f32_16x16x32_bf16 v[124:127], v[148:151], v[204:207], v[124:127]
	v_mfma_f32_16x16x32_bf16 v[120:123], v[156:159], v[204:207], v[120:123]
	v_mfma_f32_16x16x32_bf16 v[108:111], v[148:151], v[232:235], v[108:111]
	v_mfma_f32_16x16x32_bf16 v[104:107], v[156:159], v[232:235], v[104:107]
	v_mfma_f32_16x16x32_bf16 v[92:95], v[148:151], v[240:243], v[92:95]
	v_mfma_f32_16x16x32_bf16 v[88:91], v[156:159], v[240:243], v[88:91]
	v_mfma_f32_16x16x32_bf16 v[76:79], v[148:151], v[248:251], v[76:79]
	v_mfma_f32_16x16x32_bf16 v[72:75], v[156:159], v[248:251], v[72:75]
	v_mfma_f32_16x16x32_bf16 v[116:119], v[184:187], v[200:203], v[116:119]
	v_mfma_f32_16x16x32_bf16 v[112:115], v[192:195], v[200:203], v[112:115]
	v_mfma_f32_16x16x32_bf16 v[100:103], v[184:187], v[208:211], v[100:103]
	v_mfma_f32_16x16x32_bf16 v[96:99], v[192:195], v[208:211], v[96:99]
	v_mfma_f32_16x16x32_bf16 v[84:87], v[184:187], v[236:239], v[84:87]
	v_mfma_f32_16x16x32_bf16 v[80:83], v[192:195], v[236:239], v[80:83]
	v_mfma_f32_16x16x32_bf16 v[68:71], v[184:187], v[244:247], v[68:71]
	v_mfma_f32_16x16x32_bf16 v[64:67], v[192:195], v[244:247], v[64:67]
	v_mfma_f32_16x16x32_bf16 v[116:119], v[188:191], v[204:207], v[116:119]
	v_mfma_f32_16x16x32_bf16 v[112:115], v[196:199], v[204:207], v[112:115]
	v_mfma_f32_16x16x32_bf16 v[100:103], v[188:191], v[232:235], v[100:103]
	v_mfma_f32_16x16x32_bf16 v[96:99], v[196:199], v[232:235], v[96:99]
	v_mfma_f32_16x16x32_bf16 v[84:87], v[188:191], v[240:243], v[84:87]
	v_mfma_f32_16x16x32_bf16 v[80:83], v[196:199], v[240:243], v[80:83]
	v_mfma_f32_16x16x32_bf16 v[68:71], v[188:191], v[248:251], v[68:71]
	v_mfma_f32_16x16x32_bf16 v[64:67], v[196:199], v[248:251], v[64:67]
	s_barrier
	s_add_i32 s24, s24, s57
	v_lshl_add_u64 v[160:161], s[0:1], 0, v[132:133]
	s_mov_b32 m0, s24
	ds_read_b128 v[200:203], v165 offset:16384
	ds_read_b128 v[204:207], v165 offset:17408
	ds_read_b128 v[208:211], v165 offset:18432
	ds_read_b128 v[232:235], v165 offset:19456
	ds_read_b128 v[236:239], v165 offset:20480
	ds_read_b128 v[240:243], v165 offset:21504
	ds_read_b128 v[244:247], v165 offset:22528
	ds_read_b128 v[248:251], v165 offset:23552
	global_load_lds_dwordx4 v[160:161], off
	s_add_i32 m0, s24, 0x2000
	s_add_u32 s24, s0, 0x80000
	v_lshl_add_u64 v[166:167], s[0:1], 0, v[128:129]
	s_addc_u32 s25, s1, 0
	s_add_i32 s55, s55, s57
	global_load_lds_dwordx4 v[166:167], off
	v_lshl_add_u64 v[170:171], s[24:25], 0, v[132:133]
	s_mov_b32 m0, s55
	v_lshl_add_u64 v[212:213], s[42:43], 0, v[130:131]
	global_load_lds_dwordx4 v[170:171], off
	v_lshl_add_u64 v[170:171], s[24:25], 0, v[128:129]
	s_add_i32 m0, s55, 0x2000
	s_nop 0
	global_load_lds_dwordx4 v[170:171], off
	v_lshl_add_u64 v[170:171], s[42:43], 0, v[134:135]
	s_mov_b32 m0, s58
	s_nop 0
	global_load_lds_dwordx4 v[170:171], off
	s_mov_b32 m0, s59
	s_nop 0
	global_load_lds_dwordx4 v[212:213], off
	s_waitcnt vmcnt(8)
	s_waitcnt lgkmcnt(0)
	s_barrier
	s_waitcnt lgkmcnt(0)
	v_mfma_f32_16x16x32_bf16 v[60:63], v[144:147], v[200:203], v[60:63]
	v_mfma_f32_16x16x32_bf16 v[56:59], v[152:155], v[200:203], v[56:59]
	v_mfma_f32_16x16x32_bf16 v[44:47], v[144:147], v[208:211], v[44:47]
	v_mfma_f32_16x16x32_bf16 v[40:43], v[152:155], v[208:211], v[40:43]
	v_mfma_f32_16x16x32_bf16 v[28:31], v[144:147], v[236:239], v[28:31]
	v_mfma_f32_16x16x32_bf16 v[24:27], v[152:155], v[236:239], v[24:27]
	v_mfma_f32_16x16x32_bf16 v[12:15], v[144:147], v[244:247], v[12:15]
	v_mfma_f32_16x16x32_bf16 v[8:11], v[152:155], v[244:247], v[8:11]
	v_mfma_f32_16x16x32_bf16 v[60:63], v[148:151], v[204:207], v[60:63]
	v_mfma_f32_16x16x32_bf16 v[56:59], v[156:159], v[204:207], v[56:59]
	v_mfma_f32_16x16x32_bf16 v[44:47], v[148:151], v[232:235], v[44:47]
	v_mfma_f32_16x16x32_bf16 v[40:43], v[156:159], v[232:235], v[40:43]
	v_mfma_f32_16x16x32_bf16 v[28:31], v[148:151], v[240:243], v[28:31]
	v_mfma_f32_16x16x32_bf16 v[24:27], v[156:159], v[240:243], v[24:27]
	v_mfma_f32_16x16x32_bf16 v[12:15], v[148:151], v[248:251], v[12:15]
	v_mfma_f32_16x16x32_bf16 v[8:11], v[156:159], v[248:251], v[8:11]
	v_mfma_f32_16x16x32_bf16 v[52:55], v[184:187], v[200:203], v[52:55]
	v_mfma_f32_16x16x32_bf16 v[48:51], v[192:195], v[200:203], v[48:51]
	v_mfma_f32_16x16x32_bf16 v[36:39], v[184:187], v[208:211], v[36:39]
	v_mfma_f32_16x16x32_bf16 v[32:35], v[192:195], v[208:211], v[32:35]
	v_mfma_f32_16x16x32_bf16 v[20:23], v[184:187], v[236:239], v[20:23]
	v_mfma_f32_16x16x32_bf16 v[16:19], v[192:195], v[236:239], v[16:19]
	v_mfma_f32_16x16x32_bf16 v[4:7], v[184:187], v[244:247], v[4:7]
	v_mfma_f32_16x16x32_bf16 v[0:3], v[192:195], v[244:247], v[0:3]
	v_mfma_f32_16x16x32_bf16 v[52:55], v[188:191], v[204:207], v[52:55]
	v_mfma_f32_16x16x32_bf16 v[48:51], v[196:199], v[204:207], v[48:51]
	v_mfma_f32_16x16x32_bf16 v[36:39], v[188:191], v[232:235], v[36:39]
	v_mfma_f32_16x16x32_bf16 v[32:35], v[196:199], v[232:235], v[32:35]
	v_mfma_f32_16x16x32_bf16 v[20:23], v[188:191], v[240:243], v[20:23]
	v_mfma_f32_16x16x32_bf16 v[16:19], v[196:199], v[240:243], v[16:19]
	v_mfma_f32_16x16x32_bf16 v[4:7], v[188:191], v[248:251], v[4:7]
	v_mfma_f32_16x16x32_bf16 v[0:3], v[196:199], v[248:251], v[0:3]
	s_barrier
; #define PG8_STAGE(bufoff, gbase, voff) do { _Pragma("unroll") for (int _i = 0; _i < 2; ++_i) \
;         __builtin_amdgcn_global_load_lds((const unsigned*)((const char*)(gbase) + (voff)[_i]), (LAS unsigned*)(lds + (bufoff) + ldsw + _i * 8192), 16, 0, 0); } while (0)
; #define PG8_LDA(dst, b, h) do { _Pragma("unroll") for (int m = 0; m < 4; ++m) _Pragma("unroll") for (int k = 0; k < 2; ++k) dst[m][k] = *(const LAS bf16x8*)(lds + PG8_SA(b, h) + aoff + m * 2048 + k * 1024); } while (0)
; #define PG8_LDB(dst, b, h) do { _Pragma("unroll") for (int n = 0; n < 2; ++n) _Pragma("unroll") for (int k = 0; k < 2; ++k) dst[n][k] = *(const LAS bf16x8*)(lds + PG8_SB(b, h) + boff + n * 2048 + k * 1024); } while (0)
; #define PG8_MMA(ai, bj, At, Bt) do { __builtin_amdgcn_s_setprio(1); _Pragma("unroll") for (int m = 0; m < 4; ++m) _Pragma("unroll") for (int n = 0; n < 2; ++n) _Pragma("unroll") for (int k = 0; k < 2; ++k) \
;         acc[ai][bj][m][n] = __builtin_amdgcn_mfma_f32_16x16x32_bf16(Bt[n][k], At[m][k], acc[ai][bj][m][n], 0, 0, 0); __builtin_amdgcn_s_setprio(0); } while (0)
; #define PG8_WAIT_V(n) asm volatile("s_waitcnt vmcnt(" #n ")" ::: "memory")
; #define PG8_WAIT_L(n) asm volatile("s_waitcnt lgkmcnt(" #n ")" ::: "memory")
; #define PG8_BAR __builtin_amdgcn_s_barrier()
; #define PG8_SCHED __builtin_amdgcn_sched_barrier(0)
; template <class Epi>
; __device__ __forceinline__ void gemm_phase(LAS unsigned char* lds, const Gemm g, const StaticOrder& S, const Epi& E, const int tid) {
;     ...
;             PG8_LDB(B0, 1, 0); PG8_LDB(B1, 1, 1); PG8_SCHED; PG8_LDA(At, 1, 0); PG8_STAGE(PG8_SA(0, 1), a2 + hsA, voffA);
;             PG8_WAIT_V(8); PG8_WAIT_L(0); PG8_BAR; PG8_MMA(0, 0, At, B0); PG8_MMA(0, 1, At, B1); PG8_BAR; PG8_SCHED;
	s_add_i32 s55, 0, 0x18000
	v_add_u32_e32 v143, s55, v163
	s_add_i32 s67, 0, 0x1c000
	ds_read_b128 v[144:147], v143
	ds_read_b128 v[148:151], v143 offset:1024
	ds_read_b128 v[152:155], v143 offset:2048
	ds_read_b128 v[156:159], v143 offset:3072
	v_add_u32_e32 v143, s67, v163
	ds_read_b128 v[184:187], v143
	ds_read_b128 v[188:191], v143 offset:1024
	ds_read_b128 v[192:195], v143 offset:2048
	ds_read_b128 v[196:199], v143 offset:3072
	s_add_u32 s24, s42, 0x80000
	s_addc_u32 s25, s43, 0
	s_mov_b32 m0, s27
	v_lshl_add_u64 v[172:173], s[24:25], 0, v[134:135]
	ds_read_b128 v[200:203], v165 offset:32768
	ds_read_b128 v[204:207], v165 offset:33792
	ds_read_b128 v[208:211], v165 offset:34816
	ds_read_b128 v[232:235], v165 offset:35840
	ds_read_b128 v[236:239], v165 offset:36864
	ds_read_b128 v[240:243], v165 offset:37888
	ds_read_b128 v[244:247], v165 offset:38912
	ds_read_b128 v[248:251], v165 offset:39936
	global_load_lds_dwordx4 v[172:173], off
	v_lshl_add_u64 v[172:173], s[24:25], 0, v[130:131]
	s_mov_b32 m0, s96
	s_nop 0
	global_load_lds_dwordx4 v[172:173], off
	s_waitcnt vmcnt(8)
	s_waitcnt lgkmcnt(0)
	s_barrier
	s_waitcnt lgkmcnt(0)
	v_mfma_f32_16x16x32_bf16 v[124:127], v[144:147], v[200:203], v[124:127]
	v_mfma_f32_16x16x32_bf16 v[120:123], v[152:155], v[200:203], v[120:123]
	v_mfma_f32_16x16x32_bf16 v[108:111], v[144:147], v[208:211], v[108:111]
	v_mfma_f32_16x16x32_bf16 v[104:107], v[152:155], v[208:211], v[104:107]
	v_mfma_f32_16x16x32_bf16 v[92:95], v[144:147], v[236:239], v[92:95]
	v_mfma_f32_16x16x32_bf16 v[88:91], v[152:155], v[236:239], v[88:91]
	v_mfma_f32_16x16x32_bf16 v[76:79], v[144:147], v[244:247], v[76:79]
	v_mfma_f32_16x16x32_bf16 v[72:75], v[152:155], v[244:247], v[72:75]
	v_mfma_f32_16x16x32_bf16 v[124:127], v[148:151], v[204:207], v[124:127]
	v_mfma_f32_16x16x32_bf16 v[120:123], v[156:159], v[204:207], v[120:123]
	v_mfma_f32_16x16x32_bf16 v[108:111], v[148:151], v[232:235], v[108:111]
	v_mfma_f32_16x16x32_bf16 v[104:107], v[156:159], v[232:235], v[104:107]
	v_mfma_f32_16x16x32_bf16 v[92:95], v[148:151], v[240:243], v[92:95]
	v_mfma_f32_16x16x32_bf16 v[88:91], v[156:159], v[240:243], v[88:91]
	v_mfma_f32_16x16x32_bf16 v[76:79], v[148:151], v[248:251], v[76:79]
	v_mfma_f32_16x16x32_bf16 v[72:75], v[156:159], v[248:251], v[72:75]
	v_mfma_f32_16x16x32_bf16 v[116:119], v[184:187], v[200:203], v[116:119]
	v_mfma_f32_16x16x32_bf16 v[112:115], v[192:195], v[200:203], v[112:115]
	v_mfma_f32_16x16x32_bf16 v[100:103], v[184:187], v[208:211], v[100:103]
	v_mfma_f32_16x16x32_bf16 v[96:99], v[192:195], v[208:211], v[96:99]
	v_mfma_f32_16x16x32_bf16 v[84:87], v[184:187], v[236:239], v[84:87]
	v_mfma_f32_16x16x32_bf16 v[80:83], v[192:195], v[236:239], v[80:83]
	v_mfma_f32_16x16x32_bf16 v[68:71], v[184:187], v[244:247], v[68:71]
	v_mfma_f32_16x16x32_bf16 v[64:67], v[192:195], v[244:247], v[64:67]
	v_mfma_f32_16x16x32_bf16 v[116:119], v[188:191], v[204:207], v[116:119]
	v_mfma_f32_16x16x32_bf16 v[112:115], v[196:199], v[204:207], v[112:115]
	v_mfma_f32_16x16x32_bf16 v[100:103], v[188:191], v[232:235], v[100:103]
	v_mfma_f32_16x16x32_bf16 v[96:99], v[196:199], v[232:235], v[96:99]
	v_mfma_f32_16x16x32_bf16 v[84:87], v[188:191], v[240:243], v[84:87]
	v_mfma_f32_16x16x32_bf16 v[80:83], v[196:199], v[240:243], v[80:83]
	v_mfma_f32_16x16x32_bf16 v[68:71], v[188:191], v[248:251], v[68:71]
	v_mfma_f32_16x16x32_bf16 v[64:67], v[196:199], v[248:251], v[64:67]
	s_barrier
; #define PG8_STAGE(bufoff, gbase, voff) do { _Pragma("unroll") for (int _i = 0; _i < 2; ++_i) \
;         __builtin_amdgcn_global_load_lds((const unsigned*)((const char*)(gbase) + (voff)[_i]), (LAS unsigned*)(lds + (bufoff) + ldsw + _i * 8192), 16, 0, 0); } while (0)
; #define PG8_LDA(dst, b, h) do { _Pragma("unroll") for (int m = 0; m < 4; ++m) _Pragma("unroll") for (int k = 0; k < 2; ++k) dst[m][k] = *(const LAS bf16x8*)(lds + PG8_SA(b, h) + aoff + m * 2048 + k * 1024); } while (0)
; #define PG8_MMA(ai, bj, At, Bt) do { __builtin_amdgcn_s_setprio(1); _Pragma("unroll") for (int m = 0; m < 4; ++m) _Pragma("unroll") for (int n = 0; n < 2; ++n) _Pragma("unroll") for (int k = 0; k < 2; ++k) \
;         acc[ai][bj][m][n] = __builtin_amdgcn_mfma_f32_16x16x32_bf16(Bt[n][k], At[m][k], acc[ai][bj][m][n], 0, 0, 0); __builtin_amdgcn_s_setprio(0); } while (0)
; #define PG8_WAIT_V(n) asm volatile("s_waitcnt vmcnt(" #n ")" ::: "memory")
; #define PG8_WAIT_L(n) asm volatile("s_waitcnt lgkmcnt(" #n ")" ::: "memory")
; #define PG8_BAR __builtin_amdgcn_s_barrier()
; #define PG8_SCHED __builtin_amdgcn_sched_barrier(0)
; template <class Epi>
; __device__ __forceinline__ void gemm_phase(LAS unsigned char* lds, const Gemm g, const StaticOrder& S, const Epi& E, const int tid) {
;     ...
;             PG8_LDA(At, 1, 1); PG8_STAGE(PG8_SB(1, 0), b3, voffB); PG8_STAGE(PG8_SB(1, 1), b3 + hsB, voffB); PG8_STAGE(PG8_SA(1, 0), a3, voffA);
;             PG8_WAIT_V(8); PG8_WAIT_L(0); PG8_BAR; PG8_MMA(1, 0, At, B0); PG8_MMA(1, 1, At, B1); PG8_BAR; PG8_SCHED;
;         }
;         if (wr == 0) PG8_BAR;
;     __device__ __forceinline__ void operator()(f32x4 (&acc)[2][2][4][2], const Unit& u, int wr, int wc, int fr, int fq) const {
;         const int row0 = u.pm * BM + wr * 64 + fr;
;         if (u.pn < 8) {
	s_add_i32 s24, s55, s57
	v_lshl_add_u64 v[160:161], v[160:161], 0, s[28:29]
	s_mov_b32 m0, s24
	ds_read_b128 v[200:203], v165 offset:49152
	ds_read_b128 v[204:207], v165 offset:50176
	ds_read_b128 v[208:211], v165 offset:51200
	ds_read_b128 v[232:235], v165 offset:52224
	ds_read_b128 v[236:239], v165 offset:53248
	ds_read_b128 v[240:243], v165 offset:54272
	ds_read_b128 v[244:247], v165 offset:55296
	ds_read_b128 v[248:251], v165 offset:56320
	global_load_lds_dwordx4 v[160:161], off
	s_add_i32 m0, s24, 0x2000
	s_add_u32 s0, s0, 0x80080
	v_lshl_add_u64 v[160:161], v[166:167], 0, s[28:29]
	s_addc_u32 s1, s1, 0
	s_add_i32 s24, s67, s57
	global_load_lds_dwordx4 v[160:161], off
	v_lshl_add_u64 v[160:161], s[0:1], 0, v[132:133]
	s_mov_b32 m0, s24
	s_nop 0
	global_load_lds_dwordx4 v[160:161], off
	v_lshl_add_u64 v[160:161], s[0:1], 0, v[128:129]
	s_add_i32 m0, s24, 0x2000
	s_nop 0
	global_load_lds_dwordx4 v[160:161], off
	v_lshl_add_u64 v[160:161], v[170:171], 0, s[28:29]
	s_mov_b32 m0, s6
	s_nop 0
	global_load_lds_dwordx4 v[160:161], off
	v_lshl_add_u64 v[160:161], v[212:213], 0, s[28:29]
	s_mov_b32 m0, s7
	s_nop 0
	global_load_lds_dwordx4 v[160:161], off
	s_waitcnt vmcnt(8)
	s_waitcnt lgkmcnt(0)
	s_barrier
	s_waitcnt lgkmcnt(0)
	v_mfma_f32_16x16x32_bf16 v[60:63], v[144:147], v[200:203], v[60:63]
	v_mfma_f32_16x16x32_bf16 v[56:59], v[152:155], v[200:203], v[56:59]
	v_mfma_f32_16x16x32_bf16 v[44:47], v[144:147], v[208:211], v[44:47]
	v_mfma_f32_16x16x32_bf16 v[40:43], v[152:155], v[208:211], v[40:43]
	v_mfma_f32_16x16x32_bf16 v[28:31], v[144:147], v[236:239], v[28:31]
	v_mfma_f32_16x16x32_bf16 v[24:27], v[152:155], v[236:239], v[24:27]
	v_mfma_f32_16x16x32_bf16 v[12:15], v[144:147], v[244:247], v[12:15]
	v_mfma_f32_16x16x32_bf16 v[8:11], v[152:155], v[244:247], v[8:11]
	v_mfma_f32_16x16x32_bf16 v[60:63], v[148:151], v[204:207], v[60:63]
	v_mfma_f32_16x16x32_bf16 v[56:59], v[156:159], v[204:207], v[56:59]
	v_mfma_f32_16x16x32_bf16 v[44:47], v[148:151], v[232:235], v[44:47]
	v_mfma_f32_16x16x32_bf16 v[40:43], v[156:159], v[232:235], v[40:43]
	v_mfma_f32_16x16x32_bf16 v[28:31], v[148:151], v[240:243], v[28:31]
	v_mfma_f32_16x16x32_bf16 v[24:27], v[156:159], v[240:243], v[24:27]
	v_mfma_f32_16x16x32_bf16 v[12:15], v[148:151], v[248:251], v[12:15]
	v_mfma_f32_16x16x32_bf16 v[8:11], v[156:159], v[248:251], v[8:11]
	v_mfma_f32_16x16x32_bf16 v[52:55], v[184:187], v[200:203], v[52:55]
	v_mfma_f32_16x16x32_bf16 v[48:51], v[192:195], v[200:203], v[48:51]
	v_mfma_f32_16x16x32_bf16 v[36:39], v[184:187], v[208:211], v[36:39]
	v_mfma_f32_16x16x32_bf16 v[32:35], v[192:195], v[208:211], v[32:35]
	v_mfma_f32_16x16x32_bf16 v[20:23], v[184:187], v[236:239], v[20:23]
	v_mfma_f32_16x16x32_bf16 v[16:19], v[192:195], v[236:239], v[16:19]
	v_mfma_f32_16x16x32_bf16 v[4:7], v[184:187], v[244:247], v[4:7]
	v_mfma_f32_16x16x32_bf16 v[0:3], v[192:195], v[244:247], v[0:3]
	v_mfma_f32_16x16x32_bf16 v[52:55], v[188:191], v[204:207], v[52:55]
	v_mfma_f32_16x16x32_bf16 v[48:51], v[196:199], v[204:207], v[48:51]
	v_mfma_f32_16x16x32_bf16 v[36:39], v[188:191], v[232:235], v[36:39]
	v_mfma_f32_16x16x32_bf16 v[32:35], v[196:199], v[232:235], v[32:35]
	v_mfma_f32_16x16x32_bf16 v[20:23], v[188:191], v[240:243], v[20:23]
	v_mfma_f32_16x16x32_bf16 v[16:19], v[196:199], v[240:243], v[16:19]
	v_mfma_f32_16x16x32_bf16 v[4:7], v[188:191], v[248:251], v[4:7]
	v_mfma_f32_16x16x32_bf16 v[0:3], v[196:199], v[248:251], v[0:3]
	s_barrier
	s_add_i32 vcc_hi, vcc_hi, 2
	s_add_u32 s36, s36, 0x100
	s_addc_u32 s37, s37, 0
	s_add_u32 s69, s69, 0x100
	s_addc_u32 vcc_lo, vcc_lo, 0
	s_cmp_gt_u32 vcc_hi, 29
	s_cbranch_scc0 .LBB0_354
	s_and_b64 vcc, exec, s[34:35]
	s_cbranch_vccz .LBB0_357
	s_barrier
.LBB0_357:
	s_setprio 0
	v_lshl_add_u32 v166, s60, 8, v162
	s_cmp_gt_i32 s45, 7
	s_mov_b64 s[0:1], -1
	s_cbranch_scc0 .LBB0_421
	s_cmp_gt_u32 s45, 11
	s_mov_b64 s[10:11], -1
	s_cbranch_scc0 .LBB0_368
	s_lshl_b32 s49, s45, 8
	s_cmp_gt_u32 s45, 27
	s_cbranch_scc0 .LBB0_365
	s_mov_b64 s[0:1], -1
	s_cmp_gt_u32 s45, 41
	s_cbranch_scc0 .LBB0_362
	s_add_i32 s47, s49, 0xffffd600
	s_mov_b64 s[10:11], 0

; #define PG8_STAGE(bufoff, gbase, voff) do { _Pragma("unroll") for (int _i = 0; _i < 2; ++_i) \
;         __builtin_amdgcn_global_load_lds((const unsigned*)((const char*)(gbase) + (voff)[_i]), (LAS unsigned*)(lds + (bufoff) + ldsw + _i * 8192), 16, 0, 0); } while (0)
; #define PG8_LDA(dst, b, h) do { _Pragma("unroll") for (int m = 0; m < 4; ++m) _Pragma("unroll") for (int k = 0; k < 2; ++k) dst[m][k] = *(const LAS bf16x8*)(lds + PG8_SA(b, h) + aoff + m * 2048 + k * 1024); } while (0)
; #define PG8_LDB(dst, b, h) do { _Pragma("unroll") for (int n = 0; n < 2; ++n) _Pragma("unroll") for (int k = 0; k < 2; ++k) dst[n][k] = *(const LAS bf16x8*)(lds + PG8_SB(b, h) + boff + n * 2048 + k * 1024); } while (0)
; #define PG8_MMA(ai, bj, At, Bt) do { __builtin_amdgcn_s_setprio(1); _Pragma("unroll") for (int m = 0; m < 4; ++m) _Pragma("unroll") for (int n = 0; n < 2; ++n) _Pragma("unroll") for (int k = 0; k < 2; ++k) \
;         acc[ai][bj][m][n] = __builtin_amdgcn_mfma_f32_16x16x32_bf16(Bt[n][k], At[m][k], acc[ai][bj][m][n], 0, 0, 0); __builtin_amdgcn_s_setprio(0); } while (0)
; #define PG8_WAIT_V(n) asm volatile("s_waitcnt vmcnt(" #n ")" ::: "memory")
; #define PG8_WAIT_L(n) asm volatile("s_waitcnt lgkmcnt(" #n ")" ::: "memory")
; #define PG8_BAR __builtin_amdgcn_s_barrier()
; #define PG8_SCHED __builtin_amdgcn_sched_barrier(0)
; template <class Epi>
; __device__ __forceinline__ void gemm_phase(LAS unsigned char* lds, const Gemm g, const StaticOrder& S, const Epi& E, const int tid) {
;     ...
;         const char* nA = has_next ? PG8_APTR(nxt) : cA; const char* nB = has_next ? PG8_BPTR(nxt) : cB;
;         for (int t = 0; t < nt; t += 2) {
;             const bool last = (t == nt - 2);
;             const char* a1 = cA + (size_t)(t + 1) * kstep;
;             const char* a2 = last ? nA : cA + (size_t)(t + 2) * kstep; const char* b2 = last ? nB : cB + (size_t)(t + 2) * kstep;
;             const char* a3 = a2 + kstep; const char* b3 = b2 + kstep;
;             PG8_LDB(B0, 0, 0); PG8_LDB(B1, 0, 1); PG8_SCHED; PG8_LDA(At, 0, 0); PG8_STAGE(PG8_SA(1, 1), a1 + hsA, voffA);
;             PG8_WAIT_V(8); PG8_WAIT_L(0); PG8_BAR; PG8_MMA(0, 0, At, B0); PG8_MMA(0, 1, At, B1); PG8_BAR; PG8_SCHED;
;             PG8_LDA(At, 0, 1); PG8_STAGE(PG8_SB(0, 0), b2, voffB); PG8_STAGE(PG8_SB(0, 1), b2 + hsB, voffB); PG8_STAGE(PG8_SA(0, 0), a2, voffA);
.LBB0_822:
	s_lshl_b64 s[0:1], s[44:45], 22
	v_readlane_b32 s14, v255, 24
	s_add_u32 s24, s14, s0
	v_readlane_b32 s0, v255, 25
	s_addc_u32 s25, s0, s1
	s_ashr_i32 s35, s34, 31
	s_lshl_b64 s[0:1], s[34:35], 19
	s_add_u32 s0, s24, s0
	s_addc_u32 s1, s25, s1
	s_and_b64 s[24:25], s[42:43], exec
	s_cselect_b32 s35, s1, s49
	s_cselect_b32 s45, s0, s48
	s_add_u32 s68, s48, 0x100
	s_addc_u32 s69, s49, 0
	s_mov_b32 s96, -2
	s_cmp_lg_u64 s[12:13], 0
	s_cbranch_scc1 .Lgprio_d
	s_setprio 1
.Lgprio_d:
.LBB0_823:
	s_add_u32 s42, s36, 0x100
	s_addc_u32 s43, s37, 0
	s_add_i32 s24, 0, 0x10000
	s_cmp_eq_u32 s96, 12
	s_cselect_b32 vcc_hi, s47, s43
	s_cselect_b32 vcc_lo, s46, s42
	s_cselect_b32 s49, s35, s69
	s_cselect_b32 s48, s45, s68
	s_add_i32 s55, 0, 0x14000
	v_add_u32_e32 v150, s24, v232
	v_add_u32_e32 v166, s55, v232
	ds_read_b128 v[138:141], v150
	ds_read_b128 v[142:145], v150 offset:1024
	ds_read_b128 v[146:149], v150 offset:2048
	ds_read_b128 v[150:153], v150 offset:3072
	ds_read_b128 v[154:157], v166
	ds_read_b128 v[158:161], v166 offset:1024
	ds_read_b128 v[162:165], v166 offset:2048
	ds_read_b128 v[184:187], v166 offset:3072
	v_lshl_add_u64 v[166:167], s[36:37], 0, v[134:135]
	s_add_i32 m0, s7, 0xc000
	ds_read_b128 v[188:191], v234
	ds_read_b128 v[192:195], v234 offset:1024
	ds_read_b128 v[196:199], v234 offset:2048
	ds_read_b128 v[200:203], v234 offset:3072
	ds_read_b128 v[204:207], v234 offset:4096
	ds_read_b128 v[208:211], v234 offset:5120
	ds_read_b128 v[236:239], v234 offset:6144
	ds_read_b128 v[240:243], v234 offset:7168
	global_load_lds_dwordx4 v[166:167], off
	v_lshl_add_u64 v[166:167], s[36:37], 0, v[136:137]
	s_add_i32 m0, s7, 0xe000
	s_nop 0
	global_load_lds_dwordx4 v[166:167], off
	s_waitcnt vmcnt(8)
	s_waitcnt lgkmcnt(0)
	s_barrier
	s_waitcnt lgkmcnt(0)
	v_mfma_f32_16x16x32_bf16 v[124:127], v[138:141], v[188:191], v[124:127]
	v_mfma_f32_16x16x32_bf16 v[120:123], v[146:149], v[188:191], v[120:123]
	v_mfma_f32_16x16x32_bf16 v[116:119], v[138:141], v[196:199], v[116:119]
	v_mfma_f32_16x16x32_bf16 v[112:115], v[146:149], v[196:199], v[112:115]
	v_mfma_f32_16x16x32_bf16 v[108:111], v[138:141], v[204:207], v[108:111]
	v_mfma_f32_16x16x32_bf16 v[104:107], v[146:149], v[204:207], v[104:107]
	v_mfma_f32_16x16x32_bf16 v[100:103], v[138:141], v[236:239], v[100:103]
	v_mfma_f32_16x16x32_bf16 v[96:99], v[146:149], v[236:239], v[96:99]
	v_mfma_f32_16x16x32_bf16 v[124:127], v[142:145], v[192:195], v[124:127]
	v_mfma_f32_16x16x32_bf16 v[120:123], v[150:153], v[192:195], v[120:123]
	v_mfma_f32_16x16x32_bf16 v[116:119], v[142:145], v[200:203], v[116:119]
	v_mfma_f32_16x16x32_bf16 v[112:115], v[150:153], v[200:203], v[112:115]
	v_mfma_f32_16x16x32_bf16 v[108:111], v[142:145], v[208:211], v[108:111]
	v_mfma_f32_16x16x32_bf16 v[104:107], v[150:153], v[208:211], v[104:107]
	v_mfma_f32_16x16x32_bf16 v[100:103], v[142:145], v[240:243], v[100:103]
	v_mfma_f32_16x16x32_bf16 v[96:99], v[150:153], v[240:243], v[96:99]
	v_mfma_f32_16x16x32_bf16 v[92:95], v[154:157], v[188:191], v[92:95]
	v_mfma_f32_16x16x32_bf16 v[88:91], v[162:165], v[188:191], v[88:91]
	v_mfma_f32_16x16x32_bf16 v[84:87], v[154:157], v[196:199], v[84:87]
	v_mfma_f32_16x16x32_bf16 v[80:83], v[162:165], v[196:199], v[80:83]
	v_mfma_f32_16x16x32_bf16 v[76:79], v[154:157], v[204:207], v[76:79]
	v_mfma_f32_16x16x32_bf16 v[72:75], v[162:165], v[204:207], v[72:75]
	v_mfma_f32_16x16x32_bf16 v[68:71], v[154:157], v[236:239], v[68:71]
	v_mfma_f32_16x16x32_bf16 v[64:67], v[162:165], v[236:239], v[64:67]
	v_mfma_f32_16x16x32_bf16 v[92:95], v[158:161], v[192:195], v[92:95]
	v_mfma_f32_16x16x32_bf16 v[88:91], v[184:187], v[192:195], v[88:91]
	v_mfma_f32_16x16x32_bf16 v[84:87], v[158:161], v[200:203], v[84:87]
	v_mfma_f32_16x16x32_bf16 v[80:83], v[184:187], v[200:203], v[80:83]
	v_mfma_f32_16x16x32_bf16 v[76:79], v[158:161], v[208:211], v[76:79]
	v_mfma_f32_16x16x32_bf16 v[72:75], v[184:187], v[208:211], v[72:75]
	v_mfma_f32_16x16x32_bf16 v[68:71], v[158:161], v[240:243], v[68:71]
	v_mfma_f32_16x16x32_bf16 v[64:67], v[184:187], v[240:243], v[64:67]
	s_barrier
	s_add_i32 s24, s24, s6
	v_lshl_add_u64 v[166:167], s[48:49], 0, v[168:169]
	s_mov_b32 m0, s24
	ds_read_b128 v[188:191], v234 offset:16384
	ds_read_b128 v[192:195], v234 offset:17408
	ds_read_b128 v[196:199], v234 offset:18432
	ds_read_b128 v[200:203], v234 offset:19456
	ds_read_b128 v[204:207], v234 offset:20480
	ds_read_b128 v[208:211], v234 offset:21504
	ds_read_b128 v[236:239], v234 offset:22528
	ds_read_b128 v[240:243], v234 offset:23552
	global_load_lds_dwordx4 v[166:167], off
	s_add_i32 m0, s24, 0x2000
	s_add_u32 s24, s48, 0x40000
	v_lshl_add_u64 v[170:171], s[48:49], 0, v[128:129]
	s_addc_u32 s25, s49, 0
	s_add_i32 s36, s55, s6
	global_load_lds_dwordx4 v[170:171], off
	v_lshl_add_u64 v[172:173], s[24:25], 0, v[168:169]
	s_mov_b32 m0, s36
	v_lshl_add_u64 v[212:213], vcc, 0, v[130:131]
	global_load_lds_dwordx4 v[172:173], off
	v_lshl_add_u64 v[172:173], s[24:25], 0, v[128:129]
	s_add_i32 m0, s36, 0x2000
	s_nop 0
	global_load_lds_dwordx4 v[172:173], off
	v_lshl_add_u64 v[172:173], vcc, 0, v[132:133]
	s_mov_b32 m0, s7
	s_nop 0
	global_load_lds_dwordx4 v[172:173], off
	s_mov_b32 m0, s10
	s_nop 0
	global_load_lds_dwordx4 v[212:213], off
	s_waitcnt vmcnt(8)
	s_waitcnt lgkmcnt(0)
	s_barrier
; #define PG8_STAGE(bufoff, gbase, voff) do { _Pragma("unroll") for (int _i = 0; _i < 2; ++_i) \
;         __builtin_amdgcn_global_load_lds((const unsigned*)((const char*)(gbase) + (voff)[_i]), (LAS unsigned*)(lds + (bufoff) + ldsw + _i * 8192), 16, 0, 0); } while (0)
; #define PG8_LDA(dst, b, h) do { _Pragma("unroll") for (int m = 0; m < 4; ++m) _Pragma("unroll") for (int k = 0; k < 2; ++k) dst[m][k] = *(const LAS bf16x8*)(lds + PG8_SA(b, h) + aoff + m * 2048 + k * 1024); } while (0)
; #define PG8_LDB(dst, b, h) do { _Pragma("unroll") for (int n = 0; n < 2; ++n) _Pragma("unroll") for (int k = 0; k < 2; ++k) dst[n][k] = *(const LAS bf16x8*)(lds + PG8_SB(b, h) + boff + n * 2048 + k * 1024); } while (0)
; #define PG8_MMA(ai, bj, At, Bt) do { __builtin_amdgcn_s_setprio(1); _Pragma("unroll") for (int m = 0; m < 4; ++m) _Pragma("unroll") for (int n = 0; n < 2; ++n) _Pragma("unroll") for (int k = 0; k < 2; ++k) \
;         acc[ai][bj][m][n] = __builtin_amdgcn_mfma_f32_16x16x32_bf16(Bt[n][k], At[m][k], acc[ai][bj][m][n], 0, 0, 0); __builtin_amdgcn_s_setprio(0); } while (0)
; #define PG8_WAIT_V(n) asm volatile("s_waitcnt vmcnt(" #n ")" ::: "memory")
; #define PG8_WAIT_L(n) asm volatile("s_waitcnt lgkmcnt(" #n ")" ::: "memory")
; #define PG8_BAR __builtin_amdgcn_s_barrier()
; #define PG8_SCHED __builtin_amdgcn_sched_barrier(0)
; template <class Epi>
; __device__ __forceinline__ void gemm_phase(LAS unsigned char* lds, const Gemm g, const StaticOrder& S, const Epi& E, const int tid) {
;     ...
;             PG8_WAIT_V(8); PG8_WAIT_L(0); PG8_BAR; PG8_MMA(1, 0, At, B0); PG8_MMA(1, 1, At, B1); PG8_BAR; PG8_SCHED;
;             PG8_LDB(B0, 1, 0); PG8_LDB(B1, 1, 1); PG8_SCHED; PG8_LDA(At, 1, 0); PG8_STAGE(PG8_SA(0, 1), a2 + hsA, voffA);
;             PG8_WAIT_V(8); PG8_WAIT_L(0); PG8_BAR; PG8_MMA(0, 0, At, B0); PG8_MMA(0, 1, At, B1); PG8_BAR; PG8_SCHED;
	s_waitcnt lgkmcnt(0)
	v_mfma_f32_16x16x32_bf16 v[60:63], v[138:141], v[188:191], v[60:63]
	v_mfma_f32_16x16x32_bf16 v[56:59], v[146:149], v[188:191], v[56:59]
	v_mfma_f32_16x16x32_bf16 v[52:55], v[138:141], v[196:199], v[52:55]
	v_mfma_f32_16x16x32_bf16 v[48:51], v[146:149], v[196:199], v[48:51]
	v_mfma_f32_16x16x32_bf16 v[44:47], v[138:141], v[204:207], v[44:47]
	v_mfma_f32_16x16x32_bf16 v[40:43], v[146:149], v[204:207], v[40:43]
	v_mfma_f32_16x16x32_bf16 v[36:39], v[138:141], v[236:239], v[36:39]
	v_mfma_f32_16x16x32_bf16 v[32:35], v[146:149], v[236:239], v[32:35]
	v_mfma_f32_16x16x32_bf16 v[60:63], v[142:145], v[192:195], v[60:63]
	v_mfma_f32_16x16x32_bf16 v[56:59], v[150:153], v[192:195], v[56:59]
	v_mfma_f32_16x16x32_bf16 v[52:55], v[142:145], v[200:203], v[52:55]
	v_mfma_f32_16x16x32_bf16 v[48:51], v[150:153], v[200:203], v[48:51]
	v_mfma_f32_16x16x32_bf16 v[44:47], v[142:145], v[208:211], v[44:47]
	v_mfma_f32_16x16x32_bf16 v[40:43], v[150:153], v[208:211], v[40:43]
	v_mfma_f32_16x16x32_bf16 v[36:39], v[142:145], v[240:243], v[36:39]
	v_mfma_f32_16x16x32_bf16 v[32:35], v[150:153], v[240:243], v[32:35]
	v_mfma_f32_16x16x32_bf16 v[28:31], v[154:157], v[188:191], v[28:31]
	v_mfma_f32_16x16x32_bf16 v[24:27], v[162:165], v[188:191], v[24:27]
	v_mfma_f32_16x16x32_bf16 v[20:23], v[154:157], v[196:199], v[20:23]
	v_mfma_f32_16x16x32_bf16 v[16:19], v[162:165], v[196:199], v[16:19]
	v_mfma_f32_16x16x32_bf16 v[12:15], v[154:157], v[204:207], v[12:15]
	v_mfma_f32_16x16x32_bf16 v[8:11], v[162:165], v[204:207], v[8:11]
	v_mfma_f32_16x16x32_bf16 v[4:7], v[154:157], v[236:239], v[4:7]
	v_mfma_f32_16x16x32_bf16 v[0:3], v[162:165], v[236:239], v[0:3]
	v_mfma_f32_16x16x32_bf16 v[28:31], v[158:161], v[192:195], v[28:31]
	v_mfma_f32_16x16x32_bf16 v[24:27], v[184:187], v[192:195], v[24:27]
	v_mfma_f32_16x16x32_bf16 v[20:23], v[158:161], v[200:203], v[20:23]
	v_mfma_f32_16x16x32_bf16 v[16:19], v[184:187], v[200:203], v[16:19]
	v_mfma_f32_16x16x32_bf16 v[12:15], v[158:161], v[208:211], v[12:15]
	v_mfma_f32_16x16x32_bf16 v[8:11], v[184:187], v[208:211], v[8:11]
	v_mfma_f32_16x16x32_bf16 v[4:7], v[158:161], v[240:243], v[4:7]
	v_mfma_f32_16x16x32_bf16 v[0:3], v[184:187], v[240:243], v[0:3]
	s_barrier
	s_add_i32 s36, 0, 0x18000
	s_add_i32 s37, 0, 0x1c000
	v_add_u32_e32 v150, s36, v232
	v_add_u32_e32 v184, s37, v232
	ds_read_b128 v[138:141], v150
	ds_read_b128 v[142:145], v150 offset:1024
	ds_read_b128 v[146:149], v150 offset:2048
	ds_read_b128 v[150:153], v150 offset:3072
	ds_read_b128 v[154:157], v184
	ds_read_b128 v[158:161], v184 offset:1024
	ds_read_b128 v[162:165], v184 offset:2048
	ds_read_b128 v[184:187], v184 offset:3072
	s_add_u32 s24, vcc_lo, 0xc0000
	s_addc_u32 s25, vcc_hi, 0
	s_mov_b32 m0, s11
	v_lshl_add_u64 v[244:245], s[24:25], 0, v[132:133]
	ds_read_b128 v[188:191], v234 offset:32768
	ds_read_b128 v[192:195], v234 offset:33792
	ds_read_b128 v[196:199], v234 offset:34816
	ds_read_b128 v[200:203], v234 offset:35840
	ds_read_b128 v[204:207], v234 offset:36864
	ds_read_b128 v[208:211], v234 offset:37888
	ds_read_b128 v[236:239], v234 offset:38912
	ds_read_b128 v[240:243], v234 offset:39936
	global_load_lds_dwordx4 v[244:245], off
	v_lshl_add_u64 v[244:245], s[24:25], 0, v[130:131]
	s_mov_b32 m0, s27
	s_nop 0
	global_load_lds_dwordx4 v[244:245], off
	s_waitcnt vmcnt(8)
	s_waitcnt lgkmcnt(0)
	s_barrier
	s_waitcnt lgkmcnt(0)
	v_mfma_f32_16x16x32_bf16 v[124:127], v[138:141], v[188:191], v[124:127]
	v_mfma_f32_16x16x32_bf16 v[120:123], v[146:149], v[188:191], v[120:123]
	v_mfma_f32_16x16x32_bf16 v[116:119], v[138:141], v[196:199], v[116:119]
	v_mfma_f32_16x16x32_bf16 v[112:115], v[146:149], v[196:199], v[112:115]
	v_mfma_f32_16x16x32_bf16 v[108:111], v[138:141], v[204:207], v[108:111]
	v_mfma_f32_16x16x32_bf16 v[104:107], v[146:149], v[204:207], v[104:107]
	v_mfma_f32_16x16x32_bf16 v[100:103], v[138:141], v[236:239], v[100:103]
	v_mfma_f32_16x16x32_bf16 v[96:99], v[146:149], v[236:239], v[96:99]
	v_mfma_f32_16x16x32_bf16 v[124:127], v[142:145], v[192:195], v[124:127]
	v_mfma_f32_16x16x32_bf16 v[120:123], v[150:153], v[192:195], v[120:123]
	v_mfma_f32_16x16x32_bf16 v[116:119], v[142:145], v[200:203], v[116:119]
	v_mfma_f32_16x16x32_bf16 v[112:115], v[150:153], v[200:203], v[112:115]
	v_mfma_f32_16x16x32_bf16 v[108:111], v[142:145], v[208:211], v[108:111]
	v_mfma_f32_16x16x32_bf16 v[104:107], v[150:153], v[208:211], v[104:107]
	v_mfma_f32_16x16x32_bf16 v[100:103], v[142:145], v[240:243], v[100:103]
	v_mfma_f32_16x16x32_bf16 v[96:99], v[150:153], v[240:243], v[96:99]
	v_mfma_f32_16x16x32_bf16 v[92:95], v[154:157], v[188:191], v[92:95]
	v_mfma_f32_16x16x32_bf16 v[88:91], v[162:165], v[188:191], v[88:91]
	v_mfma_f32_16x16x32_bf16 v[84:87], v[154:157], v[196:199], v[84:87]
	v_mfma_f32_16x16x32_bf16 v[80:83], v[162:165], v[196:199], v[80:83]
	v_mfma_f32_16x16x32_bf16 v[76:79], v[154:157], v[204:207], v[76:79]
	v_mfma_f32_16x16x32_bf16 v[72:75], v[162:165], v[204:207], v[72:75]
	v_mfma_f32_16x16x32_bf16 v[68:71], v[154:157], v[236:239], v[68:71]
	v_mfma_f32_16x16x32_bf16 v[64:67], v[162:165], v[236:239], v[64:67]
	v_mfma_f32_16x16x32_bf16 v[92:95], v[158:161], v[192:195], v[92:95]
	v_mfma_f32_16x16x32_bf16 v[88:91], v[184:187], v[192:195], v[88:91]
	v_mfma_f32_16x16x32_bf16 v[84:87], v[158:161], v[200:203], v[84:87]
	v_mfma_f32_16x16x32_bf16 v[80:83], v[184:187], v[200:203], v[80:83]
	v_mfma_f32_16x16x32_bf16 v[76:79], v[158:161], v[208:211], v[76:79]
	v_mfma_f32_16x16x32_bf16 v[72:75], v[184:187], v[208:211], v[72:75]
	v_mfma_f32_16x16x32_bf16 v[68:71], v[158:161], v[240:243], v[68:71]
	v_mfma_f32_16x16x32_bf16 v[64:67], v[184:187], v[240:243], v[64:67]
	s_barrier
; #define PG8_STAGE(bufoff, gbase, voff) do { _Pragma("unroll") for (int _i = 0; _i < 2; ++_i) \
;         __builtin_amdgcn_global_load_lds((const unsigned*)((const char*)(gbase) + (voff)[_i]), (LAS unsigned*)(lds + (bufoff) + ldsw + _i * 8192), 16, 0, 0); } while (0)
; #define PG8_LDA(dst, b, h) do { _Pragma("unroll") for (int m = 0; m < 4; ++m) _Pragma("unroll") for (int k = 0; k < 2; ++k) dst[m][k] = *(const LAS bf16x8*)(lds + PG8_SA(b, h) + aoff + m * 2048 + k * 1024); } while (0)
; #define PG8_MMA(ai, bj, At, Bt) do { __builtin_amdgcn_s_setprio(1); _Pragma("unroll") for (int m = 0; m < 4; ++m) _Pragma("unroll") for (int n = 0; n < 2; ++n) _Pragma("unroll") for (int k = 0; k < 2; ++k) \
;         acc[ai][bj][m][n] = __builtin_amdgcn_mfma_f32_16x16x32_bf16(Bt[n][k], At[m][k], acc[ai][bj][m][n], 0, 0, 0); __builtin_amdgcn_s_setprio(0); } while (0)
; #define PG8_WAIT_V(n) asm volatile("s_waitcnt vmcnt(" #n ")" ::: "memory")
; #define PG8_WAIT_L(n) asm volatile("s_waitcnt lgkmcnt(" #n ")" ::: "memory")
; #define PG8_BAR __builtin_amdgcn_s_barrier()
; #define PG8_SCHED __builtin_amdgcn_sched_barrier(0)
; template <class Epi>
; __device__ __forceinline__ void gemm_phase(LAS unsigned char* lds, const Gemm g, const StaticOrder& S, const Epi& E, const int tid) {
;     ...
;             PG8_LDA(At, 1, 1); PG8_STAGE(PG8_SB(1, 0), b3, voffB); PG8_STAGE(PG8_SB(1, 1), b3 + hsB, voffB); PG8_STAGE(PG8_SA(1, 0), a3, voffA);
;             PG8_WAIT_V(8); PG8_WAIT_L(0); PG8_BAR; PG8_MMA(1, 0, At, B0); PG8_MMA(1, 1, At, B1); PG8_BAR; PG8_SCHED;
;         }
;         if (wr == 0) PG8_BAR;
;     __device__ __forceinline__ void operator()(f32x4 (&acc)[2][2][4][2], const Unit& u, int wr, int wc, int fr, int fq) const {
;         const int row0 = u.pm * BM + wr * 64 + fr, col0 = u.pn * BM + wc * 32 + 8 * fq;
;         const unsigned char* gb = (const unsigned char*)UG + (size_t)row0 * 6144 + (size_t)u.n * D + col0;
;         const bool mid = u.n < 2; const int doff = mid ? D : 0;
;         u32x2 gw[2][4][2], g2[2][4][2];
; #pragma unroll
;         for (int ai = 0; ai < 2; ++ai)
; #pragma unroll
;             for (int m = 0; m < 4; ++m)
; #pragma unroll
;                 for (int bj = 0; bj < 2; ++bj) { const unsigned char* p = gb + (size_t)(ai * HALF + m * 16) * 6144 + bj * HALF; gw[ai][m][bj] = *(const u32x2*)p; g2[ai][m][bj] = *(const u32x2*)(p + doff); }
	s_add_i32 s24, s36, s6
	v_lshl_add_u64 v[166:167], v[166:167], 0, s[28:29]
	s_mov_b32 m0, s24
	ds_read_b128 v[188:191], v234 offset:49152
	ds_read_b128 v[192:195], v234 offset:50176
	ds_read_b128 v[196:199], v234 offset:51200
	ds_read_b128 v[200:203], v234 offset:52224
	ds_read_b128 v[204:207], v234 offset:53248
	ds_read_b128 v[208:211], v234 offset:54272
	ds_read_b128 v[236:239], v234 offset:55296
	ds_read_b128 v[240:243], v234 offset:56320
	global_load_lds_dwordx4 v[166:167], off
	s_add_i32 m0, s24, 0x2000
	s_add_u32 s24, s48, 0x40080
	v_lshl_add_u64 v[166:167], v[170:171], 0, s[28:29]
	s_addc_u32 s25, s49, 0
	s_add_i32 s36, s37, s6
	global_load_lds_dwordx4 v[166:167], off
	v_lshl_add_u64 v[166:167], s[24:25], 0, v[168:169]
	s_mov_b32 m0, s36
	s_nop 0
	global_load_lds_dwordx4 v[166:167], off
	v_lshl_add_u64 v[166:167], s[24:25], 0, v[128:129]
	s_add_i32 m0, s36, 0x2000
	s_nop 0
	global_load_lds_dwordx4 v[166:167], off
	v_lshl_add_u64 v[166:167], v[172:173], 0, s[28:29]
	s_mov_b32 m0, s56
	s_nop 0
	global_load_lds_dwordx4 v[166:167], off
	v_lshl_add_u64 v[166:167], v[212:213], 0, s[28:29]
	s_mov_b32 m0, s57
	s_nop 0
	global_load_lds_dwordx4 v[166:167], off
	s_waitcnt vmcnt(8)
	s_waitcnt lgkmcnt(0)
	s_barrier
	s_waitcnt lgkmcnt(0)
	v_mfma_f32_16x16x32_bf16 v[60:63], v[138:141], v[188:191], v[60:63]
	v_mfma_f32_16x16x32_bf16 v[56:59], v[146:149], v[188:191], v[56:59]
	v_mfma_f32_16x16x32_bf16 v[52:55], v[138:141], v[196:199], v[52:55]
	v_mfma_f32_16x16x32_bf16 v[48:51], v[146:149], v[196:199], v[48:51]
	v_mfma_f32_16x16x32_bf16 v[44:47], v[138:141], v[204:207], v[44:47]
	v_mfma_f32_16x16x32_bf16 v[40:43], v[146:149], v[204:207], v[40:43]
	v_mfma_f32_16x16x32_bf16 v[36:39], v[138:141], v[236:239], v[36:39]
	v_mfma_f32_16x16x32_bf16 v[32:35], v[146:149], v[236:239], v[32:35]
	v_mfma_f32_16x16x32_bf16 v[60:63], v[142:145], v[192:195], v[60:63]
	v_mfma_f32_16x16x32_bf16 v[56:59], v[150:153], v[192:195], v[56:59]
	v_mfma_f32_16x16x32_bf16 v[52:55], v[142:145], v[200:203], v[52:55]
	v_mfma_f32_16x16x32_bf16 v[48:51], v[150:153], v[200:203], v[48:51]
	v_mfma_f32_16x16x32_bf16 v[44:47], v[142:145], v[208:211], v[44:47]
	v_mfma_f32_16x16x32_bf16 v[40:43], v[150:153], v[208:211], v[40:43]
	v_mfma_f32_16x16x32_bf16 v[36:39], v[142:145], v[240:243], v[36:39]
	v_mfma_f32_16x16x32_bf16 v[32:35], v[150:153], v[240:243], v[32:35]
	v_mfma_f32_16x16x32_bf16 v[28:31], v[154:157], v[188:191], v[28:31]
	v_mfma_f32_16x16x32_bf16 v[24:27], v[162:165], v[188:191], v[24:27]
	v_mfma_f32_16x16x32_bf16 v[20:23], v[154:157], v[196:199], v[20:23]
	v_mfma_f32_16x16x32_bf16 v[16:19], v[162:165], v[196:199], v[16:19]
	v_mfma_f32_16x16x32_bf16 v[12:15], v[154:157], v[204:207], v[12:15]
	v_mfma_f32_16x16x32_bf16 v[8:11], v[162:165], v[204:207], v[8:11]
	v_mfma_f32_16x16x32_bf16 v[4:7], v[154:157], v[236:239], v[4:7]
	v_mfma_f32_16x16x32_bf16 v[0:3], v[162:165], v[236:239], v[0:3]
	v_mfma_f32_16x16x32_bf16 v[28:31], v[158:161], v[192:195], v[28:31]
	v_mfma_f32_16x16x32_bf16 v[24:27], v[184:187], v[192:195], v[24:27]
	v_mfma_f32_16x16x32_bf16 v[20:23], v[158:161], v[200:203], v[20:23]
	v_mfma_f32_16x16x32_bf16 v[16:19], v[184:187], v[200:203], v[16:19]
	v_mfma_f32_16x16x32_bf16 v[12:15], v[158:161], v[208:211], v[12:15]
	v_mfma_f32_16x16x32_bf16 v[8:11], v[184:187], v[208:211], v[8:11]
	v_mfma_f32_16x16x32_bf16 v[4:7], v[158:161], v[240:243], v[4:7]
	v_mfma_f32_16x16x32_bf16 v[0:3], v[184:187], v[240:243], v[0:3]
	s_barrier
	s_add_i32 s96, s96, 2
	s_add_u32 s68, s68, 0x100
	s_addc_u32 s69, s69, 0
	s_cmp_gt_u32 s96, 13
	s_mov_b64 s[36:37], s[42:43]
	s_cbranch_scc0 .LBB0_823
	s_and_b64 vcc, exec, s[12:13]
	s_cbranch_vccz .LBB0_826
	s_barrier
.LBB0_826:
	s_setprio 0
	v_lshl_add_u32 v140, s60, 8, v231
	v_mov_b64_e32 v[142:143], s[92:93]
	v_lshl_or_b32 v138, s53, 8, v233
	v_mad_i64_i32 v[142:143], s[24:25], v140, s97, v[142:143]
	s_ashr_i32 s53, s52, 31
	s_lshl_b64 s[24:25], s[52:53], 11
	s_cmp_gt_i32 s52, 1
	s_cselect_b64 s[36:37], -1, 0
	s_cmp_lt_i32 s52, 2
	s_cselect_b64 vcc, -1, 0
	v_lshl_add_u64 v[142:143], v[142:143], 0, s[24:25]
	v_ashrrev_i32_e32 v139, 31, v138
	s_and_b64 s[24:25], vcc, exec
	v_lshl_add_u64 v[142:143], v[142:143], 0, v[138:139]
	s_cselect_b32 s60, 0x800, 0
	v_lshl_add_u64 v[144:145], v[142:143], 0, s[60:61]
	global_load_dwordx2 v[170:171], v[142:143], off
	global_load_dwordx2 v[172:173], v[144:145], off
	global_load_dwordx2 v[236:237], v[144:145], off offset:128
	global_load_dwordx2 v[238:239], v[142:143], off offset:128
	s_mov_b64 s[14:15], 0x18000
	v_lshl_add_u64 v[144:145], v[142:143], 0, s[14:15]
	s_mov_b32 s14, 0x18000
	v_add_co_u32_e64 v146, s[42:43], s14, v142
	s_mov_b64 s[24:25], 0x18080
	s_nop 0
	v_addc_co_u32_e64 v147, s[42:43], 0, v143, s[42:43]
	v_lshl_add_u64 v[148:149], v[142:143], 0, s[24:25]
	v_lshl_add_u64 v[144:145], v[144:145], 0, s[60:61]
	v_lshl_add_u64 v[148:149], v[148:149], 0, s[60:61]
	global_load_dwordx2 v[210:211], v[146:147], off
	global_load_dwordx2 v[212:213], v[144:145], off
	global_load_dwordx2 v[208:209], v[148:149], off
	global_load_dwordx2 v[206:207], v[146:147], off offset:128
	s_mov_b64 s[24:25], 0x30000
	s_mov_b32 s14, 0x30000
	v_lshl_add_u64 v[144:145], v[142:143], 0, s[24:25]
	v_add_co_u32_e64 v146, s[42:43], s14, v142
	s_mov_b64 s[24:25], 0x30080
	s_nop 0
	v_addc_co_u32_e64 v147, s[42:43], 0, v143, s[42:43]
	v_lshl_add_u64 v[144:145], v[144:145], 0, s[60:61]
	v_lshl_add_u64 v[148:149], v[142:143], 0, s[24:25]
	s_mov_b64 s[24:25], 0x48000
	v_lshl_add_u64 v[148:149], v[148:149], 0, s[60:61]
	global_load_dwordx2 v[202:203], v[146:147], off
	global_load_dwordx2 v[204:205], v[144:145], off
	global_load_dwordx2 v[200:201], v[148:149], off
; __device__ __forceinline__ float fast_rcp(float x) { return __builtin_amdgcn_rcpf(x); }
;     __device__ __forceinline__ void operator()(f32x4 (&acc)[2][2][4][2], const Unit& u, int wr, int wc, int fr, int fq) const {
;     ...
;                 for (int bj = 0; bj < 2; ++bj) { const unsigned char* p = gb + (size_t)(ai * HALF + m * 16) * 6144 + bj * HALF; gw[ai][m][bj] = *(const u32x2*)p; g2[ai][m][bj] = *(const u32x2*)(p + doff); }
; #pragma unroll
;         for (int ai = 0; ai < 2; ++ai)
; #pragma unroll
;             for (int m = 0; m < 4; ++m)
; #pragma unroll
;                 for (int bj = 0; bj < 2; ++bj) { const u32x2 a = gw[ai][m][bj], c = g2[ai][m][bj];
;                     float s[8];
; #pragma unroll
;                     for (int e = 0; e < 8; ++e) { const float den = (float)(((e < 4 ? c.x : c.y) >> (8 * (e & 3))) & 255u);
;                         s[e] = (float)(((e < 4 ? a.x : a.y) >> (8 * (e & 3))) & 255u) * fast_rcp(mid ? den : 255.0f); }
;                     f32x4& v0 = acc[ai][bj][m][0]; f32x4& v1 = acc[ai][bj][m][1];
;                     v0 = v0 * (f32x4){s[0], s[1], s[2], s[3]}; v1 = v1 * (f32x4){s[4], s[5], s[6], s[7]}; }
	global_load_dwordx2 v[198:199], v[146:147], off offset:128
	v_lshl_add_u64 v[144:145], v[142:143], 0, s[24:25]
	s_mov_b32 s24, 0x48000
	v_add_co_u32_e64 v146, s[42:43], s24, v142
	s_mov_b64 s[24:25], 0x48080
	s_nop 0
	v_addc_co_u32_e64 v147, s[42:43], 0, v143, s[42:43]
	v_lshl_add_u64 v[144:145], v[144:145], 0, s[60:61]
	v_lshl_add_u64 v[148:149], v[142:143], 0, s[24:25]
	s_mov_b64 s[24:25], 0xc0000
	v_lshl_add_u64 v[148:149], v[148:149], 0, s[60:61]
	global_load_dwordx2 v[194:195], v[146:147], off
	global_load_dwordx2 v[196:197], v[144:145], off
	global_load_dwordx2 v[192:193], v[148:149], off
	global_load_dwordx2 v[190:191], v[146:147], off offset:128
	v_lshl_add_u64 v[144:145], v[142:143], 0, s[24:25]
	s_mov_b32 s24, 0xc0000
	v_add_co_u32_e64 v146, s[42:43], s24, v142
	v_lshl_add_u64 v[144:145], v[144:145], 0, s[60:61]
	s_nop 0
	v_addc_co_u32_e64 v147, s[42:43], 0, v143, s[42:43]
	v_lshl_add_u64 v[148:149], v[142:143], 0, s[16:17]
	s_mov_b64 s[24:25], 0xd8000
	v_lshl_add_u64 v[148:149], v[148:149], 0, s[60:61]
	global_load_dwordx2 v[186:187], v[146:147], off
	global_load_dwordx2 v[188:189], v[144:145], off
	global_load_dwordx2 v[184:185], v[148:149], off
	global_load_dwordx2 v[166:167], v[146:147], off offset:128
	v_lshl_add_u64 v[144:145], v[142:143], 0, s[24:25]
	s_mov_b32 s24, 0xd8000
	v_add_co_u32_e64 v146, s[42:43], s24, v142
	s_mov_b64 s[24:25], 0xd8080
	s_nop 0
	v_addc_co_u32_e64 v147, s[42:43], 0, v143, s[42:43]
	v_lshl_add_u64 v[144:145], v[144:145], 0, s[60:61]
	v_lshl_add_u64 v[148:149], v[142:143], 0, s[24:25]
	s_mov_b64 s[24:25], 0xf0000
	v_lshl_add_u64 v[148:149], v[148:149], 0, s[60:61]
	global_load_dwordx2 v[162:163], v[146:147], off
	global_load_dwordx2 v[164:165], v[144:145], off
	global_load_dwordx2 v[160:161], v[148:149], off
	global_load_dwordx2 v[158:159], v[146:147], off offset:128
	v_lshl_add_u64 v[144:145], v[142:143], 0, s[24:25]
	s_mov_b32 s24, 0xf0000
	v_add_co_u32_e64 v146, s[42:43], s24, v142
	s_mov_b64 s[24:25], 0xf0080
	s_nop 0
	v_addc_co_u32_e64 v147, s[42:43], 0, v143, s[42:43]
	v_lshl_add_u64 v[144:145], v[144:145], 0, s[60:61]
	v_lshl_add_u64 v[148:149], v[142:143], 0, s[24:25]
	s_mov_b64 s[24:25], 0x108000
	v_lshl_add_u64 v[148:149], v[148:149], 0, s[60:61]
	global_load_dwordx2 v[154:155], v[146:147], off
	global_load_dwordx2 v[156:157], v[144:145], off
	global_load_dwordx2 v[152:153], v[148:149], off
	global_load_dwordx2 v[150:151], v[146:147], off offset:128
	v_lshl_add_u64 v[144:145], v[142:143], 0, s[24:25]
	s_mov_b32 s24, 0x108000
	v_add_co_u32_e64 v240, s[42:43], s24, v142
	s_mov_b64 s[24:25], 0x108080
	s_nop 0
	v_addc_co_u32_e64 v241, s[42:43], 0, v143, s[42:43]
	v_lshl_add_u64 v[142:143], v[142:143], 0, s[24:25]
	s_waitcnt vmcnt(0)
	v_cvt_f32_ubyte0_e32 v141, v172
	v_lshl_add_u64 v[144:145], v[144:145], 0, s[60:61]
	v_lshl_add_u64 v[142:143], v[142:143], 0, s[60:61]
	v_cndmask_b32_e32 v141, v228, v141, vcc
	global_load_dwordx2 v[146:147], v[240:241], off
	global_load_dwordx2 v[148:149], v[144:145], off
	s_nop 0
	global_load_dwordx2 v[144:145], v[142:143], off
	s_nop 0
	global_load_dwordx2 v[142:143], v[240:241], off offset:128
	v_rcp_f32_e32 v240, v141
	v_cvt_f32_ubyte1_e32 v141, v172
	v_cndmask_b32_e32 v141, v228, v141, vcc
	v_rcp_f32_e32 v241, v141
	v_cvt_f32_ubyte2_e32 v141, v172
	v_cndmask_b32_e32 v141, v228, v141, vcc
	v_rcp_f32_e32 v242, v141
	v_cvt_f32_ubyte3_e32 v141, v172
	v_cndmask_b32_e32 v141, v228, v141, vcc
	v_rcp_f32_e32 v243, v141
	v_cvt_f32_ubyte0_e32 v141, v173
	v_cvt_f32_ubyte3_e32 v245, v170
	v_cvt_f32_ubyte2_e32 v244, v170
	v_cndmask_b32_e32 v141, v228, v141, vcc
	v_pk_mul_f32 v[242:243], v[242:243], v[244:245]
	v_rcp_f32_e32 v244, v141
	v_cvt_f32_ubyte1_e32 v141, v173
	v_cndmask_b32_e32 v141, v228, v141, vcc
	v_rcp_f32_e32 v245, v141
	v_cvt_f32_ubyte2_e32 v141, v173
	v_cndmask_b32_e32 v141, v228, v141, vcc
	v_rcp_f32_e32 v172, v141
	v_cvt_f32_ubyte3_e32 v141, v173
	v_cndmask_b32_e32 v141, v228, v141, vcc
	v_cvt_f32_ubyte1_e32 v247, v170
	v_cvt_f32_ubyte0_e32 v246, v170
	v_rcp_f32_e32 v173, v141
	v_cvt_f32_ubyte1_e32 v249, v171
	v_cvt_f32_ubyte0_e32 v248, v171
	v_cvt_f32_ubyte0_e32 v141, v236
	v_pk_mul_f32 v[240:241], v[240:241], v[246:247]
	v_cvt_f32_ubyte3_e32 v247, v171
	v_cvt_f32_ubyte2_e32 v246, v171
	v_pk_mul_f32 v[170:171], v[244:245], v[248:249]
	v_cndmask_b32_e32 v141, v228, v141, vcc
	v_pk_mul_f32 v[120:121], v[120:121], v[170:171]
	v_rcp_f32_e32 v170, v141
	v_cvt_f32_ubyte1_e32 v141, v236
	v_cndmask_b32_e32 v141, v228, v141, vcc
	v_rcp_f32_e32 v171, v141
	v_cvt_f32_ubyte2_e32 v141, v236
	v_pk_mul_f32 v[172:173], v[172:173], v[246:247]
	v_cndmask_b32_e32 v141, v228, v141, vcc
	v_pk_mul_f32 v[122:123], v[122:123], v[172:173]
	v_rcp_f32_e32 v172, v141
	v_cvt_f32_ubyte3_e32 v141, v236
	v_cndmask_b32_e32 v141, v228, v141, vcc
	v_rcp_f32_e32 v173, v141
	v_cvt_f32_ubyte0_e32 v141, v237
	v_pk_mul_f32 v[124:125], v[124:125], v[240:241]
	v_cvt_f32_ubyte3_e32 v241, v238
	v_cvt_f32_ubyte2_e32 v240, v238
	v_cndmask_b32_e32 v141, v228, v141, vcc
	v_pk_mul_f32 v[172:173], v[172:173], v[240:241]
	v_rcp_f32_e32 v240, v141
	v_cvt_f32_ubyte1_e32 v141, v237
	v_cndmask_b32_e32 v141, v228, v141, vcc
	v_rcp_f32_e32 v241, v141
	v_cvt_f32_ubyte2_e32 v141, v237
	v_cndmask_b32_e32 v141, v228, v141, vcc
	v_rcp_f32_e32 v236, v141
	v_cvt_f32_ubyte3_e32 v141, v237
	v_cndmask_b32_e32 v141, v228, v141, vcc
	v_pk_mul_f32 v[126:127], v[126:127], v[242:243]
	v_cvt_f32_ubyte1_e32 v243, v238
	v_cvt_f32_ubyte0_e32 v242, v238
	v_rcp_f32_e32 v237, v141
	v_cvt_f32_ubyte0_e32 v141, v212
	v_pk_mul_f32 v[170:171], v[170:171], v[242:243]
	v_cndmask_b32_e32 v141, v228, v141, vcc
; __device__ __forceinline__ float fast_rcp(float x) { return __builtin_amdgcn_rcpf(x); }
;     __device__ __forceinline__ void operator()(f32x4 (&acc)[2][2][4][2], const Unit& u, int wr, int wc, int fr, int fq) const {
;     ...
;                 for (int bj = 0; bj < 2; ++bj) { const u32x2 a = gw[ai][m][bj], c = g2[ai][m][bj];
;                     float s[8];
; #pragma unroll
;                     for (int e = 0; e < 8; ++e) { const float den = (float)(((e < 4 ? c.x : c.y) >> (8 * (e & 3))) & 255u);
;                         s[e] = (float)(((e < 4 ? a.x : a.y) >> (8 * (e & 3))) & 255u) * fast_rcp(mid ? den : 255.0f); }
;                     f32x4& v0 = acc[ai][bj][m][0]; f32x4& v1 = acc[ai][bj][m][1];
;                     v0 = v0 * (f32x4){s[0], s[1], s[2], s[3]}; v1 = v1 * (f32x4){s[4], s[5], s[6], s[7]}; }
	v_pk_mul_f32 v[92:93], v[92:93], v[170:171]
	v_rcp_f32_e32 v170, v141
	v_cvt_f32_ubyte1_e32 v141, v212
	v_cndmask_b32_e32 v141, v228, v141, vcc
	v_rcp_f32_e32 v171, v141
	v_cvt_f32_ubyte2_e32 v141, v212
	v_cndmask_b32_e32 v141, v228, v141, vcc
	v_pk_mul_f32 v[94:95], v[94:95], v[172:173]
	v_rcp_f32_e32 v172, v141
	v_cvt_f32_ubyte3_e32 v141, v212
	v_cndmask_b32_e32 v141, v228, v141, vcc
	v_rcp_f32_e32 v173, v141
	v_cvt_f32_ubyte3_e32 v243, v239
	v_cvt_f32_ubyte2_e32 v242, v239
	v_pk_mul_f32 v[236:237], v[236:237], v[242:243]
	v_cvt_f32_ubyte0_e32 v141, v213
	v_pk_mul_f32 v[90:91], v[90:91], v[236:237]
	v_cvt_f32_ubyte3_e32 v237, v210
	v_cvt_f32_ubyte2_e32 v236, v210
	v_cndmask_b32_e32 v141, v228, v141, vcc
	v_pk_mul_f32 v[172:173], v[172:173], v[236:237]
	v_rcp_f32_e32 v236, v141
	v_cvt_f32_ubyte1_e32 v141, v213
	v_cndmask_b32_e32 v141, v228, v141, vcc
	v_rcp_f32_e32 v237, v141
	v_cvt_f32_ubyte2_e32 v141, v213
	v_cndmask_b32_e32 v141, v228, v141, vcc
	v_cvt_f32_ubyte1_e32 v245, v239
	v_cvt_f32_ubyte0_e32 v244, v239
	v_rcp_f32_e32 v212, v141
	v_cvt_f32_ubyte3_e32 v141, v213
	v_pk_mul_f32 v[238:239], v[240:241], v[244:245]
	v_cndmask_b32_e32 v141, v228, v141, vcc
	v_pk_mul_f32 v[88:89], v[88:89], v[238:239]
	v_cvt_f32_ubyte1_e32 v239, v210
	v_cvt_f32_ubyte0_e32 v238, v210
	v_rcp_f32_e32 v213, v141
	v_cvt_f32_ubyte0_e32 v141, v208
	v_pk_mul_f32 v[170:171], v[170:171], v[238:239]
	v_cndmask_b32_e32 v141, v228, v141, vcc
	v_pk_mul_f32 v[116:117], v[116:117], v[170:171]
	v_rcp_f32_e32 v170, v141
	v_cvt_f32_ubyte1_e32 v141, v208
	v_cndmask_b32_e32 v141, v228, v141, vcc
	v_rcp_f32_e32 v171, v141
	v_cvt_f32_ubyte2_e32 v141, v208
	v_cndmask_b32_e32 v141, v228, v141, vcc
	v_pk_mul_f32 v[118:119], v[118:119], v[172:173]
	v_rcp_f32_e32 v172, v141
	v_cvt_f32_ubyte3_e32 v141, v208
	v_cndmask_b32_e32 v141, v228, v141, vcc
	v_rcp_f32_e32 v173, v141
	v_cvt_f32_ubyte1_e32 v241, v211
	v_cvt_f32_ubyte0_e32 v240, v211
	v_cvt_f32_ubyte3_e32 v239, v211
	v_cvt_f32_ubyte2_e32 v238, v211
	v_pk_mul_f32 v[210:211], v[236:237], v[240:241]
	v_cvt_f32_ubyte0_e32 v141, v209
	v_pk_mul_f32 v[112:113], v[112:113], v[210:211]
	v_cvt_f32_ubyte3_e32 v211, v206
	v_cvt_f32_ubyte2_e32 v210, v206
	v_cndmask_b32_e32 v141, v228, v141, vcc
	v_pk_mul_f32 v[172:173], v[172:173], v[210:211]
	v_rcp_f32_e32 v210, v141
	v_cvt_f32_ubyte1_e32 v141, v209
	v_cndmask_b32_e32 v141, v228, v141, vcc
	v_rcp_f32_e32 v211, v141
	v_cvt_f32_ubyte2_e32 v141, v209
	v_cndmask_b32_e32 v141, v228, v141, vcc
	v_rcp_f32_e32 v208, v141
	v_cvt_f32_ubyte3_e32 v141, v209
	v_pk_mul_f32 v[212:213], v[212:213], v[238:239]
	v_cndmask_b32_e32 v141, v228, v141, vcc
	v_pk_mul_f32 v[114:115], v[114:115], v[212:213]
	v_cvt_f32_ubyte1_e32 v213, v206
	v_cvt_f32_ubyte0_e32 v212, v206
	v_rcp_f32_e32 v209, v141
	v_cvt_f32_ubyte0_e32 v141, v204
	v_pk_mul_f32 v[170:171], v[170:171], v[212:213]
	v_cndmask_b32_e32 v141, v228, v141, vcc
	v_pk_mul_f32 v[84:85], v[84:85], v[170:171]
	v_rcp_f32_e32 v170, v141
	v_cvt_f32_ubyte1_e32 v141, v204
	v_cndmask_b32_e32 v141, v228, v141, vcc
	v_rcp_f32_e32 v171, v141
	v_cvt_f32_ubyte2_e32 v141, v204
	v_cndmask_b32_e32 v141, v228, v141, vcc
	v_pk_mul_f32 v[86:87], v[86:87], v[172:173]
	v_rcp_f32_e32 v172, v141
	v_cvt_f32_ubyte3_e32 v141, v204
	v_cndmask_b32_e32 v141, v228, v141, vcc
	v_rcp_f32_e32 v173, v141
	v_cvt_f32_ubyte1_e32 v237, v207
	v_cvt_f32_ubyte0_e32 v236, v207
	v_cvt_f32_ubyte3_e32 v213, v207
	v_cvt_f32_ubyte2_e32 v212, v207
	v_pk_mul_f32 v[206:207], v[210:211], v[236:237]
	v_cvt_f32_ubyte0_e32 v141, v205
	v_pk_mul_f32 v[80:81], v[80:81], v[206:207]
	v_cvt_f32_ubyte3_e32 v207, v202
	v_cvt_f32_ubyte2_e32 v206, v202
	v_cndmask_b32_e32 v141, v228, v141, vcc
	v_pk_mul_f32 v[172:173], v[172:173], v[206:207]
	v_rcp_f32_e32 v206, v141
	v_cvt_f32_ubyte1_e32 v141, v205
	v_cndmask_b32_e32 v141, v228, v141, vcc
	v_rcp_f32_e32 v207, v141
	v_cvt_f32_ubyte2_e32 v141, v205
	v_cndmask_b32_e32 v141, v228, v141, vcc
	v_rcp_f32_e32 v204, v141
	v_cvt_f32_ubyte3_e32 v141, v205
	v_pk_mul_f32 v[208:209], v[208:209], v[212:213]
	v_cndmask_b32_e32 v141, v228, v141, vcc
	v_pk_mul_f32 v[82:83], v[82:83], v[208:209]
	v_cvt_f32_ubyte1_e32 v209, v202
	v_cvt_f32_ubyte0_e32 v208, v202
	v_rcp_f32_e32 v205, v141
	v_cvt_f32_ubyte0_e32 v141, v200
	v_pk_mul_f32 v[170:171], v[170:171], v[208:209]
	v_cndmask_b32_e32 v141, v228, v141, vcc
	v_pk_mul_f32 v[108:109], v[108:109], v[170:171]
	v_rcp_f32_e32 v170, v141
	v_cvt_f32_ubyte1_e32 v141, v200
	v_cndmask_b32_e32 v141, v228, v141, vcc
	v_rcp_f32_e32 v171, v141
	v_cvt_f32_ubyte2_e32 v141, v200
	v_cndmask_b32_e32 v141, v228, v141, vcc
	v_pk_mul_f32 v[110:111], v[110:111], v[172:173]
	v_rcp_f32_e32 v172, v141
	v_cvt_f32_ubyte3_e32 v141, v200
	v_cndmask_b32_e32 v141, v228, v141, vcc
	v_rcp_f32_e32 v173, v141
	v_cvt_f32_ubyte1_e32 v211, v203
	v_cvt_f32_ubyte0_e32 v210, v203
	v_cvt_f32_ubyte3_e32 v209, v203
	v_cvt_f32_ubyte2_e32 v208, v203
	v_pk_mul_f32 v[202:203], v[206:207], v[210:211]
	v_cvt_f32_ubyte0_e32 v141, v201
	v_pk_mul_f32 v[104:105], v[104:105], v[202:203]
	v_cvt_f32_ubyte3_e32 v203, v198
	v_cvt_f32_ubyte2_e32 v202, v198
	v_cndmask_b32_e32 v141, v228, v141, vcc
	v_pk_mul_f32 v[172:173], v[172:173], v[202:203]
	v_rcp_f32_e32 v202, v141
	v_cvt_f32_ubyte1_e32 v141, v201
	v_cndmask_b32_e32 v141, v228, v141, vcc
	v_rcp_f32_e32 v203, v141
	v_cvt_f32_ubyte2_e32 v141, v201
	v_cndmask_b32_e32 v141, v228, v141, vcc
	v_rcp_f32_e32 v200, v141
	v_cvt_f32_ubyte3_e32 v141, v201
	v_pk_mul_f32 v[204:205], v[204:205], v[208:209]
	v_cndmask_b32_e32 v141, v228, v141, vcc
	v_pk_mul_f32 v[106:107], v[106:107], v[204:205]
	v_cvt_f32_ubyte1_e32 v205, v198
	v_cvt_f32_ubyte0_e32 v204, v198
; __device__ __forceinline__ float fast_rcp(float x) { return __builtin_amdgcn_rcpf(x); }
;     __device__ __forceinline__ void operator()(f32x4 (&acc)[2][2][4][2], const Unit& u, int wr, int wc, int fr, int fq) const {
;     ...
;                 for (int bj = 0; bj < 2; ++bj) { const u32x2 a = gw[ai][m][bj], c = g2[ai][m][bj];
;                     float s[8];
; #pragma unroll
;                     for (int e = 0; e < 8; ++e) { const float den = (float)(((e < 4 ? c.x : c.y) >> (8 * (e & 3))) & 255u);
;                         s[e] = (float)(((e < 4 ? a.x : a.y) >> (8 * (e & 3))) & 255u) * fast_rcp(mid ? den : 255.0f); }
;                     f32x4& v0 = acc[ai][bj][m][0]; f32x4& v1 = acc[ai][bj][m][1];
;                     v0 = v0 * (f32x4){s[0], s[1], s[2], s[3]}; v1 = v1 * (f32x4){s[4], s[5], s[6], s[7]}; }
	v_rcp_f32_e32 v201, v141
	v_cvt_f32_ubyte0_e32 v141, v196
	v_pk_mul_f32 v[170:171], v[170:171], v[204:205]
	v_cndmask_b32_e32 v141, v228, v141, vcc
	v_pk_mul_f32 v[76:77], v[76:77], v[170:171]
	v_rcp_f32_e32 v170, v141
	v_cvt_f32_ubyte1_e32 v141, v196
	v_cndmask_b32_e32 v141, v228, v141, vcc
	v_rcp_f32_e32 v171, v141
	v_cvt_f32_ubyte2_e32 v141, v196
	v_cndmask_b32_e32 v141, v228, v141, vcc
	v_pk_mul_f32 v[78:79], v[78:79], v[172:173]
	v_rcp_f32_e32 v172, v141
	v_cvt_f32_ubyte3_e32 v141, v196
	v_cndmask_b32_e32 v141, v228, v141, vcc
	v_rcp_f32_e32 v173, v141
	v_cvt_f32_ubyte1_e32 v207, v199
	v_cvt_f32_ubyte0_e32 v206, v199
	v_cvt_f32_ubyte3_e32 v205, v199
	v_cvt_f32_ubyte2_e32 v204, v199
	v_pk_mul_f32 v[198:199], v[202:203], v[206:207]
	v_cvt_f32_ubyte0_e32 v141, v197
	v_pk_mul_f32 v[72:73], v[72:73], v[198:199]
	v_cvt_f32_ubyte3_e32 v199, v194
	v_cvt_f32_ubyte2_e32 v198, v194
	v_cndmask_b32_e32 v141, v228, v141, vcc
	v_pk_mul_f32 v[172:173], v[172:173], v[198:199]
	v_rcp_f32_e32 v198, v141
	v_cvt_f32_ubyte1_e32 v141, v197
	v_cndmask_b32_e32 v141, v228, v141, vcc
	v_rcp_f32_e32 v199, v141
	v_cvt_f32_ubyte2_e32 v141, v197
	v_cndmask_b32_e32 v141, v228, v141, vcc
	v_rcp_f32_e32 v196, v141
	v_cvt_f32_ubyte3_e32 v141, v197
	v_pk_mul_f32 v[200:201], v[200:201], v[204:205]
	v_cndmask_b32_e32 v141, v228, v141, vcc
	v_pk_mul_f32 v[74:75], v[74:75], v[200:201]
	v_cvt_f32_ubyte1_e32 v201, v194
	v_cvt_f32_ubyte0_e32 v200, v194
	v_rcp_f32_e32 v197, v141
	v_cvt_f32_ubyte0_e32 v141, v192
	v_pk_mul_f32 v[170:171], v[170:171], v[200:201]
	v_cndmask_b32_e32 v141, v228, v141, vcc
	v_pk_mul_f32 v[100:101], v[100:101], v[170:171]
	v_rcp_f32_e32 v170, v141
	v_cvt_f32_ubyte1_e32 v141, v192
	v_cndmask_b32_e32 v141, v228, v141, vcc
	v_rcp_f32_e32 v171, v141
	v_cvt_f32_ubyte2_e32 v141, v192
	v_cndmask_b32_e32 v141, v228, v141, vcc
	v_pk_mul_f32 v[102:103], v[102:103], v[172:173]
	v_rcp_f32_e32 v172, v141
	v_cvt_f32_ubyte3_e32 v141, v192
	v_cndmask_b32_e32 v141, v228, v141, vcc
	v_rcp_f32_e32 v173, v141
	v_cvt_f32_ubyte1_e32 v203, v195
	v_cvt_f32_ubyte0_e32 v202, v195
	v_cvt_f32_ubyte3_e32 v201, v195
	v_cvt_f32_ubyte2_e32 v200, v195
	v_pk_mul_f32 v[194:195], v[198:199], v[202:203]
	v_cvt_f32_ubyte0_e32 v141, v193
	v_pk_mul_f32 v[96:97], v[96:97], v[194:195]
	v_cvt_f32_ubyte3_e32 v195, v190
	v_cvt_f32_ubyte2_e32 v194, v190
	v_cndmask_b32_e32 v141, v228, v141, vcc
	v_pk_mul_f32 v[172:173], v[172:173], v[194:195]
	v_rcp_f32_e32 v194, v141
	v_cvt_f32_ubyte1_e32 v141, v193
	v_cndmask_b32_e32 v141, v228, v141, vcc
	v_rcp_f32_e32 v195, v141
	v_cvt_f32_ubyte2_e32 v141, v193
	v_cndmask_b32_e32 v141, v228, v141, vcc
	v_rcp_f32_e32 v192, v141
	v_cvt_f32_ubyte3_e32 v141, v193
	v_pk_mul_f32 v[196:197], v[196:197], v[200:201]
	v_cndmask_b32_e32 v141, v228, v141, vcc
	v_pk_mul_f32 v[98:99], v[98:99], v[196:197]
	v_cvt_f32_ubyte1_e32 v197, v190
	v_cvt_f32_ubyte0_e32 v196, v190
	v_rcp_f32_e32 v193, v141
	v_cvt_f32_ubyte0_e32 v141, v188
	v_pk_mul_f32 v[170:171], v[170:171], v[196:197]
	v_cndmask_b32_e32 v141, v228, v141, vcc
	v_pk_mul_f32 v[68:69], v[68:69], v[170:171]
	v_rcp_f32_e32 v170, v141
	v_cvt_f32_ubyte1_e32 v141, v188
	v_cndmask_b32_e32 v141, v228, v141, vcc
	v_rcp_f32_e32 v171, v141
	v_cvt_f32_ubyte2_e32 v141, v188
	v_cndmask_b32_e32 v141, v228, v141, vcc
	v_pk_mul_f32 v[70:71], v[70:71], v[172:173]
	v_rcp_f32_e32 v172, v141
	v_cvt_f32_ubyte3_e32 v141, v188
	v_cndmask_b32_e32 v141, v228, v141, vcc
	v_rcp_f32_e32 v173, v141
	v_cvt_f32_ubyte1_e32 v199, v191
	v_cvt_f32_ubyte0_e32 v198, v191
	v_cvt_f32_ubyte3_e32 v197, v191
	v_cvt_f32_ubyte2_e32 v196, v191
	v_pk_mul_f32 v[190:191], v[194:195], v[198:199]
	v_cvt_f32_ubyte0_e32 v141, v189
	v_pk_mul_f32 v[64:65], v[64:65], v[190:191]
	v_cvt_f32_ubyte3_e32 v191, v186
	v_cvt_f32_ubyte2_e32 v190, v186
	v_cndmask_b32_e32 v141, v228, v141, vcc
	v_pk_mul_f32 v[172:173], v[172:173], v[190:191]
	v_rcp_f32_e32 v190, v141
	v_cvt_f32_ubyte1_e32 v141, v189
	v_cndmask_b32_e32 v141, v228, v141, vcc
	v_rcp_f32_e32 v191, v141
	v_cvt_f32_ubyte2_e32 v141, v189
	v_cndmask_b32_e32 v141, v228, v141, vcc
	v_rcp_f32_e32 v188, v141
	v_cvt_f32_ubyte3_e32 v141, v189
	v_pk_mul_f32 v[192:193], v[192:193], v[196:197]
	v_cndmask_b32_e32 v141, v228, v141, vcc
	v_pk_mul_f32 v[66:67], v[66:67], v[192:193]
	v_cvt_f32_ubyte1_e32 v193, v186
	v_cvt_f32_ubyte0_e32 v192, v186
	v_rcp_f32_e32 v189, v141
	v_cvt_f32_ubyte0_e32 v141, v184
	v_pk_mul_f32 v[170:171], v[170:171], v[192:193]
	v_cndmask_b32_e32 v141, v228, v141, vcc
	v_pk_mul_f32 v[60:61], v[60:61], v[170:171]
	v_rcp_f32_e32 v170, v141
	v_cvt_f32_ubyte1_e32 v141, v184
	v_cndmask_b32_e32 v141, v228, v141, vcc
	v_rcp_f32_e32 v171, v141
	v_cvt_f32_ubyte2_e32 v141, v184
	v_cndmask_b32_e32 v141, v228, v141, vcc
	v_pk_mul_f32 v[62:63], v[62:63], v[172:173]
	v_rcp_f32_e32 v172, v141
	v_cvt_f32_ubyte3_e32 v141, v184
	v_cndmask_b32_e32 v141, v228, v141, vcc
	v_rcp_f32_e32 v173, v141
	v_cvt_f32_ubyte1_e32 v195, v187
	v_cvt_f32_ubyte0_e32 v194, v187
	v_cvt_f32_ubyte3_e32 v193, v187
	v_cvt_f32_ubyte2_e32 v192, v187
	v_pk_mul_f32 v[186:187], v[190:191], v[194:195]
	v_cvt_f32_ubyte0_e32 v141, v185
	v_pk_mul_f32 v[56:57], v[56:57], v[186:187]
	v_cvt_f32_ubyte3_e32 v187, v166
	v_cvt_f32_ubyte2_e32 v186, v166
	v_cndmask_b32_e32 v141, v228, v141, vcc
	v_pk_mul_f32 v[172:173], v[172:173], v[186:187]
	v_rcp_f32_e32 v186, v141
	v_cvt_f32_ubyte1_e32 v141, v185
	v_cndmask_b32_e32 v141, v228, v141, vcc
	v_rcp_f32_e32 v187, v141
	v_cvt_f32_ubyte2_e32 v141, v185
	v_cndmask_b32_e32 v141, v228, v141, vcc
	v_rcp_f32_e32 v184, v141
	v_cvt_f32_ubyte3_e32 v141, v185
	v_pk_mul_f32 v[188:189], v[188:189], v[192:193]
	v_cndmask_b32_e32 v141, v228, v141, vcc
; __device__ __forceinline__ float fast_rcp(float x) { return __builtin_amdgcn_rcpf(x); }
;     __device__ __forceinline__ void operator()(f32x4 (&acc)[2][2][4][2], const Unit& u, int wr, int wc, int fr, int fq) const {
;     ...
;                 for (int bj = 0; bj < 2; ++bj) { const u32x2 a = gw[ai][m][bj], c = g2[ai][m][bj];
;                     float s[8];
; #pragma unroll
;                     for (int e = 0; e < 8; ++e) { const float den = (float)(((e < 4 ? c.x : c.y) >> (8 * (e & 3))) & 255u);
;                         s[e] = (float)(((e < 4 ? a.x : a.y) >> (8 * (e & 3))) & 255u) * fast_rcp(mid ? den : 255.0f); }
;                     f32x4& v0 = acc[ai][bj][m][0]; f32x4& v1 = acc[ai][bj][m][1];
;                     v0 = v0 * (f32x4){s[0], s[1], s[2], s[3]}; v1 = v1 * (f32x4){s[4], s[5], s[6], s[7]}; }
	v_pk_mul_f32 v[58:59], v[58:59], v[188:189]
	v_cvt_f32_ubyte1_e32 v189, v166
	v_cvt_f32_ubyte0_e32 v188, v166
	v_rcp_f32_e32 v185, v141
	v_cvt_f32_ubyte1_e32 v191, v167
	v_cvt_f32_ubyte0_e32 v190, v167
	v_cvt_f32_ubyte0_e32 v141, v164
	v_pk_mul_f32 v[170:171], v[170:171], v[188:189]
	v_cvt_f32_ubyte3_e32 v189, v167
	v_cvt_f32_ubyte2_e32 v188, v167
	v_pk_mul_f32 v[166:167], v[186:187], v[190:191]
	v_cndmask_b32_e32 v141, v228, v141, vcc
	v_pk_mul_f32 v[24:25], v[24:25], v[166:167]
	v_rcp_f32_e32 v166, v141
	v_cvt_f32_ubyte1_e32 v141, v164
	v_cndmask_b32_e32 v141, v228, v141, vcc
	v_rcp_f32_e32 v167, v141
	v_cvt_f32_ubyte2_e32 v141, v164
	v_cndmask_b32_e32 v141, v228, v141, vcc
	v_pk_mul_f32 v[28:29], v[28:29], v[170:171]
	v_rcp_f32_e32 v170, v141
	v_cvt_f32_ubyte3_e32 v141, v164
	v_cndmask_b32_e32 v141, v228, v141, vcc
	v_rcp_f32_e32 v171, v141
	v_cvt_f32_ubyte0_e32 v141, v165
	v_pk_mul_f32 v[30:31], v[30:31], v[172:173]
	v_cvt_f32_ubyte3_e32 v173, v162
	v_cvt_f32_ubyte2_e32 v172, v162
	v_cndmask_b32_e32 v141, v228, v141, vcc
	v_pk_mul_f32 v[170:171], v[170:171], v[172:173]
	v_rcp_f32_e32 v172, v141
	v_cvt_f32_ubyte1_e32 v141, v165
	v_cndmask_b32_e32 v141, v228, v141, vcc
	v_rcp_f32_e32 v173, v141
	v_cvt_f32_ubyte2_e32 v141, v165
	v_cndmask_b32_e32 v141, v228, v141, vcc
	v_rcp_f32_e32 v164, v141
	v_cvt_f32_ubyte3_e32 v141, v165
	v_pk_mul_f32 v[184:185], v[184:185], v[188:189]
	v_cndmask_b32_e32 v141, v228, v141, vcc
	v_pk_mul_f32 v[26:27], v[26:27], v[184:185]
	v_cvt_f32_ubyte1_e32 v185, v162
	v_cvt_f32_ubyte0_e32 v184, v162
	v_rcp_f32_e32 v165, v141
	v_cvt_f32_ubyte1_e32 v187, v163
	v_cvt_f32_ubyte0_e32 v186, v163
	v_cvt_f32_ubyte0_e32 v141, v160
	v_pk_mul_f32 v[166:167], v[166:167], v[184:185]
	v_cvt_f32_ubyte3_e32 v185, v163
	v_cvt_f32_ubyte2_e32 v184, v163
	v_pk_mul_f32 v[162:163], v[172:173], v[186:187]
	v_cndmask_b32_e32 v141, v228, v141, vcc
	v_pk_mul_f32 v[48:49], v[48:49], v[162:163]
	v_rcp_f32_e32 v162, v141
	v_cvt_f32_ubyte1_e32 v141, v160
	v_cndmask_b32_e32 v141, v228, v141, vcc
	v_rcp_f32_e32 v163, v141
	v_cvt_f32_ubyte2_e32 v141, v160
	v_pk_mul_f32 v[164:165], v[164:165], v[184:185]
	v_cndmask_b32_e32 v141, v228, v141, vcc
	v_pk_mul_f32 v[50:51], v[50:51], v[164:165]
	v_rcp_f32_e32 v164, v141
	v_cvt_f32_ubyte3_e32 v141, v160
	v_cndmask_b32_e32 v141, v228, v141, vcc
	v_rcp_f32_e32 v165, v141
	v_cvt_f32_ubyte0_e32 v141, v161
	v_pk_mul_f32 v[52:53], v[52:53], v[166:167]
	v_cvt_f32_ubyte3_e32 v167, v158
	v_cvt_f32_ubyte2_e32 v166, v158
	v_cndmask_b32_e32 v141, v228, v141, vcc
	v_pk_mul_f32 v[164:165], v[164:165], v[166:167]
	v_rcp_f32_e32 v166, v141
	v_cvt_f32_ubyte1_e32 v141, v161
	v_cndmask_b32_e32 v141, v228, v141, vcc
	v_rcp_f32_e32 v167, v141
	v_cvt_f32_ubyte2_e32 v141, v161
	v_cndmask_b32_e32 v141, v228, v141, vcc
	v_rcp_f32_e32 v160, v141
	v_cvt_f32_ubyte3_e32 v141, v161
	v_cndmask_b32_e32 v141, v228, v141, vcc
	v_pk_mul_f32 v[54:55], v[54:55], v[170:171]
	v_cvt_f32_ubyte1_e32 v171, v158
	v_cvt_f32_ubyte0_e32 v170, v158
	v_rcp_f32_e32 v161, v141
	v_cvt_f32_ubyte1_e32 v173, v159
	v_cvt_f32_ubyte0_e32 v172, v159
	v_cvt_f32_ubyte0_e32 v141, v156
	v_pk_mul_f32 v[162:163], v[162:163], v[170:171]
	v_cvt_f32_ubyte3_e32 v171, v159
	v_cvt_f32_ubyte2_e32 v170, v159
	v_pk_mul_f32 v[158:159], v[166:167], v[172:173]
	v_cndmask_b32_e32 v141, v228, v141, vcc
	v_pk_mul_f32 v[16:17], v[16:17], v[158:159]
	v_rcp_f32_e32 v158, v141
	v_cvt_f32_ubyte1_e32 v141, v156
	v_cndmask_b32_e32 v141, v228, v141, vcc
	v_rcp_f32_e32 v159, v141
	v_cvt_f32_ubyte2_e32 v141, v156
	v_pk_mul_f32 v[160:161], v[160:161], v[170:171]
	v_cndmask_b32_e32 v141, v228, v141, vcc
	v_pk_mul_f32 v[18:19], v[18:19], v[160:161]
	v_rcp_f32_e32 v160, v141
	v_cvt_f32_ubyte3_e32 v141, v156
	v_cndmask_b32_e32 v141, v228, v141, vcc
	v_rcp_f32_e32 v161, v141
	v_cvt_f32_ubyte0_e32 v141, v157
	v_pk_mul_f32 v[20:21], v[20:21], v[162:163]
	v_cvt_f32_ubyte3_e32 v163, v154
	v_cvt_f32_ubyte2_e32 v162, v154
	v_cndmask_b32_e32 v141, v228, v141, vcc
	v_pk_mul_f32 v[160:161], v[160:161], v[162:163]
	v_rcp_f32_e32 v162, v141
	v_cvt_f32_ubyte1_e32 v141, v157
	v_cndmask_b32_e32 v141, v228, v141, vcc
	v_rcp_f32_e32 v163, v141
	v_cvt_f32_ubyte2_e32 v141, v157
	v_cndmask_b32_e32 v141, v228, v141, vcc
	v_rcp_f32_e32 v156, v141
	v_cvt_f32_ubyte3_e32 v141, v157
	v_cndmask_b32_e32 v141, v228, v141, vcc
	v_pk_mul_f32 v[22:23], v[22:23], v[164:165]
	v_cvt_f32_ubyte1_e32 v165, v154
	v_cvt_f32_ubyte0_e32 v164, v154
	v_rcp_f32_e32 v157, v141
	v_cvt_f32_ubyte1_e32 v167, v155
	v_cvt_f32_ubyte0_e32 v166, v155
	v_cvt_f32_ubyte0_e32 v141, v152
	v_pk_mul_f32 v[158:159], v[158:159], v[164:165]
	v_cvt_f32_ubyte3_e32 v165, v155
	v_cvt_f32_ubyte2_e32 v164, v155
	v_pk_mul_f32 v[154:155], v[162:163], v[166:167]
	v_cndmask_b32_e32 v141, v228, v141, vcc
	v_pk_mul_f32 v[40:41], v[40:41], v[154:155]
	v_rcp_f32_e32 v154, v141
	v_cvt_f32_ubyte1_e32 v141, v152
	v_cndmask_b32_e32 v141, v228, v141, vcc
	v_rcp_f32_e32 v155, v141
	v_cvt_f32_ubyte2_e32 v141, v152
	v_pk_mul_f32 v[156:157], v[156:157], v[164:165]
	v_cndmask_b32_e32 v141, v228, v141, vcc
	v_pk_mul_f32 v[42:43], v[42:43], v[156:157]
	v_rcp_f32_e32 v156, v141
	v_cvt_f32_ubyte3_e32 v141, v152
	v_cndmask_b32_e32 v141, v228, v141, vcc
	v_rcp_f32_e32 v157, v141
	v_cvt_f32_ubyte0_e32 v141, v153
	v_pk_mul_f32 v[44:45], v[44:45], v[158:159]
	v_cvt_f32_ubyte3_e32 v159, v150
	v_cvt_f32_ubyte2_e32 v158, v150
	v_cndmask_b32_e32 v141, v228, v141, vcc
	v_pk_mul_f32 v[156:157], v[156:157], v[158:159]
	v_rcp_f32_e32 v158, v141
	v_cvt_f32_ubyte1_e32 v141, v153
	v_cndmask_b32_e32 v141, v228, v141, vcc
	v_rcp_f32_e32 v159, v141
	v_cvt_f32_ubyte2_e32 v141, v153
	v_cndmask_b32_e32 v141, v228, v141, vcc
	v_rcp_f32_e32 v152, v141
	v_cvt_f32_ubyte3_e32 v141, v153
	v_cndmask_b32_e32 v141, v228, v141, vcc
	v_pk_mul_f32 v[46:47], v[46:47], v[160:161]
	v_cvt_f32_ubyte1_e32 v161, v150
	v_cvt_f32_ubyte0_e32 v160, v150
	v_rcp_f32_e32 v153, v141
	v_cvt_f32_ubyte1_e32 v163, v151
	v_cvt_f32_ubyte0_e32 v162, v151
	s_waitcnt vmcnt(2)
; __device__ __forceinline__ float fast_rcp(float x) { return __builtin_amdgcn_rcpf(x); }
;     __device__ __forceinline__ void operator()(f32x4 (&acc)[2][2][4][2], const Unit& u, int wr, int wc, int fr, int fq) const {
;     ...
;                 for (int bj = 0; bj < 2; ++bj) { const u32x2 a = gw[ai][m][bj], c = g2[ai][m][bj];
;                     float s[8];
; #pragma unroll
;                     for (int e = 0; e < 8; ++e) { const float den = (float)(((e < 4 ? c.x : c.y) >> (8 * (e & 3))) & 255u);
;                         s[e] = (float)(((e < 4 ? a.x : a.y) >> (8 * (e & 3))) & 255u) * fast_rcp(mid ? den : 255.0f); }
;                     f32x4& v0 = acc[ai][bj][m][0]; f32x4& v1 = acc[ai][bj][m][1];
;                     v0 = v0 * (f32x4){s[0], s[1], s[2], s[3]}; v1 = v1 * (f32x4){s[4], s[5], s[6], s[7]}; }
;         if (u.n == 2) {
	v_cvt_f32_ubyte0_e32 v141, v148
	v_pk_mul_f32 v[154:155], v[154:155], v[160:161]
	v_cvt_f32_ubyte3_e32 v161, v151
	v_cvt_f32_ubyte2_e32 v160, v151
	v_pk_mul_f32 v[150:151], v[158:159], v[162:163]
	v_cndmask_b32_e32 v141, v228, v141, vcc
	v_pk_mul_f32 v[8:9], v[8:9], v[150:151]
	v_rcp_f32_e32 v150, v141
	v_cvt_f32_ubyte1_e32 v141, v148
	v_cndmask_b32_e32 v141, v228, v141, vcc
	v_rcp_f32_e32 v151, v141
	v_cvt_f32_ubyte2_e32 v141, v148
	v_pk_mul_f32 v[152:153], v[152:153], v[160:161]
	v_cndmask_b32_e32 v141, v228, v141, vcc
	v_pk_mul_f32 v[10:11], v[10:11], v[152:153]
	v_rcp_f32_e32 v152, v141
	v_cvt_f32_ubyte3_e32 v141, v148
	v_cndmask_b32_e32 v141, v228, v141, vcc
	v_rcp_f32_e32 v153, v141
	v_cvt_f32_ubyte0_e32 v141, v149
	v_pk_mul_f32 v[12:13], v[12:13], v[154:155]
	v_cvt_f32_ubyte3_e32 v155, v146
	v_cvt_f32_ubyte2_e32 v154, v146
	v_cndmask_b32_e32 v141, v228, v141, vcc
	v_pk_mul_f32 v[152:153], v[152:153], v[154:155]
	v_rcp_f32_e32 v154, v141
	v_cvt_f32_ubyte1_e32 v141, v149
	v_cndmask_b32_e32 v141, v228, v141, vcc
	v_rcp_f32_e32 v155, v141
	v_cvt_f32_ubyte2_e32 v141, v149
	v_cndmask_b32_e32 v141, v228, v141, vcc
	v_rcp_f32_e32 v148, v141
	v_cvt_f32_ubyte3_e32 v141, v149
	v_cndmask_b32_e32 v141, v228, v141, vcc
	v_pk_mul_f32 v[14:15], v[14:15], v[156:157]
	v_cvt_f32_ubyte1_e32 v157, v146
	v_cvt_f32_ubyte0_e32 v156, v146
	v_rcp_f32_e32 v149, v141
	v_cvt_f32_ubyte1_e32 v159, v147
	v_cvt_f32_ubyte0_e32 v158, v147
	s_waitcnt vmcnt(1)
	v_cvt_f32_ubyte0_e32 v141, v144
	v_pk_mul_f32 v[150:151], v[150:151], v[156:157]
	v_cvt_f32_ubyte3_e32 v157, v147
	v_cvt_f32_ubyte2_e32 v156, v147
	v_pk_mul_f32 v[146:147], v[154:155], v[158:159]
	v_cndmask_b32_e32 v141, v228, v141, vcc
	v_pk_mul_f32 v[32:33], v[32:33], v[146:147]
	v_rcp_f32_e32 v146, v141
	v_cvt_f32_ubyte1_e32 v141, v144
	v_cndmask_b32_e32 v141, v228, v141, vcc
	v_rcp_f32_e32 v147, v141
	v_cvt_f32_ubyte2_e32 v141, v144
	v_pk_mul_f32 v[148:149], v[148:149], v[156:157]
	v_cndmask_b32_e32 v141, v228, v141, vcc
	v_pk_mul_f32 v[34:35], v[34:35], v[148:149]
	v_rcp_f32_e32 v148, v141
	v_cvt_f32_ubyte3_e32 v141, v144
	v_cndmask_b32_e32 v141, v228, v141, vcc
	v_rcp_f32_e32 v149, v141
	v_cvt_f32_ubyte0_e32 v141, v145
	v_pk_mul_f32 v[36:37], v[36:37], v[150:151]
	s_waitcnt vmcnt(0)
	v_cvt_f32_ubyte3_e32 v151, v142
	v_cvt_f32_ubyte2_e32 v150, v142
	v_cndmask_b32_e32 v141, v228, v141, vcc
	v_pk_mul_f32 v[148:149], v[148:149], v[150:151]
	v_rcp_f32_e32 v150, v141
	v_cvt_f32_ubyte1_e32 v141, v145
	v_cndmask_b32_e32 v141, v228, v141, vcc
	v_rcp_f32_e32 v151, v141
	v_cvt_f32_ubyte2_e32 v141, v145
	v_cndmask_b32_e32 v141, v228, v141, vcc
	v_rcp_f32_e32 v144, v141
	v_cvt_f32_ubyte3_e32 v141, v145
	v_cndmask_b32_e32 v141, v228, v141, vcc
	v_rcp_f32_e32 v145, v141
	v_pk_mul_f32 v[38:39], v[38:39], v[152:153]
	v_cvt_f32_ubyte1_e32 v153, v142
	v_cvt_f32_ubyte0_e32 v152, v142
	v_pk_mul_f32 v[146:147], v[146:147], v[152:153]
	v_cvt_f32_ubyte3_e32 v153, v143
	v_cvt_f32_ubyte2_e32 v152, v143
	v_cvt_f32_ubyte1_e32 v155, v143
	v_cvt_f32_ubyte0_e32 v154, v143
	v_pk_mul_f32 v[142:143], v[150:151], v[154:155]
	v_pk_mul_f32 v[144:145], v[144:145], v[152:153]
	v_pk_mul_f32 v[6:7], v[6:7], v[148:149]
	v_pk_mul_f32 v[4:5], v[4:5], v[146:147]
	v_pk_mul_f32 v[2:3], v[2:3], v[144:145]
	s_cmp_lg_u32 s52, 2
	v_pk_mul_f32 v[0:1], v[0:1], v[142:143]
	s_cbranch_scc1 .LBB0_828
; __device__ __forceinline__ unsigned cvt_pk_bf16(float lo, float hi) { unsigned r; asm volatile("v_cvt_pk_bf16_f32 %0, %1, %2" : "=v"(r) : "v"(lo), "v"(hi)); return r; }
;     __device__ __forceinline__ void operator()(f32x4 (&acc)[2][2][4][2], const Unit& u, int wr, int wc, int fr, int fq) const {
;     ...
;             bf16* mp = Mb + (size_t)row0 * D + col0;
; #pragma unroll
;             for (int ai = 0; ai < 2; ++ai)
; #pragma unroll
;                 for (int m = 0; m < 4; ++m)
; #pragma unroll
;                     for (int bj = 0; bj < 2; ++bj) { const f32x4 v0 = acc[ai][bj][m][0], v1 = acc[ai][bj][m][1];
;                         u32x4 w; w.x = cvt_pk_bf16(v0[0], v0[1]); w.y = cvt_pk_bf16(v0[2], v0[3]); w.z = cvt_pk_bf16(v1[0], v1[1]); w.w = cvt_pk_bf16(v1[2], v1[3]);
;                         *(u32x4*)(mp + (size_t)(ai * HALF + m * 16) * D + bj * HALF) = w; }
	v_ashrrev_i32_e32 v141, 31, v140
	v_lshlrev_b64 v[140:141], 12, v[140:141]
	v_lshl_add_u64 v[140:141], s[38:39], 0, v[140:141]
	v_lshl_add_u64 v[138:139], v[138:139], 1, v[140:141]
	v_cvt_pk_bf16_f32 v140, v124, v125
	v_cvt_pk_bf16_f32 v141, v126, v127
	v_cvt_pk_bf16_f32 v142, v120, v121
	v_cvt_pk_bf16_f32 v143, v122, v123
	s_mov_b32 s14, 0x10000
	global_store_dwordx4 v[138:139], v[140:143], off
	v_add_co_u32_e32 v144, vcc, s14, v138
	s_nop 0
	v_cvt_pk_bf16_f32 v140, v92, v93
	v_cvt_pk_bf16_f32 v141, v94, v95
	v_cvt_pk_bf16_f32 v142, v88, v89
	v_cvt_pk_bf16_f32 v143, v90, v91
	global_store_dwordx4 v[138:139], v[140:143], off offset:256
	v_addc_co_u32_e32 v145, vcc, 0, v139, vcc
	s_nop 0
	v_cvt_pk_bf16_f32 v140, v116, v117
	v_cvt_pk_bf16_f32 v141, v118, v119
	v_cvt_pk_bf16_f32 v142, v112, v113
	v_cvt_pk_bf16_f32 v143, v114, v115
	s_mov_b32 s14, 0x20000
	global_store_dwordx4 v[144:145], v[140:143], off
	s_nop 1
	v_cvt_pk_bf16_f32 v140, v84, v85
	v_cvt_pk_bf16_f32 v141, v86, v87
	v_cvt_pk_bf16_f32 v142, v80, v81
	v_cvt_pk_bf16_f32 v143, v82, v83
	global_store_dwordx4 v[144:145], v[140:143], off offset:256
	v_add_co_u32_e32 v144, vcc, s14, v138
	s_nop 0
	v_cvt_pk_bf16_f32 v140, v108, v109
	v_cvt_pk_bf16_f32 v141, v110, v111
	v_cvt_pk_bf16_f32 v142, v104, v105
	v_cvt_pk_bf16_f32 v143, v106, v107
	s_nop 0
	v_addc_co_u32_e32 v145, vcc, 0, v139, vcc
	s_mov_b32 s14, 0x30000
	global_store_dwordx4 v[144:145], v[140:143], off
	s_nop 1
	v_cvt_pk_bf16_f32 v140, v76, v77
	v_cvt_pk_bf16_f32 v141, v78, v79
	v_cvt_pk_bf16_f32 v142, v72, v73
	v_cvt_pk_bf16_f32 v143, v74, v75
	global_store_dwordx4 v[144:145], v[140:143], off offset:256
	v_add_co_u32_e32 v144, vcc, s14, v138
	s_nop 0
	v_cvt_pk_bf16_f32 v140, v100, v101
	v_cvt_pk_bf16_f32 v141, v102, v103
	v_cvt_pk_bf16_f32 v142, v96, v97
	v_cvt_pk_bf16_f32 v143, v98, v99
	s_nop 0
	v_addc_co_u32_e32 v145, vcc, 0, v139, vcc
	s_mov_b32 s14, 0x80000
	global_store_dwordx4 v[144:145], v[140:143], off
	s_nop 1
	v_cvt_pk_bf16_f32 v140, v68, v69
	v_cvt_pk_bf16_f32 v141, v70, v71
	v_cvt_pk_bf16_f32 v142, v64, v65
	v_cvt_pk_bf16_f32 v143, v66, v67
	global_store_dwordx4 v[144:145], v[140:143], off offset:256
	v_add_co_u32_e32 v144, vcc, s14, v138
	s_nop 0
	v_cvt_pk_bf16_f32 v140, v60, v61
	v_cvt_pk_bf16_f32 v141, v62, v63
	v_cvt_pk_bf16_f32 v142, v56, v57
	v_cvt_pk_bf16_f32 v143, v58, v59
	s_nop 0
	v_addc_co_u32_e32 v145, vcc, 0, v139, vcc
	s_mov_b32 s14, 0x90000
	global_store_dwordx4 v[144:145], v[140:143], off
	s_nop 1
	v_cvt_pk_bf16_f32 v140, v28, v29
	v_cvt_pk_bf16_f32 v141, v30, v31
	v_cvt_pk_bf16_f32 v142, v24, v25
	v_cvt_pk_bf16_f32 v143, v26, v27
	global_store_dwordx4 v[144:145], v[140:143], off offset:256
	v_add_co_u32_e32 v144, vcc, s14, v138
	s_nop 0
	v_cvt_pk_bf16_f32 v140, v52, v53
	v_cvt_pk_bf16_f32 v141, v54, v55
	v_cvt_pk_bf16_f32 v142, v48, v49
	v_cvt_pk_bf16_f32 v143, v50, v51
	s_nop 0
	v_addc_co_u32_e32 v145, vcc, 0, v139, vcc
	s_mov_b32 s14, 0xa0000
	global_store_dwordx4 v[144:145], v[140:143], off
	s_nop 1
	v_cvt_pk_bf16_f32 v140, v20, v21
	v_cvt_pk_bf16_f32 v141, v22, v23
	v_cvt_pk_bf16_f32 v142, v16, v17
	v_cvt_pk_bf16_f32 v143, v18, v19
	global_store_dwordx4 v[144:145], v[140:143], off offset:256
	v_add_co_u32_e32 v144, vcc, s14, v138
	s_nop 0
	v_cvt_pk_bf16_f32 v140, v44, v45
	v_cvt_pk_bf16_f32 v141, v46, v47
	v_cvt_pk_bf16_f32 v142, v40, v41
	v_cvt_pk_bf16_f32 v143, v42, v43
	s_nop 0
	v_addc_co_u32_e32 v145, vcc, 0, v139, vcc
	s_mov_b32 s14, 0xb0000
	global_store_dwordx4 v[144:145], v[140:143], off
	s_nop 1
	v_cvt_pk_bf16_f32 v140, v12, v13
	v_cvt_pk_bf16_f32 v141, v14, v15
	v_cvt_pk_bf16_f32 v142, v8, v9
	v_cvt_pk_bf16_f32 v143, v10, v11
	global_store_dwordx4 v[144:145], v[140:143], off offset:256
	v_add_co_u32_e32 v144, vcc, s14, v138
	s_nop 0
	v_cvt_pk_bf16_f32 v140, v36, v37
	v_cvt_pk_bf16_f32 v141, v38, v39
	v_cvt_pk_bf16_f32 v142, v32, v33
	v_cvt_pk_bf16_f32 v143, v34, v35
	s_nop 0
	v_addc_co_u32_e32 v145, vcc, 0, v139, vcc
	global_store_dwordx4 v[144:145], v[140:143], off
	v_cvt_pk_bf16_f32 v138, v4, v5
	v_cvt_pk_bf16_f32 v139, v6, v7
	s_nop 1
	v_cvt_pk_bf16_f32 v140, v0, v1
	v_cvt_pk_bf16_f32 v141, v2, v3
	global_store_dwordx4 v[144:145], v[138:141], off offset:256

; #define PG8_STAGE(bufoff, gbase, voff) do { _Pragma("unroll") for (int _i = 0; _i < 2; ++_i) \
;         __builtin_amdgcn_global_load_lds((const unsigned*)((const char*)(gbase) + (voff)[_i]), (LAS unsigned*)(lds + (bufoff) + ldsw + _i * 8192), 16, 0, 0); } while (0)
; #define PG8_LDA(dst, b, h) do { _Pragma("unroll") for (int m = 0; m < 4; ++m) _Pragma("unroll") for (int k = 0; k < 2; ++k) dst[m][k] = *(const LAS bf16x8*)(lds + PG8_SA(b, h) + aoff + m * 2048 + k * 1024); } while (0)
; #define PG8_LDB(dst, b, h) do { _Pragma("unroll") for (int n = 0; n < 2; ++n) _Pragma("unroll") for (int k = 0; k < 2; ++k) dst[n][k] = *(const LAS bf16x8*)(lds + PG8_SB(b, h) + boff + n * 2048 + k * 1024); } while (0)
; #define PG8_MMA(ai, bj, At, Bt) do { __builtin_amdgcn_s_setprio(1); _Pragma("unroll") for (int m = 0; m < 4; ++m) _Pragma("unroll") for (int n = 0; n < 2; ++n) _Pragma("unroll") for (int k = 0; k < 2; ++k) \
;         acc[ai][bj][m][n] = __builtin_amdgcn_mfma_f32_16x16x32_bf16(Bt[n][k], At[m][k], acc[ai][bj][m][n], 0, 0, 0); __builtin_amdgcn_s_setprio(0); } while (0)
; #define PG8_WAIT_V(n) asm volatile("s_waitcnt vmcnt(" #n ")" ::: "memory")
; #define PG8_BAR __builtin_amdgcn_s_barrier()
; template <class Epi>
; __device__ __forceinline__ void gemm_phase(LAS unsigned char* lds, const Gemm g, const StaticOrder& S, const Epi& E, const int tid) {
;     ...
;         const bool has_next = S.next(ui + 1, nxt);
;         const char* nA = has_next ? PG8_APTR(nxt) : cA; const char* nB = has_next ? PG8_BPTR(nxt) : cB;
;         for (int t = 0; t < nt; t += 2) {
;             const bool last = (t == nt - 2);
;             const char* a1 = cA + (size_t)(t + 1) * kstep;
;             const char* a2 = last ? nA : cA + (size_t)(t + 2) * kstep; const char* b2 = last ? nB : cB + (size_t)(t + 2) * kstep;
;             const char* a3 = a2 + kstep; const char* b3 = b2 + kstep;
;             PG8_LDB(B0, 0, 0); PG8_LDB(B1, 0, 1); PG8_SCHED; PG8_LDA(At, 0, 0); PG8_STAGE(PG8_SA(1, 1), a1 + hsA, voffA);
;             PG8_WAIT_V(8); PG8_WAIT_L(0); PG8_BAR; PG8_MMA(0, 0, At, B0); PG8_MMA(0, 1, At, B1); PG8_BAR; PG8_SCHED;
;     ...
;         for (int a = 0; a < 2; ++a)
; #pragma unroll
;             for (int b = 0; b < 2; ++b)
; #pragma unroll
;                 for (int m = 0; m < 4; ++m)
; #pragma unroll
;                     for (int n = 0; n < 2; ++n) acc[a][b][m][n] = (f32x4){0.f, 0.f, 0.f, 0.f};
.LBB0_892:
	s_ashr_i32 s11, s10, 31
	s_lshl_b64 s[12:13], s[10:11], 20
	s_add_u32 s12, s58, s12
	s_addc_u32 s13, s59, s13
	s_and_b64 s[14:15], s[40:41], exec
	s_cselect_b32 s11, s13, s17
	s_cselect_b32 s49, s12, s16
	s_ashr_i32 s9, s8, 31
	s_lshl_b64 s[14:15], s[8:9], 20
	s_add_u32 s14, s27, s14
	s_addc_u32 s15, s34, s15
	s_and_b64 s[18:19], s[40:41], exec
	s_cselect_b32 s9, s15, s1
	s_cselect_b32 s52, s14, s0
	s_add_u32 s16, s16, 0x80080
	s_addc_u32 s17, s17, 0
	s_add_u32 s53, s0, 0x100
	v_mov_b32_e32 v0, 0
	s_addc_u32 s56, s1, 0
	s_mov_b32 s57, -2
	v_mov_b32_e32 v1, v0
	v_mov_b32_e32 v2, v0
	v_mov_b32_e32 v3, v0
	v_mov_b32_e32 v4, v0
	v_mov_b32_e32 v5, v0
	v_mov_b32_e32 v6, v0
	v_mov_b32_e32 v7, v0
	v_mov_b32_e32 v16, v0
	v_mov_b32_e32 v17, v0
	v_mov_b32_e32 v18, v0
	v_mov_b32_e32 v19, v0
	v_mov_b32_e32 v20, v0
	v_mov_b32_e32 v21, v0
	v_mov_b32_e32 v22, v0
	v_mov_b32_e32 v23, v0
	v_mov_b32_e32 v32, v0
	v_mov_b32_e32 v33, v0
	v_mov_b32_e32 v34, v0
	v_mov_b32_e32 v35, v0
	v_mov_b32_e32 v36, v0
	v_mov_b32_e32 v37, v0
	v_mov_b32_e32 v38, v0
	v_mov_b32_e32 v39, v0
	v_mov_b32_e32 v48, v0
	v_mov_b32_e32 v49, v0
	v_mov_b32_e32 v50, v0
	v_mov_b32_e32 v51, v0
	v_mov_b32_e32 v52, v0
	v_mov_b32_e32 v53, v0
	v_mov_b32_e32 v54, v0
	v_mov_b32_e32 v55, v0
	v_mov_b32_e32 v8, v0
	v_mov_b32_e32 v9, v0
	v_mov_b32_e32 v10, v0
	v_mov_b32_e32 v11, v0
	v_mov_b32_e32 v12, v0
	v_mov_b32_e32 v13, v0
	v_mov_b32_e32 v14, v0
	v_mov_b32_e32 v15, v0
	v_mov_b32_e32 v24, v0
	v_mov_b32_e32 v25, v0
	v_mov_b32_e32 v26, v0
	v_mov_b32_e32 v27, v0
	v_mov_b32_e32 v28, v0
	v_mov_b32_e32 v29, v0
	v_mov_b32_e32 v30, v0
	v_mov_b32_e32 v31, v0
	v_mov_b32_e32 v40, v0
	v_mov_b32_e32 v41, v0
	v_mov_b32_e32 v42, v0
	v_mov_b32_e32 v43, v0
	v_mov_b32_e32 v44, v0
	v_mov_b32_e32 v45, v0
	v_mov_b32_e32 v46, v0
	v_mov_b32_e32 v47, v0
	v_mov_b32_e32 v56, v0
	v_mov_b32_e32 v57, v0
	v_mov_b32_e32 v58, v0
	v_mov_b32_e32 v59, v0
	v_mov_b32_e32 v60, v0
	v_mov_b32_e32 v61, v0
	v_mov_b32_e32 v62, v0
	v_mov_b32_e32 v63, v0
	v_mov_b32_e32 v80, v0
	v_mov_b32_e32 v81, v0
	v_mov_b32_e32 v82, v0
	v_mov_b32_e32 v83, v0
	v_mov_b32_e32 v84, v0
	v_mov_b32_e32 v85, v0
	v_mov_b32_e32 v86, v0
	v_mov_b32_e32 v87, v0
	v_mov_b32_e32 v92, v0
	v_mov_b32_e32 v93, v0
	v_mov_b32_e32 v94, v0
	v_mov_b32_e32 v95, v0
	v_mov_b32_e32 v100, v0
	v_mov_b32_e32 v101, v0
	v_mov_b32_e32 v102, v0
	v_mov_b32_e32 v103, v0
	v_mov_b32_e32 v112, v0
	v_mov_b32_e32 v113, v0
	v_mov_b32_e32 v114, v0
	v_mov_b32_e32 v115, v0
	v_mov_b32_e32 v116, v0
	v_mov_b32_e32 v117, v0
	v_mov_b32_e32 v118, v0
	v_mov_b32_e32 v119, v0
	v_mov_b32_e32 v128, v0
	v_mov_b32_e32 v129, v0
	v_mov_b32_e32 v130, v0
	v_mov_b32_e32 v131, v0
	v_mov_b32_e32 v132, v0
	v_mov_b32_e32 v133, v0
	v_mov_b32_e32 v134, v0
	v_mov_b32_e32 v135, v0
	v_mov_b32_e32 v88, v0
	v_mov_b32_e32 v89, v0
	v_mov_b32_e32 v90, v0
	v_mov_b32_e32 v91, v0
	v_mov_b32_e32 v96, v0
	v_mov_b32_e32 v97, v0
	v_mov_b32_e32 v98, v0
	v_mov_b32_e32 v99, v0
	v_mov_b32_e32 v104, v0
	v_mov_b32_e32 v105, v0
	v_mov_b32_e32 v106, v0
	v_mov_b32_e32 v107, v0
	v_mov_b32_e32 v108, v0
	v_mov_b32_e32 v109, v0
	v_mov_b32_e32 v110, v0
	v_mov_b32_e32 v111, v0
	v_mov_b32_e32 v120, v0
	v_mov_b32_e32 v121, v0
	v_mov_b32_e32 v122, v0
	v_mov_b32_e32 v123, v0
	v_mov_b32_e32 v124, v0
	v_mov_b32_e32 v125, v0
	v_mov_b32_e32 v126, v0
	v_mov_b32_e32 v127, v0
	v_mov_b32_e32 v136, v0
	v_mov_b32_e32 v137, v0
	v_mov_b32_e32 v138, v0
	v_mov_b32_e32 v139, v0
	v_mov_b32_e32 v140, v0
	v_mov_b32_e32 v141, v0
	v_mov_b32_e32 v142, v0
	v_mov_b32_e32 v143, v0
	s_cmp_lg_u64 s[6:7], 0
	s_cbranch_scc1 .Lgprio_e
	s_setprio 1
.Lgprio_e:
.LBB0_893:
	s_add_u32 s0, s16, 0xfff80080
	s_addc_u32 s1, s17, -1
	s_add_i32 s2, 0, 0x10000
	s_cmp_eq_u32 s57, 28
	s_cselect_b32 s19, s11, s1
	s_cselect_b32 s18, s49, s0
	s_cselect_b32 s1, s9, s56
	s_cselect_b32 s0, s52, s53
	s_add_i32 s55, 0, 0x14000
	v_add_u32_e32 v76, s2, v204
	v_add_u32_e32 v156, s55, v204
	ds_read_b128 v[64:67], v76
	ds_read_b128 v[68:71], v76 offset:1024
	ds_read_b128 v[72:75], v76 offset:2048
	ds_read_b128 v[76:79], v76 offset:3072
	ds_read_b128 v[144:147], v156
	ds_read_b128 v[148:151], v156 offset:1024
	ds_read_b128 v[152:155], v156 offset:2048
	ds_read_b128 v[156:159], v156 offset:3072
	v_lshl_add_u64 v[170:171], s[16:17], 0, v[192:193]
	s_add_i32 m0, s36, 0xc000
	ds_read_b128 v[160:163], v209
	ds_read_b128 v[164:167], v209 offset:1024
	ds_read_b128 v[196:199], v209 offset:2048
	ds_read_b128 v[200:203], v209 offset:3072
	ds_read_b128 v[210:213], v209 offset:4096
	ds_read_b128 v[230:233], v209 offset:5120
	ds_read_b128 v[234:237], v209 offset:6144
	ds_read_b128 v[238:241], v209 offset:7168
	global_load_lds_dwordx4 v[170:171], off
	v_lshl_add_u64 v[170:171], s[16:17], 0, v[194:195]
	s_add_i32 m0, s36, 0xe000
	s_nop 0
	global_load_lds_dwordx4 v[170:171], off
	s_waitcnt vmcnt(8)
	s_waitcnt lgkmcnt(0)
	s_barrier
; #define PG8_STAGE(bufoff, gbase, voff) do { _Pragma("unroll") for (int _i = 0; _i < 2; ++_i) \
;         __builtin_amdgcn_global_load_lds((const unsigned*)((const char*)(gbase) + (voff)[_i]), (LAS unsigned*)(lds + (bufoff) + ldsw + _i * 8192), 16, 0, 0); } while (0)
; #define PG8_LDA(dst, b, h) do { _Pragma("unroll") for (int m = 0; m < 4; ++m) _Pragma("unroll") for (int k = 0; k < 2; ++k) dst[m][k] = *(const LAS bf16x8*)(lds + PG8_SA(b, h) + aoff + m * 2048 + k * 1024); } while (0)
; #define PG8_MMA(ai, bj, At, Bt) do { __builtin_amdgcn_s_setprio(1); _Pragma("unroll") for (int m = 0; m < 4; ++m) _Pragma("unroll") for (int n = 0; n < 2; ++n) _Pragma("unroll") for (int k = 0; k < 2; ++k) \
;         acc[ai][bj][m][n] = __builtin_amdgcn_mfma_f32_16x16x32_bf16(Bt[n][k], At[m][k], acc[ai][bj][m][n], 0, 0, 0); __builtin_amdgcn_s_setprio(0); } while (0)
; #define PG8_WAIT_V(n) asm volatile("s_waitcnt vmcnt(" #n ")" ::: "memory")
; #define PG8_WAIT_L(n) asm volatile("s_waitcnt lgkmcnt(" #n ")" ::: "memory")
; #define PG8_BAR __builtin_amdgcn_s_barrier()
; #define PG8_SCHED __builtin_amdgcn_sched_barrier(0)
; template <class Epi>
; __device__ __forceinline__ void gemm_phase(LAS unsigned char* lds, const Gemm g, const StaticOrder& S, const Epi& E, const int tid) {
;     ...
;             PG8_WAIT_V(8); PG8_WAIT_L(0); PG8_BAR; PG8_MMA(0, 0, At, B0); PG8_MMA(0, 1, At, B1); PG8_BAR; PG8_SCHED;
;             PG8_LDA(At, 0, 1); PG8_STAGE(PG8_SB(0, 0), b2, voffB); PG8_STAGE(PG8_SB(0, 1), b2 + hsB, voffB); PG8_STAGE(PG8_SA(0, 0), a2, voffA);
;             PG8_WAIT_V(8); PG8_WAIT_L(0); PG8_BAR; PG8_MMA(1, 0, At, B0); PG8_MMA(1, 1, At, B1); PG8_BAR; PG8_SCHED;
	s_waitcnt lgkmcnt(0)
	v_mfma_f32_16x16x32_bf16 v[140:143], v[64:67], v[160:163], v[140:143]
	v_mfma_f32_16x16x32_bf16 v[136:139], v[72:75], v[160:163], v[136:139]
	v_mfma_f32_16x16x32_bf16 v[124:127], v[64:67], v[196:199], v[124:127]
	v_mfma_f32_16x16x32_bf16 v[120:123], v[72:75], v[196:199], v[120:123]
	v_mfma_f32_16x16x32_bf16 v[108:111], v[64:67], v[210:213], v[108:111]
	v_mfma_f32_16x16x32_bf16 v[104:107], v[72:75], v[210:213], v[104:107]
	v_mfma_f32_16x16x32_bf16 v[96:99], v[64:67], v[234:237], v[96:99]
	v_mfma_f32_16x16x32_bf16 v[88:91], v[72:75], v[234:237], v[88:91]
	v_mfma_f32_16x16x32_bf16 v[140:143], v[68:71], v[164:167], v[140:143]
	v_mfma_f32_16x16x32_bf16 v[136:139], v[76:79], v[164:167], v[136:139]
	v_mfma_f32_16x16x32_bf16 v[124:127], v[68:71], v[200:203], v[124:127]
	v_mfma_f32_16x16x32_bf16 v[120:123], v[76:79], v[200:203], v[120:123]
	v_mfma_f32_16x16x32_bf16 v[108:111], v[68:71], v[230:233], v[108:111]
	v_mfma_f32_16x16x32_bf16 v[104:107], v[76:79], v[230:233], v[104:107]
	v_mfma_f32_16x16x32_bf16 v[96:99], v[68:71], v[238:241], v[96:99]
	v_mfma_f32_16x16x32_bf16 v[88:91], v[76:79], v[238:241], v[88:91]
	v_mfma_f32_16x16x32_bf16 v[132:135], v[144:147], v[160:163], v[132:135]
	v_mfma_f32_16x16x32_bf16 v[128:131], v[152:155], v[160:163], v[128:131]
	v_mfma_f32_16x16x32_bf16 v[116:119], v[144:147], v[196:199], v[116:119]
	v_mfma_f32_16x16x32_bf16 v[112:115], v[152:155], v[196:199], v[112:115]
	v_mfma_f32_16x16x32_bf16 v[100:103], v[144:147], v[210:213], v[100:103]
	v_mfma_f32_16x16x32_bf16 v[92:95], v[152:155], v[210:213], v[92:95]
	v_mfma_f32_16x16x32_bf16 v[84:87], v[144:147], v[234:237], v[84:87]
	v_mfma_f32_16x16x32_bf16 v[80:83], v[152:155], v[234:237], v[80:83]
	v_mfma_f32_16x16x32_bf16 v[132:135], v[148:151], v[164:167], v[132:135]
	v_mfma_f32_16x16x32_bf16 v[128:131], v[156:159], v[164:167], v[128:131]
	v_mfma_f32_16x16x32_bf16 v[116:119], v[148:151], v[200:203], v[116:119]
	v_mfma_f32_16x16x32_bf16 v[112:115], v[156:159], v[200:203], v[112:115]
	v_mfma_f32_16x16x32_bf16 v[100:103], v[148:151], v[230:233], v[100:103]
	v_mfma_f32_16x16x32_bf16 v[92:95], v[156:159], v[230:233], v[92:95]
	v_mfma_f32_16x16x32_bf16 v[84:87], v[148:151], v[238:241], v[84:87]
	v_mfma_f32_16x16x32_bf16 v[80:83], v[156:159], v[238:241], v[80:83]
	s_barrier
	s_add_i32 s2, s2, s35
	v_lshl_add_u64 v[170:171], s[0:1], 0, v[188:189]
	s_mov_b32 m0, s2
	ds_read_b128 v[160:163], v209 offset:16384
	ds_read_b128 v[164:167], v209 offset:17408
	ds_read_b128 v[196:199], v209 offset:18432
	ds_read_b128 v[200:203], v209 offset:19456
	ds_read_b128 v[210:213], v209 offset:20480
	ds_read_b128 v[230:233], v209 offset:21504
	ds_read_b128 v[234:237], v209 offset:22528
	ds_read_b128 v[238:241], v209 offset:23552
	global_load_lds_dwordx4 v[170:171], off
	s_add_i32 m0, s2, 0x2000
	s_add_u32 s24, s0, 0x80000
	v_lshl_add_u64 v[172:173], s[0:1], 0, v[184:185]
	s_addc_u32 s25, s1, 0
	s_add_i32 s2, s55, s35
	global_load_lds_dwordx4 v[172:173], off
	v_lshl_add_u64 v[242:243], s[24:25], 0, v[188:189]
	s_mov_b32 m0, s2
	v_lshl_add_u64 v[244:245], s[18:19], 0, v[186:187]
	global_load_lds_dwordx4 v[242:243], off
	v_lshl_add_u64 v[242:243], s[24:25], 0, v[184:185]
	s_add_i32 m0, s2, 0x2000
	s_nop 0
	global_load_lds_dwordx4 v[242:243], off
	v_lshl_add_u64 v[242:243], s[18:19], 0, v[190:191]
	s_mov_b32 m0, s36
	s_nop 0
	global_load_lds_dwordx4 v[242:243], off
	s_mov_b32 m0, s37
	s_nop 0
	global_load_lds_dwordx4 v[244:245], off
	s_waitcnt vmcnt(8)
	s_waitcnt lgkmcnt(0)
	s_barrier
	s_waitcnt lgkmcnt(0)
	v_mfma_f32_16x16x32_bf16 v[60:63], v[64:67], v[160:163], v[60:63]
	v_mfma_f32_16x16x32_bf16 v[56:59], v[72:75], v[160:163], v[56:59]
	v_mfma_f32_16x16x32_bf16 v[44:47], v[64:67], v[196:199], v[44:47]
	v_mfma_f32_16x16x32_bf16 v[40:43], v[72:75], v[196:199], v[40:43]
	v_mfma_f32_16x16x32_bf16 v[28:31], v[64:67], v[210:213], v[28:31]
	v_mfma_f32_16x16x32_bf16 v[24:27], v[72:75], v[210:213], v[24:27]
	v_mfma_f32_16x16x32_bf16 v[12:15], v[64:67], v[234:237], v[12:15]
	v_mfma_f32_16x16x32_bf16 v[8:11], v[72:75], v[234:237], v[8:11]
	v_mfma_f32_16x16x32_bf16 v[60:63], v[68:71], v[164:167], v[60:63]
	v_mfma_f32_16x16x32_bf16 v[56:59], v[76:79], v[164:167], v[56:59]
	v_mfma_f32_16x16x32_bf16 v[44:47], v[68:71], v[200:203], v[44:47]
	v_mfma_f32_16x16x32_bf16 v[40:43], v[76:79], v[200:203], v[40:43]
	v_mfma_f32_16x16x32_bf16 v[28:31], v[68:71], v[230:233], v[28:31]
	v_mfma_f32_16x16x32_bf16 v[24:27], v[76:79], v[230:233], v[24:27]
	v_mfma_f32_16x16x32_bf16 v[12:15], v[68:71], v[238:241], v[12:15]
	v_mfma_f32_16x16x32_bf16 v[8:11], v[76:79], v[238:241], v[8:11]
	v_mfma_f32_16x16x32_bf16 v[52:55], v[144:147], v[160:163], v[52:55]
	v_mfma_f32_16x16x32_bf16 v[48:51], v[152:155], v[160:163], v[48:51]
	v_mfma_f32_16x16x32_bf16 v[36:39], v[144:147], v[196:199], v[36:39]
	v_mfma_f32_16x16x32_bf16 v[32:35], v[152:155], v[196:199], v[32:35]
	v_mfma_f32_16x16x32_bf16 v[20:23], v[144:147], v[210:213], v[20:23]
	v_mfma_f32_16x16x32_bf16 v[16:19], v[152:155], v[210:213], v[16:19]
	v_mfma_f32_16x16x32_bf16 v[4:7], v[144:147], v[234:237], v[4:7]
	v_mfma_f32_16x16x32_bf16 v[0:3], v[152:155], v[234:237], v[0:3]
	v_mfma_f32_16x16x32_bf16 v[52:55], v[148:151], v[164:167], v[52:55]
	v_mfma_f32_16x16x32_bf16 v[48:51], v[156:159], v[164:167], v[48:51]
	v_mfma_f32_16x16x32_bf16 v[36:39], v[148:151], v[200:203], v[36:39]
	v_mfma_f32_16x16x32_bf16 v[32:35], v[156:159], v[200:203], v[32:35]
	v_mfma_f32_16x16x32_bf16 v[20:23], v[148:151], v[230:233], v[20:23]
	v_mfma_f32_16x16x32_bf16 v[16:19], v[156:159], v[230:233], v[16:19]
	v_mfma_f32_16x16x32_bf16 v[4:7], v[148:151], v[238:241], v[4:7]
	v_mfma_f32_16x16x32_bf16 v[0:3], v[156:159], v[238:241], v[0:3]
	s_barrier
; #define PG8_STAGE(bufoff, gbase, voff) do { _Pragma("unroll") for (int _i = 0; _i < 2; ++_i) \
;         __builtin_amdgcn_global_load_lds((const unsigned*)((const char*)(gbase) + (voff)[_i]), (LAS unsigned*)(lds + (bufoff) + ldsw + _i * 8192), 16, 0, 0); } while (0)
; #define PG8_LDA(dst, b, h) do { _Pragma("unroll") for (int m = 0; m < 4; ++m) _Pragma("unroll") for (int k = 0; k < 2; ++k) dst[m][k] = *(const LAS bf16x8*)(lds + PG8_SA(b, h) + aoff + m * 2048 + k * 1024); } while (0)
; #define PG8_LDB(dst, b, h) do { _Pragma("unroll") for (int n = 0; n < 2; ++n) _Pragma("unroll") for (int k = 0; k < 2; ++k) dst[n][k] = *(const LAS bf16x8*)(lds + PG8_SB(b, h) + boff + n * 2048 + k * 1024); } while (0)
; #define PG8_MMA(ai, bj, At, Bt) do { __builtin_amdgcn_s_setprio(1); _Pragma("unroll") for (int m = 0; m < 4; ++m) _Pragma("unroll") for (int n = 0; n < 2; ++n) _Pragma("unroll") for (int k = 0; k < 2; ++k) \
;         acc[ai][bj][m][n] = __builtin_amdgcn_mfma_f32_16x16x32_bf16(Bt[n][k], At[m][k], acc[ai][bj][m][n], 0, 0, 0); __builtin_amdgcn_s_setprio(0); } while (0)
; #define PG8_WAIT_V(n) asm volatile("s_waitcnt vmcnt(" #n ")" ::: "memory")
; #define PG8_WAIT_L(n) asm volatile("s_waitcnt lgkmcnt(" #n ")" ::: "memory")
; #define PG8_BAR __builtin_amdgcn_s_barrier()
; #define PG8_SCHED __builtin_amdgcn_sched_barrier(0)
; template <class Epi>
; __device__ __forceinline__ void gemm_phase(LAS unsigned char* lds, const Gemm g, const StaticOrder& S, const Epi& E, const int tid) {
;     ...
;             PG8_LDB(B0, 1, 0); PG8_LDB(B1, 1, 1); PG8_SCHED; PG8_LDA(At, 1, 0); PG8_STAGE(PG8_SA(0, 1), a2 + hsA, voffA);
;             PG8_WAIT_V(8); PG8_WAIT_L(0); PG8_BAR; PG8_MMA(0, 0, At, B0); PG8_MMA(0, 1, At, B1); PG8_BAR; PG8_SCHED;
;             PG8_LDA(At, 1, 1); PG8_STAGE(PG8_SB(1, 0), b3, voffB); PG8_STAGE(PG8_SB(1, 1), b3 + hsB, voffB); PG8_STAGE(PG8_SA(1, 0), a3, voffA);
;             PG8_WAIT_V(8); PG8_WAIT_L(0); PG8_BAR; PG8_MMA(1, 0, At, B0); PG8_MMA(1, 1, At, B1); PG8_BAR; PG8_SCHED;
	s_add_i32 s2, 0, 0x18000
	s_add_i32 s24, 0, 0x1c000
	v_add_u32_e32 v76, s2, v204
	v_add_u32_e32 v156, s24, v204
	ds_read_b128 v[64:67], v76
	ds_read_b128 v[68:71], v76 offset:1024
	ds_read_b128 v[72:75], v76 offset:2048
	ds_read_b128 v[76:79], v76 offset:3072
	ds_read_b128 v[144:147], v156
	ds_read_b128 v[148:151], v156 offset:1024
	ds_read_b128 v[152:155], v156 offset:2048
	ds_read_b128 v[156:159], v156 offset:3072
	s_add_u32 s18, s18, 0x80000
	s_addc_u32 s19, s19, 0
	s_mov_b32 m0, s38
	v_lshl_add_u64 v[246:247], s[18:19], 0, v[190:191]
	ds_read_b128 v[160:163], v209 offset:32768
	ds_read_b128 v[164:167], v209 offset:33792
	ds_read_b128 v[196:199], v209 offset:34816
	ds_read_b128 v[200:203], v209 offset:35840
	ds_read_b128 v[210:213], v209 offset:36864
	ds_read_b128 v[230:233], v209 offset:37888
	ds_read_b128 v[234:237], v209 offset:38912
	ds_read_b128 v[238:241], v209 offset:39936
	global_load_lds_dwordx4 v[246:247], off
	v_lshl_add_u64 v[246:247], s[18:19], 0, v[186:187]
	s_mov_b32 m0, s39
	s_nop 0
	global_load_lds_dwordx4 v[246:247], off
	s_waitcnt vmcnt(8)
	s_waitcnt lgkmcnt(0)
	s_barrier
	s_waitcnt lgkmcnt(0)
	v_mfma_f32_16x16x32_bf16 v[140:143], v[64:67], v[160:163], v[140:143]
	v_mfma_f32_16x16x32_bf16 v[136:139], v[72:75], v[160:163], v[136:139]
	v_mfma_f32_16x16x32_bf16 v[124:127], v[64:67], v[196:199], v[124:127]
	v_mfma_f32_16x16x32_bf16 v[120:123], v[72:75], v[196:199], v[120:123]
	v_mfma_f32_16x16x32_bf16 v[108:111], v[64:67], v[210:213], v[108:111]
	v_mfma_f32_16x16x32_bf16 v[104:107], v[72:75], v[210:213], v[104:107]
	v_mfma_f32_16x16x32_bf16 v[96:99], v[64:67], v[234:237], v[96:99]
	v_mfma_f32_16x16x32_bf16 v[88:91], v[72:75], v[234:237], v[88:91]
	v_mfma_f32_16x16x32_bf16 v[140:143], v[68:71], v[164:167], v[140:143]
	v_mfma_f32_16x16x32_bf16 v[136:139], v[76:79], v[164:167], v[136:139]
	v_mfma_f32_16x16x32_bf16 v[124:127], v[68:71], v[200:203], v[124:127]
	v_mfma_f32_16x16x32_bf16 v[120:123], v[76:79], v[200:203], v[120:123]
	v_mfma_f32_16x16x32_bf16 v[108:111], v[68:71], v[230:233], v[108:111]
	v_mfma_f32_16x16x32_bf16 v[104:107], v[76:79], v[230:233], v[104:107]
	v_mfma_f32_16x16x32_bf16 v[96:99], v[68:71], v[238:241], v[96:99]
	v_mfma_f32_16x16x32_bf16 v[88:91], v[76:79], v[238:241], v[88:91]
	v_mfma_f32_16x16x32_bf16 v[132:135], v[144:147], v[160:163], v[132:135]
	v_mfma_f32_16x16x32_bf16 v[128:131], v[152:155], v[160:163], v[128:131]
	v_mfma_f32_16x16x32_bf16 v[116:119], v[144:147], v[196:199], v[116:119]
	v_mfma_f32_16x16x32_bf16 v[112:115], v[152:155], v[196:199], v[112:115]
	v_mfma_f32_16x16x32_bf16 v[100:103], v[144:147], v[210:213], v[100:103]
	v_mfma_f32_16x16x32_bf16 v[92:95], v[152:155], v[210:213], v[92:95]
	v_mfma_f32_16x16x32_bf16 v[84:87], v[144:147], v[234:237], v[84:87]
	v_mfma_f32_16x16x32_bf16 v[80:83], v[152:155], v[234:237], v[80:83]
	v_mfma_f32_16x16x32_bf16 v[132:135], v[148:151], v[164:167], v[132:135]
	v_mfma_f32_16x16x32_bf16 v[128:131], v[156:159], v[164:167], v[128:131]
	v_mfma_f32_16x16x32_bf16 v[116:119], v[148:151], v[200:203], v[116:119]
	v_mfma_f32_16x16x32_bf16 v[112:115], v[156:159], v[200:203], v[112:115]
	v_mfma_f32_16x16x32_bf16 v[100:103], v[148:151], v[230:233], v[100:103]
	v_mfma_f32_16x16x32_bf16 v[92:95], v[156:159], v[230:233], v[92:95]
	v_mfma_f32_16x16x32_bf16 v[84:87], v[148:151], v[238:241], v[84:87]
	v_mfma_f32_16x16x32_bf16 v[80:83], v[156:159], v[238:241], v[80:83]
	s_barrier
	s_add_i32 s2, s2, s35
	v_lshl_add_u64 v[170:171], v[170:171], 0, s[28:29]
	s_mov_b32 m0, s2
	ds_read_b128 v[160:163], v209 offset:49152
	ds_read_b128 v[164:167], v209 offset:50176
	ds_read_b128 v[196:199], v209 offset:51200
	ds_read_b128 v[200:203], v209 offset:52224
	ds_read_b128 v[210:213], v209 offset:53248
	ds_read_b128 v[230:233], v209 offset:54272
	ds_read_b128 v[234:237], v209 offset:55296
	ds_read_b128 v[238:241], v209 offset:56320
	global_load_lds_dwordx4 v[170:171], off
	s_add_i32 m0, s2, 0x2000
	s_add_u32 s0, s0, 0x80080
	v_lshl_add_u64 v[170:171], v[172:173], 0, s[28:29]
	s_addc_u32 s1, s1, 0
	s_add_i32 s2, s24, s35
	global_load_lds_dwordx4 v[170:171], off
	v_lshl_add_u64 v[170:171], s[0:1], 0, v[188:189]
	s_mov_b32 m0, s2
	s_nop 0
	global_load_lds_dwordx4 v[170:171], off
	v_lshl_add_u64 v[170:171], s[0:1], 0, v[184:185]
	s_add_i32 m0, s2, 0x2000
	s_nop 0
	global_load_lds_dwordx4 v[170:171], off
	v_lshl_add_u64 v[170:171], v[242:243], 0, s[28:29]
	s_mov_b32 m0, s44
	s_nop 0
	global_load_lds_dwordx4 v[170:171], off
	v_lshl_add_u64 v[170:171], v[244:245], 0, s[28:29]
	s_mov_b32 m0, s45
	s_nop 0
	global_load_lds_dwordx4 v[170:171], off
	s_waitcnt vmcnt(8)
	s_waitcnt lgkmcnt(0)
	s_barrier
; template <class Epi>
; __device__ __forceinline__ void gemm_phase(LAS unsigned char* lds, const Gemm g, const StaticOrder& S, const Epi& E, const int tid) {
;     ...
;             PG8_WAIT_V(8); PG8_WAIT_L(0); PG8_BAR; PG8_MMA(1, 0, At, B0); PG8_MMA(1, 1, At, B1); PG8_BAR; PG8_SCHED;
;         }
;         if (wr == 0) PG8_BAR;
;         E(acc, cur, wr, wc, fr, fq);
;     __device__ __forceinline__ void operator()(f32x4 (&acc)[2][2][4][2], const Unit& u, int wr, int wc, int fr, int fq) const {
;         const int lrow0 = row_off + u.pm * BM + wr * 64 + fr, col0 = u.pn * BM + wc * 32 + 8 * fq;
;         const int b = (row_off + u.pm * BM) >> 12;
;         const float* gp = gate + (size_t)b * NMOD + col0;
;         f32x4 gv[2][2];
; #pragma unroll
;         for (int bj = 0; bj < 2; ++bj)
; #pragma unroll
;             for (int n = 0; n < 2; ++n) gv[bj][n] = *(const f32x4*)(gp + bj * HALF + 4 * n) * coef;
;         _Float16* xp = xh + (size_t)lrow0 * D + col0;
;         if (base32) {
;             const float* bp = base32 + (size_t)lrow0 * D + col0;
; #pragma unroll
;             for (int am = 0; am < 8; am += 2) {
;                 f32x4 xb[2][2][2];
; #pragma unroll
;                 for (int mm = 0; mm < 2; ++mm)
; #pragma unroll
;                     for (int bj = 0; bj < 2; ++bj) { const int ai = (am + mm) >> 2, m = (am + mm) & 3; const float* p = bp + (size_t)(ai * HALF + m * 16) * D + bj * HALF; xb[mm][bj][0] = *(const f32x4*)p; xb[mm][bj][1] = *(const f32x4*)(p + 4); }
; #pragma unroll
;                 for (int mm = 0; mm < 2; ++mm)
; #pragma unroll
;                     for (int bj = 0; bj < 2; ++bj) { const int ai = (am + mm) >> 2, m = (am + mm) & 3;
;                         *(h16x8*)(xp + (size_t)(ai * HALF + m * 16) * D + bj * HALF) = f_to_h8(xb[mm][bj][0] + gv[bj][0] * acc[ai][bj][m][0], xb[mm][bj][1] + gv[bj][1] * acc[ai][bj][m][1]); }
;                 __builtin_amdgcn_sched_barrier(0);
;             }
;         } else {
;             const int lane = fr + 16 * fq, rr = lane >> 2, cg = lane & 3;
;             const int pullx = (4 * fr + fq) * 4, pullr = (rr + 16 * cg) * 4;
;             _Float16* xc = xh + (size_t)(row_off + u.pm * BM + wr * 64 + rr) * D + u.pn * BM + wc * 32 + 8 * cg;
; #pragma unroll
;             for (int ai = 0; ai < 2; ++ai) {
;                 u32x4 xr[4][2];
; #pragma unroll
;                 for (int m = 0; m < 4; ++m)
	s_waitcnt lgkmcnt(0)
	v_mfma_f32_16x16x32_bf16 v[60:63], v[64:67], v[160:163], v[60:63]
	v_mfma_f32_16x16x32_bf16 v[56:59], v[72:75], v[160:163], v[56:59]
	v_mfma_f32_16x16x32_bf16 v[44:47], v[64:67], v[196:199], v[44:47]
	v_mfma_f32_16x16x32_bf16 v[40:43], v[72:75], v[196:199], v[40:43]
	v_mfma_f32_16x16x32_bf16 v[28:31], v[64:67], v[210:213], v[28:31]
	v_mfma_f32_16x16x32_bf16 v[24:27], v[72:75], v[210:213], v[24:27]
	v_mfma_f32_16x16x32_bf16 v[12:15], v[64:67], v[234:237], v[12:15]
	v_mfma_f32_16x16x32_bf16 v[8:11], v[72:75], v[234:237], v[8:11]
	v_mfma_f32_16x16x32_bf16 v[60:63], v[68:71], v[164:167], v[60:63]
	v_mfma_f32_16x16x32_bf16 v[56:59], v[76:79], v[164:167], v[56:59]
	v_mfma_f32_16x16x32_bf16 v[44:47], v[68:71], v[200:203], v[44:47]
	v_mfma_f32_16x16x32_bf16 v[40:43], v[76:79], v[200:203], v[40:43]
	v_mfma_f32_16x16x32_bf16 v[28:31], v[68:71], v[230:233], v[28:31]
	v_mfma_f32_16x16x32_bf16 v[24:27], v[76:79], v[230:233], v[24:27]
	v_mfma_f32_16x16x32_bf16 v[12:15], v[68:71], v[238:241], v[12:15]
	v_mfma_f32_16x16x32_bf16 v[8:11], v[76:79], v[238:241], v[8:11]
	v_mfma_f32_16x16x32_bf16 v[52:55], v[144:147], v[160:163], v[52:55]
	v_mfma_f32_16x16x32_bf16 v[48:51], v[152:155], v[160:163], v[48:51]
	v_mfma_f32_16x16x32_bf16 v[36:39], v[144:147], v[196:199], v[36:39]
	v_mfma_f32_16x16x32_bf16 v[32:35], v[152:155], v[196:199], v[32:35]
	v_mfma_f32_16x16x32_bf16 v[20:23], v[144:147], v[210:213], v[20:23]
	v_mfma_f32_16x16x32_bf16 v[16:19], v[152:155], v[210:213], v[16:19]
	v_mfma_f32_16x16x32_bf16 v[4:7], v[144:147], v[234:237], v[4:7]
	v_mfma_f32_16x16x32_bf16 v[0:3], v[152:155], v[234:237], v[0:3]
	v_mfma_f32_16x16x32_bf16 v[52:55], v[148:151], v[164:167], v[52:55]
	v_mfma_f32_16x16x32_bf16 v[48:51], v[156:159], v[164:167], v[48:51]
	v_mfma_f32_16x16x32_bf16 v[36:39], v[148:151], v[200:203], v[36:39]
	v_mfma_f32_16x16x32_bf16 v[32:35], v[156:159], v[200:203], v[32:35]
	v_mfma_f32_16x16x32_bf16 v[20:23], v[148:151], v[230:233], v[20:23]
	v_mfma_f32_16x16x32_bf16 v[16:19], v[156:159], v[230:233], v[16:19]
	v_mfma_f32_16x16x32_bf16 v[4:7], v[148:151], v[238:241], v[4:7]
	v_mfma_f32_16x16x32_bf16 v[0:3], v[156:159], v[238:241], v[0:3]
	s_barrier
	s_add_i32 s57, s57, 2
	s_add_u32 s16, s16, 0x100
	s_addc_u32 s17, s17, 0
	s_add_u32 s53, s53, 0x100
	s_addc_u32 s56, s56, 0
	s_cmp_gt_u32 s57, 29
	s_cbranch_scc0 .LBB0_893
	s_and_b64 vcc, exec, s[6:7]
	s_movk_i32 s49, 0x300
	s_mov_b64 s[52:53], 0x60000
	s_cbranch_vccz .LBB0_896
	s_barrier
.LBB0_896:
	s_setprio 0
	s_ashr_i32 s1, s47, 4
	s_lshl_b32 s0, s48, 8
	s_mul_hi_i32 s2, s1, 0x12000
	s_mul_i32 s1, s1, 0x12000
	v_or_b32_e32 v64, s0, v205
	s_add_u32 s16, s42, s1
	s_addc_u32 s17, s43, s2
	v_ashrrev_i32_e32 v65, 31, v64
	v_lshl_add_u32 v144, s47, 8, v208
	v_lshl_add_u64 v[68:69], v[64:65], 2, s[16:17]
	v_ashrrev_i32_e32 v145, 31, v144
	v_readlane_b32 s16, v252, 63
	v_lshlrev_b64 v[144:145], 12, v[144:145]
	v_readlane_b32 s17, v253, 0
	s_ashr_i32 s1, s0, 31
	global_load_dwordx4 v[72:75], v[68:69], off offset:16
	global_load_dwordx4 v[76:79], v[68:69], off
	global_load_dwordx4 v[64:67], v[68:69], off offset:528
	s_nop 0
	global_load_dwordx4 v[68:71], v[68:69], off offset:512
	v_lshl_add_u64 v[144:145], s[16:17], 0, v[144:145]
	v_lshl_add_u64 v[144:145], s[0:1], 1, v[144:145]
	v_lshl_add_u64 v[144:145], v[144:145], 0, s[60:61]
	v_lshl_add_u64 v[196:197], v[144:145], 0, v[168:169]
	global_load_dwordx4 v[210:213], v[196:197], off
	global_load_dwordx4 v[230:233], v[196:197], off offset:256
	s_mov_b32 s0, 0x10000
	v_add_co_u32_e32 v202, vcc, s0, v196
	s_mov_b32 s0, 0x20000
	s_nop 0
	v_addc_co_u32_e32 v203, vcc, 0, v197, vcc
	global_load_dwordx4 v[164:167], v[202:203], off
	global_load_dwordx4 v[160:163], v[202:203], off offset:256
	v_add_co_u32_e32 v200, vcc, s0, v196
	s_mov_b32 s0, 0x30000
	s_nop 0
	v_addc_co_u32_e32 v201, vcc, 0, v197, vcc
	global_load_dwordx4 v[156:159], v[200:201], off
	global_load_dwordx4 v[152:155], v[200:201], off offset:256
	v_add_co_u32_e32 v198, vcc, s0, v196
	s_mov_b32 s0, 0x80000
	s_nop 0
	v_addc_co_u32_e32 v199, vcc, 0, v197, vcc
	global_load_dwordx4 v[148:151], v[198:199], off
	global_load_dwordx4 v[144:147], v[198:199], off offset:256
	s_waitcnt vmcnt(0)
	ds_bpermute_b32 v171, v206, v210
	ds_bpermute_b32 v173, v206, v211
	ds_bpermute_b32 v211, v206, v212
	ds_bpermute_b32 v213, v206, v213
	s_waitcnt lgkmcnt(3)
	v_cvt_f32_f16_e32 v170, v171
	v_cvt_f32_f16_sdwa v171, v171 dst_sel:DWORD dst_unused:UNUSED_PAD src0_sel:WORD_1
	s_waitcnt lgkmcnt(2)
	v_cvt_f32_f16_e32 v172, v173
	v_cvt_f32_f16_sdwa v173, v173 dst_sel:DWORD dst_unused:UNUSED_PAD src0_sel:WORD_1
	s_waitcnt lgkmcnt(1)
	v_cvt_f32_f16_e32 v210, v211
	v_cvt_f32_f16_sdwa v211, v211 dst_sel:DWORD dst_unused:UNUSED_PAD src0_sel:WORD_1
	s_waitcnt lgkmcnt(0)
	v_cvt_f32_f16_e32 v212, v213
	v_cvt_f32_f16_sdwa v213, v213 dst_sel:DWORD dst_unused:UNUSED_PAD src0_sel:WORD_1
	v_pk_fma_f32 v[142:143], v[142:143], v[78:79], v[172:173]
	v_pk_fma_f32 v[140:141], v[140:141], v[76:77], v[170:171]
	v_pk_fma_f32 v[136:137], v[136:137], v[72:73], v[210:211]
	v_pk_fma_f32 v[138:139], v[138:139], v[74:75], v[212:213]
	s_nop 0
	v_cvt_pk_f16_f32 v139, v138, v139
	v_cvt_pk_f16_f32 v138, v142, v143
	v_cvt_pk_f16_f32 v142, v136, v137
	v_cvt_pk_f16_f32 v136, v140, v141
	ds_bpermute_b32 v136, v207, v136
	ds_bpermute_b32 v137, v207, v138
	ds_bpermute_b32 v138, v207, v142
	ds_bpermute_b32 v139, v207, v139
	ds_bpermute_b32 v141, v206, v232
	ds_bpermute_b32 v143, v206, v233
	s_waitcnt lgkmcnt(2)
	global_store_dwordx4 v[196:197], v[136:139], off
	ds_bpermute_b32 v137, v206, v230
	ds_bpermute_b32 v139, v206, v231
	s_waitcnt lgkmcnt(3)
; __device__ __forceinline__ h16x8 f_to_h8(const f32x4 a, const f32x4 b) { return (h16x8){(_Float16)a[0], (_Float16)a[1], (_Float16)a[2], (_Float16)a[3], (_Float16)b[0], (_Float16)b[1], (_Float16)b[2], (_Float16)b[3]}; }
;     __device__ __forceinline__ void operator()(f32x4 (&acc)[2][2][4][2], const Unit& u, int wr, int wc, int fr, int fq) const {
;     ...
;             const int lane = fr + 16 * fq, rr = lane >> 2, cg = lane & 3;
;             const int pullx = (4 * fr + fq) * 4, pullr = (rr + 16 * cg) * 4;
;             _Float16* xc = xh + (size_t)(row_off + u.pm * BM + wr * 64 + rr) * D + u.pn * BM + wc * 32 + 8 * cg;
; #pragma unroll
;             for (int ai = 0; ai < 2; ++ai) {
;                 u32x4 xr[4][2];
; #pragma unroll
;                 for (int m = 0; m < 4; ++m)
; #pragma unroll
;                     for (int bj = 0; bj < 2; ++bj) xr[m][bj] = *(const u32x4*)(xc + (size_t)(ai * HALF + m * 16) * D + bj * HALF);
; #pragma unroll
;                 for (int m = 0; m < 4; ++m)
; #pragma unroll
;                     for (int bj = 0; bj < 2; ++bj) {
;                         u32x4 t;
; #pragma unroll
;                         for (int k = 0; k < 4; ++k) t[k] = (unsigned)__builtin_amdgcn_ds_bpermute(pullx, (int)xr[m][bj][k]);
;                         f32x4 b0, b1; h8_to_f(__builtin_bit_cast(h16x8, t), b0, b1);
;                         const u32x4 r = __builtin_bit_cast(u32x4, f_to_h8(b0 + gv[bj][0] * acc[ai][bj][m][0], b1 + gv[bj][1] * acc[ai][bj][m][1]));
;                         u32x4 o;
; #pragma unroll
;                         for (int k = 0; k < 4; ++k) o[k] = (unsigned)__builtin_amdgcn_ds_bpermute(pullr, (int)r[k]);
;                         *(u32x4*)(xc + (size_t)(ai * HALF + m * 16) * D + bj * HALF) = o; }
	v_cvt_f32_f16_e32 v140, v141
	v_cvt_f32_f16_sdwa v141, v141 dst_sel:DWORD dst_unused:UNUSED_PAD src0_sel:WORD_1
	s_waitcnt lgkmcnt(2)
	v_cvt_f32_f16_e32 v142, v143
	s_waitcnt lgkmcnt(1)
	v_cvt_f32_f16_e32 v136, v137
	v_cvt_f32_f16_sdwa v137, v137 dst_sel:DWORD dst_unused:UNUSED_PAD src0_sel:WORD_1
	s_waitcnt lgkmcnt(0)
	v_cvt_f32_f16_e32 v138, v139
	v_cvt_f32_f16_sdwa v139, v139 dst_sel:DWORD dst_unused:UNUSED_PAD src0_sel:WORD_1
	v_cvt_f32_f16_sdwa v143, v143 dst_sel:DWORD dst_unused:UNUSED_PAD src0_sel:WORD_1
	v_pk_fma_f32 v[132:133], v[132:133], v[68:69], v[136:137]
	v_pk_fma_f32 v[128:129], v[128:129], v[64:65], v[140:141]
	v_pk_fma_f32 v[134:135], v[134:135], v[70:71], v[138:139]
	v_pk_fma_f32 v[130:131], v[130:131], v[66:67], v[142:143]
	s_nop 0
	v_cvt_pk_f16_f32 v131, v130, v131
	v_cvt_pk_f16_f32 v130, v134, v135
	v_cvt_pk_f16_f32 v134, v128, v129
	v_cvt_pk_f16_f32 v128, v132, v133
	ds_bpermute_b32 v128, v207, v128
	ds_bpermute_b32 v129, v207, v130
	ds_bpermute_b32 v130, v207, v134
	ds_bpermute_b32 v131, v207, v131
	ds_bpermute_b32 v133, v206, v166
	ds_bpermute_b32 v135, v206, v167
	s_waitcnt lgkmcnt(2)
	global_store_dwordx4 v[196:197], v[128:131], off offset:256
	ds_bpermute_b32 v129, v206, v164
	ds_bpermute_b32 v131, v206, v165
	s_waitcnt lgkmcnt(3)
	v_cvt_f32_f16_e32 v132, v133
	v_cvt_f32_f16_sdwa v133, v133 dst_sel:DWORD dst_unused:UNUSED_PAD src0_sel:WORD_1
	s_waitcnt lgkmcnt(2)
	v_cvt_f32_f16_e32 v134, v135
	s_waitcnt lgkmcnt(1)
	v_cvt_f32_f16_e32 v128, v129
	v_cvt_f32_f16_sdwa v129, v129 dst_sel:DWORD dst_unused:UNUSED_PAD src0_sel:WORD_1
	s_waitcnt lgkmcnt(0)
	v_cvt_f32_f16_e32 v130, v131
	v_cvt_f32_f16_sdwa v131, v131 dst_sel:DWORD dst_unused:UNUSED_PAD src0_sel:WORD_1
	v_cvt_f32_f16_sdwa v135, v135 dst_sel:DWORD dst_unused:UNUSED_PAD src0_sel:WORD_1
	v_pk_fma_f32 v[124:125], v[124:125], v[76:77], v[128:129]
	v_pk_fma_f32 v[120:121], v[120:121], v[72:73], v[132:133]
	v_pk_fma_f32 v[126:127], v[126:127], v[78:79], v[130:131]
	v_pk_fma_f32 v[122:123], v[122:123], v[74:75], v[134:135]
	s_nop 0
	v_cvt_pk_f16_f32 v123, v122, v123
	v_cvt_pk_f16_f32 v122, v120, v121
	v_cvt_pk_f16_f32 v121, v126, v127
	v_cvt_pk_f16_f32 v120, v124, v125
	ds_bpermute_b32 v120, v207, v120
	ds_bpermute_b32 v121, v207, v121
	ds_bpermute_b32 v122, v207, v122
	ds_bpermute_b32 v123, v207, v123
	ds_bpermute_b32 v125, v206, v162
	ds_bpermute_b32 v127, v206, v163
	s_waitcnt lgkmcnt(2)
	global_store_dwordx4 v[202:203], v[120:123], off
	ds_bpermute_b32 v121, v206, v160
	ds_bpermute_b32 v123, v206, v161
	s_waitcnt lgkmcnt(3)
	v_cvt_f32_f16_e32 v124, v125
	v_cvt_f32_f16_sdwa v125, v125 dst_sel:DWORD dst_unused:UNUSED_PAD src0_sel:WORD_1
	s_waitcnt lgkmcnt(2)
	v_cvt_f32_f16_e32 v126, v127
	s_waitcnt lgkmcnt(1)
	v_cvt_f32_f16_e32 v120, v121
	v_cvt_f32_f16_sdwa v121, v121 dst_sel:DWORD dst_unused:UNUSED_PAD src0_sel:WORD_1
	s_waitcnt lgkmcnt(0)
	v_cvt_f32_f16_e32 v122, v123
	v_cvt_f32_f16_sdwa v123, v123 dst_sel:DWORD dst_unused:UNUSED_PAD src0_sel:WORD_1
	v_cvt_f32_f16_sdwa v127, v127 dst_sel:DWORD dst_unused:UNUSED_PAD src0_sel:WORD_1
	v_pk_fma_f32 v[116:117], v[116:117], v[68:69], v[120:121]
	v_pk_fma_f32 v[112:113], v[112:113], v[64:65], v[124:125]
	v_pk_fma_f32 v[118:119], v[118:119], v[70:71], v[122:123]
	v_pk_fma_f32 v[114:115], v[114:115], v[66:67], v[126:127]
	s_nop 0
	v_cvt_pk_f16_f32 v115, v114, v115
	v_cvt_pk_f16_f32 v114, v112, v113
	v_cvt_pk_f16_f32 v113, v118, v119
	v_cvt_pk_f16_f32 v112, v116, v117
	ds_bpermute_b32 v112, v207, v112
	ds_bpermute_b32 v113, v207, v113
	ds_bpermute_b32 v114, v207, v114
	ds_bpermute_b32 v115, v207, v115
	ds_bpermute_b32 v117, v206, v158
	ds_bpermute_b32 v119, v206, v159
	s_waitcnt lgkmcnt(2)
	global_store_dwordx4 v[202:203], v[112:115], off offset:256
	ds_bpermute_b32 v113, v206, v156
	ds_bpermute_b32 v115, v206, v157
	s_waitcnt lgkmcnt(3)
	v_cvt_f32_f16_e32 v116, v117
	v_cvt_f32_f16_sdwa v117, v117 dst_sel:DWORD dst_unused:UNUSED_PAD src0_sel:WORD_1
	s_waitcnt lgkmcnt(2)
	v_cvt_f32_f16_e32 v118, v119
	s_waitcnt lgkmcnt(1)
	v_cvt_f32_f16_e32 v112, v113
	v_cvt_f32_f16_sdwa v113, v113 dst_sel:DWORD dst_unused:UNUSED_PAD src0_sel:WORD_1
	s_waitcnt lgkmcnt(0)
	v_cvt_f32_f16_e32 v114, v115
	v_cvt_f32_f16_sdwa v115, v115 dst_sel:DWORD dst_unused:UNUSED_PAD src0_sel:WORD_1
	v_cvt_f32_f16_sdwa v119, v119 dst_sel:DWORD dst_unused:UNUSED_PAD src0_sel:WORD_1
	v_pk_fma_f32 v[108:109], v[108:109], v[76:77], v[112:113]
	v_pk_fma_f32 v[104:105], v[104:105], v[72:73], v[116:117]
	v_pk_fma_f32 v[110:111], v[110:111], v[78:79], v[114:115]
	v_pk_fma_f32 v[106:107], v[106:107], v[74:75], v[118:119]
	s_nop 0
	v_cvt_pk_f16_f32 v107, v106, v107
	v_cvt_pk_f16_f32 v106, v104, v105
	v_cvt_pk_f16_f32 v105, v110, v111
	v_cvt_pk_f16_f32 v104, v108, v109
	ds_bpermute_b32 v104, v207, v104
	ds_bpermute_b32 v105, v207, v105
	ds_bpermute_b32 v106, v207, v106
	ds_bpermute_b32 v107, v207, v107
	ds_bpermute_b32 v109, v206, v154
	ds_bpermute_b32 v111, v206, v155
	s_waitcnt lgkmcnt(2)
	global_store_dwordx4 v[200:201], v[104:107], off
	ds_bpermute_b32 v105, v206, v152
	ds_bpermute_b32 v107, v206, v153
	s_waitcnt lgkmcnt(3)
	v_cvt_f32_f16_e32 v108, v109
	v_cvt_f32_f16_sdwa v109, v109 dst_sel:DWORD dst_unused:UNUSED_PAD src0_sel:WORD_1
	s_waitcnt lgkmcnt(2)
	v_cvt_f32_f16_e32 v110, v111
	s_waitcnt lgkmcnt(1)
	v_cvt_f32_f16_e32 v104, v105
	v_cvt_f32_f16_sdwa v105, v105 dst_sel:DWORD dst_unused:UNUSED_PAD src0_sel:WORD_1
	s_waitcnt lgkmcnt(0)
; __device__ __forceinline__ h16x8 f_to_h8(const f32x4 a, const f32x4 b) { return (h16x8){(_Float16)a[0], (_Float16)a[1], (_Float16)a[2], (_Float16)a[3], (_Float16)b[0], (_Float16)b[1], (_Float16)b[2], (_Float16)b[3]}; }
;     __device__ __forceinline__ void operator()(f32x4 (&acc)[2][2][4][2], const Unit& u, int wr, int wc, int fr, int fq) const {
;     ...
;             const int lane = fr + 16 * fq, rr = lane >> 2, cg = lane & 3;
;             const int pullx = (4 * fr + fq) * 4, pullr = (rr + 16 * cg) * 4;
;             _Float16* xc = xh + (size_t)(row_off + u.pm * BM + wr * 64 + rr) * D + u.pn * BM + wc * 32 + 8 * cg;
; #pragma unroll
;             for (int ai = 0; ai < 2; ++ai) {
;                 u32x4 xr[4][2];
; #pragma unroll
;                 for (int m = 0; m < 4; ++m)
; #pragma unroll
;                     for (int bj = 0; bj < 2; ++bj) xr[m][bj] = *(const u32x4*)(xc + (size_t)(ai * HALF + m * 16) * D + bj * HALF);
; #pragma unroll
;                 for (int m = 0; m < 4; ++m)
; #pragma unroll
;                     for (int bj = 0; bj < 2; ++bj) {
;                         u32x4 t;
; #pragma unroll
;                         for (int k = 0; k < 4; ++k) t[k] = (unsigned)__builtin_amdgcn_ds_bpermute(pullx, (int)xr[m][bj][k]);
;                         f32x4 b0, b1; h8_to_f(__builtin_bit_cast(h16x8, t), b0, b1);
;                         const u32x4 r = __builtin_bit_cast(u32x4, f_to_h8(b0 + gv[bj][0] * acc[ai][bj][m][0], b1 + gv[bj][1] * acc[ai][bj][m][1]));
;                         u32x4 o;
; #pragma unroll
;                         for (int k = 0; k < 4; ++k) o[k] = (unsigned)__builtin_amdgcn_ds_bpermute(pullr, (int)r[k]);
;                         *(u32x4*)(xc + (size_t)(ai * HALF + m * 16) * D + bj * HALF) = o; }
	v_cvt_f32_f16_e32 v106, v107
	v_cvt_f32_f16_sdwa v107, v107 dst_sel:DWORD dst_unused:UNUSED_PAD src0_sel:WORD_1
	v_cvt_f32_f16_sdwa v111, v111 dst_sel:DWORD dst_unused:UNUSED_PAD src0_sel:WORD_1
	v_pk_fma_f32 v[100:101], v[100:101], v[68:69], v[104:105]
	v_pk_fma_f32 v[92:93], v[92:93], v[64:65], v[108:109]
	v_pk_fma_f32 v[102:103], v[102:103], v[70:71], v[106:107]
	v_pk_fma_f32 v[94:95], v[94:95], v[66:67], v[110:111]
	v_add_co_u32_e32 v106, vcc, s0, v196
	v_cvt_pk_f16_f32 v95, v94, v95
	v_cvt_pk_f16_f32 v94, v92, v93
	v_cvt_pk_f16_f32 v93, v102, v103
	v_cvt_pk_f16_f32 v92, v100, v101
	ds_bpermute_b32 v92, v207, v92
	ds_bpermute_b32 v93, v207, v93
	ds_bpermute_b32 v94, v207, v94
	ds_bpermute_b32 v95, v207, v95
	ds_bpermute_b32 v101, v206, v150
	ds_bpermute_b32 v103, v206, v151
	v_addc_co_u32_e32 v107, vcc, 0, v197, vcc
	s_waitcnt lgkmcnt(2)
	global_store_dwordx4 v[200:201], v[92:95], off offset:256
	ds_bpermute_b32 v93, v206, v148
	ds_bpermute_b32 v95, v206, v149
	s_waitcnt lgkmcnt(3)
	v_cvt_f32_f16_e32 v100, v101
	v_cvt_f32_f16_sdwa v101, v101 dst_sel:DWORD dst_unused:UNUSED_PAD src0_sel:WORD_1
	s_waitcnt lgkmcnt(2)
	v_cvt_f32_f16_e32 v102, v103
	s_waitcnt lgkmcnt(1)
	v_cvt_f32_f16_e32 v92, v93
	v_cvt_f32_f16_sdwa v93, v93 dst_sel:DWORD dst_unused:UNUSED_PAD src0_sel:WORD_1
	s_waitcnt lgkmcnt(0)
	v_cvt_f32_f16_e32 v94, v95
	v_cvt_f32_f16_sdwa v95, v95 dst_sel:DWORD dst_unused:UNUSED_PAD src0_sel:WORD_1
	v_cvt_f32_f16_sdwa v103, v103 dst_sel:DWORD dst_unused:UNUSED_PAD src0_sel:WORD_1
	v_pk_fma_f32 v[92:93], v[96:97], v[76:77], v[92:93]
	v_pk_fma_f32 v[88:89], v[88:89], v[72:73], v[100:101]
	v_pk_fma_f32 v[94:95], v[98:99], v[78:79], v[94:95]
	v_pk_fma_f32 v[90:91], v[90:91], v[74:75], v[102:103]
	s_mov_b32 s0, 0x90000
	v_cvt_pk_f16_f32 v91, v90, v91
	v_cvt_pk_f16_f32 v90, v88, v89
	v_cvt_pk_f16_f32 v89, v94, v95
	v_cvt_pk_f16_f32 v88, v92, v93
	ds_bpermute_b32 v88, v207, v88
	ds_bpermute_b32 v89, v207, v89
	ds_bpermute_b32 v90, v207, v90
	ds_bpermute_b32 v91, v207, v91
	ds_bpermute_b32 v93, v206, v146
	ds_bpermute_b32 v95, v206, v147
	v_add_co_u32_e32 v110, vcc, s0, v196
	s_waitcnt lgkmcnt(2)
	global_store_dwordx4 v[198:199], v[88:91], off
	ds_bpermute_b32 v89, v206, v144
	ds_bpermute_b32 v91, v206, v145
	s_waitcnt lgkmcnt(3)
	v_cvt_f32_f16_e32 v92, v93
	v_cvt_f32_f16_sdwa v93, v93 dst_sel:DWORD dst_unused:UNUSED_PAD src0_sel:WORD_1
	s_waitcnt lgkmcnt(2)
	v_cvt_f32_f16_e32 v94, v95
	s_waitcnt lgkmcnt(1)
	v_cvt_f32_f16_e32 v88, v89
	v_cvt_f32_f16_sdwa v89, v89 dst_sel:DWORD dst_unused:UNUSED_PAD src0_sel:WORD_1
	s_waitcnt lgkmcnt(0)
	v_cvt_f32_f16_e32 v90, v91
	v_cvt_f32_f16_sdwa v91, v91 dst_sel:DWORD dst_unused:UNUSED_PAD src0_sel:WORD_1
	v_cvt_f32_f16_sdwa v95, v95 dst_sel:DWORD dst_unused:UNUSED_PAD src0_sel:WORD_1
	v_pk_fma_f32 v[84:85], v[84:85], v[68:69], v[88:89]
	v_pk_fma_f32 v[80:81], v[80:81], v[64:65], v[92:93]
	v_pk_fma_f32 v[86:87], v[86:87], v[70:71], v[90:91]
	v_pk_fma_f32 v[82:83], v[82:83], v[66:67], v[94:95]
	v_addc_co_u32_e32 v111, vcc, 0, v197, vcc
	v_cvt_pk_f16_f32 v83, v82, v83
	v_cvt_pk_f16_f32 v82, v80, v81
	v_cvt_pk_f16_f32 v81, v86, v87
	v_cvt_pk_f16_f32 v80, v84, v85
	ds_bpermute_b32 v80, v207, v80
	ds_bpermute_b32 v81, v207, v81
	ds_bpermute_b32 v82, v207, v82
	ds_bpermute_b32 v83, v207, v83
	s_mov_b32 s0, 0xa0000
	v_add_co_u32_e32 v108, vcc, s0, v196
	s_mov_b32 s0, 0xb0000
	s_waitcnt lgkmcnt(0)
	global_store_dwordx4 v[198:199], v[80:83], off offset:256
	global_load_dwordx4 v[92:95], v[106:107], off
	global_load_dwordx4 v[100:103], v[106:107], off offset:256
	global_load_dwordx4 v[112:115], v[110:111], off
	global_load_dwordx4 v[116:119], v[110:111], off offset:256
	v_addc_co_u32_e32 v109, vcc, 0, v197, vcc
	global_load_dwordx4 v[96:99], v[108:109], off
	global_load_dwordx4 v[88:91], v[108:109], off offset:256
	v_add_co_u32_e32 v104, vcc, s0, v196
	s_mov_b64 s[0:1], -1
	s_nop 0
	v_addc_co_u32_e32 v105, vcc, 0, v197, vcc
	global_load_dwordx4 v[84:87], v[104:105], off
	global_load_dwordx4 v[80:83], v[104:105], off offset:256
	s_andn2_b64 vcc, exec, s[40:41]
	s_waitcnt vmcnt(7)
	ds_bpermute_b32 v120, v206, v92
	ds_bpermute_b32 v121, v206, v93
	ds_bpermute_b32 v122, v206, v94
	ds_bpermute_b32 v123, v206, v95
	s_waitcnt lgkmcnt(3)
	v_cvt_f32_f16_e32 v92, v120
	v_cvt_f32_f16_sdwa v93, v120 dst_sel:DWORD dst_unused:UNUSED_PAD src0_sel:WORD_1
	s_waitcnt lgkmcnt(2)
	v_cvt_f32_f16_e32 v94, v121
	v_cvt_f32_f16_sdwa v95, v121 dst_sel:DWORD dst_unused:UNUSED_PAD src0_sel:WORD_1
	s_waitcnt lgkmcnt(1)
	v_cvt_f32_f16_e32 v120, v122
	v_cvt_f32_f16_sdwa v121, v122 dst_sel:DWORD dst_unused:UNUSED_PAD src0_sel:WORD_1
	s_waitcnt lgkmcnt(0)
	v_cvt_f32_f16_e32 v122, v123
	v_cvt_f32_f16_sdwa v123, v123 dst_sel:DWORD dst_unused:UNUSED_PAD src0_sel:WORD_1
	v_pk_fma_f32 v[62:63], v[62:63], v[78:79], v[94:95]
	v_pk_fma_f32 v[60:61], v[60:61], v[76:77], v[92:93]
	v_pk_fma_f32 v[56:57], v[56:57], v[72:73], v[120:121]
	v_pk_fma_f32 v[58:59], v[58:59], v[74:75], v[122:123]
	s_nop 0
	v_cvt_pk_f16_f32 v59, v58, v59
	v_cvt_pk_f16_f32 v58, v56, v57
	v_cvt_pk_f16_f32 v57, v62, v63
	v_cvt_pk_f16_f32 v56, v60, v61
	ds_bpermute_b32 v56, v207, v56
	ds_bpermute_b32 v57, v207, v57
	ds_bpermute_b32 v58, v207, v58
	ds_bpermute_b32 v59, v207, v59
	s_waitcnt vmcnt(6)
	ds_bpermute_b32 v61, v206, v102
	ds_bpermute_b32 v63, v206, v103
	s_waitcnt lgkmcnt(2)
	global_store_dwordx4 v[106:107], v[56:59], off
	ds_bpermute_b32 v57, v206, v100
	ds_bpermute_b32 v59, v206, v101
	s_waitcnt lgkmcnt(3)
	v_cvt_f32_f16_e32 v60, v61
	v_cvt_f32_f16_sdwa v61, v61 dst_sel:DWORD dst_unused:UNUSED_PAD src0_sel:WORD_1
	s_waitcnt lgkmcnt(2)
	v_cvt_f32_f16_e32 v62, v63
	s_waitcnt lgkmcnt(1)
; __device__ __forceinline__ h16x8 f_to_h8(const f32x4 a, const f32x4 b) { return (h16x8){(_Float16)a[0], (_Float16)a[1], (_Float16)a[2], (_Float16)a[3], (_Float16)b[0], (_Float16)b[1], (_Float16)b[2], (_Float16)b[3]}; }
;     __device__ __forceinline__ void operator()(f32x4 (&acc)[2][2][4][2], const Unit& u, int wr, int wc, int fr, int fq) const {
;     ...
;             const int lane = fr + 16 * fq, rr = lane >> 2, cg = lane & 3;
;             const int pullx = (4 * fr + fq) * 4, pullr = (rr + 16 * cg) * 4;
;             _Float16* xc = xh + (size_t)(row_off + u.pm * BM + wr * 64 + rr) * D + u.pn * BM + wc * 32 + 8 * cg;
; #pragma unroll
;             for (int ai = 0; ai < 2; ++ai) {
;                 u32x4 xr[4][2];
; #pragma unroll
;                 for (int m = 0; m < 4; ++m)
; #pragma unroll
;                     for (int bj = 0; bj < 2; ++bj) xr[m][bj] = *(const u32x4*)(xc + (size_t)(ai * HALF + m * 16) * D + bj * HALF);
; #pragma unroll
;                 for (int m = 0; m < 4; ++m)
; #pragma unroll
;                     for (int bj = 0; bj < 2; ++bj) {
;                         u32x4 t;
; #pragma unroll
;                         for (int k = 0; k < 4; ++k) t[k] = (unsigned)__builtin_amdgcn_ds_bpermute(pullx, (int)xr[m][bj][k]);
;                         f32x4 b0, b1; h8_to_f(__builtin_bit_cast(h16x8, t), b0, b1);
;                         const u32x4 r = __builtin_bit_cast(u32x4, f_to_h8(b0 + gv[bj][0] * acc[ai][bj][m][0], b1 + gv[bj][1] * acc[ai][bj][m][1]));
;                         u32x4 o;
; #pragma unroll
;                         for (int k = 0; k < 4; ++k) o[k] = (unsigned)__builtin_amdgcn_ds_bpermute(pullr, (int)r[k]);
;                         *(u32x4*)(xc + (size_t)(ai * HALF + m * 16) * D + bj * HALF) = o; }
	v_cvt_f32_f16_e32 v56, v57
	v_cvt_f32_f16_sdwa v57, v57 dst_sel:DWORD dst_unused:UNUSED_PAD src0_sel:WORD_1
	s_waitcnt lgkmcnt(0)
	v_cvt_f32_f16_e32 v58, v59
	v_cvt_f32_f16_sdwa v59, v59 dst_sel:DWORD dst_unused:UNUSED_PAD src0_sel:WORD_1
	v_cvt_f32_f16_sdwa v63, v63 dst_sel:DWORD dst_unused:UNUSED_PAD src0_sel:WORD_1
	v_pk_fma_f32 v[52:53], v[52:53], v[68:69], v[56:57]
	v_pk_fma_f32 v[48:49], v[48:49], v[64:65], v[60:61]
	v_pk_fma_f32 v[54:55], v[54:55], v[70:71], v[58:59]
	v_pk_fma_f32 v[50:51], v[50:51], v[66:67], v[62:63]
	s_nop 0
	v_cvt_pk_f16_f32 v51, v50, v51
	v_cvt_pk_f16_f32 v50, v48, v49
	v_cvt_pk_f16_f32 v49, v54, v55
	v_cvt_pk_f16_f32 v48, v52, v53
	ds_bpermute_b32 v48, v207, v48
	ds_bpermute_b32 v49, v207, v49
	ds_bpermute_b32 v50, v207, v50
	ds_bpermute_b32 v51, v207, v51
	s_waitcnt vmcnt(6)
	ds_bpermute_b32 v53, v206, v114
	ds_bpermute_b32 v55, v206, v115
	s_waitcnt lgkmcnt(2)
	global_store_dwordx4 v[106:107], v[48:51], off offset:256
	ds_bpermute_b32 v49, v206, v112
	ds_bpermute_b32 v51, v206, v113
	s_waitcnt lgkmcnt(3)
	v_cvt_f32_f16_e32 v52, v53
	v_cvt_f32_f16_sdwa v53, v53 dst_sel:DWORD dst_unused:UNUSED_PAD src0_sel:WORD_1
	s_waitcnt lgkmcnt(2)
	v_cvt_f32_f16_e32 v54, v55
	s_waitcnt lgkmcnt(1)
	v_cvt_f32_f16_e32 v48, v49
	v_cvt_f32_f16_sdwa v49, v49 dst_sel:DWORD dst_unused:UNUSED_PAD src0_sel:WORD_1
	s_waitcnt lgkmcnt(0)
	v_cvt_f32_f16_e32 v50, v51
	v_cvt_f32_f16_sdwa v51, v51 dst_sel:DWORD dst_unused:UNUSED_PAD src0_sel:WORD_1
	v_cvt_f32_f16_sdwa v55, v55 dst_sel:DWORD dst_unused:UNUSED_PAD src0_sel:WORD_1
	v_pk_fma_f32 v[44:45], v[44:45], v[76:77], v[48:49]
	v_pk_fma_f32 v[40:41], v[40:41], v[72:73], v[52:53]
	v_pk_fma_f32 v[46:47], v[46:47], v[78:79], v[50:51]
	v_pk_fma_f32 v[42:43], v[42:43], v[74:75], v[54:55]
	s_nop 0
	v_cvt_pk_f16_f32 v43, v42, v43
	v_cvt_pk_f16_f32 v42, v40, v41
	v_cvt_pk_f16_f32 v41, v46, v47
	v_cvt_pk_f16_f32 v40, v44, v45
	ds_bpermute_b32 v40, v207, v40
	ds_bpermute_b32 v41, v207, v41
	ds_bpermute_b32 v42, v207, v42
	ds_bpermute_b32 v43, v207, v43
	s_waitcnt vmcnt(6)
	ds_bpermute_b32 v45, v206, v118
	ds_bpermute_b32 v47, v206, v119
	s_waitcnt lgkmcnt(2)
	global_store_dwordx4 v[110:111], v[40:43], off
	ds_bpermute_b32 v41, v206, v116
	ds_bpermute_b32 v43, v206, v117
	s_waitcnt lgkmcnt(3)
	v_cvt_f32_f16_e32 v44, v45
	v_cvt_f32_f16_sdwa v45, v45 dst_sel:DWORD dst_unused:UNUSED_PAD src0_sel:WORD_1
	s_waitcnt lgkmcnt(2)
	v_cvt_f32_f16_e32 v46, v47
	s_waitcnt lgkmcnt(1)
	v_cvt_f32_f16_e32 v40, v41
	v_cvt_f32_f16_sdwa v41, v41 dst_sel:DWORD dst_unused:UNUSED_PAD src0_sel:WORD_1
	s_waitcnt lgkmcnt(0)
	v_cvt_f32_f16_e32 v42, v43
	v_cvt_f32_f16_sdwa v43, v43 dst_sel:DWORD dst_unused:UNUSED_PAD src0_sel:WORD_1
	v_cvt_f32_f16_sdwa v47, v47 dst_sel:DWORD dst_unused:UNUSED_PAD src0_sel:WORD_1
	v_pk_fma_f32 v[36:37], v[36:37], v[68:69], v[40:41]
	v_pk_fma_f32 v[32:33], v[32:33], v[64:65], v[44:45]
	v_pk_fma_f32 v[38:39], v[38:39], v[70:71], v[42:43]
	v_pk_fma_f32 v[34:35], v[34:35], v[66:67], v[46:47]
	s_nop 0
	v_cvt_pk_f16_f32 v35, v34, v35
	v_cvt_pk_f16_f32 v34, v32, v33
	v_cvt_pk_f16_f32 v33, v38, v39
	v_cvt_pk_f16_f32 v32, v36, v37
	ds_bpermute_b32 v32, v207, v32
	ds_bpermute_b32 v33, v207, v33
	ds_bpermute_b32 v34, v207, v34
	ds_bpermute_b32 v35, v207, v35
	s_waitcnt vmcnt(6)
	ds_bpermute_b32 v37, v206, v98
	ds_bpermute_b32 v39, v206, v99
	s_waitcnt lgkmcnt(2)
	global_store_dwordx4 v[110:111], v[32:35], off offset:256
	ds_bpermute_b32 v33, v206, v96
	ds_bpermute_b32 v35, v206, v97
	s_waitcnt lgkmcnt(3)
	v_cvt_f32_f16_e32 v36, v37
	v_cvt_f32_f16_sdwa v37, v37 dst_sel:DWORD dst_unused:UNUSED_PAD src0_sel:WORD_1
	s_waitcnt lgkmcnt(2)
	v_cvt_f32_f16_e32 v38, v39
	s_waitcnt lgkmcnt(1)
	v_cvt_f32_f16_e32 v32, v33
	v_cvt_f32_f16_sdwa v33, v33 dst_sel:DWORD dst_unused:UNUSED_PAD src0_sel:WORD_1
	s_waitcnt lgkmcnt(0)
; __device__ __forceinline__ h16x8 f_to_h8(const f32x4 a, const f32x4 b) { return (h16x8){(_Float16)a[0], (_Float16)a[1], (_Float16)a[2], (_Float16)a[3], (_Float16)b[0], (_Float16)b[1], (_Float16)b[2], (_Float16)b[3]}; }
; #define PG8_BAR __builtin_amdgcn_s_barrier()
; template <class Epi>
; __device__ __forceinline__ void gemm_phase(LAS unsigned char* lds, const Gemm g, const StaticOrder& S, const Epi& E, const int tid) {
;     ...
;         if (!has_next) break;
;         if (!(Epi::CHAIN && cur.n + 1 < S.NS)) {
; #pragma unroll
;         for (int a = 0; a < 2; ++a)
; #pragma unroll
;             for (int b = 0; b < 2; ++b)
; #pragma unroll
;                 for (int m = 0; m < 4; ++m)
; #pragma unroll
;                     for (int n = 0; n < 2; ++n) acc[a][b][m][n] = (f32x4){0.f, 0.f, 0.f, 0.f};
;         }
;         cur = nxt; cA = nA; cB = nB; ++ui;
;         if (wr == 1) PG8_BAR;
;     __device__ __forceinline__ void operator()(f32x4 (&acc)[2][2][4][2], const Unit& u, int wr, int wc, int fr, int fq) const {
;     ...
;             for (int ai = 0; ai < 2; ++ai) {
;                 u32x4 xr[4][2];
; #pragma unroll
;                 for (int m = 0; m < 4; ++m)
; #pragma unroll
;                     for (int bj = 0; bj < 2; ++bj) xr[m][bj] = *(const u32x4*)(xc + (size_t)(ai * HALF + m * 16) * D + bj * HALF);
; #pragma unroll
;                 for (int m = 0; m < 4; ++m)
; #pragma unroll
;                     for (int bj = 0; bj < 2; ++bj) {
;                         u32x4 t;
; #pragma unroll
;                         for (int k = 0; k < 4; ++k) t[k] = (unsigned)__builtin_amdgcn_ds_bpermute(pullx, (int)xr[m][bj][k]);
;                         f32x4 b0, b1; h8_to_f(__builtin_bit_cast(h16x8, t), b0, b1);
;                         const u32x4 r = __builtin_bit_cast(u32x4, f_to_h8(b0 + gv[bj][0] * acc[ai][bj][m][0], b1 + gv[bj][1] * acc[ai][bj][m][1]));
;                         u32x4 o;
; #pragma unroll
;                         for (int k = 0; k < 4; ++k) o[k] = (unsigned)__builtin_amdgcn_ds_bpermute(pullr, (int)r[k]);
;                         *(u32x4*)(xc + (size_t)(ai * HALF + m * 16) * D + bj * HALF) = o; }
	v_cvt_f32_f16_e32 v34, v35
	v_cvt_f32_f16_sdwa v35, v35 dst_sel:DWORD dst_unused:UNUSED_PAD src0_sel:WORD_1
	v_cvt_f32_f16_sdwa v39, v39 dst_sel:DWORD dst_unused:UNUSED_PAD src0_sel:WORD_1
	v_pk_fma_f32 v[28:29], v[28:29], v[76:77], v[32:33]
	v_pk_fma_f32 v[24:25], v[24:25], v[72:73], v[36:37]
	v_pk_fma_f32 v[30:31], v[30:31], v[78:79], v[34:35]
	v_pk_fma_f32 v[26:27], v[26:27], v[74:75], v[38:39]
	s_nop 0
	v_cvt_pk_f16_f32 v27, v26, v27
	v_cvt_pk_f16_f32 v26, v24, v25
	v_cvt_pk_f16_f32 v25, v30, v31
	v_cvt_pk_f16_f32 v24, v28, v29
	ds_bpermute_b32 v24, v207, v24
	ds_bpermute_b32 v25, v207, v25
	ds_bpermute_b32 v26, v207, v26
	ds_bpermute_b32 v27, v207, v27
	s_waitcnt vmcnt(6)
	ds_bpermute_b32 v29, v206, v90
	ds_bpermute_b32 v31, v206, v91
	s_waitcnt lgkmcnt(2)
	global_store_dwordx4 v[108:109], v[24:27], off
	ds_bpermute_b32 v25, v206, v88
	ds_bpermute_b32 v27, v206, v89
	s_waitcnt lgkmcnt(3)
	v_cvt_f32_f16_e32 v28, v29
	v_cvt_f32_f16_sdwa v29, v29 dst_sel:DWORD dst_unused:UNUSED_PAD src0_sel:WORD_1
	s_waitcnt lgkmcnt(2)
	v_cvt_f32_f16_e32 v30, v31
	s_waitcnt lgkmcnt(1)
	v_cvt_f32_f16_e32 v24, v25
	v_cvt_f32_f16_sdwa v25, v25 dst_sel:DWORD dst_unused:UNUSED_PAD src0_sel:WORD_1
	s_waitcnt lgkmcnt(0)
	v_cvt_f32_f16_e32 v26, v27
	v_cvt_f32_f16_sdwa v27, v27 dst_sel:DWORD dst_unused:UNUSED_PAD src0_sel:WORD_1
	v_cvt_f32_f16_sdwa v31, v31 dst_sel:DWORD dst_unused:UNUSED_PAD src0_sel:WORD_1
	v_pk_fma_f32 v[20:21], v[20:21], v[68:69], v[24:25]
	v_pk_fma_f32 v[16:17], v[16:17], v[64:65], v[28:29]
	v_pk_fma_f32 v[22:23], v[22:23], v[70:71], v[26:27]
	v_pk_fma_f32 v[18:19], v[18:19], v[66:67], v[30:31]
	s_nop 0
	v_cvt_pk_f16_f32 v19, v18, v19
	v_cvt_pk_f16_f32 v18, v16, v17
	v_cvt_pk_f16_f32 v17, v22, v23
	v_cvt_pk_f16_f32 v16, v20, v21
	ds_bpermute_b32 v16, v207, v16
	ds_bpermute_b32 v17, v207, v17
	ds_bpermute_b32 v18, v207, v18
	ds_bpermute_b32 v19, v207, v19
	s_waitcnt vmcnt(6)
	ds_bpermute_b32 v21, v206, v86
	ds_bpermute_b32 v23, v206, v87
	s_waitcnt lgkmcnt(2)
	global_store_dwordx4 v[108:109], v[16:19], off offset:256
	ds_bpermute_b32 v17, v206, v84
	ds_bpermute_b32 v19, v206, v85
	s_waitcnt lgkmcnt(3)
	v_cvt_f32_f16_e32 v20, v21
	v_cvt_f32_f16_sdwa v21, v21 dst_sel:DWORD dst_unused:UNUSED_PAD src0_sel:WORD_1
	s_waitcnt lgkmcnt(2)
	v_cvt_f32_f16_e32 v22, v23
	s_waitcnt lgkmcnt(1)
	v_cvt_f32_f16_e32 v16, v17
	v_cvt_f32_f16_sdwa v17, v17 dst_sel:DWORD dst_unused:UNUSED_PAD src0_sel:WORD_1
	s_waitcnt lgkmcnt(0)
	v_cvt_f32_f16_e32 v18, v19
	v_cvt_f32_f16_sdwa v19, v19 dst_sel:DWORD dst_unused:UNUSED_PAD src0_sel:WORD_1
	v_cvt_f32_f16_sdwa v23, v23 dst_sel:DWORD dst_unused:UNUSED_PAD src0_sel:WORD_1
	v_pk_fma_f32 v[12:13], v[12:13], v[76:77], v[16:17]
	v_pk_fma_f32 v[8:9], v[8:9], v[72:73], v[20:21]
	v_pk_fma_f32 v[14:15], v[14:15], v[78:79], v[18:19]
	v_pk_fma_f32 v[10:11], v[10:11], v[74:75], v[22:23]
	s_nop 0
	v_cvt_pk_f16_f32 v11, v10, v11
	v_cvt_pk_f16_f32 v10, v8, v9
	v_cvt_pk_f16_f32 v9, v14, v15
	v_cvt_pk_f16_f32 v8, v12, v13
	ds_bpermute_b32 v8, v207, v8
	ds_bpermute_b32 v9, v207, v9
	ds_bpermute_b32 v10, v207, v10
	ds_bpermute_b32 v11, v207, v11
	s_waitcnt vmcnt(6)
	ds_bpermute_b32 v13, v206, v82
	ds_bpermute_b32 v15, v206, v83
	s_waitcnt lgkmcnt(2)
	global_store_dwordx4 v[104:105], v[8:11], off
	ds_bpermute_b32 v9, v206, v80
	ds_bpermute_b32 v11, v206, v81
	s_waitcnt lgkmcnt(3)
	v_cvt_f32_f16_e32 v12, v13
	v_cvt_f32_f16_sdwa v13, v13 dst_sel:DWORD dst_unused:UNUSED_PAD src0_sel:WORD_1
	s_waitcnt lgkmcnt(2)
	v_cvt_f32_f16_e32 v14, v15
	s_waitcnt lgkmcnt(1)
	v_cvt_f32_f16_e32 v8, v9
	v_cvt_f32_f16_sdwa v9, v9 dst_sel:DWORD dst_unused:UNUSED_PAD src0_sel:WORD_1
	s_waitcnt lgkmcnt(0)
	v_cvt_f32_f16_e32 v10, v11
	v_cvt_f32_f16_sdwa v11, v11 dst_sel:DWORD dst_unused:UNUSED_PAD src0_sel:WORD_1
	v_cvt_f32_f16_sdwa v15, v15 dst_sel:DWORD dst_unused:UNUSED_PAD src0_sel:WORD_1
	v_pk_fma_f32 v[4:5], v[4:5], v[68:69], v[8:9]
	v_pk_fma_f32 v[0:1], v[0:1], v[64:65], v[12:13]
	v_pk_fma_f32 v[6:7], v[6:7], v[70:71], v[10:11]
	v_pk_fma_f32 v[2:3], v[2:3], v[66:67], v[14:15]
	s_nop 0
	v_cvt_pk_f16_f32 v3, v2, v3
	v_cvt_pk_f16_f32 v2, v0, v1
	v_cvt_pk_f16_f32 v1, v6, v7
	v_cvt_pk_f16_f32 v0, v4, v5
	ds_bpermute_b32 v0, v207, v0
	ds_bpermute_b32 v1, v207, v1
	ds_bpermute_b32 v2, v207, v2
	ds_bpermute_b32 v3, v207, v3
	s_waitcnt lgkmcnt(0)
	global_store_dwordx4 v[104:105], v[0:3], off offset:256
	s_cbranch_vccnz .LBB0_885
	s_andn2_b64 vcc, exec, s[4:5]
	s_cbranch_vccnz .LBB0_884
	s_barrier
	s_branch .LBB0_884

; #define PG8_STAGE(bufoff, gbase, voff) do { _Pragma("unroll") for (int _i = 0; _i < 2; ++_i) \
;         __builtin_amdgcn_global_load_lds((const unsigned*)((const char*)(gbase) + (voff)[_i]), (LAS unsigned*)(lds + (bufoff) + ldsw + _i * 8192), 16, 0, 0); } while (0)
; #define PG8_LDA(dst, b, h) do { _Pragma("unroll") for (int m = 0; m < 4; ++m) _Pragma("unroll") for (int k = 0; k < 2; ++k) dst[m][k] = *(const LAS bf16x8*)(lds + PG8_SA(b, h) + aoff + m * 2048 + k * 1024); } while (0)
; #define PG8_LDB(dst, b, h) do { _Pragma("unroll") for (int n = 0; n < 2; ++n) _Pragma("unroll") for (int k = 0; k < 2; ++k) dst[n][k] = *(const LAS bf16x8*)(lds + PG8_SB(b, h) + boff + n * 2048 + k * 1024); } while (0)
; #define PG8_MMA(ai, bj, At, Bt) do { __builtin_amdgcn_s_setprio(1); _Pragma("unroll") for (int m = 0; m < 4; ++m) _Pragma("unroll") for (int n = 0; n < 2; ++n) _Pragma("unroll") for (int k = 0; k < 2; ++k) \
;         acc[ai][bj][m][n] = __builtin_amdgcn_mfma_f32_16x16x32_bf16(Bt[n][k], At[m][k], acc[ai][bj][m][n], 0, 0, 0); __builtin_amdgcn_s_setprio(0); } while (0)
; #define PG8_WAIT_V(n) asm volatile("s_waitcnt vmcnt(" #n ")" ::: "memory")
; #define PG8_BAR __builtin_amdgcn_s_barrier()
; template <class Epi>
; __device__ __forceinline__ void gemm_phase(LAS unsigned char* lds, const Gemm g, const StaticOrder& S, const Epi& E, const int tid) {
;     ...
;         const bool has_next = S.next(ui + 1, nxt);
;         const char* nA = has_next ? PG8_APTR(nxt) : cA; const char* nB = has_next ? PG8_BPTR(nxt) : cB;
;         for (int t = 0; t < nt; t += 2) {
;             const bool last = (t == nt - 2);
;             const char* a1 = cA + (size_t)(t + 1) * kstep;
;             const char* a2 = last ? nA : cA + (size_t)(t + 2) * kstep; const char* b2 = last ? nB : cB + (size_t)(t + 2) * kstep;
;             const char* a3 = a2 + kstep; const char* b3 = b2 + kstep;
;             PG8_LDB(B0, 0, 0); PG8_LDB(B1, 0, 1); PG8_SCHED; PG8_LDA(At, 0, 0); PG8_STAGE(PG8_SA(1, 1), a1 + hsA, voffA);
;             PG8_WAIT_V(8); PG8_WAIT_L(0); PG8_BAR; PG8_MMA(0, 0, At, B0); PG8_MMA(0, 1, At, B1); PG8_BAR; PG8_SCHED;
;     ...
;         for (int a = 0; a < 2; ++a)
; #pragma unroll
;             for (int b = 0; b < 2; ++b)
; #pragma unroll
;                 for (int m = 0; m < 4; ++m)
; #pragma unroll
;                     for (int n = 0; n < 2; ++n) acc[a][b][m][n] = (f32x4){0.f, 0.f, 0.f, 0.f};
.LBB0_1003:
	s_ashr_i32 s13, s12, 31
	s_lshl_b64 s[14:15], s[12:13], 20
	s_add_u32 s14, s58, s14
	s_addc_u32 s15, s59, s15
	s_and_b64 s[16:17], s[38:39], exec
	s_cselect_b32 s13, s15, s19
	s_cselect_b32 s49, s14, s18
	s_ashr_i32 s11, s10, 31
	s_lshl_b64 s[16:17], s[10:11], 20
	s_add_u32 s16, s36, s16
	s_addc_u32 s17, s37, s17
	s_and_b64 s[24:25], s[38:39], exec
	s_cselect_b32 s11, s17, s1
	s_cselect_b32 s52, s16, s0
	s_add_u32 s18, s18, 0x80080
	s_addc_u32 s19, s19, 0
	s_add_u32 s53, s0, 0x100
	v_mov_b32_e32 v0, 0
	s_addc_u32 s56, s1, 0
	s_mov_b32 s57, -2
	v_mov_b32_e32 v1, v0
	v_mov_b32_e32 v2, v0
	v_mov_b32_e32 v3, v0
	v_mov_b32_e32 v8, v0
	v_mov_b32_e32 v9, v0
	v_mov_b32_e32 v10, v0
	v_mov_b32_e32 v11, v0
	v_mov_b32_e32 v16, v0
	v_mov_b32_e32 v17, v0
	v_mov_b32_e32 v18, v0
	v_mov_b32_e32 v19, v0
	v_mov_b32_e32 v24, v0
	v_mov_b32_e32 v25, v0
	v_mov_b32_e32 v26, v0
	v_mov_b32_e32 v27, v0
	v_mov_b32_e32 v32, v0
	v_mov_b32_e32 v33, v0
	v_mov_b32_e32 v34, v0
	v_mov_b32_e32 v35, v0
	v_mov_b32_e32 v40, v0
	v_mov_b32_e32 v41, v0
	v_mov_b32_e32 v42, v0
	v_mov_b32_e32 v43, v0
	v_mov_b32_e32 v48, v0
	v_mov_b32_e32 v49, v0
	v_mov_b32_e32 v50, v0
	v_mov_b32_e32 v51, v0
	v_mov_b32_e32 v56, v0
	v_mov_b32_e32 v57, v0
	v_mov_b32_e32 v58, v0
	v_mov_b32_e32 v59, v0
	v_mov_b32_e32 v4, v0
	v_mov_b32_e32 v5, v0
	v_mov_b32_e32 v6, v0
	v_mov_b32_e32 v7, v0
	v_mov_b32_e32 v12, v0
	v_mov_b32_e32 v13, v0
	v_mov_b32_e32 v14, v0
	v_mov_b32_e32 v15, v0
	v_mov_b32_e32 v20, v0
	v_mov_b32_e32 v21, v0
	v_mov_b32_e32 v22, v0
	v_mov_b32_e32 v23, v0
	v_mov_b32_e32 v28, v0
	v_mov_b32_e32 v29, v0
	v_mov_b32_e32 v30, v0
	v_mov_b32_e32 v31, v0
	v_mov_b32_e32 v36, v0
	v_mov_b32_e32 v37, v0
	v_mov_b32_e32 v38, v0
	v_mov_b32_e32 v39, v0
	v_mov_b32_e32 v44, v0
	v_mov_b32_e32 v45, v0
	v_mov_b32_e32 v46, v0
	v_mov_b32_e32 v47, v0
	v_mov_b32_e32 v52, v0
	v_mov_b32_e32 v53, v0
	v_mov_b32_e32 v54, v0
	v_mov_b32_e32 v55, v0
	v_mov_b32_e32 v60, v0
	v_mov_b32_e32 v61, v0
	v_mov_b32_e32 v62, v0
	v_mov_b32_e32 v63, v0
	v_mov_b32_e32 v64, v0
	v_mov_b32_e32 v65, v0
	v_mov_b32_e32 v66, v0
	v_mov_b32_e32 v67, v0
	v_mov_b32_e32 v72, v0
	v_mov_b32_e32 v73, v0
	v_mov_b32_e32 v74, v0
	v_mov_b32_e32 v75, v0
	v_mov_b32_e32 v80, v0
	v_mov_b32_e32 v81, v0
	v_mov_b32_e32 v82, v0
	v_mov_b32_e32 v83, v0
	v_mov_b32_e32 v88, v0
	v_mov_b32_e32 v89, v0
	v_mov_b32_e32 v90, v0
	v_mov_b32_e32 v91, v0
	v_mov_b32_e32 v96, v0
	v_mov_b32_e32 v97, v0
	v_mov_b32_e32 v98, v0
	v_mov_b32_e32 v99, v0
	v_mov_b32_e32 v104, v0
	v_mov_b32_e32 v105, v0
	v_mov_b32_e32 v106, v0
	v_mov_b32_e32 v107, v0
	v_mov_b32_e32 v112, v0
	v_mov_b32_e32 v113, v0
	v_mov_b32_e32 v114, v0
	v_mov_b32_e32 v115, v0
	v_mov_b32_e32 v120, v0
	v_mov_b32_e32 v121, v0
	v_mov_b32_e32 v122, v0
	v_mov_b32_e32 v123, v0
	v_mov_b32_e32 v68, v0
	v_mov_b32_e32 v69, v0
	v_mov_b32_e32 v70, v0
	v_mov_b32_e32 v71, v0
	v_mov_b32_e32 v76, v0
	v_mov_b32_e32 v77, v0
	v_mov_b32_e32 v78, v0
	v_mov_b32_e32 v79, v0
	v_mov_b32_e32 v84, v0
	v_mov_b32_e32 v85, v0
	v_mov_b32_e32 v86, v0
	v_mov_b32_e32 v87, v0
	v_mov_b32_e32 v92, v0
	v_mov_b32_e32 v93, v0
	v_mov_b32_e32 v94, v0
	v_mov_b32_e32 v95, v0
	v_mov_b32_e32 v100, v0
	v_mov_b32_e32 v101, v0
	v_mov_b32_e32 v102, v0
	v_mov_b32_e32 v103, v0
	v_mov_b32_e32 v108, v0
	v_mov_b32_e32 v109, v0
	v_mov_b32_e32 v110, v0
	v_mov_b32_e32 v111, v0
	v_mov_b32_e32 v116, v0
	v_mov_b32_e32 v117, v0
	v_mov_b32_e32 v118, v0
	v_mov_b32_e32 v119, v0
	v_mov_b32_e32 v124, v0
	v_mov_b32_e32 v125, v0
	v_mov_b32_e32 v126, v0
	v_mov_b32_e32 v127, v0
	s_cmp_lg_u64 s[8:9], 0
	s_cbranch_scc1 .Lgprio_f
	s_setprio 1
.Lgprio_f:
.LBB0_1004:
	s_add_u32 s0, s18, 0xfff80080
	s_addc_u32 s1, s19, -1
	s_add_i32 s2, 0, 0x10000
	s_cmp_eq_u32 s57, 28
	s_cselect_b32 s35, s13, s1
	s_cselect_b32 s34, s49, s0
	s_cselect_b32 s1, s11, s56
	s_cselect_b32 s0, s52, s53
	s_add_i32 s55, 0, 0x14000
	v_add_u32_e32 v154, s2, v143
	v_add_u32_e32 v166, s55, v143
	ds_read_b128 v[138:141], v154
	ds_read_b128 v[146:149], v154 offset:1024
	ds_read_b128 v[150:153], v154 offset:2048
	ds_read_b128 v[154:157], v154 offset:3072
	ds_read_b128 v[158:161], v166
	ds_read_b128 v[162:165], v166 offset:1024
	ds_read_b128 v[184:187], v166 offset:2048
	ds_read_b128 v[188:191], v166 offset:3072
	v_lshl_add_u64 v[166:167], s[18:19], 0, v[134:135]
	s_add_i32 m0, s40, 0xc000
	ds_read_b128 v[192:195], v145
	ds_read_b128 v[196:199], v145 offset:1024
	ds_read_b128 v[200:203], v145 offset:2048
	ds_read_b128 v[204:207], v145 offset:3072
	ds_read_b128 v[208:211], v145 offset:4096
	ds_read_b128 v[230:233], v145 offset:5120
	ds_read_b128 v[234:237], v145 offset:6144
	ds_read_b128 v[238:241], v145 offset:7168
	global_load_lds_dwordx4 v[166:167], off
	v_lshl_add_u64 v[166:167], s[18:19], 0, v[136:137]
	s_add_i32 m0, s40, 0xe000
	s_nop 0
	global_load_lds_dwordx4 v[166:167], off
	s_waitcnt vmcnt(8)
	s_waitcnt lgkmcnt(0)
	s_barrier
; #define PG8_STAGE(bufoff, gbase, voff) do { _Pragma("unroll") for (int _i = 0; _i < 2; ++_i) \
;         __builtin_amdgcn_global_load_lds((const unsigned*)((const char*)(gbase) + (voff)[_i]), (LAS unsigned*)(lds + (bufoff) + ldsw + _i * 8192), 16, 0, 0); } while (0)
; #define PG8_LDA(dst, b, h) do { _Pragma("unroll") for (int m = 0; m < 4; ++m) _Pragma("unroll") for (int k = 0; k < 2; ++k) dst[m][k] = *(const LAS bf16x8*)(lds + PG8_SA(b, h) + aoff + m * 2048 + k * 1024); } while (0)
; #define PG8_MMA(ai, bj, At, Bt) do { __builtin_amdgcn_s_setprio(1); _Pragma("unroll") for (int m = 0; m < 4; ++m) _Pragma("unroll") for (int n = 0; n < 2; ++n) _Pragma("unroll") for (int k = 0; k < 2; ++k) \
;         acc[ai][bj][m][n] = __builtin_amdgcn_mfma_f32_16x16x32_bf16(Bt[n][k], At[m][k], acc[ai][bj][m][n], 0, 0, 0); __builtin_amdgcn_s_setprio(0); } while (0)
; #define PG8_WAIT_V(n) asm volatile("s_waitcnt vmcnt(" #n ")" ::: "memory")
; #define PG8_WAIT_L(n) asm volatile("s_waitcnt lgkmcnt(" #n ")" ::: "memory")
; #define PG8_BAR __builtin_amdgcn_s_barrier()
; #define PG8_SCHED __builtin_amdgcn_sched_barrier(0)
; template <class Epi>
; __device__ __forceinline__ void gemm_phase(LAS unsigned char* lds, const Gemm g, const StaticOrder& S, const Epi& E, const int tid) {
;     ...
;             PG8_WAIT_V(8); PG8_WAIT_L(0); PG8_BAR; PG8_MMA(0, 0, At, B0); PG8_MMA(0, 1, At, B1); PG8_BAR; PG8_SCHED;
;             PG8_LDA(At, 0, 1); PG8_STAGE(PG8_SB(0, 0), b2, voffB); PG8_STAGE(PG8_SB(0, 1), b2 + hsB, voffB); PG8_STAGE(PG8_SA(0, 0), a2, voffA);
;             PG8_WAIT_V(8); PG8_WAIT_L(0); PG8_BAR; PG8_MMA(1, 0, At, B0); PG8_MMA(1, 1, At, B1); PG8_BAR; PG8_SCHED;
	s_waitcnt lgkmcnt(0)
	v_mfma_f32_16x16x32_bf16 v[124:127], v[138:141], v[192:195], v[124:127]
	v_mfma_f32_16x16x32_bf16 v[116:119], v[150:153], v[192:195], v[116:119]
	v_mfma_f32_16x16x32_bf16 v[108:111], v[138:141], v[200:203], v[108:111]
	v_mfma_f32_16x16x32_bf16 v[100:103], v[150:153], v[200:203], v[100:103]
	v_mfma_f32_16x16x32_bf16 v[92:95], v[138:141], v[208:211], v[92:95]
	v_mfma_f32_16x16x32_bf16 v[84:87], v[150:153], v[208:211], v[84:87]
	v_mfma_f32_16x16x32_bf16 v[76:79], v[138:141], v[234:237], v[76:79]
	v_mfma_f32_16x16x32_bf16 v[68:71], v[150:153], v[234:237], v[68:71]
	v_mfma_f32_16x16x32_bf16 v[124:127], v[146:149], v[196:199], v[124:127]
	v_mfma_f32_16x16x32_bf16 v[116:119], v[154:157], v[196:199], v[116:119]
	v_mfma_f32_16x16x32_bf16 v[108:111], v[146:149], v[204:207], v[108:111]
	v_mfma_f32_16x16x32_bf16 v[100:103], v[154:157], v[204:207], v[100:103]
	v_mfma_f32_16x16x32_bf16 v[92:95], v[146:149], v[230:233], v[92:95]
	v_mfma_f32_16x16x32_bf16 v[84:87], v[154:157], v[230:233], v[84:87]
	v_mfma_f32_16x16x32_bf16 v[76:79], v[146:149], v[238:241], v[76:79]
	v_mfma_f32_16x16x32_bf16 v[68:71], v[154:157], v[238:241], v[68:71]
	v_mfma_f32_16x16x32_bf16 v[120:123], v[158:161], v[192:195], v[120:123]
	v_mfma_f32_16x16x32_bf16 v[112:115], v[184:187], v[192:195], v[112:115]
	v_mfma_f32_16x16x32_bf16 v[104:107], v[158:161], v[200:203], v[104:107]
	v_mfma_f32_16x16x32_bf16 v[96:99], v[184:187], v[200:203], v[96:99]
	v_mfma_f32_16x16x32_bf16 v[88:91], v[158:161], v[208:211], v[88:91]
	v_mfma_f32_16x16x32_bf16 v[80:83], v[184:187], v[208:211], v[80:83]
	v_mfma_f32_16x16x32_bf16 v[72:75], v[158:161], v[234:237], v[72:75]
	v_mfma_f32_16x16x32_bf16 v[64:67], v[184:187], v[234:237], v[64:67]
	v_mfma_f32_16x16x32_bf16 v[120:123], v[162:165], v[196:199], v[120:123]
	v_mfma_f32_16x16x32_bf16 v[112:115], v[188:191], v[196:199], v[112:115]
	v_mfma_f32_16x16x32_bf16 v[104:107], v[162:165], v[204:207], v[104:107]
	v_mfma_f32_16x16x32_bf16 v[96:99], v[188:191], v[204:207], v[96:99]
	v_mfma_f32_16x16x32_bf16 v[88:91], v[162:165], v[230:233], v[88:91]
	v_mfma_f32_16x16x32_bf16 v[80:83], v[188:191], v[230:233], v[80:83]
	v_mfma_f32_16x16x32_bf16 v[72:75], v[162:165], v[238:241], v[72:75]
	v_mfma_f32_16x16x32_bf16 v[64:67], v[188:191], v[238:241], v[64:67]
	s_barrier
	s_add_i32 s2, s2, s27
	v_lshl_add_u64 v[166:167], s[0:1], 0, v[168:169]
	s_mov_b32 m0, s2
	ds_read_b128 v[192:195], v145 offset:16384
	ds_read_b128 v[196:199], v145 offset:17408
	ds_read_b128 v[200:203], v145 offset:18432
	ds_read_b128 v[204:207], v145 offset:19456
	ds_read_b128 v[208:211], v145 offset:20480
	ds_read_b128 v[230:233], v145 offset:21504
	ds_read_b128 v[234:237], v145 offset:22528
	ds_read_b128 v[238:241], v145 offset:23552
	global_load_lds_dwordx4 v[166:167], off
	s_add_i32 m0, s2, 0x2000
	s_add_u32 s24, s0, 0x80000
	v_lshl_add_u64 v[170:171], s[0:1], 0, v[132:133]
	s_addc_u32 s25, s1, 0
	s_add_i32 s2, s55, s27
	global_load_lds_dwordx4 v[170:171], off
	v_lshl_add_u64 v[172:173], s[24:25], 0, v[168:169]
	s_mov_b32 m0, s2
	v_lshl_add_u64 v[212:213], s[34:35], 0, v[130:131]
	global_load_lds_dwordx4 v[172:173], off
	v_lshl_add_u64 v[172:173], s[24:25], 0, v[132:133]
	s_add_i32 m0, s2, 0x2000
	s_nop 0
	global_load_lds_dwordx4 v[172:173], off
	v_lshl_add_u64 v[172:173], s[34:35], 0, v[128:129]
	s_mov_b32 m0, s40
	s_nop 0
	global_load_lds_dwordx4 v[172:173], off
	s_mov_b32 m0, s41
	s_nop 0
	global_load_lds_dwordx4 v[212:213], off
	s_waitcnt vmcnt(8)
	s_waitcnt lgkmcnt(0)
	s_barrier
	s_waitcnt lgkmcnt(0)
	v_mfma_f32_16x16x32_bf16 v[60:63], v[138:141], v[192:195], v[60:63]
	v_mfma_f32_16x16x32_bf16 v[52:55], v[150:153], v[192:195], v[52:55]
	v_mfma_f32_16x16x32_bf16 v[44:47], v[138:141], v[200:203], v[44:47]
	v_mfma_f32_16x16x32_bf16 v[36:39], v[150:153], v[200:203], v[36:39]
	v_mfma_f32_16x16x32_bf16 v[28:31], v[138:141], v[208:211], v[28:31]
	v_mfma_f32_16x16x32_bf16 v[20:23], v[150:153], v[208:211], v[20:23]
	v_mfma_f32_16x16x32_bf16 v[12:15], v[138:141], v[234:237], v[12:15]
	v_mfma_f32_16x16x32_bf16 v[4:7], v[150:153], v[234:237], v[4:7]
	v_mfma_f32_16x16x32_bf16 v[60:63], v[146:149], v[196:199], v[60:63]
	v_mfma_f32_16x16x32_bf16 v[52:55], v[154:157], v[196:199], v[52:55]
	v_mfma_f32_16x16x32_bf16 v[44:47], v[146:149], v[204:207], v[44:47]
	v_mfma_f32_16x16x32_bf16 v[36:39], v[154:157], v[204:207], v[36:39]
	v_mfma_f32_16x16x32_bf16 v[28:31], v[146:149], v[230:233], v[28:31]
	v_mfma_f32_16x16x32_bf16 v[20:23], v[154:157], v[230:233], v[20:23]
	v_mfma_f32_16x16x32_bf16 v[12:15], v[146:149], v[238:241], v[12:15]
	v_mfma_f32_16x16x32_bf16 v[4:7], v[154:157], v[238:241], v[4:7]
	v_mfma_f32_16x16x32_bf16 v[56:59], v[158:161], v[192:195], v[56:59]
	v_mfma_f32_16x16x32_bf16 v[48:51], v[184:187], v[192:195], v[48:51]
	v_mfma_f32_16x16x32_bf16 v[40:43], v[158:161], v[200:203], v[40:43]
	v_mfma_f32_16x16x32_bf16 v[32:35], v[184:187], v[200:203], v[32:35]
	v_mfma_f32_16x16x32_bf16 v[24:27], v[158:161], v[208:211], v[24:27]
	v_mfma_f32_16x16x32_bf16 v[16:19], v[184:187], v[208:211], v[16:19]
	v_mfma_f32_16x16x32_bf16 v[8:11], v[158:161], v[234:237], v[8:11]
	v_mfma_f32_16x16x32_bf16 v[0:3], v[184:187], v[234:237], v[0:3]
	v_mfma_f32_16x16x32_bf16 v[56:59], v[162:165], v[196:199], v[56:59]
	v_mfma_f32_16x16x32_bf16 v[48:51], v[188:191], v[196:199], v[48:51]
	v_mfma_f32_16x16x32_bf16 v[40:43], v[162:165], v[204:207], v[40:43]
	v_mfma_f32_16x16x32_bf16 v[32:35], v[188:191], v[204:207], v[32:35]
	v_mfma_f32_16x16x32_bf16 v[24:27], v[162:165], v[230:233], v[24:27]
	v_mfma_f32_16x16x32_bf16 v[16:19], v[188:191], v[230:233], v[16:19]
	v_mfma_f32_16x16x32_bf16 v[8:11], v[162:165], v[238:241], v[8:11]
	v_mfma_f32_16x16x32_bf16 v[0:3], v[188:191], v[238:241], v[0:3]
	s_barrier
; #define PG8_STAGE(bufoff, gbase, voff) do { _Pragma("unroll") for (int _i = 0; _i < 2; ++_i) \
;         __builtin_amdgcn_global_load_lds((const unsigned*)((const char*)(gbase) + (voff)[_i]), (LAS unsigned*)(lds + (bufoff) + ldsw + _i * 8192), 16, 0, 0); } while (0)
; #define PG8_LDA(dst, b, h) do { _Pragma("unroll") for (int m = 0; m < 4; ++m) _Pragma("unroll") for (int k = 0; k < 2; ++k) dst[m][k] = *(const LAS bf16x8*)(lds + PG8_SA(b, h) + aoff + m * 2048 + k * 1024); } while (0)
; #define PG8_LDB(dst, b, h) do { _Pragma("unroll") for (int n = 0; n < 2; ++n) _Pragma("unroll") for (int k = 0; k < 2; ++k) dst[n][k] = *(const LAS bf16x8*)(lds + PG8_SB(b, h) + boff + n * 2048 + k * 1024); } while (0)
; #define PG8_MMA(ai, bj, At, Bt) do { __builtin_amdgcn_s_setprio(1); _Pragma("unroll") for (int m = 0; m < 4; ++m) _Pragma("unroll") for (int n = 0; n < 2; ++n) _Pragma("unroll") for (int k = 0; k < 2; ++k) \
;         acc[ai][bj][m][n] = __builtin_amdgcn_mfma_f32_16x16x32_bf16(Bt[n][k], At[m][k], acc[ai][bj][m][n], 0, 0, 0); __builtin_amdgcn_s_setprio(0); } while (0)
; #define PG8_WAIT_V(n) asm volatile("s_waitcnt vmcnt(" #n ")" ::: "memory")
; #define PG8_WAIT_L(n) asm volatile("s_waitcnt lgkmcnt(" #n ")" ::: "memory")
; #define PG8_BAR __builtin_amdgcn_s_barrier()
; #define PG8_SCHED __builtin_amdgcn_sched_barrier(0)
; template <class Epi>
; __device__ __forceinline__ void gemm_phase(LAS unsigned char* lds, const Gemm g, const StaticOrder& S, const Epi& E, const int tid) {
;     ...
;             PG8_LDB(B0, 1, 0); PG8_LDB(B1, 1, 1); PG8_SCHED; PG8_LDA(At, 1, 0); PG8_STAGE(PG8_SA(0, 1), a2 + hsA, voffA);
;             PG8_WAIT_V(8); PG8_WAIT_L(0); PG8_BAR; PG8_MMA(0, 0, At, B0); PG8_MMA(0, 1, At, B1); PG8_BAR; PG8_SCHED;
;             PG8_LDA(At, 1, 1); PG8_STAGE(PG8_SB(1, 0), b3, voffB); PG8_STAGE(PG8_SB(1, 1), b3 + hsB, voffB); PG8_STAGE(PG8_SA(1, 0), a3, voffA);
;             PG8_WAIT_V(8); PG8_WAIT_L(0); PG8_BAR; PG8_MMA(1, 0, At, B0); PG8_MMA(1, 1, At, B1); PG8_BAR; PG8_SCHED;
	s_add_i32 s2, 0, 0x18000
	s_add_i32 s55, 0, 0x1c000
	v_add_u32_e32 v154, s2, v143
	v_add_u32_e32 v188, s55, v143
	ds_read_b128 v[138:141], v154
	ds_read_b128 v[146:149], v154 offset:1024
	ds_read_b128 v[150:153], v154 offset:2048
	ds_read_b128 v[154:157], v154 offset:3072
	ds_read_b128 v[158:161], v188
	ds_read_b128 v[162:165], v188 offset:1024
	ds_read_b128 v[184:187], v188 offset:2048
	ds_read_b128 v[188:191], v188 offset:3072
	s_add_u32 s24, s34, 0x80000
	s_addc_u32 s25, s35, 0
	s_mov_b32 m0, s42
	v_lshl_add_u64 v[242:243], s[24:25], 0, v[128:129]
	ds_read_b128 v[192:195], v145 offset:32768
	ds_read_b128 v[196:199], v145 offset:33792
	ds_read_b128 v[200:203], v145 offset:34816
	ds_read_b128 v[204:207], v145 offset:35840
	ds_read_b128 v[208:211], v145 offset:36864
	ds_read_b128 v[230:233], v145 offset:37888
	ds_read_b128 v[234:237], v145 offset:38912
	ds_read_b128 v[238:241], v145 offset:39936
	global_load_lds_dwordx4 v[242:243], off
	v_lshl_add_u64 v[242:243], s[24:25], 0, v[130:131]
	s_mov_b32 m0, s43
	s_nop 0
	global_load_lds_dwordx4 v[242:243], off
	s_waitcnt vmcnt(8)
	s_waitcnt lgkmcnt(0)
	s_barrier
	s_waitcnt lgkmcnt(0)
	v_mfma_f32_16x16x32_bf16 v[124:127], v[138:141], v[192:195], v[124:127]
	v_mfma_f32_16x16x32_bf16 v[116:119], v[150:153], v[192:195], v[116:119]
	v_mfma_f32_16x16x32_bf16 v[108:111], v[138:141], v[200:203], v[108:111]
	v_mfma_f32_16x16x32_bf16 v[100:103], v[150:153], v[200:203], v[100:103]
	v_mfma_f32_16x16x32_bf16 v[92:95], v[138:141], v[208:211], v[92:95]
	v_mfma_f32_16x16x32_bf16 v[84:87], v[150:153], v[208:211], v[84:87]
	v_mfma_f32_16x16x32_bf16 v[76:79], v[138:141], v[234:237], v[76:79]
	v_mfma_f32_16x16x32_bf16 v[68:71], v[150:153], v[234:237], v[68:71]
	v_mfma_f32_16x16x32_bf16 v[124:127], v[146:149], v[196:199], v[124:127]
	v_mfma_f32_16x16x32_bf16 v[116:119], v[154:157], v[196:199], v[116:119]
	v_mfma_f32_16x16x32_bf16 v[108:111], v[146:149], v[204:207], v[108:111]
	v_mfma_f32_16x16x32_bf16 v[100:103], v[154:157], v[204:207], v[100:103]
	v_mfma_f32_16x16x32_bf16 v[92:95], v[146:149], v[230:233], v[92:95]
	v_mfma_f32_16x16x32_bf16 v[84:87], v[154:157], v[230:233], v[84:87]
	v_mfma_f32_16x16x32_bf16 v[76:79], v[146:149], v[238:241], v[76:79]
	v_mfma_f32_16x16x32_bf16 v[68:71], v[154:157], v[238:241], v[68:71]
	v_mfma_f32_16x16x32_bf16 v[120:123], v[158:161], v[192:195], v[120:123]
	v_mfma_f32_16x16x32_bf16 v[112:115], v[184:187], v[192:195], v[112:115]
	v_mfma_f32_16x16x32_bf16 v[104:107], v[158:161], v[200:203], v[104:107]
	v_mfma_f32_16x16x32_bf16 v[96:99], v[184:187], v[200:203], v[96:99]
	v_mfma_f32_16x16x32_bf16 v[88:91], v[158:161], v[208:211], v[88:91]
	v_mfma_f32_16x16x32_bf16 v[80:83], v[184:187], v[208:211], v[80:83]
	v_mfma_f32_16x16x32_bf16 v[72:75], v[158:161], v[234:237], v[72:75]
	v_mfma_f32_16x16x32_bf16 v[64:67], v[184:187], v[234:237], v[64:67]
	v_mfma_f32_16x16x32_bf16 v[120:123], v[162:165], v[196:199], v[120:123]
	v_mfma_f32_16x16x32_bf16 v[112:115], v[188:191], v[196:199], v[112:115]
	v_mfma_f32_16x16x32_bf16 v[104:107], v[162:165], v[204:207], v[104:107]
	v_mfma_f32_16x16x32_bf16 v[96:99], v[188:191], v[204:207], v[96:99]
	v_mfma_f32_16x16x32_bf16 v[88:91], v[162:165], v[230:233], v[88:91]
	v_mfma_f32_16x16x32_bf16 v[80:83], v[188:191], v[230:233], v[80:83]
	v_mfma_f32_16x16x32_bf16 v[72:75], v[162:165], v[238:241], v[72:75]
	v_mfma_f32_16x16x32_bf16 v[64:67], v[188:191], v[238:241], v[64:67]
	s_barrier
	s_add_i32 s2, s2, s27
	v_lshl_add_u64 v[166:167], v[166:167], 0, s[28:29]
	s_mov_b32 m0, s2
	ds_read_b128 v[192:195], v145 offset:49152
	ds_read_b128 v[196:199], v145 offset:50176
	ds_read_b128 v[200:203], v145 offset:51200
	ds_read_b128 v[204:207], v145 offset:52224
	ds_read_b128 v[208:211], v145 offset:53248
	ds_read_b128 v[230:233], v145 offset:54272
	ds_read_b128 v[234:237], v145 offset:55296
	ds_read_b128 v[238:241], v145 offset:56320
	global_load_lds_dwordx4 v[166:167], off
	s_add_i32 m0, s2, 0x2000
	s_add_u32 s0, s0, 0x80080
	v_lshl_add_u64 v[166:167], v[170:171], 0, s[28:29]
	s_addc_u32 s1, s1, 0
	s_add_i32 s2, s55, s27
	global_load_lds_dwordx4 v[166:167], off
	v_lshl_add_u64 v[166:167], s[0:1], 0, v[168:169]
	s_mov_b32 m0, s2
	s_nop 0
	global_load_lds_dwordx4 v[166:167], off
	v_lshl_add_u64 v[166:167], s[0:1], 0, v[132:133]
	s_add_i32 m0, s2, 0x2000
	s_nop 0
	global_load_lds_dwordx4 v[166:167], off
	v_lshl_add_u64 v[166:167], v[172:173], 0, s[28:29]
	s_mov_b32 m0, s44
	s_nop 0
	global_load_lds_dwordx4 v[166:167], off
	v_lshl_add_u64 v[166:167], v[212:213], 0, s[28:29]
	s_mov_b32 m0, s45
	s_nop 0
	global_load_lds_dwordx4 v[166:167], off
	s_waitcnt vmcnt(8)
	s_waitcnt lgkmcnt(0)
	s_barrier
; __device__ __forceinline__ unsigned cvt_pk_bf16(float lo, float hi) { unsigned r; asm volatile("v_cvt_pk_bf16_f32 %0, %1, %2" : "=v"(r) : "v"(lo), "v"(hi)); return r; }
; #define PG8_MMA(ai, bj, At, Bt) do { __builtin_amdgcn_s_setprio(1); _Pragma("unroll") for (int m = 0; m < 4; ++m) _Pragma("unroll") for (int n = 0; n < 2; ++n) _Pragma("unroll") for (int k = 0; k < 2; ++k) \
;         acc[ai][bj][m][n] = __builtin_amdgcn_mfma_f32_16x16x32_bf16(Bt[n][k], At[m][k], acc[ai][bj][m][n], 0, 0, 0); __builtin_amdgcn_s_setprio(0); } while (0)
; #define PG8_WAIT_V(n) asm volatile("s_waitcnt vmcnt(" #n ")" ::: "memory")
; #define PG8_WAIT_L(n) asm volatile("s_waitcnt lgkmcnt(" #n ")" ::: "memory")
; #define PG8_BAR __builtin_amdgcn_s_barrier()
; #define PG8_SCHED __builtin_amdgcn_sched_barrier(0)
; template <class Epi>
; __device__ __forceinline__ void gemm_phase(LAS unsigned char* lds, const Gemm g, const StaticOrder& S, const Epi& E, const int tid) {
;     ...
;             PG8_WAIT_V(8); PG8_WAIT_L(0); PG8_BAR; PG8_MMA(1, 0, At, B0); PG8_MMA(1, 1, At, B1); PG8_BAR; PG8_SCHED;
;         }
;         if (wr == 0) PG8_BAR;
;         E(acc, cur, wr, wc, fr, fq);
;     __device__ __forceinline__ void operator()(f32x4 (&acc)[2][2][4][2], const Unit& u, int wr, int wc, int fr, int fq) const {
;         const int row0 = u.pm * BM + wr * 64 + fr, col0 = u.pn * 128 + wc * 32 + 8 * fq;
; #pragma unroll
;         for (int ai = 0; ai < 2; ++ai)
; #pragma unroll
;             for (int m = 0; m < 4; ++m) {
;                 bf16* rowp = O + (size_t)(row0 + ai * HALF + m * 16) * FF + col0;
;                 const f32x4 g0 = acc[ai][0][m][0], g1 = acc[ai][0][m][1], u0 = acc[ai][1][m][0], u1 = acc[ai][1][m][1];
;                 u32x4 w;
;                 const f32x4 a0 = swiglu4(g0, u0), a1 = swiglu4(g1, u1);
;                 w.x = cvt_pk_bf16(a0[0], a0[1]); w.y = cvt_pk_bf16(a0[2], a0[3]); w.z = cvt_pk_bf16(a1[0], a1[1]); w.w = cvt_pk_bf16(a1[2], a1[3]);
;                 __builtin_nontemporal_store(w, (u32x4*)rowp);
;             }
	s_waitcnt lgkmcnt(0)
	v_mfma_f32_16x16x32_bf16 v[60:63], v[138:141], v[192:195], v[60:63]
	v_mfma_f32_16x16x32_bf16 v[52:55], v[150:153], v[192:195], v[52:55]
	v_mfma_f32_16x16x32_bf16 v[44:47], v[138:141], v[200:203], v[44:47]
	v_mfma_f32_16x16x32_bf16 v[36:39], v[150:153], v[200:203], v[36:39]
	v_mfma_f32_16x16x32_bf16 v[28:31], v[138:141], v[208:211], v[28:31]
	v_mfma_f32_16x16x32_bf16 v[20:23], v[150:153], v[208:211], v[20:23]
	v_mfma_f32_16x16x32_bf16 v[12:15], v[138:141], v[234:237], v[12:15]
	v_mfma_f32_16x16x32_bf16 v[4:7], v[150:153], v[234:237], v[4:7]
	v_mfma_f32_16x16x32_bf16 v[60:63], v[146:149], v[196:199], v[60:63]
	v_mfma_f32_16x16x32_bf16 v[52:55], v[154:157], v[196:199], v[52:55]
	v_mfma_f32_16x16x32_bf16 v[44:47], v[146:149], v[204:207], v[44:47]
	v_mfma_f32_16x16x32_bf16 v[36:39], v[154:157], v[204:207], v[36:39]
	v_mfma_f32_16x16x32_bf16 v[28:31], v[146:149], v[230:233], v[28:31]
	v_mfma_f32_16x16x32_bf16 v[20:23], v[154:157], v[230:233], v[20:23]
	v_mfma_f32_16x16x32_bf16 v[12:15], v[146:149], v[238:241], v[12:15]
	v_mfma_f32_16x16x32_bf16 v[4:7], v[154:157], v[238:241], v[4:7]
	v_mfma_f32_16x16x32_bf16 v[56:59], v[158:161], v[192:195], v[56:59]
	v_mfma_f32_16x16x32_bf16 v[48:51], v[184:187], v[192:195], v[48:51]
	v_mfma_f32_16x16x32_bf16 v[40:43], v[158:161], v[200:203], v[40:43]
	v_mfma_f32_16x16x32_bf16 v[32:35], v[184:187], v[200:203], v[32:35]
	v_mfma_f32_16x16x32_bf16 v[24:27], v[158:161], v[208:211], v[24:27]
	v_mfma_f32_16x16x32_bf16 v[16:19], v[184:187], v[208:211], v[16:19]
	v_mfma_f32_16x16x32_bf16 v[8:11], v[158:161], v[234:237], v[8:11]
	v_mfma_f32_16x16x32_bf16 v[0:3], v[184:187], v[234:237], v[0:3]
	v_mfma_f32_16x16x32_bf16 v[56:59], v[162:165], v[196:199], v[56:59]
	v_mfma_f32_16x16x32_bf16 v[48:51], v[188:191], v[196:199], v[48:51]
	v_mfma_f32_16x16x32_bf16 v[40:43], v[162:165], v[204:207], v[40:43]
	v_mfma_f32_16x16x32_bf16 v[32:35], v[188:191], v[204:207], v[32:35]
	v_mfma_f32_16x16x32_bf16 v[24:27], v[162:165], v[230:233], v[24:27]
	v_mfma_f32_16x16x32_bf16 v[16:19], v[188:191], v[230:233], v[16:19]
	v_mfma_f32_16x16x32_bf16 v[8:11], v[162:165], v[238:241], v[8:11]
	v_mfma_f32_16x16x32_bf16 v[0:3], v[188:191], v[238:241], v[0:3]
	s_barrier
	s_add_i32 s57, s57, 2
	s_add_u32 s18, s18, 0x100
	s_addc_u32 s19, s19, 0
	s_add_u32 s53, s53, 0x100
	s_addc_u32 s56, s56, 0
	s_cmp_gt_u32 s57, 29
	s_cbranch_scc0 .LBB0_1004
	s_and_b64 vcc, exec, s[8:9]
	s_cbranch_vccz .LBB0_1007
	s_barrier
.LBB0_1007:
	s_setprio 0
	v_pk_mul_f32 v[150:151], v[126:127], s[74:75] op_sel_hi:[1,0]
	v_pk_mul_f32 v[152:153], v[124:125], s[74:75] op_sel_hi:[1,0]
	v_pk_mul_f32 v[122:123], v[126:127], v[122:123]
	v_pk_mul_f32 v[120:121], v[124:125], v[120:121]
	v_pk_mul_f32 v[124:125], v[118:119], s[74:75] op_sel_hi:[1,0]
	v_pk_mul_f32 v[126:127], v[116:117], s[74:75] op_sel_hi:[1,0]
	v_exp_f32_e32 v124, v124
	v_exp_f32_e32 v126, v126
	v_exp_f32_e32 v125, v125
	v_exp_f32_e32 v127, v127
	v_exp_f32_e32 v152, v152
	v_exp_f32_e32 v150, v150
	v_exp_f32_e32 v151, v151
	v_exp_f32_e32 v153, v153
	v_pk_add_f32 v[124:125], v[124:125], 1.0 op_sel_hi:[1,0]
	v_pk_add_f32 v[126:127], v[126:127], 1.0 op_sel_hi:[1,0]
	v_pk_add_f32 v[150:151], v[150:151], 1.0 op_sel_hi:[1,0]
	v_pk_add_f32 v[152:153], v[152:153], 1.0 op_sel_hi:[1,0]
	v_rcp_f32_e32 v126, v126
	v_rcp_f32_e32 v124, v124
	v_rcp_f32_e32 v125, v125
	v_rcp_f32_e32 v127, v127
	v_readlane_b32 s0, v254, 23
	v_rcp_f32_e32 v152, v152
	v_rcp_f32_e32 v153, v153
	v_rcp_f32_e32 v150, v150
	v_rcp_f32_e32 v151, v151
	v_lshl_or_b32 v140, s47, 7, v144
	v_readlane_b32 s1, v254, 24
	v_lshl_add_u32 v146, s48, 8, v142
	v_ashrrev_i32_e32 v141, 31, v140
	v_mov_b64_e32 v[138:139], s[0:1]
	s_movk_i32 s2, 0x2c00
	v_pk_mul_f32 v[114:115], v[118:119], v[114:115]
	v_pk_mul_f32 v[112:113], v[116:117], v[112:113]
	v_mad_i64_i32 v[148:149], s[0:1], v146, s2, v[138:139]
	v_lshlrev_b64 v[140:141], 1, v[140:141]
	v_pk_mul_f32 v[116:117], v[124:125], v[114:115]
	v_pk_mul_f32 v[114:115], v[126:127], v[112:113]
	v_lshl_add_u64 v[148:149], v[148:149], 0, v[140:141]
	v_pk_mul_f32 v[122:123], v[150:151], v[122:123]
	v_pk_mul_f32 v[120:121], v[152:153], v[120:121]
	v_pk_mul_f32 v[106:107], v[110:111], v[106:107]
	v_cvt_pk_bf16_f32 v112, v120, v121
	v_cvt_pk_bf16_f32 v113, v122, v123
	v_cvt_pk_bf16_f32 v114, v114, v115
	v_cvt_pk_bf16_f32 v115, v116, v117
	global_store_dwordx4 v[148:149], v[112:115], off nt
	v_pk_mul_f32 v[104:105], v[108:109], v[104:105]
	v_or_b32_e32 v116, 16, v146
	v_pk_mul_f32 v[112:113], v[110:111], s[74:75] op_sel_hi:[1,0]
	v_pk_mul_f32 v[114:115], v[108:109], s[74:75] op_sel_hi:[1,0]
	v_pk_mul_f32 v[108:109], v[102:103], s[74:75] op_sel_hi:[1,0]
	v_pk_mul_f32 v[110:111], v[100:101], s[74:75] op_sel_hi:[1,0]
	v_exp_f32_e32 v108, v108
	v_exp_f32_e32 v110, v110
	v_exp_f32_e32 v109, v109
	v_exp_f32_e32 v111, v111
	v_exp_f32_e32 v114, v114
	v_exp_f32_e32 v115, v115
	v_exp_f32_e32 v112, v112
	v_exp_f32_e32 v113, v113
	v_pk_add_f32 v[108:109], v[108:109], 1.0 op_sel_hi:[1,0]
	v_pk_add_f32 v[110:111], v[110:111], 1.0 op_sel_hi:[1,0]
	v_pk_add_f32 v[114:115], v[114:115], 1.0 op_sel_hi:[1,0]
	v_pk_add_f32 v[112:113], v[112:113], 1.0 op_sel_hi:[1,0]
	v_rcp_f32_e32 v110, v110
	v_rcp_f32_e32 v108, v108
	v_rcp_f32_e32 v109, v109
	v_rcp_f32_e32 v111, v111
	v_rcp_f32_e32 v114, v114
	v_rcp_f32_e32 v115, v115
	v_rcp_f32_e32 v112, v112
	v_rcp_f32_e32 v113, v113
	v_pk_mul_f32 v[98:99], v[102:103], v[98:99]
	v_pk_mul_f32 v[96:97], v[100:101], v[96:97]
	v_mad_i64_i32 v[116:117], s[0:1], v116, s2, v[138:139]
	v_pk_mul_f32 v[100:101], v[108:109], v[98:99]
	v_pk_mul_f32 v[98:99], v[110:111], v[96:97]
	v_lshl_add_u64 v[116:117], v[116:117], 0, v[140:141]
; __device__ __forceinline__ unsigned cvt_pk_bf16(float lo, float hi) { unsigned r; asm volatile("v_cvt_pk_bf16_f32 %0, %1, %2" : "=v"(r) : "v"(lo), "v"(hi)); return r; }
;     __device__ __forceinline__ void operator()(f32x4 (&acc)[2][2][4][2], const Unit& u, int wr, int wc, int fr, int fq) const {
;         const int row0 = u.pm * BM + wr * 64 + fr, col0 = u.pn * 128 + wc * 32 + 8 * fq;
; #pragma unroll
;         for (int ai = 0; ai < 2; ++ai)
; #pragma unroll
;             for (int m = 0; m < 4; ++m) {
;                 bf16* rowp = O + (size_t)(row0 + ai * HALF + m * 16) * FF + col0;
;                 const f32x4 g0 = acc[ai][0][m][0], g1 = acc[ai][0][m][1], u0 = acc[ai][1][m][0], u1 = acc[ai][1][m][1];
;                 u32x4 w;
;                 const f32x4 a0 = swiglu4(g0, u0), a1 = swiglu4(g1, u1);
;                 w.x = cvt_pk_bf16(a0[0], a0[1]); w.y = cvt_pk_bf16(a0[2], a0[3]); w.z = cvt_pk_bf16(a1[0], a1[1]); w.w = cvt_pk_bf16(a1[2], a1[3]);
;                 __builtin_nontemporal_store(w, (u32x4*)rowp);
;             }
	v_pk_mul_f32 v[106:107], v[112:113], v[106:107]
	v_pk_mul_f32 v[104:105], v[114:115], v[104:105]
	v_pk_mul_f32 v[90:91], v[94:95], v[90:91]
	v_cvt_pk_bf16_f32 v96, v104, v105
	v_cvt_pk_bf16_f32 v97, v106, v107
	v_cvt_pk_bf16_f32 v98, v98, v99
	v_cvt_pk_bf16_f32 v99, v100, v101
	global_store_dwordx4 v[116:117], v[96:99], off nt
	v_pk_mul_f32 v[88:89], v[92:93], v[88:89]
	v_or_b32_e32 v100, 32, v146
	v_pk_mul_f32 v[96:97], v[94:95], s[74:75] op_sel_hi:[1,0]
	v_pk_mul_f32 v[98:99], v[92:93], s[74:75] op_sel_hi:[1,0]
	v_pk_mul_f32 v[92:93], v[86:87], s[74:75] op_sel_hi:[1,0]
	v_pk_mul_f32 v[94:95], v[84:85], s[74:75] op_sel_hi:[1,0]
	v_exp_f32_e32 v92, v92
	v_exp_f32_e32 v94, v94
	v_exp_f32_e32 v93, v93
	v_exp_f32_e32 v95, v95
	v_exp_f32_e32 v98, v98
	v_exp_f32_e32 v99, v99
	v_exp_f32_e32 v96, v96
	v_exp_f32_e32 v97, v97
	v_pk_add_f32 v[92:93], v[92:93], 1.0 op_sel_hi:[1,0]
	v_pk_add_f32 v[94:95], v[94:95], 1.0 op_sel_hi:[1,0]
	v_pk_add_f32 v[98:99], v[98:99], 1.0 op_sel_hi:[1,0]
	v_pk_add_f32 v[96:97], v[96:97], 1.0 op_sel_hi:[1,0]
	v_rcp_f32_e32 v94, v94
	v_rcp_f32_e32 v92, v92
	v_rcp_f32_e32 v93, v93
	v_rcp_f32_e32 v95, v95
	v_rcp_f32_e32 v98, v98
	v_rcp_f32_e32 v99, v99
	v_rcp_f32_e32 v96, v96
	v_rcp_f32_e32 v97, v97
	v_pk_mul_f32 v[82:83], v[86:87], v[82:83]
	v_pk_mul_f32 v[80:81], v[84:85], v[80:81]
	v_mad_i64_i32 v[100:101], s[0:1], v100, s2, v[138:139]
	v_pk_mul_f32 v[84:85], v[92:93], v[82:83]
	v_pk_mul_f32 v[82:83], v[94:95], v[80:81]
	v_lshl_add_u64 v[100:101], v[100:101], 0, v[140:141]
	v_pk_mul_f32 v[90:91], v[96:97], v[90:91]
	v_pk_mul_f32 v[88:89], v[98:99], v[88:89]
	v_pk_mul_f32 v[74:75], v[78:79], v[74:75]
	v_cvt_pk_bf16_f32 v80, v88, v89
	v_cvt_pk_bf16_f32 v81, v90, v91
	v_cvt_pk_bf16_f32 v82, v82, v83
	v_cvt_pk_bf16_f32 v83, v84, v85
	global_store_dwordx4 v[100:101], v[80:83], off nt
	v_pk_mul_f32 v[72:73], v[76:77], v[72:73]
	v_or_b32_e32 v84, 48, v146
	v_pk_mul_f32 v[80:81], v[78:79], s[74:75] op_sel_hi:[1,0]
	v_pk_mul_f32 v[82:83], v[76:77], s[74:75] op_sel_hi:[1,0]
	v_pk_mul_f32 v[76:77], v[70:71], s[74:75] op_sel_hi:[1,0]
	v_pk_mul_f32 v[78:79], v[68:69], s[74:75] op_sel_hi:[1,0]
	v_exp_f32_e32 v76, v76
	v_exp_f32_e32 v78, v78
	v_exp_f32_e32 v77, v77
	v_exp_f32_e32 v79, v79
	v_exp_f32_e32 v82, v82
	v_exp_f32_e32 v83, v83
	v_exp_f32_e32 v80, v80
	v_exp_f32_e32 v81, v81
	v_pk_add_f32 v[76:77], v[76:77], 1.0 op_sel_hi:[1,0]
	v_pk_add_f32 v[78:79], v[78:79], 1.0 op_sel_hi:[1,0]
	v_pk_add_f32 v[82:83], v[82:83], 1.0 op_sel_hi:[1,0]
	v_pk_add_f32 v[80:81], v[80:81], 1.0 op_sel_hi:[1,0]
	v_rcp_f32_e32 v78, v78
	v_rcp_f32_e32 v76, v76
	v_rcp_f32_e32 v77, v77
	v_rcp_f32_e32 v79, v79
	v_rcp_f32_e32 v82, v82
	v_rcp_f32_e32 v83, v83
	v_rcp_f32_e32 v80, v80
	v_rcp_f32_e32 v81, v81
	v_pk_mul_f32 v[66:67], v[70:71], v[66:67]
	v_pk_mul_f32 v[64:65], v[68:69], v[64:65]
	v_mad_i64_i32 v[84:85], s[0:1], v84, s2, v[138:139]
	v_pk_mul_f32 v[68:69], v[76:77], v[66:67]
	v_pk_mul_f32 v[66:67], v[78:79], v[64:65]
	v_lshl_add_u64 v[84:85], v[84:85], 0, v[140:141]
	v_pk_mul_f32 v[74:75], v[80:81], v[74:75]
	v_pk_mul_f32 v[72:73], v[82:83], v[72:73]
	v_pk_mul_f32 v[58:59], v[62:63], v[58:59]
	v_cvt_pk_bf16_f32 v64, v72, v73
	v_cvt_pk_bf16_f32 v65, v74, v75
	v_cvt_pk_bf16_f32 v66, v66, v67
	v_cvt_pk_bf16_f32 v67, v68, v69
	global_store_dwordx4 v[84:85], v[64:67], off nt
	v_pk_mul_f32 v[56:57], v[60:61], v[56:57]
	v_add_u32_e32 v68, 0x80, v146
	v_pk_mul_f32 v[64:65], v[62:63], s[74:75] op_sel_hi:[1,0]
	v_pk_mul_f32 v[66:67], v[60:61], s[74:75] op_sel_hi:[1,0]
	v_pk_mul_f32 v[60:61], v[54:55], s[74:75] op_sel_hi:[1,0]
	v_pk_mul_f32 v[62:63], v[52:53], s[74:75] op_sel_hi:[1,0]
	v_exp_f32_e32 v60, v60
	v_exp_f32_e32 v62, v62
	v_exp_f32_e32 v61, v61
	v_exp_f32_e32 v63, v63
	v_exp_f32_e32 v66, v66
	v_exp_f32_e32 v67, v67
	v_exp_f32_e32 v64, v64
	v_exp_f32_e32 v65, v65
	v_pk_add_f32 v[60:61], v[60:61], 1.0 op_sel_hi:[1,0]
	v_pk_add_f32 v[62:63], v[62:63], 1.0 op_sel_hi:[1,0]
	v_pk_add_f32 v[66:67], v[66:67], 1.0 op_sel_hi:[1,0]
	v_pk_add_f32 v[64:65], v[64:65], 1.0 op_sel_hi:[1,0]
	v_rcp_f32_e32 v62, v62
	v_rcp_f32_e32 v60, v60
	v_rcp_f32_e32 v61, v61
	v_rcp_f32_e32 v63, v63
	v_rcp_f32_e32 v66, v66
	v_rcp_f32_e32 v67, v67
	v_rcp_f32_e32 v64, v64
	v_rcp_f32_e32 v65, v65
	v_pk_mul_f32 v[50:51], v[54:55], v[50:51]
	v_pk_mul_f32 v[48:49], v[52:53], v[48:49]
	v_mad_i64_i32 v[68:69], s[0:1], v68, s2, v[138:139]
	v_pk_mul_f32 v[52:53], v[60:61], v[50:51]
	v_pk_mul_f32 v[50:51], v[62:63], v[48:49]
	v_lshl_add_u64 v[68:69], v[68:69], 0, v[140:141]
	v_pk_mul_f32 v[58:59], v[64:65], v[58:59]
	v_pk_mul_f32 v[56:57], v[66:67], v[56:57]
	v_pk_mul_f32 v[42:43], v[46:47], v[42:43]
	v_cvt_pk_bf16_f32 v48, v56, v57
	v_cvt_pk_bf16_f32 v49, v58, v59
	v_cvt_pk_bf16_f32 v50, v50, v51
; __device__ __forceinline__ unsigned cvt_pk_bf16(float lo, float hi) { unsigned r; asm volatile("v_cvt_pk_bf16_f32 %0, %1, %2" : "=v"(r) : "v"(lo), "v"(hi)); return r; }
; #define PG8_BAR __builtin_amdgcn_s_barrier()
; template <class Epi>
; __device__ __forceinline__ void gemm_phase(LAS unsigned char* lds, const Gemm g, const StaticOrder& S, const Epi& E, const int tid) {
;     ...
;         if (!has_next) break;
;         if (!(Epi::CHAIN && cur.n + 1 < S.NS)) {
; #pragma unroll
;         for (int a = 0; a < 2; ++a)
; #pragma unroll
;             for (int b = 0; b < 2; ++b)
; #pragma unroll
;                 for (int m = 0; m < 4; ++m)
; #pragma unroll
;                     for (int n = 0; n < 2; ++n) acc[a][b][m][n] = (f32x4){0.f, 0.f, 0.f, 0.f};
;         }
;         cur = nxt; cA = nA; cB = nB; ++ui;
;         if (wr == 1) PG8_BAR;
;     __device__ __forceinline__ void operator()(f32x4 (&acc)[2][2][4][2], const Unit& u, int wr, int wc, int fr, int fq) const {
;         const int row0 = u.pm * BM + wr * 64 + fr, col0 = u.pn * 128 + wc * 32 + 8 * fq;
; #pragma unroll
;         for (int ai = 0; ai < 2; ++ai)
; #pragma unroll
;             for (int m = 0; m < 4; ++m) {
;                 bf16* rowp = O + (size_t)(row0 + ai * HALF + m * 16) * FF + col0;
;                 const f32x4 g0 = acc[ai][0][m][0], g1 = acc[ai][0][m][1], u0 = acc[ai][1][m][0], u1 = acc[ai][1][m][1];
;                 u32x4 w;
;                 const f32x4 a0 = swiglu4(g0, u0), a1 = swiglu4(g1, u1);
;                 w.x = cvt_pk_bf16(a0[0], a0[1]); w.y = cvt_pk_bf16(a0[2], a0[3]); w.z = cvt_pk_bf16(a1[0], a1[1]); w.w = cvt_pk_bf16(a1[2], a1[3]);
;                 __builtin_nontemporal_store(w, (u32x4*)rowp);
;             }
	v_cvt_pk_bf16_f32 v51, v52, v53
	global_store_dwordx4 v[68:69], v[48:51], off nt
	v_pk_mul_f32 v[40:41], v[44:45], v[40:41]
	v_add_u32_e32 v52, 0x90, v146
	v_pk_mul_f32 v[48:49], v[46:47], s[74:75] op_sel_hi:[1,0]
	v_pk_mul_f32 v[50:51], v[44:45], s[74:75] op_sel_hi:[1,0]
	v_pk_mul_f32 v[44:45], v[38:39], s[74:75] op_sel_hi:[1,0]
	v_pk_mul_f32 v[46:47], v[36:37], s[74:75] op_sel_hi:[1,0]
	v_exp_f32_e32 v44, v44
	v_exp_f32_e32 v46, v46
	v_exp_f32_e32 v45, v45
	v_exp_f32_e32 v47, v47
	v_exp_f32_e32 v50, v50
	v_exp_f32_e32 v51, v51
	v_exp_f32_e32 v48, v48
	v_exp_f32_e32 v49, v49
	v_pk_add_f32 v[44:45], v[44:45], 1.0 op_sel_hi:[1,0]
	v_pk_add_f32 v[46:47], v[46:47], 1.0 op_sel_hi:[1,0]
	v_pk_add_f32 v[50:51], v[50:51], 1.0 op_sel_hi:[1,0]
	v_pk_add_f32 v[48:49], v[48:49], 1.0 op_sel_hi:[1,0]
	v_rcp_f32_e32 v46, v46
	v_rcp_f32_e32 v44, v44
	v_rcp_f32_e32 v45, v45
	v_rcp_f32_e32 v47, v47
	v_rcp_f32_e32 v50, v50
	v_rcp_f32_e32 v51, v51
	v_rcp_f32_e32 v48, v48
	v_rcp_f32_e32 v49, v49
	v_pk_mul_f32 v[34:35], v[38:39], v[34:35]
	v_pk_mul_f32 v[32:33], v[36:37], v[32:33]
	v_mad_i64_i32 v[52:53], s[0:1], v52, s2, v[138:139]
	v_pk_mul_f32 v[36:37], v[44:45], v[34:35]
	v_pk_mul_f32 v[34:35], v[46:47], v[32:33]
	v_lshl_add_u64 v[52:53], v[52:53], 0, v[140:141]
	v_pk_mul_f32 v[42:43], v[48:49], v[42:43]
	v_pk_mul_f32 v[40:41], v[50:51], v[40:41]
	v_pk_mul_f32 v[26:27], v[30:31], v[26:27]
	v_cvt_pk_bf16_f32 v32, v40, v41
	v_cvt_pk_bf16_f32 v33, v42, v43
	v_cvt_pk_bf16_f32 v34, v34, v35
	v_cvt_pk_bf16_f32 v35, v36, v37
	global_store_dwordx4 v[52:53], v[32:35], off nt
	v_pk_mul_f32 v[24:25], v[28:29], v[24:25]
	v_add_u32_e32 v36, 0xa0, v146
	v_pk_mul_f32 v[32:33], v[30:31], s[74:75] op_sel_hi:[1,0]
	v_pk_mul_f32 v[34:35], v[28:29], s[74:75] op_sel_hi:[1,0]
	v_pk_mul_f32 v[28:29], v[22:23], s[74:75] op_sel_hi:[1,0]
	v_pk_mul_f32 v[30:31], v[20:21], s[74:75] op_sel_hi:[1,0]
	v_exp_f32_e32 v28, v28
	v_exp_f32_e32 v30, v30
	v_exp_f32_e32 v29, v29
	v_exp_f32_e32 v31, v31
	v_exp_f32_e32 v34, v34
	v_exp_f32_e32 v35, v35
	v_exp_f32_e32 v32, v32
	v_exp_f32_e32 v33, v33
	v_pk_add_f32 v[28:29], v[28:29], 1.0 op_sel_hi:[1,0]
	v_pk_add_f32 v[30:31], v[30:31], 1.0 op_sel_hi:[1,0]
	v_pk_add_f32 v[34:35], v[34:35], 1.0 op_sel_hi:[1,0]
	v_pk_add_f32 v[32:33], v[32:33], 1.0 op_sel_hi:[1,0]
	v_rcp_f32_e32 v30, v30
	v_rcp_f32_e32 v28, v28
	v_rcp_f32_e32 v29, v29
	v_rcp_f32_e32 v31, v31
	v_rcp_f32_e32 v34, v34
	v_rcp_f32_e32 v35, v35
	v_rcp_f32_e32 v32, v32
	v_rcp_f32_e32 v33, v33
	v_pk_mul_f32 v[18:19], v[22:23], v[18:19]
	v_pk_mul_f32 v[16:17], v[20:21], v[16:17]
	v_mad_i64_i32 v[36:37], s[0:1], v36, s2, v[138:139]
	v_pk_mul_f32 v[20:21], v[28:29], v[18:19]
	v_pk_mul_f32 v[18:19], v[30:31], v[16:17]
	v_lshl_add_u64 v[36:37], v[36:37], 0, v[140:141]
	v_pk_mul_f32 v[26:27], v[32:33], v[26:27]
	v_pk_mul_f32 v[24:25], v[34:35], v[24:25]
	v_pk_mul_f32 v[10:11], v[14:15], v[10:11]
	v_cvt_pk_bf16_f32 v16, v24, v25
	v_cvt_pk_bf16_f32 v17, v26, v27
	v_cvt_pk_bf16_f32 v18, v18, v19
	v_cvt_pk_bf16_f32 v19, v20, v21
	global_store_dwordx4 v[36:37], v[16:19], off nt
	v_pk_mul_f32 v[8:9], v[12:13], v[8:9]
	v_add_u32_e32 v20, 0xb0, v146
	v_pk_mul_f32 v[16:17], v[14:15], s[74:75] op_sel_hi:[1,0]
	v_pk_mul_f32 v[18:19], v[12:13], s[74:75] op_sel_hi:[1,0]
	v_pk_mul_f32 v[12:13], v[6:7], s[74:75] op_sel_hi:[1,0]
	v_pk_mul_f32 v[14:15], v[4:5], s[74:75] op_sel_hi:[1,0]
	v_exp_f32_e32 v12, v12
	v_exp_f32_e32 v14, v14
	v_exp_f32_e32 v13, v13
	v_exp_f32_e32 v15, v15
	v_exp_f32_e32 v18, v18
	v_exp_f32_e32 v19, v19
	v_exp_f32_e32 v16, v16
	v_exp_f32_e32 v17, v17
	v_pk_add_f32 v[12:13], v[12:13], 1.0 op_sel_hi:[1,0]
	v_pk_add_f32 v[14:15], v[14:15], 1.0 op_sel_hi:[1,0]
	v_pk_add_f32 v[18:19], v[18:19], 1.0 op_sel_hi:[1,0]
	v_pk_add_f32 v[16:17], v[16:17], 1.0 op_sel_hi:[1,0]
	v_rcp_f32_e32 v14, v14
	v_rcp_f32_e32 v12, v12
	v_rcp_f32_e32 v13, v13
	v_rcp_f32_e32 v15, v15
	v_rcp_f32_e32 v18, v18
	v_rcp_f32_e32 v19, v19
	v_rcp_f32_e32 v16, v16
	v_rcp_f32_e32 v17, v17
	v_mad_i64_i32 v[20:21], s[0:1], v20, s2, v[138:139]
	v_pk_mul_f32 v[2:3], v[6:7], v[2:3]
	v_pk_mul_f32 v[0:1], v[4:5], v[0:1]
	v_lshl_add_u64 v[20:21], v[20:21], 0, v[140:141]
	v_pk_mul_f32 v[4:5], v[12:13], v[2:3]
	v_pk_mul_f32 v[2:3], v[14:15], v[0:1]
	s_andn2_b64 vcc, exec, s[38:39]
	s_mov_b64 s[0:1], -1
	s_movk_i32 s49, 0x300
	s_mov_b64 s[52:53], 0x60000
	v_pk_mul_f32 v[10:11], v[16:17], v[10:11]
	v_pk_mul_f32 v[8:9], v[18:19], v[8:9]
	s_nop 0
	v_cvt_pk_bf16_f32 v0, v8, v9
	v_cvt_pk_bf16_f32 v1, v10, v11
	v_cvt_pk_bf16_f32 v2, v2, v3
	v_cvt_pk_bf16_f32 v3, v4, v5
	global_store_dwordx4 v[20:21], v[0:3], off nt
	s_cbranch_vccnz .LBB0_1000
	s_andn2_b64 vcc, exec, s[6:7]
	s_cbranch_vccnz .LBB0_999
	s_barrier
	s_branch .LBB0_999

; #define PG8_STAGE(bufoff, gbase, voff) do { _Pragma("unroll") for (int _i = 0; _i < 2; ++_i) \
;         __builtin_amdgcn_global_load_lds((const unsigned*)((const char*)(gbase) + (voff)[_i]), (LAS unsigned*)(lds + (bufoff) + ldsw + _i * 8192), 16, 0, 0); } while (0)
; #define PG8_LDA(dst, b, h) do { _Pragma("unroll") for (int m = 0; m < 4; ++m) _Pragma("unroll") for (int k = 0; k < 2; ++k) dst[m][k] = *(const LAS bf16x8*)(lds + PG8_SA(b, h) + aoff + m * 2048 + k * 1024); } while (0)
; #define PG8_LDB(dst, b, h) do { _Pragma("unroll") for (int n = 0; n < 2; ++n) _Pragma("unroll") for (int k = 0; k < 2; ++k) dst[n][k] = *(const LAS bf16x8*)(lds + PG8_SB(b, h) + boff + n * 2048 + k * 1024); } while (0)
; #define PG8_WAIT_V(n) asm volatile("s_waitcnt vmcnt(" #n ")" ::: "memory")
; #define PG8_WAIT_L(n) asm volatile("s_waitcnt lgkmcnt(" #n ")" ::: "memory")
; #define PG8_BAR __builtin_amdgcn_s_barrier()
; template <class Epi>
; __device__ __forceinline__ void gemm_phase(LAS unsigned char* lds, const Gemm g, const StaticOrder& S, const Epi& E, const int tid) {
;     ...
;         const bool has_next = S.next(ui + 1, nxt);
;         const char* nA = has_next ? PG8_APTR(nxt) : cA; const char* nB = has_next ? PG8_BPTR(nxt) : cB;
;         for (int t = 0; t < nt; t += 2) {
;             const bool last = (t == nt - 2);
;             const char* a1 = cA + (size_t)(t + 1) * kstep;
;             const char* a2 = last ? nA : cA + (size_t)(t + 2) * kstep; const char* b2 = last ? nB : cB + (size_t)(t + 2) * kstep;
;             const char* a3 = a2 + kstep; const char* b3 = b2 + kstep;
;             PG8_LDB(B0, 0, 0); PG8_LDB(B1, 0, 1); PG8_SCHED; PG8_LDA(At, 0, 0); PG8_STAGE(PG8_SA(1, 1), a1 + hsA, voffA);
;             PG8_WAIT_V(8); PG8_WAIT_L(0); PG8_BAR; PG8_MMA(0, 0, At, B0); PG8_MMA(0, 1, At, B1); PG8_BAR; PG8_SCHED;
;             PG8_LDA(At, 0, 1); PG8_STAGE(PG8_SB(0, 0), b2, voffB); PG8_STAGE(PG8_SB(0, 1), b2 + hsB, voffB); PG8_STAGE(PG8_SA(0, 0), a2, voffA);
;             PG8_WAIT_V(8); PG8_WAIT_L(0); PG8_BAR; PG8_MMA(1, 0, At, B0); PG8_MMA(1, 1, At, B1); PG8_BAR; PG8_SCHED;
;     ...
;         for (int a = 0; a < 2; ++a)
; #pragma unroll
;             for (int b = 0; b < 2; ++b)
; #pragma unroll
;                 for (int m = 0; m < 4; ++m)
; #pragma unroll
;                     for (int n = 0; n < 2; ++n) acc[a][b][m][n] = (f32x4){0.f, 0.f, 0.f, 0.f};
.LBB0_1075:
	s_add_u32 s38, s0, 0x100
	v_mov_b32_e32 v0, 0
	s_addc_u32 s39, s1, 0
	s_mov_b32 s53, -2
	v_mov_b32_e32 v1, v0
	v_mov_b32_e32 v2, v0
	v_mov_b32_e32 v3, v0
	v_mov_b32_e32 v4, v0
	v_mov_b32_e32 v5, v0
	v_mov_b32_e32 v6, v0
	v_mov_b32_e32 v7, v0
	v_mov_b32_e32 v16, v0
	v_mov_b32_e32 v17, v0
	v_mov_b32_e32 v18, v0
	v_mov_b32_e32 v19, v0
	v_mov_b32_e32 v20, v0
	v_mov_b32_e32 v21, v0
	v_mov_b32_e32 v22, v0
	v_mov_b32_e32 v23, v0
	v_mov_b32_e32 v32, v0
	v_mov_b32_e32 v33, v0
	v_mov_b32_e32 v34, v0
	v_mov_b32_e32 v35, v0
	v_mov_b32_e32 v36, v0
	v_mov_b32_e32 v37, v0
	v_mov_b32_e32 v38, v0
	v_mov_b32_e32 v39, v0
	v_mov_b32_e32 v48, v0
	v_mov_b32_e32 v49, v0
	v_mov_b32_e32 v50, v0
	v_mov_b32_e32 v51, v0
	v_mov_b32_e32 v52, v0
	v_mov_b32_e32 v53, v0
	v_mov_b32_e32 v54, v0
	v_mov_b32_e32 v55, v0
	v_mov_b32_e32 v8, v0
	v_mov_b32_e32 v9, v0
	v_mov_b32_e32 v10, v0
	v_mov_b32_e32 v11, v0
	v_mov_b32_e32 v12, v0
	v_mov_b32_e32 v13, v0
	v_mov_b32_e32 v14, v0
	v_mov_b32_e32 v15, v0
	v_mov_b32_e32 v24, v0
	v_mov_b32_e32 v25, v0
	v_mov_b32_e32 v26, v0
	v_mov_b32_e32 v27, v0
	v_mov_b32_e32 v28, v0
	v_mov_b32_e32 v29, v0
	v_mov_b32_e32 v30, v0
	v_mov_b32_e32 v31, v0
	v_mov_b32_e32 v40, v0
	v_mov_b32_e32 v41, v0
	v_mov_b32_e32 v42, v0
	v_mov_b32_e32 v43, v0
	v_mov_b32_e32 v44, v0
	v_mov_b32_e32 v45, v0
	v_mov_b32_e32 v46, v0
	v_mov_b32_e32 v47, v0
	v_mov_b32_e32 v56, v0
	v_mov_b32_e32 v57, v0
	v_mov_b32_e32 v58, v0
	v_mov_b32_e32 v59, v0
	v_mov_b32_e32 v60, v0
	v_mov_b32_e32 v61, v0
	v_mov_b32_e32 v62, v0
	v_mov_b32_e32 v63, v0
	v_mov_b32_e32 v64, v0
	v_mov_b32_e32 v65, v0
	v_mov_b32_e32 v66, v0
	v_mov_b32_e32 v67, v0
	v_mov_b32_e32 v68, v0
	v_mov_b32_e32 v69, v0
	v_mov_b32_e32 v70, v0
	v_mov_b32_e32 v71, v0
	v_mov_b32_e32 v76, v0
	v_mov_b32_e32 v77, v0
	v_mov_b32_e32 v78, v0
	v_mov_b32_e32 v79, v0
	v_mov_b32_e32 v84, v0
	v_mov_b32_e32 v85, v0
	v_mov_b32_e32 v86, v0
	v_mov_b32_e32 v87, v0
	v_mov_b32_e32 v96, v0
	v_mov_b32_e32 v97, v0
	v_mov_b32_e32 v98, v0
	v_mov_b32_e32 v99, v0
	v_mov_b32_e32 v100, v0
	v_mov_b32_e32 v101, v0
	v_mov_b32_e32 v102, v0
	v_mov_b32_e32 v103, v0
	v_mov_b32_e32 v112, v0
	v_mov_b32_e32 v113, v0
	v_mov_b32_e32 v114, v0
	v_mov_b32_e32 v115, v0
	v_mov_b32_e32 v116, v0
	v_mov_b32_e32 v117, v0
	v_mov_b32_e32 v118, v0
	v_mov_b32_e32 v119, v0
	v_mov_b32_e32 v72, v0
	v_mov_b32_e32 v73, v0
	v_mov_b32_e32 v74, v0
	v_mov_b32_e32 v75, v0
	v_mov_b32_e32 v80, v0
	v_mov_b32_e32 v81, v0
	v_mov_b32_e32 v82, v0
	v_mov_b32_e32 v83, v0
	v_mov_b32_e32 v88, v0
	v_mov_b32_e32 v89, v0
	v_mov_b32_e32 v90, v0
	v_mov_b32_e32 v91, v0
	v_mov_b32_e32 v92, v0
	v_mov_b32_e32 v93, v0
	v_mov_b32_e32 v94, v0
	v_mov_b32_e32 v95, v0
	v_mov_b32_e32 v104, v0
	v_mov_b32_e32 v105, v0
	v_mov_b32_e32 v106, v0
	v_mov_b32_e32 v107, v0
	v_mov_b32_e32 v108, v0
	v_mov_b32_e32 v109, v0
	v_mov_b32_e32 v110, v0
	v_mov_b32_e32 v111, v0
	v_mov_b32_e32 v120, v0
	v_mov_b32_e32 v121, v0
	v_mov_b32_e32 v122, v0
	v_mov_b32_e32 v123, v0
	v_mov_b32_e32 v124, v0
	v_mov_b32_e32 v125, v0
	v_mov_b32_e32 v126, v0
	v_mov_b32_e32 v127, v0
	s_cmp_lg_u64 s[6:7], 0
	s_cbranch_scc1 .Lgprio_g
	s_setprio 1
.Lgprio_g:
.LBB0_1076:
	s_add_u32 s0, s12, 0x100
	s_addc_u32 s1, s13, 0
	s_add_i32 s2, 0, 0x10000
	s_cmpk_eq_i32 s53, 0x54
	s_cselect_b32 s17, s9, s1
	s_cselect_b32 s16, s8, s0
	s_cselect_b32 s15, s11, s39
	s_cselect_b32 s14, s10, s38
	s_add_i32 s24, 0, 0x14000
	v_add_u32_e32 v152, s2, v184
	v_add_u32_e32 v170, s24, v184
	ds_read_b128 v[128:131], v152
	ds_read_b128 v[144:147], v152 offset:1024
	ds_read_b128 v[148:151], v152 offset:2048
	ds_read_b128 v[152:155], v152 offset:3072
	ds_read_b128 v[156:159], v170
	ds_read_b128 v[160:163], v170 offset:1024
	ds_read_b128 v[164:167], v170 offset:2048
	ds_read_b128 v[190:193], v170 offset:3072
	v_lshl_add_u64 v[170:171], s[12:13], 0, v[140:141]
	s_add_i32 m0, s34, 0xc000
	ds_read_b128 v[194:197], v189
	ds_read_b128 v[198:201], v189 offset:1024
	ds_read_b128 v[202:205], v189 offset:2048
	ds_read_b128 v[206:209], v189 offset:3072
	ds_read_b128 v[210:213], v189 offset:4096
	ds_read_b128 v[230:233], v189 offset:5120
	ds_read_b128 v[234:237], v189 offset:6144
	ds_read_b128 v[238:241], v189 offset:7168
	global_load_lds_dwordx4 v[170:171], off
	v_lshl_add_u64 v[170:171], s[12:13], 0, v[142:143]
	s_add_i32 m0, s34, 0xe000
	s_nop 0
	global_load_lds_dwordx4 v[170:171], off
	s_waitcnt vmcnt(8)
	s_waitcnt lgkmcnt(0)
	s_barrier
	s_waitcnt lgkmcnt(0)
	v_mfma_f32_16x16x32_bf16 v[124:127], v[128:131], v[194:197], v[124:127]
	v_mfma_f32_16x16x32_bf16 v[120:123], v[148:151], v[194:197], v[120:123]
	v_mfma_f32_16x16x32_bf16 v[108:111], v[128:131], v[202:205], v[108:111]
	v_mfma_f32_16x16x32_bf16 v[104:107], v[148:151], v[202:205], v[104:107]
	v_mfma_f32_16x16x32_bf16 v[92:95], v[128:131], v[210:213], v[92:95]
	v_mfma_f32_16x16x32_bf16 v[88:91], v[148:151], v[210:213], v[88:91]
	v_mfma_f32_16x16x32_bf16 v[80:83], v[128:131], v[234:237], v[80:83]
	v_mfma_f32_16x16x32_bf16 v[72:75], v[148:151], v[234:237], v[72:75]
	v_mfma_f32_16x16x32_bf16 v[124:127], v[144:147], v[198:201], v[124:127]
	v_mfma_f32_16x16x32_bf16 v[120:123], v[152:155], v[198:201], v[120:123]
	v_mfma_f32_16x16x32_bf16 v[108:111], v[144:147], v[206:209], v[108:111]
	v_mfma_f32_16x16x32_bf16 v[104:107], v[152:155], v[206:209], v[104:107]
	v_mfma_f32_16x16x32_bf16 v[92:95], v[144:147], v[230:233], v[92:95]
	v_mfma_f32_16x16x32_bf16 v[88:91], v[152:155], v[230:233], v[88:91]
	v_mfma_f32_16x16x32_bf16 v[80:83], v[144:147], v[238:241], v[80:83]
	v_mfma_f32_16x16x32_bf16 v[72:75], v[152:155], v[238:241], v[72:75]
	v_mfma_f32_16x16x32_bf16 v[116:119], v[156:159], v[194:197], v[116:119]
	v_mfma_f32_16x16x32_bf16 v[112:115], v[164:167], v[194:197], v[112:115]
	v_mfma_f32_16x16x32_bf16 v[100:103], v[156:159], v[202:205], v[100:103]
	v_mfma_f32_16x16x32_bf16 v[96:99], v[164:167], v[202:205], v[96:99]
	v_mfma_f32_16x16x32_bf16 v[84:87], v[156:159], v[210:213], v[84:87]
	v_mfma_f32_16x16x32_bf16 v[76:79], v[164:167], v[210:213], v[76:79]
	v_mfma_f32_16x16x32_bf16 v[68:71], v[156:159], v[234:237], v[68:71]
	v_mfma_f32_16x16x32_bf16 v[64:67], v[164:167], v[234:237], v[64:67]
	v_mfma_f32_16x16x32_bf16 v[116:119], v[160:163], v[198:201], v[116:119]
	v_mfma_f32_16x16x32_bf16 v[112:115], v[190:193], v[198:201], v[112:115]
	v_mfma_f32_16x16x32_bf16 v[100:103], v[160:163], v[206:209], v[100:103]
	v_mfma_f32_16x16x32_bf16 v[96:99], v[190:193], v[206:209], v[96:99]
	v_mfma_f32_16x16x32_bf16 v[84:87], v[160:163], v[230:233], v[84:87]
	v_mfma_f32_16x16x32_bf16 v[76:79], v[190:193], v[230:233], v[76:79]
	v_mfma_f32_16x16x32_bf16 v[68:71], v[160:163], v[238:241], v[68:71]
	v_mfma_f32_16x16x32_bf16 v[64:67], v[190:193], v[238:241], v[64:67]
	s_barrier
; #define PG8_STAGE(bufoff, gbase, voff) do { _Pragma("unroll") for (int _i = 0; _i < 2; ++_i) \
;         __builtin_amdgcn_global_load_lds((const unsigned*)((const char*)(gbase) + (voff)[_i]), (LAS unsigned*)(lds + (bufoff) + ldsw + _i * 8192), 16, 0, 0); } while (0)
; #define PG8_LDA(dst, b, h) do { _Pragma("unroll") for (int m = 0; m < 4; ++m) _Pragma("unroll") for (int k = 0; k < 2; ++k) dst[m][k] = *(const LAS bf16x8*)(lds + PG8_SA(b, h) + aoff + m * 2048 + k * 1024); } while (0)
; #define PG8_LDB(dst, b, h) do { _Pragma("unroll") for (int n = 0; n < 2; ++n) _Pragma("unroll") for (int k = 0; k < 2; ++k) dst[n][k] = *(const LAS bf16x8*)(lds + PG8_SB(b, h) + boff + n * 2048 + k * 1024); } while (0)
; #define PG8_MMA(ai, bj, At, Bt) do { __builtin_amdgcn_s_setprio(1); _Pragma("unroll") for (int m = 0; m < 4; ++m) _Pragma("unroll") for (int n = 0; n < 2; ++n) _Pragma("unroll") for (int k = 0; k < 2; ++k) \
;         acc[ai][bj][m][n] = __builtin_amdgcn_mfma_f32_16x16x32_bf16(Bt[n][k], At[m][k], acc[ai][bj][m][n], 0, 0, 0); __builtin_amdgcn_s_setprio(0); } while (0)
; #define PG8_WAIT_V(n) asm volatile("s_waitcnt vmcnt(" #n ")" ::: "memory")
; #define PG8_WAIT_L(n) asm volatile("s_waitcnt lgkmcnt(" #n ")" ::: "memory")
; #define PG8_BAR __builtin_amdgcn_s_barrier()
; #define PG8_SCHED __builtin_amdgcn_sched_barrier(0)
; template <class Epi>
; __device__ __forceinline__ void gemm_phase(LAS unsigned char* lds, const Gemm g, const StaticOrder& S, const Epi& E, const int tid) {
;     ...
;             PG8_LDA(At, 0, 1); PG8_STAGE(PG8_SB(0, 0), b2, voffB); PG8_STAGE(PG8_SB(0, 1), b2 + hsB, voffB); PG8_STAGE(PG8_SA(0, 0), a2, voffA);
;             PG8_WAIT_V(8); PG8_WAIT_L(0); PG8_BAR; PG8_MMA(1, 0, At, B0); PG8_MMA(1, 1, At, B1); PG8_BAR; PG8_SCHED;
;             PG8_LDB(B0, 1, 0); PG8_LDB(B1, 1, 1); PG8_SCHED; PG8_LDA(At, 1, 0); PG8_STAGE(PG8_SA(0, 1), a2 + hsA, voffA);
;             PG8_WAIT_V(8); PG8_WAIT_L(0); PG8_BAR; PG8_MMA(0, 0, At, B0); PG8_MMA(0, 1, At, B1); PG8_BAR; PG8_SCHED;
	s_add_i32 s2, s2, s27
	v_lshl_add_u64 v[170:171], s[14:15], 0, v[136:137]
	s_mov_b32 m0, s2
	ds_read_b128 v[194:197], v189 offset:16384
	ds_read_b128 v[198:201], v189 offset:17408
	ds_read_b128 v[202:205], v189 offset:18432
	ds_read_b128 v[206:209], v189 offset:19456
	ds_read_b128 v[210:213], v189 offset:20480
	ds_read_b128 v[230:233], v189 offset:21504
	ds_read_b128 v[234:237], v189 offset:22528
	ds_read_b128 v[238:241], v189 offset:23552
	global_load_lds_dwordx4 v[170:171], off
	s_add_i32 m0, s2, 0x2000
	s_add_u32 s12, s14, 0x160000
	v_lshl_add_u64 v[172:173], s[14:15], 0, v[132:133]
	s_addc_u32 s13, s15, 0
	s_add_i32 s2, s24, s27
	global_load_lds_dwordx4 v[172:173], off
	v_lshl_add_u64 v[242:243], s[12:13], 0, v[136:137]
	s_mov_b32 m0, s2
	v_lshl_add_u64 v[244:245], s[16:17], 0, v[134:135]
	global_load_lds_dwordx4 v[242:243], off
	v_lshl_add_u64 v[242:243], s[12:13], 0, v[132:133]
	s_add_i32 m0, s2, 0x2000
	s_nop 0
	global_load_lds_dwordx4 v[242:243], off
	v_lshl_add_u64 v[242:243], s[16:17], 0, v[138:139]
	s_mov_b32 m0, s34
	s_nop 0
	global_load_lds_dwordx4 v[242:243], off
	s_mov_b32 m0, s35
	s_nop 0
	global_load_lds_dwordx4 v[244:245], off
	s_waitcnt vmcnt(8)
	s_waitcnt lgkmcnt(0)
	s_barrier
	s_waitcnt lgkmcnt(0)
	v_mfma_f32_16x16x32_bf16 v[60:63], v[128:131], v[194:197], v[60:63]
	v_mfma_f32_16x16x32_bf16 v[56:59], v[148:151], v[194:197], v[56:59]
	v_mfma_f32_16x16x32_bf16 v[44:47], v[128:131], v[202:205], v[44:47]
	v_mfma_f32_16x16x32_bf16 v[40:43], v[148:151], v[202:205], v[40:43]
	v_mfma_f32_16x16x32_bf16 v[28:31], v[128:131], v[210:213], v[28:31]
	v_mfma_f32_16x16x32_bf16 v[24:27], v[148:151], v[210:213], v[24:27]
	v_mfma_f32_16x16x32_bf16 v[12:15], v[128:131], v[234:237], v[12:15]
	v_mfma_f32_16x16x32_bf16 v[8:11], v[148:151], v[234:237], v[8:11]
	v_mfma_f32_16x16x32_bf16 v[60:63], v[144:147], v[198:201], v[60:63]
	v_mfma_f32_16x16x32_bf16 v[56:59], v[152:155], v[198:201], v[56:59]
	v_mfma_f32_16x16x32_bf16 v[44:47], v[144:147], v[206:209], v[44:47]
	v_mfma_f32_16x16x32_bf16 v[40:43], v[152:155], v[206:209], v[40:43]
	v_mfma_f32_16x16x32_bf16 v[28:31], v[144:147], v[230:233], v[28:31]
	v_mfma_f32_16x16x32_bf16 v[24:27], v[152:155], v[230:233], v[24:27]
	v_mfma_f32_16x16x32_bf16 v[12:15], v[144:147], v[238:241], v[12:15]
	v_mfma_f32_16x16x32_bf16 v[8:11], v[152:155], v[238:241], v[8:11]
	v_mfma_f32_16x16x32_bf16 v[52:55], v[156:159], v[194:197], v[52:55]
	v_mfma_f32_16x16x32_bf16 v[48:51], v[164:167], v[194:197], v[48:51]
	v_mfma_f32_16x16x32_bf16 v[36:39], v[156:159], v[202:205], v[36:39]
	v_mfma_f32_16x16x32_bf16 v[32:35], v[164:167], v[202:205], v[32:35]
	v_mfma_f32_16x16x32_bf16 v[20:23], v[156:159], v[210:213], v[20:23]
	v_mfma_f32_16x16x32_bf16 v[16:19], v[164:167], v[210:213], v[16:19]
	v_mfma_f32_16x16x32_bf16 v[4:7], v[156:159], v[234:237], v[4:7]
	v_mfma_f32_16x16x32_bf16 v[0:3], v[164:167], v[234:237], v[0:3]
	v_mfma_f32_16x16x32_bf16 v[52:55], v[160:163], v[198:201], v[52:55]
	v_mfma_f32_16x16x32_bf16 v[48:51], v[190:193], v[198:201], v[48:51]
	v_mfma_f32_16x16x32_bf16 v[36:39], v[160:163], v[206:209], v[36:39]
	v_mfma_f32_16x16x32_bf16 v[32:35], v[190:193], v[206:209], v[32:35]
	v_mfma_f32_16x16x32_bf16 v[20:23], v[160:163], v[230:233], v[20:23]
	v_mfma_f32_16x16x32_bf16 v[16:19], v[190:193], v[230:233], v[16:19]
	v_mfma_f32_16x16x32_bf16 v[4:7], v[160:163], v[238:241], v[4:7]
	v_mfma_f32_16x16x32_bf16 v[0:3], v[190:193], v[238:241], v[0:3]
	s_barrier
	s_add_i32 s2, 0, 0x18000
	s_add_i32 s24, 0, 0x1c000
	v_add_u32_e32 v152, s2, v184
	v_add_u32_e32 v190, s24, v184
	ds_read_b128 v[128:131], v152
	ds_read_b128 v[144:147], v152 offset:1024
	ds_read_b128 v[148:151], v152 offset:2048
	ds_read_b128 v[152:155], v152 offset:3072
	ds_read_b128 v[156:159], v190
	ds_read_b128 v[160:163], v190 offset:1024
	ds_read_b128 v[164:167], v190 offset:2048
	ds_read_b128 v[190:193], v190 offset:3072
	s_add_u32 s12, s16, 0x160000
	s_addc_u32 s13, s17, 0
	s_mov_b32 m0, s40
	v_lshl_add_u64 v[246:247], s[12:13], 0, v[138:139]
	ds_read_b128 v[194:197], v189 offset:32768
	ds_read_b128 v[198:201], v189 offset:33792
	ds_read_b128 v[202:205], v189 offset:34816
	ds_read_b128 v[206:209], v189 offset:35840
	ds_read_b128 v[210:213], v189 offset:36864
	ds_read_b128 v[230:233], v189 offset:37888
	ds_read_b128 v[234:237], v189 offset:38912
	ds_read_b128 v[238:241], v189 offset:39936
	global_load_lds_dwordx4 v[246:247], off
	v_lshl_add_u64 v[246:247], s[12:13], 0, v[134:135]
	s_mov_b32 m0, s41
	s_nop 0
	global_load_lds_dwordx4 v[246:247], off
	s_waitcnt vmcnt(8)
	s_waitcnt lgkmcnt(0)
	s_barrier
; #define PG8_STAGE(bufoff, gbase, voff) do { _Pragma("unroll") for (int _i = 0; _i < 2; ++_i) \
;         __builtin_amdgcn_global_load_lds((const unsigned*)((const char*)(gbase) + (voff)[_i]), (LAS unsigned*)(lds + (bufoff) + ldsw + _i * 8192), 16, 0, 0); } while (0)
; #define PG8_LDA(dst, b, h) do { _Pragma("unroll") for (int m = 0; m < 4; ++m) _Pragma("unroll") for (int k = 0; k < 2; ++k) dst[m][k] = *(const LAS bf16x8*)(lds + PG8_SA(b, h) + aoff + m * 2048 + k * 1024); } while (0)
; #define PG8_MMA(ai, bj, At, Bt) do { __builtin_amdgcn_s_setprio(1); _Pragma("unroll") for (int m = 0; m < 4; ++m) _Pragma("unroll") for (int n = 0; n < 2; ++n) _Pragma("unroll") for (int k = 0; k < 2; ++k) \
;         acc[ai][bj][m][n] = __builtin_amdgcn_mfma_f32_16x16x32_bf16(Bt[n][k], At[m][k], acc[ai][bj][m][n], 0, 0, 0); __builtin_amdgcn_s_setprio(0); } while (0)
; #define PG8_WAIT_V(n) asm volatile("s_waitcnt vmcnt(" #n ")" ::: "memory")
; #define PG8_WAIT_L(n) asm volatile("s_waitcnt lgkmcnt(" #n ")" ::: "memory")
; #define PG8_BAR __builtin_amdgcn_s_barrier()
; #define PG8_SCHED __builtin_amdgcn_sched_barrier(0)
; template <class Epi>
; __device__ __forceinline__ void gemm_phase(LAS unsigned char* lds, const Gemm g, const StaticOrder& S, const Epi& E, const int tid) {
;     ...
;             PG8_WAIT_V(8); PG8_WAIT_L(0); PG8_BAR; PG8_MMA(0, 0, At, B0); PG8_MMA(0, 1, At, B1); PG8_BAR; PG8_SCHED;
;             PG8_LDA(At, 1, 1); PG8_STAGE(PG8_SB(1, 0), b3, voffB); PG8_STAGE(PG8_SB(1, 1), b3 + hsB, voffB); PG8_STAGE(PG8_SA(1, 0), a3, voffA);
;             PG8_WAIT_V(8); PG8_WAIT_L(0); PG8_BAR; PG8_MMA(1, 0, At, B0); PG8_MMA(1, 1, At, B1); PG8_BAR; PG8_SCHED;
;         }
;         if (wr == 0) PG8_BAR;
	s_waitcnt lgkmcnt(0)
	v_mfma_f32_16x16x32_bf16 v[124:127], v[128:131], v[194:197], v[124:127]
	v_mfma_f32_16x16x32_bf16 v[120:123], v[148:151], v[194:197], v[120:123]
	v_mfma_f32_16x16x32_bf16 v[108:111], v[128:131], v[202:205], v[108:111]
	v_mfma_f32_16x16x32_bf16 v[104:107], v[148:151], v[202:205], v[104:107]
	v_mfma_f32_16x16x32_bf16 v[92:95], v[128:131], v[210:213], v[92:95]
	v_mfma_f32_16x16x32_bf16 v[88:91], v[148:151], v[210:213], v[88:91]
	v_mfma_f32_16x16x32_bf16 v[80:83], v[128:131], v[234:237], v[80:83]
	v_mfma_f32_16x16x32_bf16 v[72:75], v[148:151], v[234:237], v[72:75]
	v_mfma_f32_16x16x32_bf16 v[124:127], v[144:147], v[198:201], v[124:127]
	v_mfma_f32_16x16x32_bf16 v[120:123], v[152:155], v[198:201], v[120:123]
	v_mfma_f32_16x16x32_bf16 v[108:111], v[144:147], v[206:209], v[108:111]
	v_mfma_f32_16x16x32_bf16 v[104:107], v[152:155], v[206:209], v[104:107]
	v_mfma_f32_16x16x32_bf16 v[92:95], v[144:147], v[230:233], v[92:95]
	v_mfma_f32_16x16x32_bf16 v[88:91], v[152:155], v[230:233], v[88:91]
	v_mfma_f32_16x16x32_bf16 v[80:83], v[144:147], v[238:241], v[80:83]
	v_mfma_f32_16x16x32_bf16 v[72:75], v[152:155], v[238:241], v[72:75]
	v_mfma_f32_16x16x32_bf16 v[116:119], v[156:159], v[194:197], v[116:119]
	v_mfma_f32_16x16x32_bf16 v[112:115], v[164:167], v[194:197], v[112:115]
	v_mfma_f32_16x16x32_bf16 v[100:103], v[156:159], v[202:205], v[100:103]
	v_mfma_f32_16x16x32_bf16 v[96:99], v[164:167], v[202:205], v[96:99]
	v_mfma_f32_16x16x32_bf16 v[84:87], v[156:159], v[210:213], v[84:87]
	v_mfma_f32_16x16x32_bf16 v[76:79], v[164:167], v[210:213], v[76:79]
	v_mfma_f32_16x16x32_bf16 v[68:71], v[156:159], v[234:237], v[68:71]
	v_mfma_f32_16x16x32_bf16 v[64:67], v[164:167], v[234:237], v[64:67]
	v_mfma_f32_16x16x32_bf16 v[116:119], v[160:163], v[198:201], v[116:119]
	v_mfma_f32_16x16x32_bf16 v[112:115], v[190:193], v[198:201], v[112:115]
	v_mfma_f32_16x16x32_bf16 v[100:103], v[160:163], v[206:209], v[100:103]
	v_mfma_f32_16x16x32_bf16 v[96:99], v[190:193], v[206:209], v[96:99]
	v_mfma_f32_16x16x32_bf16 v[84:87], v[160:163], v[230:233], v[84:87]
	v_mfma_f32_16x16x32_bf16 v[76:79], v[190:193], v[230:233], v[76:79]
	v_mfma_f32_16x16x32_bf16 v[68:71], v[160:163], v[238:241], v[68:71]
	v_mfma_f32_16x16x32_bf16 v[64:67], v[190:193], v[238:241], v[64:67]
	s_barrier
	s_add_i32 s2, s2, s27
	v_lshl_add_u64 v[170:171], v[170:171], 0, s[28:29]
	s_mov_b32 m0, s2
	ds_read_b128 v[194:197], v189 offset:49152
	ds_read_b128 v[198:201], v189 offset:50176
	ds_read_b128 v[202:205], v189 offset:51200
	ds_read_b128 v[206:209], v189 offset:52224
	ds_read_b128 v[210:213], v189 offset:53248
	ds_read_b128 v[230:233], v189 offset:54272
	ds_read_b128 v[234:237], v189 offset:55296
	ds_read_b128 v[238:241], v189 offset:56320
	global_load_lds_dwordx4 v[170:171], off
	s_add_i32 m0, s2, 0x2000
	s_add_u32 s12, s14, 0x160080
	v_lshl_add_u64 v[170:171], v[172:173], 0, s[28:29]
	s_addc_u32 s13, s15, 0
	s_add_i32 s2, s24, s27
	global_load_lds_dwordx4 v[170:171], off
	v_lshl_add_u64 v[170:171], s[12:13], 0, v[136:137]
	s_mov_b32 m0, s2
	s_nop 0
	global_load_lds_dwordx4 v[170:171], off
	v_lshl_add_u64 v[170:171], s[12:13], 0, v[132:133]
	s_add_i32 m0, s2, 0x2000
	s_nop 0
	global_load_lds_dwordx4 v[170:171], off
	v_lshl_add_u64 v[170:171], v[242:243], 0, s[28:29]
	s_mov_b32 m0, s44
	s_nop 0
	global_load_lds_dwordx4 v[170:171], off
	v_lshl_add_u64 v[170:171], v[244:245], 0, s[28:29]
	s_mov_b32 m0, s45
	s_nop 0
	global_load_lds_dwordx4 v[170:171], off
	s_waitcnt vmcnt(8)
	s_waitcnt lgkmcnt(0)
	s_barrier
	s_waitcnt lgkmcnt(0)
	v_mfma_f32_16x16x32_bf16 v[60:63], v[128:131], v[194:197], v[60:63]
	v_mfma_f32_16x16x32_bf16 v[56:59], v[148:151], v[194:197], v[56:59]
	v_mfma_f32_16x16x32_bf16 v[44:47], v[128:131], v[202:205], v[44:47]
	v_mfma_f32_16x16x32_bf16 v[40:43], v[148:151], v[202:205], v[40:43]
	v_mfma_f32_16x16x32_bf16 v[28:31], v[128:131], v[210:213], v[28:31]
	v_mfma_f32_16x16x32_bf16 v[24:27], v[148:151], v[210:213], v[24:27]
	v_mfma_f32_16x16x32_bf16 v[12:15], v[128:131], v[234:237], v[12:15]
	v_mfma_f32_16x16x32_bf16 v[8:11], v[148:151], v[234:237], v[8:11]
	v_mfma_f32_16x16x32_bf16 v[60:63], v[144:147], v[198:201], v[60:63]
	v_mfma_f32_16x16x32_bf16 v[56:59], v[152:155], v[198:201], v[56:59]
	v_mfma_f32_16x16x32_bf16 v[44:47], v[144:147], v[206:209], v[44:47]
	v_mfma_f32_16x16x32_bf16 v[40:43], v[152:155], v[206:209], v[40:43]
	v_mfma_f32_16x16x32_bf16 v[28:31], v[144:147], v[230:233], v[28:31]
	v_mfma_f32_16x16x32_bf16 v[24:27], v[152:155], v[230:233], v[24:27]
	v_mfma_f32_16x16x32_bf16 v[12:15], v[144:147], v[238:241], v[12:15]
	v_mfma_f32_16x16x32_bf16 v[8:11], v[152:155], v[238:241], v[8:11]
	v_mfma_f32_16x16x32_bf16 v[52:55], v[156:159], v[194:197], v[52:55]
	v_mfma_f32_16x16x32_bf16 v[48:51], v[164:167], v[194:197], v[48:51]
	v_mfma_f32_16x16x32_bf16 v[36:39], v[156:159], v[202:205], v[36:39]
	v_mfma_f32_16x16x32_bf16 v[32:35], v[164:167], v[202:205], v[32:35]
	v_mfma_f32_16x16x32_bf16 v[20:23], v[156:159], v[210:213], v[20:23]
	v_mfma_f32_16x16x32_bf16 v[16:19], v[164:167], v[210:213], v[16:19]
	v_mfma_f32_16x16x32_bf16 v[4:7], v[156:159], v[234:237], v[4:7]
	v_mfma_f32_16x16x32_bf16 v[0:3], v[164:167], v[234:237], v[0:3]
	v_mfma_f32_16x16x32_bf16 v[52:55], v[160:163], v[198:201], v[52:55]
	v_mfma_f32_16x16x32_bf16 v[48:51], v[190:193], v[198:201], v[48:51]
	v_mfma_f32_16x16x32_bf16 v[36:39], v[160:163], v[206:209], v[36:39]
	v_mfma_f32_16x16x32_bf16 v[32:35], v[190:193], v[206:209], v[32:35]
	v_mfma_f32_16x16x32_bf16 v[20:23], v[160:163], v[230:233], v[20:23]
	v_mfma_f32_16x16x32_bf16 v[16:19], v[190:193], v[230:233], v[16:19]
	v_mfma_f32_16x16x32_bf16 v[4:7], v[160:163], v[238:241], v[4:7]
	v_mfma_f32_16x16x32_bf16 v[0:3], v[190:193], v[238:241], v[0:3]
	s_barrier
	s_add_i32 s53, s53, 2
	s_add_u32 s38, s38, 0x100
	s_addc_u32 s39, s39, 0
	s_cmpk_gt_u32 s53, 0x55
	s_mov_b64 s[12:13], s[0:1]
	s_cbranch_scc0 .LBB0_1076
	s_and_b64 vcc, exec, s[6:7]
	s_cbranch_vccz .LBB0_1079
	s_barrier
;     __device__ __forceinline__ void operator()(f32x4 (&acc)[2][2][4][2], const Unit& u, int wr, int wc, int fr, int fq) const {
;         const int lrow0 = row_off + u.pm * BM + wr * 64 + fr, col0 = u.pn * BM + wc * 32 + 8 * fq;
;         const int b = (row_off + u.pm * BM) >> 12;
;         const float* gp = gate + (size_t)b * NMOD + col0;
;         f32x4 gv[2][2];
; #pragma unroll
;         for (int bj = 0; bj < 2; ++bj)
; #pragma unroll
;             for (int n = 0; n < 2; ++n) gv[bj][n] = *(const f32x4*)(gp + bj * HALF + 4 * n) * coef;
;         _Float16* xp = xh + (size_t)lrow0 * D + col0;
;         if (base32) {
;             const float* bp = base32 + (size_t)lrow0 * D + col0;
; #pragma unroll
;             for (int am = 0; am < 8; am += 2) {
;                 f32x4 xb[2][2][2];
; #pragma unroll
;                 for (int mm = 0; mm < 2; ++mm)
; #pragma unroll
;                     for (int bj = 0; bj < 2; ++bj) { const int ai = (am + mm) >> 2, m = (am + mm) & 3; const float* p = bp + (size_t)(ai * HALF + m * 16) * D + bj * HALF; xb[mm][bj][0] = *(const f32x4*)p; xb[mm][bj][1] = *(const f32x4*)(p + 4); }
; #pragma unroll
;                 for (int mm = 0; mm < 2; ++mm)
; #pragma unroll
;                     for (int bj = 0; bj < 2; ++bj) { const int ai = (am + mm) >> 2, m = (am + mm) & 3;
;                         *(h16x8*)(xp + (size_t)(ai * HALF + m * 16) * D + bj * HALF) = f_to_h8(xb[mm][bj][0] + gv[bj][0] * acc[ai][bj][m][0], xb[mm][bj][1] + gv[bj][1] * acc[ai][bj][m][1]); }
;                 __builtin_amdgcn_sched_barrier(0);
;             }
;         } else {
;             const int lane = fr + 16 * fq, rr = lane >> 2, cg = lane & 3;
;             const int pullx = (4 * fr + fq) * 4, pullr = (rr + 16 * cg) * 4;
;             _Float16* xc = xh + (size_t)(row_off + u.pm * BM + wr * 64 + rr) * D + u.pn * BM + wc * 32 + 8 * cg;
; #pragma unroll
;             for (int ai = 0; ai < 2; ++ai) {
;                 u32x4 xr[4][2];
; #pragma unroll
;                 for (int m = 0; m < 4; ++m)
; #pragma unroll
;                     for (int bj = 0; bj < 2; ++bj) xr[m][bj] = *(const u32x4*)(xc + (size_t)(ai * HALF + m * 16) * D + bj * HALF);
; #pragma unroll
;                 for (int m = 0; m < 4; ++m)
; #pragma unroll
;                     for (int bj = 0; bj < 2; ++bj) {
;                         u32x4 t;
; #pragma unroll
.LBB0_1079:
	s_setprio 0
	s_ashr_i32 s1, s49, 4
	s_lshl_b32 s0, s52, 8
	s_mul_hi_i32 s2, s1, 0x12000
	s_mul_i32 s1, s1, 0x12000
	v_or_b32_e32 v128, s0, v185
	s_add_u32 s12, s42, s1
	s_addc_u32 s13, s43, s2
	v_ashrrev_i32_e32 v129, 31, v128
	v_lshl_add_u64 v[128:129], v[128:129], 2, s[12:13]
	global_load_dwordx4 v[144:147], v[128:129], off offset:16
	global_load_dwordx4 v[148:151], v[128:129], off
	global_load_dwordx4 v[190:193], v[128:129], off offset:528
	global_load_dwordx4 v[194:197], v[128:129], off offset:512
	v_lshl_add_u32 v128, s49, 8, v188
	v_ashrrev_i32_e32 v129, 31, v128
	v_readlane_b32 s12, v252, 63
	v_lshlrev_b64 v[128:129], 12, v[128:129]
	v_readlane_b32 s13, v253, 0
	s_ashr_i32 s1, s0, 31
	s_waitcnt vmcnt(0)
	v_pk_mul_f32 v[152:153], v[146:147], 0.5 op_sel_hi:[1,0]
	v_lshl_add_u64 v[128:129], s[12:13], 0, v[128:129]
	v_lshl_add_u64 v[128:129], s[0:1], 1, v[128:129]
	v_lshl_add_u64 v[128:129], v[128:129], 0, s[60:61]
	v_lshl_add_u64 v[160:161], v[128:129], 0, v[168:169]
	global_load_dwordx4 v[198:201], v[160:161], off
	global_load_dwordx4 v[202:205], v[160:161], off offset:256
	s_mov_b32 s0, 0x10000
	v_add_co_u32_e32 v162, vcc, s0, v160
	s_mov_b32 s0, 0x20000
	s_nop 0
	v_addc_co_u32_e32 v163, vcc, 0, v161, vcc
	global_load_dwordx4 v[206:209], v[162:163], off
	v_add_co_u32_e32 v164, vcc, s0, v160
	v_pk_mul_f32 v[158:159], v[148:149], 0.5 op_sel_hi:[1,0]
	s_nop 0
	v_addc_co_u32_e32 v165, vcc, 0, v161, vcc
	global_load_dwordx4 v[210:213], v[162:163], off offset:256
	global_load_dwordx4 v[230:233], v[164:165], off
	global_load_dwordx4 v[128:131], v[164:165], off offset:256
	v_pk_mul_f32 v[154:155], v[144:145], 0.5 op_sel_hi:[1,0]
	v_pk_mul_f32 v[148:149], v[196:197], 0.5 op_sel_hi:[1,0]
	v_pk_mul_f32 v[144:145], v[192:193], 0.5 op_sel_hi:[1,0]
	v_pk_mul_f32 v[146:147], v[190:191], 0.5 op_sel_hi:[1,0]
	v_pk_mul_f32 v[156:157], v[150:151], 0.5 op_sel_hi:[1,0]
	v_pk_mul_f32 v[150:151], v[194:195], 0.5 op_sel_hi:[1,0]
	s_mov_b32 s0, 0x30000
	v_add_co_u32_e32 v166, vcc, s0, v160
	s_mov_b32 s0, 0x80000
	s_nop 0
	v_addc_co_u32_e32 v167, vcc, 0, v161, vcc
	s_waitcnt vmcnt(5)
	ds_bpermute_b32 v171, v186, v198
	ds_bpermute_b32 v173, v186, v199
	ds_bpermute_b32 v191, v186, v200
	ds_bpermute_b32 v193, v186, v201
	s_waitcnt vmcnt(4)
	ds_bpermute_b32 v197, v186, v203
	ds_bpermute_b32 v199, v186, v204
	ds_bpermute_b32 v201, v186, v205
	ds_bpermute_b32 v195, v186, v202
	s_waitcnt lgkmcnt(7)
	v_cvt_f32_f16_e32 v170, v171
	v_cvt_f32_f16_sdwa v171, v171 dst_sel:DWORD dst_unused:UNUSED_PAD src0_sel:WORD_1
	s_waitcnt lgkmcnt(6)
	v_cvt_f32_f16_e32 v172, v173
	v_cvt_f32_f16_sdwa v173, v173 dst_sel:DWORD dst_unused:UNUSED_PAD src0_sel:WORD_1
	s_waitcnt lgkmcnt(5)
	v_cvt_f32_f16_e32 v190, v191
	v_cvt_f32_f16_sdwa v191, v191 dst_sel:DWORD dst_unused:UNUSED_PAD src0_sel:WORD_1
	s_waitcnt lgkmcnt(4)
	v_cvt_f32_f16_e32 v192, v193
	v_cvt_f32_f16_sdwa v193, v193 dst_sel:DWORD dst_unused:UNUSED_PAD src0_sel:WORD_1
	s_waitcnt lgkmcnt(3)
	v_cvt_f32_f16_e32 v196, v197
	v_cvt_f32_f16_sdwa v197, v197 dst_sel:DWORD dst_unused:UNUSED_PAD src0_sel:WORD_1
	s_waitcnt lgkmcnt(2)
	v_cvt_f32_f16_e32 v198, v199
	v_cvt_f32_f16_sdwa v199, v199 dst_sel:DWORD dst_unused:UNUSED_PAD src0_sel:WORD_1
	s_waitcnt lgkmcnt(1)
	v_cvt_f32_f16_e32 v200, v201
	v_cvt_f32_f16_sdwa v201, v201 dst_sel:DWORD dst_unused:UNUSED_PAD src0_sel:WORD_1
	s_waitcnt vmcnt(3)
	ds_bpermute_b32 v202, v186, v206
	ds_bpermute_b32 v203, v186, v207
	ds_bpermute_b32 v204, v186, v208
	ds_bpermute_b32 v205, v186, v209
	s_waitcnt lgkmcnt(4)
	v_cvt_f32_f16_e32 v194, v195
	v_cvt_f32_f16_sdwa v195, v195 dst_sel:DWORD dst_unused:UNUSED_PAD src0_sel:WORD_1
	v_pk_fma_f32 v[126:127], v[126:127], v[156:157], v[172:173]
	v_pk_fma_f32 v[124:125], v[124:125], v[158:159], v[170:171]
	v_pk_fma_f32 v[122:123], v[122:123], v[152:153], v[192:193]
	v_pk_fma_f32 v[120:121], v[120:121], v[154:155], v[190:191]
	v_pk_fma_f32 v[118:119], v[118:119], v[148:149], v[196:197]
	v_pk_fma_f32 v[114:115], v[114:115], v[144:145], v[200:201]
	v_pk_fma_f32 v[112:113], v[112:113], v[146:147], v[198:199]
	v_pk_fma_f32 v[116:117], v[116:117], v[150:151], v[194:195]
	v_cvt_pk_f16_f32 v122, v122, v123
	v_cvt_pk_f16_f32 v123, v126, v127
	v_cvt_pk_f16_f32 v120, v120, v121
	v_cvt_pk_f16_f32 v121, v124, v125
	v_cvt_pk_f16_f32 v124, v114, v115
	v_cvt_pk_f16_f32 v118, v118, v119
	v_cvt_pk_f16_f32 v119, v112, v113
	v_cvt_pk_f16_f32 v116, v116, v117
	ds_bpermute_b32 v112, v187, v121
	ds_bpermute_b32 v113, v187, v123
	ds_bpermute_b32 v114, v187, v120
	ds_bpermute_b32 v115, v187, v122
	ds_bpermute_b32 v117, v187, v118
	ds_bpermute_b32 v118, v187, v119
	ds_bpermute_b32 v119, v187, v124
	s_waitcnt lgkmcnt(10)
	v_cvt_f32_f16_e32 v120, v202
	v_cvt_f32_f16_sdwa v121, v202 dst_sel:DWORD dst_unused:UNUSED_PAD src0_sel:WORD_1
	s_waitcnt lgkmcnt(9)
	v_cvt_f32_f16_e32 v122, v203
	v_cvt_f32_f16_sdwa v123, v203 dst_sel:DWORD dst_unused:UNUSED_PAD src0_sel:WORD_1
	s_waitcnt lgkmcnt(8)
	v_cvt_f32_f16_e32 v124, v204
	s_waitcnt lgkmcnt(7)
	v_cvt_f32_f16_e32 v126, v205
	v_cvt_f32_f16_sdwa v127, v205 dst_sel:DWORD dst_unused:UNUSED_PAD src0_sel:WORD_1
	v_cvt_f32_f16_sdwa v125, v204 dst_sel:DWORD dst_unused:UNUSED_PAD src0_sel:WORD_1
	v_pk_fma_f32 v[110:111], v[110:111], v[156:157], v[122:123]
	v_pk_fma_f32 v[108:109], v[108:109], v[158:159], v[120:121]
	v_pk_fma_f32 v[106:107], v[106:107], v[152:153], v[126:127]
	v_pk_fma_f32 v[104:105], v[104:105], v[154:155], v[124:125]
	v_cvt_pk_f16_f32 v106, v106, v107
	v_cvt_pk_f16_f32 v104, v104, v105
	v_cvt_pk_f16_f32 v105, v110, v111
	v_cvt_pk_f16_f32 v107, v108, v109
	ds_bpermute_b32 v108, v187, v107
	ds_bpermute_b32 v109, v187, v105
	ds_bpermute_b32 v110, v187, v104
	ds_bpermute_b32 v111, v187, v106
	global_load_dwordx4 v[120:123], v[166:167], off
	global_load_dwordx4 v[104:107], v[166:167], off offset:256
	ds_bpermute_b32 v116, v187, v116
	s_waitcnt lgkmcnt(8)
; __device__ __forceinline__ h16x8 f_to_h8(const f32x4 a, const f32x4 b) { return (h16x8){(_Float16)a[0], (_Float16)a[1], (_Float16)a[2], (_Float16)a[3], (_Float16)b[0], (_Float16)b[1], (_Float16)b[2], (_Float16)b[3]}; }
;     __device__ __forceinline__ void operator()(f32x4 (&acc)[2][2][4][2], const Unit& u, int wr, int wc, int fr, int fq) const {
;     ...
;             const int lane = fr + 16 * fq, rr = lane >> 2, cg = lane & 3;
;             const int pullx = (4 * fr + fq) * 4, pullr = (rr + 16 * cg) * 4;
;             _Float16* xc = xh + (size_t)(row_off + u.pm * BM + wr * 64 + rr) * D + u.pn * BM + wc * 32 + 8 * cg;
; #pragma unroll
;             for (int ai = 0; ai < 2; ++ai) {
;                 u32x4 xr[4][2];
; #pragma unroll
;                 for (int m = 0; m < 4; ++m)
; #pragma unroll
;                     for (int bj = 0; bj < 2; ++bj) xr[m][bj] = *(const u32x4*)(xc + (size_t)(ai * HALF + m * 16) * D + bj * HALF);
; #pragma unroll
;                 for (int m = 0; m < 4; ++m)
; #pragma unroll
;                     for (int bj = 0; bj < 2; ++bj) {
;                         u32x4 t;
; #pragma unroll
;                         for (int k = 0; k < 4; ++k) t[k] = (unsigned)__builtin_amdgcn_ds_bpermute(pullx, (int)xr[m][bj][k]);
;                         f32x4 b0, b1; h8_to_f(__builtin_bit_cast(h16x8, t), b0, b1);
;                         const u32x4 r = __builtin_bit_cast(u32x4, f_to_h8(b0 + gv[bj][0] * acc[ai][bj][m][0], b1 + gv[bj][1] * acc[ai][bj][m][1]));
;                         u32x4 o;
; #pragma unroll
;                         for (int k = 0; k < 4; ++k) o[k] = (unsigned)__builtin_amdgcn_ds_bpermute(pullr, (int)r[k]);
;                         *(u32x4*)(xc + (size_t)(ai * HALF + m * 16) * D + bj * HALF) = o; }
	global_store_dwordx4 v[160:161], v[112:115], off
	s_waitcnt lgkmcnt(0)
	global_store_dwordx4 v[160:161], v[116:119], off offset:256
	s_waitcnt vmcnt(6)
	ds_bpermute_b32 v112, v186, v210
	global_store_dwordx4 v[162:163], v[108:111], off
	ds_bpermute_b32 v111, v186, v211
	ds_bpermute_b32 v113, v186, v212
	ds_bpermute_b32 v115, v186, v213
	s_waitcnt lgkmcnt(3)
	v_cvt_f32_f16_e32 v108, v112
	v_cvt_f32_f16_sdwa v109, v112 dst_sel:DWORD dst_unused:UNUSED_PAD src0_sel:WORD_1
	s_waitcnt lgkmcnt(2)
	v_cvt_f32_f16_e32 v110, v111
	v_cvt_f32_f16_sdwa v111, v111 dst_sel:DWORD dst_unused:UNUSED_PAD src0_sel:WORD_1
	s_waitcnt lgkmcnt(1)
	v_cvt_f32_f16_e32 v112, v113
	s_waitcnt lgkmcnt(0)
	v_cvt_f32_f16_e32 v114, v115
	v_cvt_f32_f16_sdwa v115, v115 dst_sel:DWORD dst_unused:UNUSED_PAD src0_sel:WORD_1
	v_cvt_f32_f16_sdwa v113, v113 dst_sel:DWORD dst_unused:UNUSED_PAD src0_sel:WORD_1
	v_pk_fma_f32 v[102:103], v[102:103], v[148:149], v[110:111]
	v_pk_fma_f32 v[100:101], v[100:101], v[150:151], v[108:109]
	v_pk_fma_f32 v[98:99], v[98:99], v[144:145], v[114:115]
	v_pk_fma_f32 v[96:97], v[96:97], v[146:147], v[112:113]
	v_cvt_pk_f16_f32 v99, v98, v99
	v_cvt_pk_f16_f32 v98, v96, v97
	v_cvt_pk_f16_f32 v97, v102, v103
	v_cvt_pk_f16_f32 v96, v100, v101
	s_waitcnt vmcnt(6)
	ds_bpermute_b32 v101, v186, v230
	ds_bpermute_b32 v103, v186, v231
	ds_bpermute_b32 v109, v186, v232
	ds_bpermute_b32 v111, v186, v233
	ds_bpermute_b32 v96, v187, v96
	s_waitcnt lgkmcnt(4)
	v_cvt_f32_f16_e32 v100, v101
	v_cvt_f32_f16_sdwa v101, v101 dst_sel:DWORD dst_unused:UNUSED_PAD src0_sel:WORD_1
	s_waitcnt lgkmcnt(3)
	v_cvt_f32_f16_e32 v102, v103
	v_cvt_f32_f16_sdwa v103, v103 dst_sel:DWORD dst_unused:UNUSED_PAD src0_sel:WORD_1
	s_waitcnt lgkmcnt(2)
	v_cvt_f32_f16_e32 v108, v109
	s_waitcnt lgkmcnt(1)
	v_cvt_f32_f16_e32 v110, v111
	v_cvt_f32_f16_sdwa v111, v111 dst_sel:DWORD dst_unused:UNUSED_PAD src0_sel:WORD_1
	v_cvt_f32_f16_sdwa v109, v109 dst_sel:DWORD dst_unused:UNUSED_PAD src0_sel:WORD_1
	v_pk_fma_f32 v[94:95], v[94:95], v[156:157], v[102:103]
	v_pk_fma_f32 v[92:93], v[92:93], v[158:159], v[100:101]
	v_pk_fma_f32 v[90:91], v[90:91], v[152:153], v[110:111]
	v_pk_fma_f32 v[88:89], v[88:89], v[154:155], v[108:109]
	v_cvt_pk_f16_f32 v91, v90, v91
	v_cvt_pk_f16_f32 v90, v88, v89
	v_cvt_pk_f16_f32 v89, v94, v95
	v_cvt_pk_f16_f32 v88, v92, v93
	s_waitcnt vmcnt(5)
	ds_bpermute_b32 v93, v186, v128
	ds_bpermute_b32 v95, v186, v129
	ds_bpermute_b32 v101, v186, v130
	ds_bpermute_b32 v103, v186, v131
	v_add_co_u32_e32 v108, vcc, s0, v160
	s_waitcnt lgkmcnt(3)
	v_cvt_f32_f16_e32 v92, v93
	v_cvt_f32_f16_sdwa v93, v93 dst_sel:DWORD dst_unused:UNUSED_PAD src0_sel:WORD_1
	s_waitcnt lgkmcnt(2)
	v_cvt_f32_f16_e32 v94, v95
	v_cvt_f32_f16_sdwa v95, v95 dst_sel:DWORD dst_unused:UNUSED_PAD src0_sel:WORD_1
	s_waitcnt lgkmcnt(1)
	v_cvt_f32_f16_e32 v100, v101
	s_waitcnt lgkmcnt(0)
	v_cvt_f32_f16_e32 v102, v103
	v_cvt_f32_f16_sdwa v103, v103 dst_sel:DWORD dst_unused:UNUSED_PAD src0_sel:WORD_1
	v_cvt_f32_f16_sdwa v101, v101 dst_sel:DWORD dst_unused:UNUSED_PAD src0_sel:WORD_1
	v_addc_co_u32_e32 v109, vcc, 0, v161, vcc
	v_pk_fma_f32 v[94:95], v[86:87], v[148:149], v[94:95]
	v_pk_fma_f32 v[92:93], v[84:85], v[150:151], v[92:93]
	v_pk_fma_f32 v[78:79], v[78:79], v[144:145], v[102:103]
	global_load_dwordx4 v[84:87], v[108:109], off
	v_pk_fma_f32 v[76:77], v[76:77], v[146:147], v[100:101]
	v_cvt_pk_f16_f32 v79, v78, v79
	v_cvt_pk_f16_f32 v78, v76, v77
	v_cvt_pk_f16_f32 v77, v94, v95
	v_cvt_pk_f16_f32 v76, v92, v93
	s_mov_b32 s0, 0x90000
	ds_bpermute_b32 v97, v187, v97
	ds_bpermute_b32 v98, v187, v98
	ds_bpermute_b32 v99, v187, v99
	ds_bpermute_b32 v88, v187, v88
	ds_bpermute_b32 v89, v187, v89
	s_waitcnt vmcnt(5)
	ds_bpermute_b32 v93, v186, v120
	ds_bpermute_b32 v95, v186, v121
	ds_bpermute_b32 v101, v186, v122
	ds_bpermute_b32 v103, v186, v123
	s_waitcnt vmcnt(4)
	ds_bpermute_b32 v112, v186, v106
	s_waitcnt lgkmcnt(4)
	v_cvt_f32_f16_e32 v92, v93
	v_cvt_f32_f16_sdwa v93, v93 dst_sel:DWORD dst_unused:UNUSED_PAD src0_sel:WORD_1
	s_waitcnt lgkmcnt(3)
	v_cvt_f32_f16_e32 v94, v95
	v_cvt_f32_f16_sdwa v95, v95 dst_sel:DWORD dst_unused:UNUSED_PAD src0_sel:WORD_1
	s_waitcnt lgkmcnt(2)
	v_cvt_f32_f16_e32 v100, v101
	v_cvt_f32_f16_sdwa v101, v101 dst_sel:DWORD dst_unused:UNUSED_PAD src0_sel:WORD_1
	s_waitcnt lgkmcnt(1)
	v_cvt_f32_f16_e32 v102, v103
	v_cvt_f32_f16_sdwa v103, v103 dst_sel:DWORD dst_unused:UNUSED_PAD src0_sel:WORD_1
	v_pk_fma_f32 v[94:95], v[82:83], v[156:157], v[94:95]
	v_pk_fma_f32 v[92:93], v[80:81], v[158:159], v[92:93]
	global_load_dwordx4 v[80:83], v[108:109], off offset:256
	v_pk_fma_f32 v[72:73], v[72:73], v[154:155], v[100:101]
	v_pk_fma_f32 v[74:75], v[74:75], v[152:153], v[102:103]
	v_cvt_pk_f16_f32 v72, v72, v73
	v_cvt_pk_f16_f32 v73, v94, v95
	ds_bpermute_b32 v94, v187, v72
	ds_bpermute_b32 v72, v186, v104
	v_cvt_pk_f16_f32 v74, v74, v75
	v_cvt_pk_f16_f32 v75, v92, v93
	ds_bpermute_b32 v93, v187, v73
	ds_bpermute_b32 v73, v186, v105
	ds_bpermute_b32 v92, v187, v75
	ds_bpermute_b32 v95, v187, v74
	s_waitcnt lgkmcnt(4)
	v_cvt_f32_f16_e32 v74, v72
	v_cvt_f32_f16_sdwa v75, v72 dst_sel:DWORD dst_unused:UNUSED_PAD src0_sel:WORD_1
	v_add_co_u32_e32 v72, vcc, s0, v160
	s_waitcnt lgkmcnt(2)
	v_cvt_f32_f16_e32 v104, v73
	v_cvt_f32_f16_sdwa v105, v73 dst_sel:DWORD dst_unused:UNUSED_PAD src0_sel:WORD_1
	v_addc_co_u32_e32 v73, vcc, 0, v161, vcc
	global_load_dwordx4 v[100:103], v[72:73], off
	ds_bpermute_b32 v107, v186, v107
	v_cvt_f32_f16_e32 v106, v112
	ds_bpermute_b32 v90, v187, v90
	ds_bpermute_b32 v91, v187, v91
	ds_bpermute_b32 v76, v187, v76
	s_waitcnt lgkmcnt(3)
; __device__ __forceinline__ h16x8 f_to_h8(const f32x4 a, const f32x4 b) { return (h16x8){(_Float16)a[0], (_Float16)a[1], (_Float16)a[2], (_Float16)a[3], (_Float16)b[0], (_Float16)b[1], (_Float16)b[2], (_Float16)b[3]}; }
;     __device__ __forceinline__ void operator()(f32x4 (&acc)[2][2][4][2], const Unit& u, int wr, int wc, int fr, int fq) const {
;     ...
;             const int lane = fr + 16 * fq, rr = lane >> 2, cg = lane & 3;
;             const int pullx = (4 * fr + fq) * 4, pullr = (rr + 16 * cg) * 4;
;             _Float16* xc = xh + (size_t)(row_off + u.pm * BM + wr * 64 + rr) * D + u.pn * BM + wc * 32 + 8 * cg;
; #pragma unroll
;             for (int ai = 0; ai < 2; ++ai) {
;                 u32x4 xr[4][2];
; #pragma unroll
;                 for (int m = 0; m < 4; ++m)
; #pragma unroll
;                     for (int bj = 0; bj < 2; ++bj) xr[m][bj] = *(const u32x4*)(xc + (size_t)(ai * HALF + m * 16) * D + bj * HALF);
; #pragma unroll
;                 for (int m = 0; m < 4; ++m)
; #pragma unroll
;                     for (int bj = 0; bj < 2; ++bj) {
;                         u32x4 t;
; #pragma unroll
;                         for (int k = 0; k < 4; ++k) t[k] = (unsigned)__builtin_amdgcn_ds_bpermute(pullx, (int)xr[m][bj][k]);
;                         f32x4 b0, b1; h8_to_f(__builtin_bit_cast(h16x8, t), b0, b1);
;                         const u32x4 r = __builtin_bit_cast(u32x4, f_to_h8(b0 + gv[bj][0] * acc[ai][bj][m][0], b1 + gv[bj][1] * acc[ai][bj][m][1]));
;                         u32x4 o;
; #pragma unroll
;                         for (int k = 0; k < 4; ++k) o[k] = (unsigned)__builtin_amdgcn_ds_bpermute(pullr, (int)r[k]);
;                         *(u32x4*)(xc + (size_t)(ai * HALF + m * 16) * D + bj * HALF) = o; }
	v_cvt_f32_f16_e32 v110, v107
	v_cvt_f32_f16_sdwa v111, v107 dst_sel:DWORD dst_unused:UNUSED_PAD src0_sel:WORD_1
	v_cvt_f32_f16_sdwa v107, v112 dst_sel:DWORD dst_unused:UNUSED_PAD src0_sel:WORD_1
	ds_bpermute_b32 v77, v187, v77
	ds_bpermute_b32 v78, v187, v78
	ds_bpermute_b32 v79, v187, v79
	v_pk_fma_f32 v[70:71], v[70:71], v[148:149], v[104:105]
	v_pk_fma_f32 v[68:69], v[68:69], v[150:151], v[74:75]
	v_pk_fma_f32 v[66:67], v[66:67], v[144:145], v[110:111]
	v_pk_fma_f32 v[64:65], v[64:65], v[146:147], v[106:107]
	v_cvt_pk_f16_f32 v67, v66, v67
	v_cvt_pk_f16_f32 v66, v64, v65
	v_cvt_pk_f16_f32 v65, v70, v71
	v_cvt_pk_f16_f32 v64, v68, v69
	ds_bpermute_b32 v64, v187, v64
	ds_bpermute_b32 v65, v187, v65
	ds_bpermute_b32 v66, v187, v66
	ds_bpermute_b32 v67, v187, v67
	global_store_dwordx4 v[162:163], v[96:99], off offset:256
	s_waitcnt lgkmcnt(8)
	global_store_dwordx4 v[164:165], v[88:91], off
	s_waitcnt lgkmcnt(4)
	global_store_dwordx4 v[164:165], v[76:79], off offset:256
	global_store_dwordx4 v[166:167], v[92:95], off
	s_waitcnt lgkmcnt(0)
	global_store_dwordx4 v[166:167], v[64:67], off offset:256
	global_load_dwordx4 v[74:77], v[72:73], off offset:256
	s_mov_b32 s0, 0xa0000
	v_add_co_u32_e32 v68, vcc, s0, v160
	s_mov_b32 s0, 0xb0000
	s_nop 0
	v_addc_co_u32_e32 v69, vcc, 0, v161, vcc
	s_waitcnt vmcnt(8)
	ds_bpermute_b32 v79, v186, v84
	ds_bpermute_b32 v85, v186, v85
	ds_bpermute_b32 v98, v186, v86
	ds_bpermute_b32 v87, v186, v87
	global_load_dwordx4 v[88:91], v[68:69], off
	global_load_dwordx4 v[92:95], v[68:69], off offset:256
	s_waitcnt lgkmcnt(3)
	v_cvt_f32_f16_e32 v78, v79
	v_cvt_f32_f16_sdwa v79, v79 dst_sel:DWORD dst_unused:UNUSED_PAD src0_sel:WORD_1
	s_waitcnt lgkmcnt(2)
	v_cvt_f32_f16_e32 v84, v85
	v_cvt_f32_f16_sdwa v85, v85 dst_sel:DWORD dst_unused:UNUSED_PAD src0_sel:WORD_1
	s_waitcnt lgkmcnt(1)
	v_cvt_f32_f16_e32 v86, v98
	s_waitcnt lgkmcnt(0)
	v_cvt_f32_f16_e32 v96, v87
	v_cvt_f32_f16_sdwa v97, v87 dst_sel:DWORD dst_unused:UNUSED_PAD src0_sel:WORD_1
	v_cvt_f32_f16_sdwa v87, v98 dst_sel:DWORD dst_unused:UNUSED_PAD src0_sel:WORD_1
	v_pk_fma_f32 v[62:63], v[62:63], v[156:157], v[84:85]
	v_pk_fma_f32 v[60:61], v[60:61], v[158:159], v[78:79]
	v_pk_fma_f32 v[58:59], v[58:59], v[152:153], v[96:97]
	v_pk_fma_f32 v[56:57], v[56:57], v[154:155], v[86:87]
	v_cvt_pk_f16_f32 v59, v58, v59
	v_cvt_pk_f16_f32 v58, v56, v57
	v_cvt_pk_f16_f32 v57, v62, v63
	v_cvt_pk_f16_f32 v56, v60, v61
	v_add_co_u32_e32 v70, vcc, s0, v160
	ds_bpermute_b32 v56, v187, v56
	s_nop 0
	v_addc_co_u32_e32 v71, vcc, 0, v161, vcc
	global_load_dwordx4 v[64:67], v[70:71], off
	s_waitcnt vmcnt(10)
	ds_bpermute_b32 v61, v186, v80
	ds_bpermute_b32 v63, v186, v81
	ds_bpermute_b32 v79, v186, v82
	ds_bpermute_b32 v81, v186, v83
	ds_bpermute_b32 v57, v187, v57
	s_waitcnt lgkmcnt(4)
	v_cvt_f32_f16_e32 v60, v61
	v_cvt_f32_f16_sdwa v61, v61 dst_sel:DWORD dst_unused:UNUSED_PAD src0_sel:WORD_1
	s_waitcnt lgkmcnt(3)
	v_cvt_f32_f16_e32 v62, v63
	v_cvt_f32_f16_sdwa v63, v63 dst_sel:DWORD dst_unused:UNUSED_PAD src0_sel:WORD_1
	s_waitcnt lgkmcnt(2)
	v_cvt_f32_f16_e32 v78, v79
	s_waitcnt lgkmcnt(1)
	v_cvt_f32_f16_e32 v80, v81
	v_cvt_f32_f16_sdwa v81, v81 dst_sel:DWORD dst_unused:UNUSED_PAD src0_sel:WORD_1
	v_cvt_f32_f16_sdwa v79, v79 dst_sel:DWORD dst_unused:UNUSED_PAD src0_sel:WORD_1
	v_pk_fma_f32 v[54:55], v[54:55], v[148:149], v[62:63]
	v_pk_fma_f32 v[52:53], v[52:53], v[150:151], v[60:61]
	v_pk_fma_f32 v[50:51], v[50:51], v[144:145], v[80:81]
	v_pk_fma_f32 v[48:49], v[48:49], v[146:147], v[78:79]
	v_cvt_pk_f16_f32 v51, v50, v51
	v_cvt_pk_f16_f32 v50, v48, v49
	v_cvt_pk_f16_f32 v49, v54, v55
	v_cvt_pk_f16_f32 v48, v52, v53
	s_waitcnt vmcnt(9)
	ds_bpermute_b32 v53, v186, v100
	ds_bpermute_b32 v55, v186, v101
	ds_bpermute_b32 v61, v186, v102
	ds_bpermute_b32 v63, v186, v103
	ds_bpermute_b32 v58, v187, v58
	s_waitcnt lgkmcnt(4)
	v_cvt_f32_f16_e32 v52, v53
	v_cvt_f32_f16_sdwa v53, v53 dst_sel:DWORD dst_unused:UNUSED_PAD src0_sel:WORD_1
	s_waitcnt lgkmcnt(3)
	v_cvt_f32_f16_e32 v54, v55
	v_cvt_f32_f16_sdwa v55, v55 dst_sel:DWORD dst_unused:UNUSED_PAD src0_sel:WORD_1
	s_waitcnt lgkmcnt(2)
	v_cvt_f32_f16_e32 v60, v61
	s_waitcnt lgkmcnt(1)
	v_cvt_f32_f16_e32 v62, v63
	v_cvt_f32_f16_sdwa v63, v63 dst_sel:DWORD dst_unused:UNUSED_PAD src0_sel:WORD_1
	v_cvt_f32_f16_sdwa v61, v61 dst_sel:DWORD dst_unused:UNUSED_PAD src0_sel:WORD_1
	v_pk_fma_f32 v[46:47], v[46:47], v[156:157], v[54:55]
	v_pk_fma_f32 v[44:45], v[44:45], v[158:159], v[52:53]
	v_pk_fma_f32 v[42:43], v[42:43], v[152:153], v[62:63]
	v_pk_fma_f32 v[40:41], v[40:41], v[154:155], v[60:61]
	v_cvt_pk_f16_f32 v43, v42, v43
	v_cvt_pk_f16_f32 v42, v40, v41
	v_cvt_pk_f16_f32 v41, v46, v47
	v_cvt_pk_f16_f32 v40, v44, v45
	global_load_dwordx4 v[44:47], v[70:71], off offset:256
	ds_bpermute_b32 v59, v187, v59
	ds_bpermute_b32 v40, v187, v40
	ds_bpermute_b32 v41, v187, v41
	ds_bpermute_b32 v42, v187, v42
	ds_bpermute_b32 v43, v187, v43
	ds_bpermute_b32 v48, v187, v48
	ds_bpermute_b32 v49, v187, v49
	ds_bpermute_b32 v50, v187, v50
	ds_bpermute_b32 v51, v187, v51
	s_waitcnt lgkmcnt(8)
	global_store_dwordx4 v[108:109], v[56:59], off
	s_waitcnt lgkmcnt(0)
	global_store_dwordx4 v[108:109], v[48:51], off offset:256
	s_waitcnt vmcnt(6)
	ds_bpermute_b32 v48, v186, v74
	global_store_dwordx4 v[72:73], v[40:43], off
	ds_bpermute_b32 v43, v186, v75
	ds_bpermute_b32 v49, v186, v76
	ds_bpermute_b32 v51, v186, v77
	s_waitcnt lgkmcnt(3)
	v_cvt_f32_f16_e32 v40, v48
	v_cvt_f32_f16_sdwa v41, v48 dst_sel:DWORD dst_unused:UNUSED_PAD src0_sel:WORD_1
	s_waitcnt lgkmcnt(2)
	v_cvt_f32_f16_e32 v42, v43
	v_cvt_f32_f16_sdwa v43, v43 dst_sel:DWORD dst_unused:UNUSED_PAD src0_sel:WORD_1
	s_waitcnt lgkmcnt(1)
; __device__ __forceinline__ h16x8 f_to_h8(const f32x4 a, const f32x4 b) { return (h16x8){(_Float16)a[0], (_Float16)a[1], (_Float16)a[2], (_Float16)a[3], (_Float16)b[0], (_Float16)b[1], (_Float16)b[2], (_Float16)b[3]}; }
; template <class Epi>
; __device__ __forceinline__ void gemm_phase(LAS unsigned char* lds, const Gemm g, const StaticOrder& S, const Epi& E, const int tid) {
;     ...
;         if (!has_next) break;
;         if (!(Epi::CHAIN && cur.n + 1 < S.NS)) {
; #pragma unroll
;         for (int a = 0; a < 2; ++a)
; #pragma unroll
;             for (int b = 0; b < 2; ++b)
; #pragma unroll
;                 for (int m = 0; m < 4; ++m)
; #pragma unroll
;                     for (int n = 0; n < 2; ++n) acc[a][b][m][n] = (f32x4){0.f, 0.f, 0.f, 0.f};
;         }
;         cur = nxt; cA = nA; cB = nB; ++ui;
;         if (wr == 1) PG8_BAR;
;     __device__ __forceinline__ void operator()(f32x4 (&acc)[2][2][4][2], const Unit& u, int wr, int wc, int fr, int fq) const {
;     ...
;             const int lane = fr + 16 * fq, rr = lane >> 2, cg = lane & 3;
;             const int pullx = (4 * fr + fq) * 4, pullr = (rr + 16 * cg) * 4;
;             _Float16* xc = xh + (size_t)(row_off + u.pm * BM + wr * 64 + rr) * D + u.pn * BM + wc * 32 + 8 * cg;
; #pragma unroll
;             for (int ai = 0; ai < 2; ++ai) {
;                 u32x4 xr[4][2];
; #pragma unroll
;                 for (int m = 0; m < 4; ++m)
; #pragma unroll
;                     for (int bj = 0; bj < 2; ++bj) xr[m][bj] = *(const u32x4*)(xc + (size_t)(ai * HALF + m * 16) * D + bj * HALF);
; #pragma unroll
;                 for (int m = 0; m < 4; ++m)
; #pragma unroll
;                     for (int bj = 0; bj < 2; ++bj) {
;                         u32x4 t;
; #pragma unroll
;                         for (int k = 0; k < 4; ++k) t[k] = (unsigned)__builtin_amdgcn_ds_bpermute(pullx, (int)xr[m][bj][k]);
;                         f32x4 b0, b1; h8_to_f(__builtin_bit_cast(h16x8, t), b0, b1);
;                         const u32x4 r = __builtin_bit_cast(u32x4, f_to_h8(b0 + gv[bj][0] * acc[ai][bj][m][0], b1 + gv[bj][1] * acc[ai][bj][m][1]));
;                         u32x4 o;
; #pragma unroll
;                         for (int k = 0; k < 4; ++k) o[k] = (unsigned)__builtin_amdgcn_ds_bpermute(pullr, (int)r[k]);
;                         *(u32x4*)(xc + (size_t)(ai * HALF + m * 16) * D + bj * HALF) = o; }
	v_cvt_f32_f16_e32 v48, v49
	s_waitcnt lgkmcnt(0)
	v_cvt_f32_f16_e32 v50, v51
	v_cvt_f32_f16_sdwa v51, v51 dst_sel:DWORD dst_unused:UNUSED_PAD src0_sel:WORD_1
	v_cvt_f32_f16_sdwa v49, v49 dst_sel:DWORD dst_unused:UNUSED_PAD src0_sel:WORD_1
	v_pk_fma_f32 v[38:39], v[38:39], v[148:149], v[42:43]
	v_pk_fma_f32 v[36:37], v[36:37], v[150:151], v[40:41]
	v_pk_fma_f32 v[34:35], v[34:35], v[144:145], v[50:51]
	v_pk_fma_f32 v[32:33], v[32:33], v[146:147], v[48:49]
	v_cvt_pk_f16_f32 v35, v34, v35
	v_cvt_pk_f16_f32 v34, v32, v33
	v_cvt_pk_f16_f32 v33, v38, v39
	v_cvt_pk_f16_f32 v32, v36, v37
	s_waitcnt vmcnt(6)
	ds_bpermute_b32 v37, v186, v88
	ds_bpermute_b32 v39, v186, v89
	ds_bpermute_b32 v41, v186, v90
	ds_bpermute_b32 v43, v186, v91
	ds_bpermute_b32 v32, v187, v32
	s_waitcnt lgkmcnt(4)
	v_cvt_f32_f16_e32 v36, v37
	v_cvt_f32_f16_sdwa v37, v37 dst_sel:DWORD dst_unused:UNUSED_PAD src0_sel:WORD_1
	s_waitcnt lgkmcnt(3)
	v_cvt_f32_f16_e32 v38, v39
	v_cvt_f32_f16_sdwa v39, v39 dst_sel:DWORD dst_unused:UNUSED_PAD src0_sel:WORD_1
	s_waitcnt lgkmcnt(2)
	v_cvt_f32_f16_e32 v40, v41
	s_waitcnt lgkmcnt(1)
	v_cvt_f32_f16_e32 v42, v43
	v_cvt_f32_f16_sdwa v43, v43 dst_sel:DWORD dst_unused:UNUSED_PAD src0_sel:WORD_1
	v_cvt_f32_f16_sdwa v41, v41 dst_sel:DWORD dst_unused:UNUSED_PAD src0_sel:WORD_1
	v_pk_fma_f32 v[30:31], v[30:31], v[156:157], v[38:39]
	v_pk_fma_f32 v[28:29], v[28:29], v[158:159], v[36:37]
	v_pk_fma_f32 v[26:27], v[26:27], v[152:153], v[42:43]
	v_pk_fma_f32 v[24:25], v[24:25], v[154:155], v[40:41]
	v_cvt_pk_f16_f32 v27, v26, v27
	v_cvt_pk_f16_f32 v26, v24, v25
	v_cvt_pk_f16_f32 v25, v30, v31
	v_cvt_pk_f16_f32 v24, v28, v29
	s_waitcnt vmcnt(5)
	ds_bpermute_b32 v29, v186, v92
	ds_bpermute_b32 v31, v186, v93
	ds_bpermute_b32 v37, v186, v94
	ds_bpermute_b32 v39, v186, v95
	ds_bpermute_b32 v33, v187, v33
	s_waitcnt lgkmcnt(4)
	v_cvt_f32_f16_e32 v28, v29
	v_cvt_f32_f16_sdwa v29, v29 dst_sel:DWORD dst_unused:UNUSED_PAD src0_sel:WORD_1
	s_waitcnt lgkmcnt(3)
	v_cvt_f32_f16_e32 v30, v31
	v_cvt_f32_f16_sdwa v31, v31 dst_sel:DWORD dst_unused:UNUSED_PAD src0_sel:WORD_1
	s_waitcnt lgkmcnt(2)
	v_cvt_f32_f16_e32 v36, v37
	s_waitcnt lgkmcnt(1)
	v_cvt_f32_f16_e32 v38, v39
	v_cvt_f32_f16_sdwa v39, v39 dst_sel:DWORD dst_unused:UNUSED_PAD src0_sel:WORD_1
	v_cvt_f32_f16_sdwa v37, v37 dst_sel:DWORD dst_unused:UNUSED_PAD src0_sel:WORD_1
	v_pk_fma_f32 v[22:23], v[22:23], v[148:149], v[30:31]
	v_pk_fma_f32 v[20:21], v[20:21], v[150:151], v[28:29]
	v_pk_fma_f32 v[18:19], v[18:19], v[144:145], v[38:39]
	v_pk_fma_f32 v[16:17], v[16:17], v[146:147], v[36:37]
	v_cvt_pk_f16_f32 v19, v18, v19
	v_cvt_pk_f16_f32 v18, v16, v17
	v_cvt_pk_f16_f32 v17, v22, v23
	v_cvt_pk_f16_f32 v16, v20, v21
	s_waitcnt vmcnt(4)
	ds_bpermute_b32 v21, v186, v64
	ds_bpermute_b32 v23, v186, v65
	ds_bpermute_b32 v29, v186, v66
	ds_bpermute_b32 v31, v186, v67
	ds_bpermute_b32 v34, v187, v34
	s_waitcnt lgkmcnt(4)
	v_cvt_f32_f16_e32 v20, v21
	v_cvt_f32_f16_sdwa v21, v21 dst_sel:DWORD dst_unused:UNUSED_PAD src0_sel:WORD_1
	s_waitcnt lgkmcnt(3)
	v_cvt_f32_f16_e32 v22, v23
	v_cvt_f32_f16_sdwa v23, v23 dst_sel:DWORD dst_unused:UNUSED_PAD src0_sel:WORD_1
	s_waitcnt lgkmcnt(2)
	v_cvt_f32_f16_e32 v28, v29
	s_waitcnt lgkmcnt(1)
	v_cvt_f32_f16_e32 v30, v31
	v_cvt_f32_f16_sdwa v31, v31 dst_sel:DWORD dst_unused:UNUSED_PAD src0_sel:WORD_1
	v_cvt_f32_f16_sdwa v29, v29 dst_sel:DWORD dst_unused:UNUSED_PAD src0_sel:WORD_1
	v_pk_fma_f32 v[14:15], v[14:15], v[156:157], v[22:23]
	v_pk_fma_f32 v[12:13], v[12:13], v[158:159], v[20:21]
	v_pk_fma_f32 v[10:11], v[10:11], v[152:153], v[30:31]
	v_pk_fma_f32 v[8:9], v[8:9], v[154:155], v[28:29]
	v_cvt_pk_f16_f32 v11, v10, v11
	v_cvt_pk_f16_f32 v10, v8, v9
	v_cvt_pk_f16_f32 v9, v14, v15
	v_cvt_pk_f16_f32 v8, v12, v13
	s_waitcnt vmcnt(3)
	ds_bpermute_b32 v13, v186, v44
	ds_bpermute_b32 v15, v186, v45
	ds_bpermute_b32 v21, v186, v46
	ds_bpermute_b32 v23, v186, v47
	ds_bpermute_b32 v35, v187, v35
	s_waitcnt lgkmcnt(4)
	v_cvt_f32_f16_e32 v12, v13
	v_cvt_f32_f16_sdwa v13, v13 dst_sel:DWORD dst_unused:UNUSED_PAD src0_sel:WORD_1
	s_waitcnt lgkmcnt(3)
	v_cvt_f32_f16_e32 v14, v15
	v_cvt_f32_f16_sdwa v15, v15 dst_sel:DWORD dst_unused:UNUSED_PAD src0_sel:WORD_1
	s_waitcnt lgkmcnt(2)
	v_cvt_f32_f16_e32 v20, v21
	s_waitcnt lgkmcnt(1)
	v_cvt_f32_f16_e32 v22, v23
	v_cvt_f32_f16_sdwa v23, v23 dst_sel:DWORD dst_unused:UNUSED_PAD src0_sel:WORD_1
	v_cvt_f32_f16_sdwa v21, v21 dst_sel:DWORD dst_unused:UNUSED_PAD src0_sel:WORD_1
	ds_bpermute_b32 v24, v187, v24
	ds_bpermute_b32 v25, v187, v25
	ds_bpermute_b32 v26, v187, v26
	ds_bpermute_b32 v27, v187, v27
	ds_bpermute_b32 v16, v187, v16
	ds_bpermute_b32 v17, v187, v17
	ds_bpermute_b32 v18, v187, v18
	ds_bpermute_b32 v19, v187, v19
	v_pk_fma_f32 v[6:7], v[6:7], v[148:149], v[14:15]
	v_pk_fma_f32 v[4:5], v[4:5], v[150:151], v[12:13]
	v_pk_fma_f32 v[2:3], v[2:3], v[144:145], v[22:23]
	v_pk_fma_f32 v[0:1], v[0:1], v[146:147], v[20:21]
	ds_bpermute_b32 v8, v187, v8
	ds_bpermute_b32 v9, v187, v9
	ds_bpermute_b32 v10, v187, v10
	ds_bpermute_b32 v11, v187, v11
	v_cvt_pk_f16_f32 v3, v2, v3
	v_cvt_pk_f16_f32 v2, v0, v1
	v_cvt_pk_f16_f32 v1, v6, v7
	v_cvt_pk_f16_f32 v0, v4, v5
	ds_bpermute_b32 v0, v187, v0
	ds_bpermute_b32 v1, v187, v1
	ds_bpermute_b32 v2, v187, v2
	ds_bpermute_b32 v3, v187, v3
	s_and_b64 vcc, exec, s[36:37]
	s_mov_b64 s[0:1], -1
	s_waitcnt lgkmcnt(14)
	global_store_dwordx4 v[72:73], v[32:35], off offset:256
	s_waitcnt lgkmcnt(12)
	global_store_dwordx4 v[68:69], v[24:27], off
	s_waitcnt lgkmcnt(8)
	global_store_dwordx4 v[68:69], v[16:19], off offset:256
	s_waitcnt lgkmcnt(4)
	global_store_dwordx4 v[70:71], v[8:11], off
	s_waitcnt lgkmcnt(0)
	global_store_dwordx4 v[70:71], v[0:3], off offset:256
	s_cbranch_vccnz .LBB0_1064
	s_andn2_b64 vcc, exec, s[4:5]
	s_cbranch_vccnz .LBB0_1063
	s_barrier
	s_branch .LBB0_1063
